# adds: lane^16 exchanges via v_permlane16_swap + row select instead of ds_swizzle (with wide-store data WAR padding)
# speedup vs baseline: 1.0106x; 1.0003x over previous
; template <int K> __device__ __forceinline__ float shx(float v) { static_assert(K < 32, "use sum32"); return __int_as_float(__builtin_amdgcn_ds_swizzle(__float_as_int(v), (K << 10) | 0x1f)); }
; __device__ __forceinline__ float sum32(float v) { auto rr = __builtin_amdgcn_permlane32_swap(__float_as_uint(v), __float_as_uint(v), false, false); return __uint_as_float(rr[0]) + __uint_as_float(rr[1]); }
; #define GAS __attribute__((address_space(1)))
; __device__ __forceinline__ float wave_sum(float v) { v += shx<1>(v); v += shx<2>(v); v += shx<4>(v); v += shx<8>(v); v += shx<16>(v); return sum32(v); }
; __device__ __forceinline__ void rms_row_to_bf16(const float* xrow, const float* g, bf16* orow, int lane) {
;     const GAS f32x4* xr = (const GAS f32x4*)xrow + lane; const GAS f32x4* gr = (const GAS f32x4*)g + lane;
;     f32x4 v[8]; float s = 0.f;
; #pragma unroll
;     for (int j = 0; j < 8; ++j) { v[j] = __builtin_nontemporal_load(xr + 64 * j); s += (v[j].x * v[j].x + v[j].y * v[j].y) + (v[j].z * v[j].z + v[j].w * v[j].w); }
;     const float rstd = 1.0f / sqrtf(wave_sum(s) * (1.f / DM) + EPS);
.LBB0_108:
	s_cmpk_gt_i32 s6, 0x1fff
	s_mov_b64 s[0:1], -1
	s_cbranch_scc0 .LBB0_110
	s_add_i32 s20, s6, 0xffffe000
	s_lshl_b64 s[0:1], s[20:21], 12
	s_add_u32 s22, s81, s0
	s_addc_u32 s23, s88, s1
	s_lshl_b64 s[0:1], s[20:21], 13
	v_lshl_add_u64 v[2:3], v[56:57], 0, s[0:1]
	global_load_dwordx4 v[62:65], v[2:3], off nt
	global_load_dwordx4 v[66:69], v[2:3], off offset:1024 nt
	global_load_dwordx4 v[22:25], v[2:3], off offset:2048 nt
	global_load_dwordx4 v[18:21], v[2:3], off offset:3072 nt
	v_add_co_u32_e32 v2, vcc, s5, v2
	s_waitcnt vmcnt(3)
	v_mul_f32_e32 v26, v63, v63
	v_addc_co_u32_e32 v3, vcc, 0, v3, vcc
	global_load_dwordx4 v[14:17], v[2:3], off nt
	global_load_dwordx4 v[10:13], v[2:3], off offset:1024 nt
	global_load_dwordx4 v[6:9], v[2:3], off offset:2048 nt
	s_nop 0
	global_load_dwordx4 v[2:5], v[2:3], off offset:3072 nt
	s_nop 0
	global_load_dwordx4 v[70:73], v[30:31], off
	v_mul_f32_e32 v27, v65, v65
	s_waitcnt vmcnt(7)
	v_mul_f32_e32 v28, v67, v67
	v_mul_f32_e32 v29, v69, v69
	s_waitcnt vmcnt(6)
	v_mul_f32_e32 v40, v23, v23
	v_mul_f32_e32 v41, v25, v25
	v_fmac_f32_e32 v26, v62, v62
	v_fmac_f32_e32 v27, v64, v64
	v_fmac_f32_e32 v28, v66, v66
	v_fmac_f32_e32 v29, v68, v68
	s_waitcnt vmcnt(5)
	v_mul_f32_e32 v74, v19, v19
	v_mul_f32_e32 v75, v21, v21
	v_fmac_f32_e32 v40, v22, v22
	v_fmac_f32_e32 v41, v24, v24
	v_add_f32_e32 v26, v26, v27
	v_add_f32_e32 v27, v28, v29
	v_fmac_f32_e32 v74, v18, v18
	v_fmac_f32_e32 v75, v20, v20
	v_add_f32_e32 v28, v40, v41
	v_add_f32_e32 v26, v26, v27
	v_add_f32_e32 v29, v74, v75
	v_add_f32_e32 v26, v26, v28
	v_add_f32_e32 v26, v26, v29
	s_waitcnt vmcnt(4)
	v_mul_f32_e32 v76, v15, v15
	v_mul_f32_e32 v77, v17, v17
	s_waitcnt vmcnt(3)
	v_mul_f32_e32 v78, v11, v11
	v_mul_f32_e32 v79, v13, v13
	v_fmac_f32_e32 v76, v14, v14
	v_fmac_f32_e32 v77, v16, v16
	s_waitcnt vmcnt(2)
	v_mul_f32_e32 v80, v7, v7
	v_mul_f32_e32 v81, v9, v9
	v_fmac_f32_e32 v78, v10, v10
	v_fmac_f32_e32 v79, v12, v12
	v_add_f32_e32 v27, v76, v77
	s_waitcnt vmcnt(1)
	global_load_dwordx4 v[96:99], v[30:31], off offset:1024
	global_load_dwordx4 v[100:103], v[30:31], off offset:2048
	global_load_dwordx4 v[104:107], v[30:31], off offset:3072
	global_load_dwordx4 v[108:111], v[32:33], off
	global_load_dwordx4 v[112:115], v[34:35], off
	global_load_dwordx4 v[116:119], v[36:37], off
	global_load_dwordx4 v[120:123], v[42:43], off
	v_mul_f32_e32 v82, v3, v3
	v_mul_f32_e32 v83, v5, v5
	v_fmac_f32_e32 v80, v6, v6
	v_fmac_f32_e32 v81, v8, v8
	v_add_f32_e32 v40, v78, v79
	v_add_f32_e32 v26, v26, v27
	v_fmac_f32_e32 v82, v2, v2
	v_fmac_f32_e32 v83, v4, v4
	v_add_f32_e32 v41, v80, v81
	v_add_f32_e32 v26, v26, v40
	v_add_f32_e32 v74, v82, v83
	v_add_f32_e32 v26, v26, v41
	v_add_f32_e32 v26, v26, v74
	s_nop 1
	v_mov_b32_dpp v27, v26 quad_perm:[1,0,3,2] row_mask:0xf bank_mask:0xf
	s_waitcnt lgkmcnt(0)
	v_add_f32_e32 v26, v26, v27
	s_nop 1
	v_mov_b32_dpp v27, v26 quad_perm:[2,3,0,1] row_mask:0xf bank_mask:0xf
	s_waitcnt lgkmcnt(0)
	v_add_f32_e32 v26, v26, v27
	s_nop 1
	v_mov_b32_dpp v27, v26 quad_perm:[3,2,1,0] row_mask:0xf bank_mask:0xf
	s_nop 1
	v_mov_b32_dpp v27, v27 row_half_mirror row_mask:0xf bank_mask:0xf
	s_waitcnt lgkmcnt(0)
	v_add_f32_e32 v26, v26, v27
	s_nop 1
	v_mov_b32_dpp v27, v26 row_half_mirror row_mask:0xf bank_mask:0xf
	s_nop 1
	v_mov_b32_dpp v27, v27 row_mirror row_mask:0xf bank_mask:0xf
	s_waitcnt lgkmcnt(0)
	v_add_f32_e32 v26, v26, v27
	s_nop 1
	v_mov_b32_e32 v27, v26
	v_mov_b32_e32 v253, v26
	s_nop 1
	v_permlane16_swap_b32_e32 v27, v253
	s_mov_b32 s98, 0xffff
	s_mov_b32 s99, 0xffff
	v_cndmask_b32_e64 v27, v27, v253, s[98:99]
	s_waitcnt lgkmcnt(0)
	v_add_f32_e32 v26, v26, v27
	v_mov_b32_e32 v27, v26
	s_nop 1
	v_permlane32_swap_b32_e32 v26, v27
	v_add_f32_e32 v26, v26, v27
	v_fmamk_f32 v26, v26, 0x3a000000, v44
	v_mul_f32_e32 v27, 0x4f800000, v26
	v_cmp_gt_f32_e32 vcc, s7, v26
	s_nop 1
	v_cndmask_b32_e32 v26, v26, v27, vcc
	v_sqrt_f32_e32 v27, v26
	s_nop 0
	v_add_u32_e32 v28, -1, v27
	v_add_u32_e32 v29, 1, v27
	v_fma_f32 v40, -v28, v27, v26
	v_fma_f32 v41, -v29, v27, v26
	v_cmp_ge_f32_e64 s[0:1], 0, v40
	s_nop 1
	v_cndmask_b32_e64 v27, v27, v28, s[0:1]
	v_cmp_lt_f32_e64 s[0:1], 0, v41
	s_nop 1
	v_cndmask_b32_e64 v27, v27, v29, s[0:1]
	v_mul_f32_e32 v28, 0x37800000, v27
	v_cndmask_b32_e32 v27, v27, v28, vcc
	v_cmp_class_f32_e32 vcc, v26, v45
	s_nop 1
	v_cndmask_b32_e32 v26, v27, v26, vcc
	v_div_scale_f32 v27, s[0:1], v26, v26, 1.0
	v_rcp_f32_e32 v28, v27
	v_div_scale_f32 v29, vcc, 1.0, v26, 1.0
	s_mov_b64 s[0:1], 0
	v_fma_f32 v40, -v27, v28, 1.0
	v_fmac_f32_e32 v28, v40, v28
	v_mul_f32_e32 v40, v29, v28
	v_fma_f32 v41, -v27, v40, v29
	v_fmac_f32_e32 v40, v41, v28
	v_fma_f32 v27, -v27, v40, v29
	v_div_fmas_f32 v27, v27, v28, v40
	v_div_fixup_f32 v26, v27, v26, 1.0
	v_mul_f32_e32 v27, v62, v26
	v_mul_f32_e32 v29, v64, v26
	v_mul_f32_e32 v28, v63, v26
	v_mul_f32_e32 v40, v65, v26
	s_waitcnt vmcnt(0)
; #define GAS __attribute__((address_space(1)))
; __device__ __forceinline__ unsigned f2bf(float f) { unsigned u = __builtin_bit_cast(unsigned, f); return (u + 0x7fffu + ((u >> 16) & 1u)) >> 16; }
; __device__ __forceinline__ unsigned pk2(float lo, float hi) { return f2bf(lo) | (f2bf(hi) << 16); }
; __device__ __forceinline__ void rms_row_to_bf16(const float* xrow, const float* g, bf16* orow, int lane) {
;     ...
;     GAS unsigned long long* o8 = (GAS unsigned long long*)orow + lane;
; #pragma unroll
;     for (int j = 0; j < 8; ++j) { const f32x4 gg = gr[64 * j]; o8[64 * j] = (unsigned long long)pk2(v[j].x * rstd * gg.x, v[j].y * rstd * gg.y) | ((unsigned long long)pk2(v[j].z * rstd * gg.z, v[j].w * rstd * gg.w) << 32); }
	v_mul_f32_e32 v27, v70, v27
	v_mul_f32_e32 v29, v72, v29
	v_mul_f32_e32 v28, v71, v28
	v_mul_f32_e32 v40, v73, v40
	v_bfe_u32 v41, v27, 16, 1
	v_bfe_u32 v63, v29, 16, 1
	v_bfe_u32 v62, v28, 16, 1
	v_bfe_u32 v64, v40, 16, 1
	v_add3_u32 v27, v27, v41, s26
	v_add3_u32 v29, v29, v63, s26
	v_add3_u32 v28, v28, v62, s26
	v_add3_u32 v40, v40, v64, s26
	v_lshrrev_b32_e32 v27, 16, v27
	v_lshrrev_b32_e32 v29, 16, v29
	v_and_or_b32 v28, v28, s27, v27
	v_and_or_b32 v29, v40, s27, v29
	global_store_dwordx2 v60, v[28:29], s[22:23]
	v_mul_f32_e32 v27, v66, v26
	v_mul_f32_e32 v29, v68, v26
	v_mul_f32_e32 v28, v67, v26
	v_mul_f32_e32 v40, v69, v26
	v_mul_f32_e32 v22, v22, v26
	v_mul_f32_e32 v24, v24, v26
	v_mul_f32_e32 v23, v23, v26
	v_mul_f32_e32 v25, v25, v26
	v_mul_f32_e32 v18, v18, v26
	v_mul_f32_e32 v20, v20, v26
	v_mul_f32_e32 v19, v19, v26
	v_mul_f32_e32 v21, v21, v26
	v_mul_f32_e32 v14, v14, v26
	v_mul_f32_e32 v16, v16, v26
	v_mul_f32_e32 v15, v15, v26
	v_mul_f32_e32 v17, v17, v26
	v_mul_f32_e32 v10, v10, v26
	v_mul_f32_e32 v12, v12, v26
	v_mul_f32_e32 v11, v11, v26
	v_mul_f32_e32 v13, v13, v26
	v_mul_f32_e32 v6, v6, v26
	v_mul_f32_e32 v8, v8, v26
	v_mul_f32_e32 v7, v7, v26
	v_mul_f32_e32 v9, v9, v26
	v_mov_b32_e32 v62, v96
	v_mov_b32_e32 v63, v97
	v_mov_b32_e32 v64, v98
	v_mov_b32_e32 v65, v99
	v_mul_f32_e32 v27, v62, v27
	v_mul_f32_e32 v29, v64, v29
	v_mul_f32_e32 v28, v63, v28
	v_mul_f32_e32 v40, v65, v40
	v_bfe_u32 v41, v27, 16, 1
	v_bfe_u32 v63, v29, 16, 1
	v_bfe_u32 v62, v28, 16, 1
	v_bfe_u32 v64, v40, 16, 1
	v_add3_u32 v27, v27, v41, s26
	v_add3_u32 v29, v29, v63, s26
	v_add3_u32 v28, v28, v62, s26
	v_add3_u32 v40, v40, v64, s26
	v_lshrrev_b32_e32 v27, 16, v27
	v_lshrrev_b32_e32 v29, 16, v29
	v_and_or_b32 v28, v28, s27, v27
	v_and_or_b32 v29, v40, s27, v29
	global_store_dwordx2 v60, v[28:29], s[22:23] offset:512
	v_mov_b32_e32 v62, v100
	v_mov_b32_e32 v63, v101
	v_mov_b32_e32 v64, v102
	v_mov_b32_e32 v65, v103
	v_mul_f32_e32 v22, v62, v22
	v_mul_f32_e32 v24, v64, v24
	v_mul_f32_e32 v23, v63, v23
	v_mul_f32_e32 v25, v65, v25
	v_bfe_u32 v27, v22, 16, 1
	v_bfe_u32 v29, v24, 16, 1
	v_bfe_u32 v28, v23, 16, 1
	v_bfe_u32 v40, v25, 16, 1
	v_add3_u32 v22, v22, v27, s26
	v_add3_u32 v24, v24, v29, s26
	v_add3_u32 v23, v23, v28, s26
	v_add3_u32 v25, v25, v40, s26
	v_lshrrev_b32_e32 v22, 16, v22
	v_lshrrev_b32_e32 v24, 16, v24
	v_and_or_b32 v22, v23, s27, v22
	v_and_or_b32 v23, v25, s27, v24
	global_store_dwordx2 v60, v[22:23], s[22:23] offset:1024
	v_pk_mul_f32 v[2:3], v[2:3], v[26:27] op_sel_hi:[1,0]
	v_mul_f32_e32 v27, v4, v26
	v_mov_b32_e32 v22, v104
	v_mov_b32_e32 v23, v105
	v_mov_b32_e32 v24, v106
	v_mov_b32_e32 v25, v107
	v_mul_f32_e32 v18, v18, v22
	v_mul_f32_e32 v20, v20, v24
	v_mul_f32_e32 v19, v19, v23
	v_mul_f32_e32 v21, v21, v25
	v_bfe_u32 v22, v18, 16, 1
	v_bfe_u32 v24, v20, 16, 1
	v_bfe_u32 v23, v19, 16, 1
	v_bfe_u32 v25, v21, 16, 1
	v_add3_u32 v18, v18, v22, s26
	v_add3_u32 v20, v20, v24, s26
	v_add3_u32 v19, v19, v23, s26
	v_add3_u32 v21, v21, v25, s26
	v_lshrrev_b32_e32 v18, 16, v18
	v_lshrrev_b32_e32 v20, 16, v20
	v_and_or_b32 v18, v19, s27, v18
	v_and_or_b32 v19, v21, s27, v20
	global_store_dwordx2 v60, v[18:19], s[22:23] offset:1536
	v_mov_b32_e32 v18, v108
	v_mov_b32_e32 v19, v109
	v_mov_b32_e32 v20, v110
	v_mov_b32_e32 v21, v111
	v_mul_f32_e32 v14, v14, v18
	v_mul_f32_e32 v16, v16, v20
	v_mul_f32_e32 v15, v15, v19
	v_mul_f32_e32 v17, v17, v21
	v_bfe_u32 v18, v14, 16, 1
	v_bfe_u32 v20, v16, 16, 1
	v_bfe_u32 v19, v15, 16, 1
	v_bfe_u32 v21, v17, 16, 1
	v_add3_u32 v14, v14, v18, s26
	v_add3_u32 v16, v16, v20, s26
	v_add3_u32 v15, v15, v19, s26
	v_add3_u32 v17, v17, v21, s26
	v_lshrrev_b32_e32 v14, 16, v14
	v_lshrrev_b32_e32 v16, 16, v16
	v_and_or_b32 v14, v15, s27, v14
	v_and_or_b32 v15, v17, s27, v16
	global_store_dwordx2 v60, v[14:15], s[22:23] offset:2048
	v_mov_b32_e32 v14, v112
	v_mov_b32_e32 v15, v113
	v_mov_b32_e32 v16, v114
	v_mov_b32_e32 v17, v115
	v_mul_f32_e32 v10, v10, v14
	v_mul_f32_e32 v12, v12, v16
	v_mul_f32_e32 v11, v11, v15
	v_mul_f32_e32 v13, v13, v17
	v_bfe_u32 v14, v10, 16, 1
	v_bfe_u32 v16, v12, 16, 1
	v_bfe_u32 v15, v11, 16, 1
	v_bfe_u32 v17, v13, 16, 1
	v_add3_u32 v10, v10, v14, s26
	v_add3_u32 v12, v12, v16, s26
	v_add3_u32 v11, v11, v15, s26
	v_add3_u32 v13, v13, v17, s26
	v_lshrrev_b32_e32 v10, 16, v10
	v_lshrrev_b32_e32 v12, 16, v12
	v_and_or_b32 v10, v11, s27, v10
	v_and_or_b32 v11, v13, s27, v12
	global_store_dwordx2 v60, v[10:11], s[22:23] offset:2560
	v_mov_b32_e32 v10, v116
	v_mov_b32_e32 v11, v117
	v_mov_b32_e32 v12, v118
	v_mov_b32_e32 v13, v119
	v_mul_f32_e32 v6, v6, v10
	v_mul_f32_e32 v8, v8, v12
	v_mul_f32_e32 v7, v7, v11
	v_mul_f32_e32 v9, v9, v13
	v_bfe_u32 v10, v6, 16, 1
	v_bfe_u32 v12, v8, 16, 1
	v_bfe_u32 v11, v7, 16, 1
	v_bfe_u32 v13, v9, 16, 1
	v_add3_u32 v6, v6, v10, s26
	v_add3_u32 v8, v8, v12, s26
	v_add3_u32 v7, v7, v11, s26
	v_add3_u32 v9, v9, v13, s26
	v_lshrrev_b32_e32 v6, 16, v6
	v_lshrrev_b32_e32 v8, 16, v8
	v_and_or_b32 v6, v7, s27, v6
	v_and_or_b32 v7, v9, s27, v8
	global_store_dwordx2 v60, v[6:7], s[22:23] offset:3072
	v_mov_b32_e32 v6, v120
	v_mov_b32_e32 v7, v121
	v_mov_b32_e32 v8, v122
	v_mov_b32_e32 v9, v123
	v_pk_mul_f32 v[2:3], v[2:3], v[6:7]
	s_nop 0
	v_and_b32_sdwa v7, v2, v61 dst_sel:DWORD dst_unused:UNUSED_PAD src0_sel:WORD_1 src1_sel:DWORD
	v_and_b32_sdwa v6, v3, v61 dst_sel:DWORD dst_unused:UNUSED_PAD src0_sel:WORD_1 src1_sel:DWORD
	v_add3_u32 v2, v2, v7, s26
	v_pk_mov_b32 v[4:5], v[4:5], v[8:9] op_sel:[1,0]
	v_add3_u32 v3, v3, v6, s26
	v_lshrrev_b32_e32 v2, 16, v2
	v_pk_mul_f32 v[4:5], v[4:5], v[26:27]
	v_and_or_b32 v2, v3, s27, v2
; template <int K> __device__ __forceinline__ float shx(float v) { static_assert(K < 32, "use sum32"); return __int_as_float(__builtin_amdgcn_ds_swizzle(__float_as_int(v), (K << 10) | 0x1f)); }
; __device__ __forceinline__ float sum32(float v) { auto rr = __builtin_amdgcn_permlane32_swap(__float_as_uint(v), __float_as_uint(v), false, false); return __uint_as_float(rr[0]) + __uint_as_float(rr[1]); }
; #define GAS __attribute__((address_space(1)))
; __device__ __forceinline__ float wave_sum(float v) { v += shx<1>(v); v += shx<2>(v); v += shx<4>(v); v += shx<8>(v); v += shx<16>(v); return sum32(v); }
; __device__ __forceinline__ void rms_row_to_bf16(const float* xrow, const float* g, bf16* orow, int lane) {
;     const GAS f32x4* xr = (const GAS f32x4*)xrow + lane; const GAS f32x4* gr = (const GAS f32x4*)g + lane;
;     f32x4 v[8]; float s = 0.f;
; #pragma unroll
;     for (int j = 0; j < 8; ++j) { v[j] = __builtin_nontemporal_load(xr + 64 * j); s += (v[j].x * v[j].x + v[j].y * v[j].y) + (v[j].z * v[j].z + v[j].w * v[j].w); }
;     const float rstd = 1.0f / sqrtf(wave_sum(s) * (1.f / DM) + EPS);
.LBB0_110:
	s_andn2_b64 vcc, exec, s[0:1]
	s_cbranch_vccnz .LBB0_107
	global_load_dwordx4 v[62:65], v[58:59], off offset:-4096 nt
	global_load_dwordx4 v[26:29], v[58:59], off offset:-3072 nt
	global_load_dwordx4 v[22:25], v[58:59], off offset:-2048 nt
	global_load_dwordx4 v[18:21], v[58:59], off offset:-1024 nt
	global_load_dwordx4 v[14:17], v[58:59], off nt
	global_load_dwordx4 v[10:13], v[58:59], off offset:1024 nt
	global_load_dwordx4 v[6:9], v[58:59], off offset:2048 nt
	global_load_dwordx4 v[2:5], v[58:59], off offset:3072 nt
	global_load_dwordx4 v[66:69], v[46:47], off
	s_add_u32 s22, s16, 0x6900000
	s_addc_u32 s23, s17, 0
	s_waitcnt vmcnt(8)
	v_mul_f32_e32 v40, v63, v63
	v_mul_f32_e32 v41, v65, v65
	s_waitcnt vmcnt(7)
	v_mul_f32_e32 v70, v27, v27
	v_mul_f32_e32 v71, v29, v29
	s_waitcnt vmcnt(6)
	v_mul_f32_e32 v72, v23, v23
	v_mul_f32_e32 v73, v25, v25
	v_fmac_f32_e32 v40, v62, v62
	v_fmac_f32_e32 v41, v64, v64
	v_fmac_f32_e32 v70, v26, v26
	v_fmac_f32_e32 v71, v28, v28
	s_waitcnt vmcnt(5)
	v_mul_f32_e32 v74, v19, v19
	v_mul_f32_e32 v75, v21, v21
	v_fmac_f32_e32 v72, v22, v22
	v_fmac_f32_e32 v73, v24, v24
	v_add_f32_e32 v40, v40, v41
	v_add_f32_e32 v41, v70, v71
	s_waitcnt vmcnt(4)
	v_mul_f32_e32 v76, v15, v15
	v_mul_f32_e32 v77, v17, v17
	v_fmac_f32_e32 v74, v18, v18
	v_fmac_f32_e32 v75, v20, v20
	v_add_f32_e32 v70, v72, v73
	v_add_f32_e32 v40, v40, v41
	s_waitcnt vmcnt(3)
	v_mul_f32_e32 v78, v11, v11
	v_mul_f32_e32 v79, v13, v13
	v_fmac_f32_e32 v76, v14, v14
	v_fmac_f32_e32 v77, v16, v16
	v_add_f32_e32 v71, v74, v75
	v_add_f32_e32 v40, v40, v70
	s_waitcnt vmcnt(2)
	v_mul_f32_e32 v80, v7, v7
	v_mul_f32_e32 v81, v9, v9
	v_fmac_f32_e32 v78, v10, v10
	v_fmac_f32_e32 v79, v12, v12
	v_add_f32_e32 v72, v76, v77
	v_add_f32_e32 v40, v40, v71
	s_waitcnt vmcnt(1)
	global_load_dwordx4 v[96:99], v[46:47], off offset:1024
	global_load_dwordx4 v[100:103], v[46:47], off offset:2048
	global_load_dwordx4 v[104:107], v[46:47], off offset:3072
	global_load_dwordx4 v[108:111], v[48:49], off
	global_load_dwordx4 v[112:115], v[50:51], off
	global_load_dwordx4 v[116:119], v[52:53], off
	global_load_dwordx4 v[120:123], v[54:55], off
	v_mul_f32_e32 v82, v3, v3
	v_mul_f32_e32 v83, v5, v5
	v_fmac_f32_e32 v80, v6, v6
	v_fmac_f32_e32 v81, v8, v8
	v_add_f32_e32 v73, v78, v79
	v_add_f32_e32 v40, v40, v72
	v_fmac_f32_e32 v82, v2, v2
	v_fmac_f32_e32 v83, v4, v4
	v_add_f32_e32 v74, v80, v81
	v_add_f32_e32 v40, v40, v73
	v_add_f32_e32 v75, v82, v83
	v_add_f32_e32 v40, v40, v74
	v_add_f32_e32 v40, v40, v75
	s_nop 1
	v_mov_b32_dpp v41, v40 quad_perm:[1,0,3,2] row_mask:0xf bank_mask:0xf
	s_waitcnt lgkmcnt(0)
	v_add_f32_e32 v40, v40, v41
	s_nop 1
	v_mov_b32_dpp v41, v40 quad_perm:[2,3,0,1] row_mask:0xf bank_mask:0xf
	s_waitcnt lgkmcnt(0)
	v_add_f32_e32 v40, v40, v41
	s_nop 1
	v_mov_b32_dpp v41, v40 quad_perm:[3,2,1,0] row_mask:0xf bank_mask:0xf
	s_nop 1
	v_mov_b32_dpp v41, v41 row_half_mirror row_mask:0xf bank_mask:0xf
	s_waitcnt lgkmcnt(0)
	v_add_f32_e32 v40, v40, v41
	s_nop 1
	v_mov_b32_dpp v41, v40 row_half_mirror row_mask:0xf bank_mask:0xf
	s_nop 1
	v_mov_b32_dpp v41, v41 row_mirror row_mask:0xf bank_mask:0xf
	s_waitcnt lgkmcnt(0)
	v_add_f32_e32 v40, v40, v41
	s_nop 1
	v_mov_b32_e32 v41, v40
	v_mov_b32_e32 v253, v40
	s_nop 1
	v_permlane16_swap_b32_e32 v41, v253
	s_mov_b32 s98, 0xffff
	s_mov_b32 s99, 0xffff
	v_cndmask_b32_e64 v41, v41, v253, s[98:99]
	s_waitcnt lgkmcnt(0)
	v_add_f32_e32 v40, v40, v41
	v_mov_b32_e32 v41, v40
	s_nop 1
	v_permlane32_swap_b32_e32 v40, v41
	v_add_f32_e32 v40, v40, v41
	v_fmamk_f32 v40, v40, 0x3a000000, v44
	v_mul_f32_e32 v41, 0x4f800000, v40
	v_cmp_gt_f32_e32 vcc, s7, v40
	s_nop 1
	v_cndmask_b32_e32 v70, v40, v41, vcc
	v_sqrt_f32_e32 v71, v70
	v_lshl_add_u64 v[40:41], s[16:17], 0, v[38:39]
	v_add_u32_e32 v72, -1, v71
	v_add_u32_e32 v73, 1, v71
	v_fma_f32 v74, -v72, v71, v70
	v_fma_f32 v75, -v73, v71, v70
	v_cmp_ge_f32_e64 s[0:1], 0, v74
	s_nop 1
	v_cndmask_b32_e64 v71, v71, v72, s[0:1]
	v_cmp_lt_f32_e64 s[0:1], 0, v75
	s_nop 1
	v_cndmask_b32_e64 v71, v71, v73, s[0:1]
	v_mul_f32_e32 v72, 0x37800000, v71
	v_cndmask_b32_e32 v71, v71, v72, vcc
	v_cmp_class_f32_e32 vcc, v70, v45
	s_nop 1
	v_cndmask_b32_e32 v72, v71, v70, vcc
	v_div_scale_f32 v73, s[0:1], v72, v72, 1.0
	v_rcp_f32_e32 v74, v73
	v_add_co_u32_e32 v70, vcc, s28, v40
	s_nop 1
	v_addc_co_u32_e32 v71, vcc, 0, v41, vcc
	v_fma_f32 v41, -v73, v74, 1.0
	v_div_scale_f32 v40, vcc, 1.0, v72, 1.0
	v_fmac_f32_e32 v74, v41, v74
	v_mul_f32_e32 v41, v40, v74
	v_fma_f32 v75, -v73, v41, v40
	v_fmac_f32_e32 v41, v75, v74
	v_fma_f32 v40, -v73, v41, v40
	v_div_fmas_f32 v40, v40, v74, v41
	v_div_fixup_f32 v40, v40, v72, 1.0
	v_mul_f32_e32 v41, v62, v40
	v_mul_f32_e32 v62, v63, v40
	v_mul_f32_e32 v63, v64, v40
	v_mul_f32_e32 v64, v65, v40
	s_waitcnt vmcnt(0)
; #define GAS __attribute__((address_space(1)))
; __device__ __forceinline__ unsigned f2bf(float f) { unsigned u = __builtin_bit_cast(unsigned, f); return (u + 0x7fffu + ((u >> 16) & 1u)) >> 16; }
; __device__ __forceinline__ unsigned pk2(float lo, float hi) { return f2bf(lo) | (f2bf(hi) << 16); }
; __device__ __forceinline__ void rms_row_to_bf16(const float* xrow, const float* g, bf16* orow, int lane) {
;     ...
;     GAS unsigned long long* o8 = (GAS unsigned long long*)orow + lane;
; #pragma unroll
;     for (int j = 0; j < 8; ++j) { const f32x4 gg = gr[64 * j]; o8[64 * j] = (unsigned long long)pk2(v[j].x * rstd * gg.x, v[j].y * rstd * gg.y) | ((unsigned long long)pk2(v[j].z * rstd * gg.z, v[j].w * rstd * gg.w) << 32); }
	v_mul_f32_e32 v41, v66, v41
	v_mul_f32_e32 v63, v68, v63
	v_mul_f32_e32 v62, v67, v62
	v_mul_f32_e32 v64, v69, v64
	v_bfe_u32 v65, v41, 16, 1
	v_bfe_u32 v67, v63, 16, 1
	v_bfe_u32 v66, v62, 16, 1
	v_bfe_u32 v68, v64, 16, 1
	v_add3_u32 v41, v41, v65, s26
	v_add3_u32 v63, v63, v67, s26
	v_add3_u32 v62, v62, v66, s26
	v_add3_u32 v64, v64, v68, s26
	v_lshrrev_b32_e32 v41, 16, v41
	v_lshrrev_b32_e32 v63, 16, v63
	v_and_or_b32 v62, v62, s27, v41
	v_and_or_b32 v63, v64, s27, v63
	global_store_dwordx2 v[70:71], v[62:63], off
	v_mul_f32_e32 v26, v26, v40
	v_mul_f32_e32 v28, v28, v40
	v_mul_f32_e32 v27, v27, v40
	v_mul_f32_e32 v29, v29, v40
	v_mul_f32_e32 v22, v22, v40
	v_mul_f32_e32 v24, v24, v40
	v_mul_f32_e32 v23, v23, v40
	v_mul_f32_e32 v25, v25, v40
	v_mul_f32_e32 v18, v18, v40
	v_mul_f32_e32 v20, v20, v40
	v_mul_f32_e32 v19, v19, v40
	v_mul_f32_e32 v21, v21, v40
	v_mul_f32_e32 v14, v14, v40
	v_mul_f32_e32 v16, v16, v40
	v_mul_f32_e32 v15, v15, v40
	v_mul_f32_e32 v17, v17, v40
	v_mul_f32_e32 v10, v10, v40
	v_mul_f32_e32 v12, v12, v40
	v_mul_f32_e32 v11, v11, v40
	v_mul_f32_e32 v13, v13, v40
	v_mul_f32_e32 v6, v6, v40
	v_mul_f32_e32 v8, v8, v40
	v_mul_f32_e32 v7, v7, v40
	v_mul_f32_e32 v9, v9, v40
	v_mov_b32_e32 v62, v96
	v_mov_b32_e32 v63, v97
	v_mov_b32_e32 v64, v98
	v_mov_b32_e32 v65, v99
	v_mul_f32_e32 v26, v62, v26
	v_mul_f32_e32 v28, v64, v28
	v_mul_f32_e32 v27, v63, v27
	v_mul_f32_e32 v29, v65, v29
	v_bfe_u32 v41, v26, 16, 1
	v_bfe_u32 v63, v28, 16, 1
	v_bfe_u32 v62, v27, 16, 1
	v_bfe_u32 v64, v29, 16, 1
	v_add3_u32 v26, v26, v41, s26
	v_add3_u32 v28, v28, v63, s26
	v_add3_u32 v27, v27, v62, s26
	v_add3_u32 v29, v29, v64, s26
	v_lshrrev_b32_e32 v26, 16, v26
	v_lshrrev_b32_e32 v28, 16, v28
	v_and_or_b32 v26, v27, s27, v26
	v_and_or_b32 v27, v29, s27, v28
	global_store_dwordx2 v[70:71], v[26:27], off offset:512
	v_pk_mul_f32 v[2:3], v[2:3], v[40:41] op_sel_hi:[1,0]
	v_mul_f32_e32 v41, v4, v40
	v_mov_b32_e32 v26, v100
	v_mov_b32_e32 v27, v101
	v_mov_b32_e32 v28, v102
	v_mov_b32_e32 v29, v103
	v_mul_f32_e32 v22, v26, v22
	v_mul_f32_e32 v24, v28, v24
	v_mul_f32_e32 v23, v27, v23
	v_mul_f32_e32 v25, v29, v25
	v_bfe_u32 v26, v22, 16, 1
	v_bfe_u32 v28, v24, 16, 1
	v_bfe_u32 v27, v23, 16, 1
	v_bfe_u32 v29, v25, 16, 1
	v_add3_u32 v22, v22, v26, s26
	v_add3_u32 v24, v24, v28, s26
	v_add3_u32 v23, v23, v27, s26
	v_add3_u32 v25, v25, v29, s26
	v_lshrrev_b32_e32 v22, 16, v22
	v_lshrrev_b32_e32 v24, 16, v24
	v_and_or_b32 v22, v23, s27, v22
	v_and_or_b32 v23, v25, s27, v24
	global_store_dwordx2 v[70:71], v[22:23], off offset:1024
	v_mov_b32_e32 v22, v104
	v_mov_b32_e32 v23, v105
	v_mov_b32_e32 v24, v106
	v_mov_b32_e32 v25, v107
	v_mul_f32_e32 v18, v18, v22
	v_mul_f32_e32 v20, v20, v24
	v_mul_f32_e32 v19, v19, v23
	v_mul_f32_e32 v21, v21, v25
	v_bfe_u32 v22, v18, 16, 1
	v_bfe_u32 v24, v20, 16, 1
	v_bfe_u32 v23, v19, 16, 1
	v_bfe_u32 v25, v21, 16, 1
	v_add3_u32 v18, v18, v22, s26
	v_add3_u32 v20, v20, v24, s26
	v_add3_u32 v19, v19, v23, s26
	v_add3_u32 v21, v21, v25, s26
	v_lshrrev_b32_e32 v18, 16, v18
	v_lshrrev_b32_e32 v20, 16, v20
	v_and_or_b32 v18, v19, s27, v18
	v_and_or_b32 v19, v21, s27, v20
	global_store_dwordx2 v[70:71], v[18:19], off offset:1536
	v_mov_b32_e32 v18, v108
	v_mov_b32_e32 v19, v109
	v_mov_b32_e32 v20, v110
	v_mov_b32_e32 v21, v111
	v_mul_f32_e32 v14, v14, v18
	v_mul_f32_e32 v16, v16, v20
	v_mul_f32_e32 v15, v15, v19
	v_mul_f32_e32 v17, v17, v21
	v_bfe_u32 v18, v14, 16, 1
	v_bfe_u32 v20, v16, 16, 1
	v_bfe_u32 v19, v15, 16, 1
	v_bfe_u32 v21, v17, 16, 1
	v_add3_u32 v14, v14, v18, s26
	v_add3_u32 v16, v16, v20, s26
	v_add3_u32 v15, v15, v19, s26
	v_add3_u32 v17, v17, v21, s26
	v_lshrrev_b32_e32 v14, 16, v14
	v_lshrrev_b32_e32 v16, 16, v16
	v_and_or_b32 v14, v15, s27, v14
	v_and_or_b32 v15, v17, s27, v16
	global_store_dwordx2 v[70:71], v[14:15], off offset:2048
	v_mov_b32_e32 v14, v112
	v_mov_b32_e32 v15, v113
	v_mov_b32_e32 v16, v114
	v_mov_b32_e32 v17, v115
	v_mul_f32_e32 v10, v10, v14
	v_mul_f32_e32 v12, v12, v16
	v_mul_f32_e32 v11, v11, v15
	v_mul_f32_e32 v13, v13, v17
	v_bfe_u32 v14, v10, 16, 1
	v_bfe_u32 v16, v12, 16, 1
	v_bfe_u32 v15, v11, 16, 1
	v_bfe_u32 v17, v13, 16, 1
	v_add3_u32 v10, v10, v14, s26
	v_add3_u32 v12, v12, v16, s26
	v_add3_u32 v11, v11, v15, s26
	v_add3_u32 v13, v13, v17, s26
	v_lshrrev_b32_e32 v10, 16, v10
	v_lshrrev_b32_e32 v12, 16, v12
	v_and_or_b32 v10, v11, s27, v10
	v_and_or_b32 v11, v13, s27, v12
	global_store_dwordx2 v[70:71], v[10:11], off offset:2560
	v_mov_b32_e32 v10, v116
	v_mov_b32_e32 v11, v117
	v_mov_b32_e32 v12, v118
	v_mov_b32_e32 v13, v119
	v_mul_f32_e32 v6, v6, v10
	v_mul_f32_e32 v8, v8, v12
	v_mul_f32_e32 v7, v7, v11
	v_mul_f32_e32 v9, v9, v13
	v_bfe_u32 v10, v6, 16, 1
	v_bfe_u32 v12, v8, 16, 1
	v_bfe_u32 v11, v7, 16, 1
	v_bfe_u32 v13, v9, 16, 1
	v_add3_u32 v6, v6, v10, s26
	v_add3_u32 v8, v8, v12, s26
	v_add3_u32 v7, v7, v11, s26
	v_add3_u32 v9, v9, v13, s26
	v_lshrrev_b32_e32 v6, 16, v6
	v_lshrrev_b32_e32 v8, 16, v8
	v_and_or_b32 v6, v7, s27, v6
	v_and_or_b32 v7, v9, s27, v8
	global_store_dwordx2 v[70:71], v[6:7], off offset:3072
	v_mov_b32_e32 v6, v120
	v_mov_b32_e32 v7, v121
	v_mov_b32_e32 v8, v122
	v_mov_b32_e32 v9, v123
	v_pk_mul_f32 v[2:3], v[2:3], v[6:7]
	s_nop 0
	v_and_b32_sdwa v7, v2, v61 dst_sel:DWORD dst_unused:UNUSED_PAD src0_sel:WORD_1 src1_sel:DWORD
	v_and_b32_sdwa v6, v3, v61 dst_sel:DWORD dst_unused:UNUSED_PAD src0_sel:WORD_1 src1_sel:DWORD
	v_add3_u32 v2, v2, v7, s26
	v_pk_mov_b32 v[4:5], v[4:5], v[8:9] op_sel:[1,0]
	v_add3_u32 v3, v3, v6, s26
	v_lshrrev_b32_e32 v2, 16, v2
	v_and_or_b32 v2, v3, s27, v2
	v_pk_mul_f32 v[4:5], v[4:5], v[40:41]
	s_branch .LBB0_107

; template <int K> __device__ __forceinline__ float shx(float v) { static_assert(K < 32, "use sum32"); return __int_as_float(__builtin_amdgcn_ds_swizzle(__float_as_int(v), (K << 10) | 0x1f)); }
; __device__ __forceinline__ float sum32(float v) { auto rr = __builtin_amdgcn_permlane32_swap(__float_as_uint(v), __float_as_uint(v), false, false); return __uint_as_float(rr[0]) + __uint_as_float(rr[1]); }
; template <bool ROWSCALE>
; __device__ __forceinline__ void head_norm_store(const f32x4 (&acc)[2][2][4][2], const float (&rs)[2][4], const float* gain, bf16_t* d0, bf16_t* d1, PG8_LAS float* red, int wr, int wc, int fr, int fq) {
;     ...
;             for (int bj = 0; bj < 2; ++bj) { float s = 0.f;
; #pragma unroll
;                 for (int n = 0; n < 2; ++n) { f32x4 v = acc[ai][bj][m][n]; if (ROWSCALE) v = v * rs[ai][m]; s += (v[0] * v[0] + v[1] * v[1]) + (v[2] * v[2] + v[3] * v[3]); }
;                 s += shx<16>(s); s = sum32(s);
;                 if (fq == 0) red[((ai * HALF + wr * 64 + m * 16 + fr) * 2 + bj) * 4 + wc] = s; }
.LBB0_461:
	s_andn2_b64 vcc, exec, s[36:37]
	s_cbranch_vccnz .LBB0_495
	v_mul_f32_e32 v129, v125, v125
	v_mul_f32_e32 v130, v127, v127
	v_fmac_f32_e32 v129, v124, v124
	v_fmac_f32_e32 v130, v126, v126
	v_add_f32_e32 v129, v129, v130
	v_mul_f32_e32 v130, v121, v121
	v_mul_f32_e32 v131, v123, v123
	v_fmac_f32_e32 v130, v120, v120
	v_fmac_f32_e32 v131, v122, v122
	v_add_f32_e32 v130, v130, v131
	v_add_f32_e32 v129, v129, v130
	s_nop 1
	v_mov_b32_e32 v130, v129
	v_mov_b32_e32 v253, v129
	s_nop 1
	v_permlane16_swap_b32_e32 v130, v253
	s_mov_b32 s98, 0xffff
	s_mov_b32 s99, 0xffff
	v_cndmask_b32_e64 v130, v130, v253, s[98:99]
	v_lshlrev_b32_e32 v128, 5, v179
	v_readlane_b32 s0, v251, 56
	v_cmp_eq_u32_e32 vcc, 0, v180
	s_waitcnt lgkmcnt(0)
	v_add_f32_e32 v129, v129, v130
	v_mov_b32_e32 v130, v129
	s_nop 1
	v_permlane32_swap_b32_e32 v129, v130
	v_add_u32_e32 v128, s0, v128
	s_and_saveexec_b64 s[0:1], vcc
	v_add_f32_e32 v129, v129, v130
	ds_write_b32 v128, v129
	s_or_b64 exec, exec, s[0:1]
	v_mul_f32_e32 v129, v117, v117
	v_mul_f32_e32 v130, v119, v119
	v_fmac_f32_e32 v129, v116, v116
	v_fmac_f32_e32 v130, v118, v118
	v_add_f32_e32 v129, v129, v130
	v_mul_f32_e32 v130, v113, v113
	v_mul_f32_e32 v131, v115, v115
	v_fmac_f32_e32 v130, v112, v112
	v_fmac_f32_e32 v131, v114, v114
	v_add_f32_e32 v130, v130, v131
	v_add_f32_e32 v129, v129, v130
	s_nop 1
	v_mov_b32_e32 v130, v129
	v_mov_b32_e32 v253, v129
	s_nop 1
	v_permlane16_swap_b32_e32 v130, v253
	s_mov_b32 s98, 0xffff
	s_mov_b32 s99, 0xffff
	v_cndmask_b32_e64 v130, v130, v253, s[98:99]
	s_waitcnt lgkmcnt(0)
	v_add_f32_e32 v129, v129, v130
	v_mov_b32_e32 v130, v129
	s_nop 1
	v_permlane32_swap_b32_e32 v129, v130
	s_and_saveexec_b64 s[0:1], vcc
	v_add_f32_e32 v129, v129, v130
	ds_write_b32 v128, v129 offset:16
	s_or_b64 exec, exec, s[0:1]
	v_mul_f32_e32 v129, v109, v109
	v_mul_f32_e32 v130, v111, v111
	v_fmac_f32_e32 v129, v108, v108
	v_fmac_f32_e32 v130, v110, v110
	v_add_f32_e32 v129, v129, v130
	v_mul_f32_e32 v130, v105, v105
	v_mul_f32_e32 v131, v107, v107
	v_fmac_f32_e32 v130, v104, v104
	v_fmac_f32_e32 v131, v106, v106
	v_add_f32_e32 v130, v130, v131
	v_add_f32_e32 v129, v129, v130
	s_nop 1
	v_mov_b32_e32 v130, v129
	v_mov_b32_e32 v253, v129
	s_nop 1
	v_permlane16_swap_b32_e32 v130, v253
	s_mov_b32 s98, 0xffff
	s_mov_b32 s99, 0xffff
	v_cndmask_b32_e64 v130, v130, v253, s[98:99]
	s_waitcnt lgkmcnt(0)
	v_add_f32_e32 v129, v129, v130
	v_mov_b32_e32 v130, v129
	s_nop 1
	v_permlane32_swap_b32_e32 v129, v130
	s_and_saveexec_b64 s[0:1], vcc
	v_add_f32_e32 v129, v129, v130
	ds_write_b32 v128, v129 offset:512
	s_or_b64 exec, exec, s[0:1]
	v_mul_f32_e32 v129, v101, v101
	v_mul_f32_e32 v130, v103, v103
	v_fmac_f32_e32 v129, v100, v100
	v_fmac_f32_e32 v130, v102, v102
	v_add_f32_e32 v129, v129, v130
	v_mul_f32_e32 v130, v97, v97
	v_mul_f32_e32 v131, v99, v99
	v_fmac_f32_e32 v130, v96, v96
	v_fmac_f32_e32 v131, v98, v98
	v_add_f32_e32 v130, v130, v131
	v_add_f32_e32 v129, v129, v130
	s_nop 1
	v_mov_b32_e32 v130, v129
	v_mov_b32_e32 v253, v129
	s_nop 1
	v_permlane16_swap_b32_e32 v130, v253
	s_mov_b32 s98, 0xffff
	s_mov_b32 s99, 0xffff
	v_cndmask_b32_e64 v130, v130, v253, s[98:99]
	s_waitcnt lgkmcnt(0)
	v_add_f32_e32 v129, v129, v130
	v_mov_b32_e32 v130, v129
	s_nop 1
	v_permlane32_swap_b32_e32 v129, v130
	s_and_saveexec_b64 s[0:1], vcc
	v_add_f32_e32 v129, v129, v130
	ds_write_b32 v128, v129 offset:528
	s_or_b64 exec, exec, s[0:1]
	v_mul_f32_e32 v129, v93, v93
	v_mul_f32_e32 v130, v95, v95
	v_fmac_f32_e32 v129, v92, v92
	v_fmac_f32_e32 v130, v94, v94
	v_add_f32_e32 v129, v129, v130
	v_mul_f32_e32 v130, v89, v89
	v_mul_f32_e32 v131, v91, v91
	v_fmac_f32_e32 v130, v88, v88
	v_fmac_f32_e32 v131, v90, v90
	v_add_f32_e32 v130, v130, v131
	v_add_f32_e32 v129, v129, v130
	s_nop 1
	v_mov_b32_e32 v130, v129
	v_mov_b32_e32 v253, v129
	s_nop 1
	v_permlane16_swap_b32_e32 v130, v253
	s_mov_b32 s98, 0xffff
	s_mov_b32 s99, 0xffff
	v_cndmask_b32_e64 v130, v130, v253, s[98:99]
	s_waitcnt lgkmcnt(0)
	v_add_f32_e32 v129, v129, v130
	v_mov_b32_e32 v130, v129
	s_nop 1
	v_permlane32_swap_b32_e32 v129, v130
	s_and_saveexec_b64 s[0:1], vcc
	v_add_f32_e32 v129, v129, v130
	ds_write_b32 v128, v129 offset:1024
	s_or_b64 exec, exec, s[0:1]
	v_mul_f32_e32 v129, v85, v85
	v_mul_f32_e32 v130, v87, v87
	v_fmac_f32_e32 v129, v84, v84
	v_fmac_f32_e32 v130, v86, v86
	v_add_f32_e32 v129, v129, v130
	v_mul_f32_e32 v130, v81, v81
	v_mul_f32_e32 v131, v83, v83
	v_fmac_f32_e32 v130, v80, v80
	v_fmac_f32_e32 v131, v82, v82
	v_add_f32_e32 v130, v130, v131
	v_add_f32_e32 v129, v129, v130
	s_nop 1
	v_mov_b32_e32 v130, v129
	v_mov_b32_e32 v253, v129
	s_nop 1
	v_permlane16_swap_b32_e32 v130, v253
	s_mov_b32 s98, 0xffff
	s_mov_b32 s99, 0xffff
	v_cndmask_b32_e64 v130, v130, v253, s[98:99]
	s_waitcnt lgkmcnt(0)
	v_add_f32_e32 v129, v129, v130
	v_mov_b32_e32 v130, v129
	s_nop 1
	v_permlane32_swap_b32_e32 v129, v130
	s_and_saveexec_b64 s[0:1], vcc
	v_add_f32_e32 v129, v129, v130
	ds_write_b32 v128, v129 offset:1040
	s_or_b64 exec, exec, s[0:1]
	v_mul_f32_e32 v129, v77, v77
	v_mul_f32_e32 v130, v79, v79
	v_fmac_f32_e32 v129, v76, v76
	v_fmac_f32_e32 v130, v78, v78
	v_add_f32_e32 v129, v129, v130
	v_mul_f32_e32 v130, v73, v73
	v_mul_f32_e32 v131, v75, v75
	v_fmac_f32_e32 v130, v72, v72
	v_fmac_f32_e32 v131, v74, v74
	v_add_f32_e32 v130, v130, v131
	v_add_f32_e32 v129, v129, v130
	s_nop 1
	v_mov_b32_e32 v130, v129
	v_mov_b32_e32 v253, v129
	s_nop 1
	v_permlane16_swap_b32_e32 v130, v253
	s_mov_b32 s98, 0xffff
	s_mov_b32 s99, 0xffff
	v_cndmask_b32_e64 v130, v130, v253, s[98:99]
	s_waitcnt lgkmcnt(0)
; template <int K> __device__ __forceinline__ float shx(float v) { static_assert(K < 32, "use sum32"); return __int_as_float(__builtin_amdgcn_ds_swizzle(__float_as_int(v), (K << 10) | 0x1f)); }
; __device__ __forceinline__ float sum32(float v) { auto rr = __builtin_amdgcn_permlane32_swap(__float_as_uint(v), __float_as_uint(v), false, false); return __uint_as_float(rr[0]) + __uint_as_float(rr[1]); }
; template <bool ROWSCALE>
; __device__ __forceinline__ void head_norm_store(const f32x4 (&acc)[2][2][4][2], const float (&rs)[2][4], const float* gain, bf16_t* d0, bf16_t* d1, PG8_LAS float* red, int wr, int wc, int fr, int fq) {
;     ...
;             for (int bj = 0; bj < 2; ++bj) { float s = 0.f;
; #pragma unroll
;                 for (int n = 0; n < 2; ++n) { f32x4 v = acc[ai][bj][m][n]; if (ROWSCALE) v = v * rs[ai][m]; s += (v[0] * v[0] + v[1] * v[1]) + (v[2] * v[2] + v[3] * v[3]); }
;                 s += shx<16>(s); s = sum32(s);
;                 if (fq == 0) red[((ai * HALF + wr * 64 + m * 16 + fr) * 2 + bj) * 4 + wc] = s; }
	v_add_f32_e32 v129, v129, v130
	v_mov_b32_e32 v130, v129
	s_nop 1
	v_permlane32_swap_b32_e32 v129, v130
	s_and_saveexec_b64 s[0:1], vcc
	v_add_f32_e32 v129, v129, v130
	ds_write_b32 v128, v129 offset:1536
	s_or_b64 exec, exec, s[0:1]
	v_mul_f32_e32 v129, v69, v69
	v_mul_f32_e32 v130, v71, v71
	v_fmac_f32_e32 v129, v68, v68
	v_fmac_f32_e32 v130, v70, v70
	v_add_f32_e32 v129, v129, v130
	v_mul_f32_e32 v130, v65, v65
	v_mul_f32_e32 v131, v67, v67
	v_fmac_f32_e32 v130, v64, v64
	v_fmac_f32_e32 v131, v66, v66
	v_add_f32_e32 v130, v130, v131
	v_add_f32_e32 v129, v129, v130
	s_nop 1
	v_mov_b32_e32 v130, v129
	v_mov_b32_e32 v253, v129
	s_nop 1
	v_permlane16_swap_b32_e32 v130, v253
	s_mov_b32 s98, 0xffff
	s_mov_b32 s99, 0xffff
	v_cndmask_b32_e64 v130, v130, v253, s[98:99]
	s_waitcnt lgkmcnt(0)
	v_add_f32_e32 v129, v129, v130
	v_mov_b32_e32 v130, v129
	s_nop 1
	v_permlane32_swap_b32_e32 v129, v130
	s_and_saveexec_b64 s[0:1], vcc
	v_add_f32_e32 v129, v129, v130
	ds_write_b32 v128, v129 offset:1552
	s_or_b64 exec, exec, s[0:1]
	v_mul_f32_e32 v129, v61, v61
	v_mul_f32_e32 v130, v63, v63
	v_fmac_f32_e32 v129, v60, v60
	v_fmac_f32_e32 v130, v62, v62
	v_add_f32_e32 v129, v129, v130
	v_mul_f32_e32 v130, v57, v57
	v_mul_f32_e32 v131, v59, v59
	v_fmac_f32_e32 v130, v56, v56
	v_fmac_f32_e32 v131, v58, v58
	v_add_f32_e32 v130, v130, v131
	v_add_f32_e32 v129, v129, v130
	s_nop 1
	v_mov_b32_e32 v130, v129
	v_mov_b32_e32 v253, v129
	s_nop 1
	v_permlane16_swap_b32_e32 v130, v253
	s_mov_b32 s98, 0xffff
	s_mov_b32 s99, 0xffff
	v_cndmask_b32_e64 v130, v130, v253, s[98:99]
	s_waitcnt lgkmcnt(0)
	v_add_f32_e32 v129, v129, v130
	v_mov_b32_e32 v130, v129
	s_nop 1
	v_permlane32_swap_b32_e32 v129, v130
	s_and_saveexec_b64 s[0:1], vcc
	v_add_f32_e32 v129, v129, v130
	ds_write_b32 v128, v129 offset:4096
	s_or_b64 exec, exec, s[0:1]
	v_mul_f32_e32 v129, v53, v53
	v_mul_f32_e32 v130, v55, v55
	v_fmac_f32_e32 v129, v52, v52
	v_fmac_f32_e32 v130, v54, v54
	v_add_f32_e32 v129, v129, v130
	v_mul_f32_e32 v130, v49, v49
	v_mul_f32_e32 v131, v51, v51
	v_fmac_f32_e32 v130, v48, v48
	v_fmac_f32_e32 v131, v50, v50
	v_add_f32_e32 v130, v130, v131
	v_add_f32_e32 v129, v129, v130
	s_nop 1
	v_mov_b32_e32 v130, v129
	v_mov_b32_e32 v253, v129
	s_nop 1
	v_permlane16_swap_b32_e32 v130, v253
	s_mov_b32 s98, 0xffff
	s_mov_b32 s99, 0xffff
	v_cndmask_b32_e64 v130, v130, v253, s[98:99]
	s_waitcnt lgkmcnt(0)
	v_add_f32_e32 v129, v129, v130
	v_mov_b32_e32 v130, v129
	s_nop 1
	v_permlane32_swap_b32_e32 v129, v130
	s_and_saveexec_b64 s[0:1], vcc
	v_add_f32_e32 v129, v129, v130
	ds_write_b32 v128, v129 offset:4112
	s_or_b64 exec, exec, s[0:1]
	v_mul_f32_e32 v129, v45, v45
	v_mul_f32_e32 v130, v47, v47
	v_fmac_f32_e32 v129, v44, v44
	v_fmac_f32_e32 v130, v46, v46
	v_add_f32_e32 v129, v129, v130
	v_mul_f32_e32 v130, v41, v41
	v_mul_f32_e32 v131, v43, v43
	v_fmac_f32_e32 v130, v40, v40
	v_fmac_f32_e32 v131, v42, v42
	v_add_f32_e32 v130, v130, v131
	v_add_f32_e32 v129, v129, v130
	s_nop 1
	v_mov_b32_e32 v130, v129
	v_mov_b32_e32 v253, v129
	s_nop 1
	v_permlane16_swap_b32_e32 v130, v253
	s_mov_b32 s98, 0xffff
	s_mov_b32 s99, 0xffff
	v_cndmask_b32_e64 v130, v130, v253, s[98:99]
	s_waitcnt lgkmcnt(0)
	v_add_f32_e32 v129, v129, v130
	v_mov_b32_e32 v130, v129
	s_nop 1
	v_permlane32_swap_b32_e32 v129, v130
	s_and_saveexec_b64 s[0:1], vcc
	v_add_f32_e32 v129, v129, v130
	ds_write_b32 v128, v129 offset:4608
	s_or_b64 exec, exec, s[0:1]
	v_mul_f32_e32 v129, v37, v37
	v_mul_f32_e32 v130, v39, v39
	v_fmac_f32_e32 v129, v36, v36
	v_fmac_f32_e32 v130, v38, v38
	v_add_f32_e32 v129, v129, v130
	v_mul_f32_e32 v130, v33, v33
	v_mul_f32_e32 v131, v35, v35
	v_fmac_f32_e32 v130, v32, v32
	v_fmac_f32_e32 v131, v34, v34
	v_add_f32_e32 v130, v130, v131
	v_add_f32_e32 v129, v129, v130
	s_nop 1
	v_mov_b32_e32 v130, v129
	v_mov_b32_e32 v253, v129
	s_nop 1
	v_permlane16_swap_b32_e32 v130, v253
	s_mov_b32 s98, 0xffff
	s_mov_b32 s99, 0xffff
	v_cndmask_b32_e64 v130, v130, v253, s[98:99]
	s_waitcnt lgkmcnt(0)
	v_add_f32_e32 v129, v129, v130
	v_mov_b32_e32 v130, v129
	s_nop 1
	v_permlane32_swap_b32_e32 v129, v130
	s_and_saveexec_b64 s[0:1], vcc
	v_add_f32_e32 v129, v129, v130
	ds_write_b32 v128, v129 offset:4624
	s_or_b64 exec, exec, s[0:1]
	v_mul_f32_e32 v129, v29, v29
	v_mul_f32_e32 v130, v31, v31
	v_fmac_f32_e32 v129, v28, v28
	v_fmac_f32_e32 v130, v30, v30
	v_add_f32_e32 v129, v129, v130
	v_mul_f32_e32 v130, v25, v25
	v_mul_f32_e32 v131, v27, v27
	v_fmac_f32_e32 v130, v24, v24
	v_fmac_f32_e32 v131, v26, v26
	v_add_f32_e32 v130, v130, v131
	v_add_f32_e32 v129, v129, v130
	s_nop 1
	v_mov_b32_e32 v130, v129
	v_mov_b32_e32 v253, v129
	s_nop 1
	v_permlane16_swap_b32_e32 v130, v253
	s_mov_b32 s98, 0xffff
	s_mov_b32 s99, 0xffff
	v_cndmask_b32_e64 v130, v130, v253, s[98:99]
	s_waitcnt lgkmcnt(0)
	v_add_f32_e32 v129, v129, v130
	v_mov_b32_e32 v130, v129
	s_nop 1
	v_permlane32_swap_b32_e32 v129, v130
	s_and_saveexec_b64 s[0:1], vcc
	v_add_f32_e32 v129, v129, v130
	ds_write_b32 v128, v129 offset:5120
	s_or_b64 exec, exec, s[0:1]
	v_mul_f32_e32 v129, v21, v21
	v_mul_f32_e32 v130, v23, v23
	v_fmac_f32_e32 v129, v20, v20
	v_fmac_f32_e32 v130, v22, v22
	v_add_f32_e32 v129, v129, v130
	v_mul_f32_e32 v130, v17, v17
	v_mul_f32_e32 v131, v19, v19
	v_fmac_f32_e32 v130, v16, v16
	v_fmac_f32_e32 v131, v18, v18
	v_add_f32_e32 v130, v130, v131
	v_add_f32_e32 v129, v129, v130
	s_nop 1
	v_mov_b32_e32 v130, v129
	v_mov_b32_e32 v253, v129
	s_nop 1
	v_permlane16_swap_b32_e32 v130, v253
	s_mov_b32 s98, 0xffff
	s_mov_b32 s99, 0xffff
	v_cndmask_b32_e64 v130, v130, v253, s[98:99]
	s_waitcnt lgkmcnt(0)
; template <int K> __device__ __forceinline__ float shx(float v) { static_assert(K < 32, "use sum32"); return __int_as_float(__builtin_amdgcn_ds_swizzle(__float_as_int(v), (K << 10) | 0x1f)); }
; __device__ __forceinline__ float sum32(float v) { auto rr = __builtin_amdgcn_permlane32_swap(__float_as_uint(v), __float_as_uint(v), false, false); return __uint_as_float(rr[0]) + __uint_as_float(rr[1]); }
; #define PG8_LAS __attribute__((address_space(3)))
; __device__ __forceinline__ u32x4 pack8(const f32x4& a, const f32x4& b) { u32x4 w; w.x = cvt_pk_bf16(a[0], a[1]); w.y = cvt_pk_bf16(a[2], a[3]); w.z = cvt_pk_bf16(b[0], b[1]); w.w = cvt_pk_bf16(b[2], b[3]); return w; }
; template <bool ROWSCALE>
; __device__ __forceinline__ void head_norm_store(const f32x4 (&acc)[2][2][4][2], const float (&rs)[2][4], const float* gain, bf16_t* d0, bf16_t* d1, PG8_LAS float* red, int wr, int wc, int fr, int fq) {
;     ...
;             for (int bj = 0; bj < 2; ++bj) { float s = 0.f;
; #pragma unroll
;                 for (int n = 0; n < 2; ++n) { f32x4 v = acc[ai][bj][m][n]; if (ROWSCALE) v = v * rs[ai][m]; s += (v[0] * v[0] + v[1] * v[1]) + (v[2] * v[2] + v[3] * v[3]); }
;                 s += shx<16>(s); s = sum32(s);
;                 if (fq == 0) red[((ai * HALF + wr * 64 + m * 16 + fr) * 2 + bj) * 4 + wc] = s; }
;     asm volatile("s_waitcnt lgkmcnt(0)" ::: "memory"); __builtin_amdgcn_s_barrier(); asm volatile("" ::: "memory");
;     const f32x4 g0 = *(const f32x4*)(gain + wc * 32 + fq * 8), g1 = *(const f32x4*)(gain + wc * 32 + fq * 8 + 4);
; #pragma unroll
;     for (int ai = 0; ai < 2; ++ai)
; #pragma unroll
;         for (int m = 0; m < 4; ++m) { const int rl = ai * HALF + wr * 64 + m * 16 + fr;
; #pragma unroll
;             for (int bj = 0; bj < 2; ++bj) { const PG8_LAS float* rp = red + (rl * 2 + bj) * 4;
;                 const float ss = (rp[0] + rp[1]) + (rp[2] + rp[3]);
;                 float sc = __builtin_amdgcn_rsqf(ss * (1.0f / 128.0f) + RMS_EPS); if (ROWSCALE) sc *= rs[ai][m];
;                 const f32x4 v0 = acc[ai][bj][m][0] * sc * g0, v1 = acc[ai][bj][m][1] * sc * g1;
;                 *(u32x4*)((bj ? d1 : d0) + (size_t)rl * 128 + wc * 32 + fq * 8) = pack8(v0, v1); } }
	v_add_f32_e32 v129, v129, v130
	v_mov_b32_e32 v130, v129
	s_nop 1
	v_permlane32_swap_b32_e32 v129, v130
	s_and_saveexec_b64 s[0:1], vcc
	v_add_f32_e32 v129, v129, v130
	ds_write_b32 v128, v129 offset:5136
	s_or_b64 exec, exec, s[0:1]
	v_mul_f32_e32 v129, v13, v13
	v_mul_f32_e32 v130, v15, v15
	v_fmac_f32_e32 v129, v12, v12
	v_fmac_f32_e32 v130, v14, v14
	v_add_f32_e32 v129, v129, v130
	v_mul_f32_e32 v130, v9, v9
	v_mul_f32_e32 v131, v11, v11
	v_fmac_f32_e32 v130, v8, v8
	v_fmac_f32_e32 v131, v10, v10
	v_add_f32_e32 v130, v130, v131
	v_add_f32_e32 v129, v129, v130
	s_nop 1
	v_mov_b32_e32 v130, v129
	v_mov_b32_e32 v253, v129
	s_nop 1
	v_permlane16_swap_b32_e32 v130, v253
	s_mov_b32 s98, 0xffff
	s_mov_b32 s99, 0xffff
	v_cndmask_b32_e64 v130, v130, v253, s[98:99]
	s_waitcnt lgkmcnt(0)
	v_add_f32_e32 v129, v129, v130
	v_mov_b32_e32 v130, v129
	s_nop 1
	v_permlane32_swap_b32_e32 v129, v130
	s_and_saveexec_b64 s[0:1], vcc
	v_add_f32_e32 v129, v129, v130
	ds_write_b32 v128, v129 offset:5632
	s_or_b64 exec, exec, s[0:1]
	v_mul_f32_e32 v129, v5, v5
	v_mul_f32_e32 v130, v7, v7
	v_fmac_f32_e32 v129, v4, v4
	v_fmac_f32_e32 v130, v6, v6
	v_add_f32_e32 v129, v129, v130
	v_mul_f32_e32 v130, v1, v1
	v_mul_f32_e32 v131, v3, v3
	v_fmac_f32_e32 v130, v0, v0
	v_fmac_f32_e32 v131, v2, v2
	v_add_f32_e32 v130, v130, v131
	v_add_f32_e32 v129, v129, v130
	s_nop 1
	v_mov_b32_e32 v130, v129
	v_mov_b32_e32 v253, v129
	s_nop 1
	v_permlane16_swap_b32_e32 v130, v253
	s_mov_b32 s98, 0xffff
	s_mov_b32 s99, 0xffff
	v_cndmask_b32_e64 v130, v130, v253, s[98:99]
	s_waitcnt lgkmcnt(0)
	v_add_f32_e32 v129, v129, v130
	v_mov_b32_e32 v130, v129
	s_nop 1
	v_permlane32_swap_b32_e32 v129, v130
	s_and_saveexec_b64 s[0:1], vcc
	v_add_f32_e32 v129, v129, v130
	ds_write_b32 v128, v129 offset:5648
	s_or_b64 exec, exec, s[0:1]
	v_readlane_b32 s80, v252, 8
	s_and_b64 s[0:1], s[18:19], exec
	v_readlane_b32 s90, v252, 18
	v_readlane_b32 s91, v252, 19
	v_readlane_b32 s92, v252, 20
	v_readlane_b32 s93, v252, 21
	s_cselect_b32 s1, s91, s93
	s_cselect_b32 s0, s90, s92
	s_lshl_b32 s15, s6, 2
	s_add_u32 s0, s0, s15
	s_addc_u32 s1, s1, 0
	s_waitcnt lgkmcnt(0)
	s_barrier
	v_lshl_add_u64 v[128:129], v[166:167], 2, s[0:1]
	global_load_dwordx4 v[132:135], v[128:129], off
	s_nop 0
	global_load_dwordx4 v[128:131], v[128:129], off offset:16
	s_add_i32 s0, 0, 0x20000
	v_lshl_add_u32 v153, v168, 5, s0
	ds_read_b128 v[180:183], v153
	v_lshlrev_b64 v[168:169], 8, v[168:169]
	s_lshl_b32 s26, s6, 1
	v_ashrrev_i32_e32 v165, 31, v164
	v_ashrrev_i32_e32 v163, 31, v162
	s_waitcnt lgkmcnt(0)
	v_mov_b32_e32 v184, v181
	v_mov_b32_e32 v185, v182
	v_mov_b32_e32 v181, v183
	v_pk_add_f32 v[180:181], v[184:185], v[180:181]
	v_ashrrev_i32_e32 v161, 31, v160
	v_add_f32_e32 v155, v180, v181
	v_fmamk_f32 v155, v155, 0x3c000000, v177
	v_rsq_f32_e32 v180, v155
	v_ashrrev_i32_e32 v159, 31, v158
	v_ashrrev_i32_e32 v157, 31, v156
	v_ashrrev_i32_e32 v155, 31, v154
	v_pk_mul_f32 v[124:125], v[124:125], v[180:181] op_sel_hi:[1,0]
	v_pk_mul_f32 v[122:123], v[122:123], v[180:181] op_sel_hi:[1,0]
	v_pk_mul_f32 v[126:127], v[126:127], v[180:181] op_sel_hi:[1,0]
	v_pk_mul_f32 v[120:121], v[120:121], v[180:181] op_sel_hi:[1,0]
	v_readlane_b32 s81, v252, 9
	v_readlane_b32 s82, v252, 10
	v_readlane_b32 s83, v252, 11
	v_readlane_b32 s84, v252, 12
	v_readlane_b32 s85, v252, 13
	v_readlane_b32 s86, v252, 14
	v_readlane_b32 s87, v252, 15
	v_readlane_b32 s88, v252, 16
	v_readlane_b32 s89, v252, 17
	v_readlane_b32 s94, v252, 22
	v_readlane_b32 s95, v252, 23
	s_waitcnt vmcnt(0)
	v_pk_mul_f32 v[124:125], v[132:133], v[124:125]
	v_pk_mul_f32 v[180:181], v[130:131], v[122:123]
	v_pk_mul_f32 v[126:127], v[134:135], v[126:127]
	v_pk_mul_f32 v[120:121], v[128:129], v[120:121]
	v_cvt_pk_bf16_f32 v122, v124, v125
	v_cvt_pk_bf16_f32 v123, v126, v127
	v_lshl_add_u64 v[126:127], s[16:17], 0, v[168:169]
	v_cvt_pk_bf16_f32 v124, v120, v121
	v_cvt_pk_bf16_f32 v125, v180, v181
	ds_read_b128 v[180:183], v153 offset:16
	v_lshlrev_b64 v[120:121], 1, v[166:167]
	v_lshl_add_u64 v[126:127], v[126:127], 0, s[26:27]
	v_lshl_add_u64 v[126:127], v[126:127], 0, v[120:121]
	global_store_dwordx4 v[126:127], v[122:125], off
	s_waitcnt lgkmcnt(0)
	v_mov_b32_e32 v166, v181
	v_mov_b32_e32 v167, v182
	v_mov_b32_e32 v181, v183
	v_pk_add_f32 v[166:167], v[166:167], v[180:181]
	s_nop 0
	v_add_f32_e32 v153, v166, v167
	v_fmamk_f32 v153, v153, 0x3c000000, v177
	v_rsq_f32_e32 v166, v153
	v_lshl_add_u32 v153, v164, 5, s0
	v_pk_mul_f32 v[116:117], v[116:117], v[166:167] op_sel_hi:[1,0]
	v_pk_mul_f32 v[118:119], v[118:119], v[166:167] op_sel_hi:[1,0]
	v_pk_mul_f32 v[112:113], v[112:113], v[166:167] op_sel_hi:[1,0]
	v_pk_mul_f32 v[114:115], v[114:115], v[166:167] op_sel_hi:[1,0]
	v_pk_mul_f32 v[118:119], v[134:135], v[118:119]
	v_pk_mul_f32 v[116:117], v[132:133], v[116:117]
	v_pk_mul_f32 v[122:123], v[130:131], v[114:115]
	v_pk_mul_f32 v[114:115], v[128:129], v[112:113]
	v_cvt_pk_bf16_f32 v112, v116, v117
	v_cvt_pk_bf16_f32 v113, v118, v119
	s_nop 0
	v_cvt_pk_bf16_f32 v114, v114, v115
	v_cvt_pk_bf16_f32 v115, v122, v123
	ds_read_b128 v[116:119], v153
	v_lshl_add_u64 v[122:123], s[12:13], 0, v[168:169]
	s_waitcnt lgkmcnt(0)
; #define PG8_LAS __attribute__((address_space(3)))
; __device__ __forceinline__ u32x4 pack8(const f32x4& a, const f32x4& b) { u32x4 w; w.x = cvt_pk_bf16(a[0], a[1]); w.y = cvt_pk_bf16(a[2], a[3]); w.z = cvt_pk_bf16(b[0], b[1]); w.w = cvt_pk_bf16(b[2], b[3]); return w; }
; template <bool ROWSCALE>
; __device__ __forceinline__ void head_norm_store(const f32x4 (&acc)[2][2][4][2], const float (&rs)[2][4], const float* gain, bf16_t* d0, bf16_t* d1, PG8_LAS float* red, int wr, int wc, int fr, int fq) {
;     ...
;     for (int ai = 0; ai < 2; ++ai)
; #pragma unroll
;         for (int m = 0; m < 4; ++m) { const int rl = ai * HALF + wr * 64 + m * 16 + fr;
; #pragma unroll
;             for (int bj = 0; bj < 2; ++bj) { const PG8_LAS float* rp = red + (rl * 2 + bj) * 4;
;                 const float ss = (rp[0] + rp[1]) + (rp[2] + rp[3]);
;                 float sc = __builtin_amdgcn_rsqf(ss * (1.0f / 128.0f) + RMS_EPS); if (ROWSCALE) sc *= rs[ai][m];
;                 const f32x4 v0 = acc[ai][bj][m][0] * sc * g0, v1 = acc[ai][bj][m][1] * sc * g1;
;                 *(u32x4*)((bj ? d1 : d0) + (size_t)rl * 128 + wc * 32 + fq * 8) = pack8(v0, v1); } }
	v_mov_b32_e32 v124, v117
	v_mov_b32_e32 v125, v118
	v_mov_b32_e32 v117, v119
	v_pk_add_f32 v[116:117], v[124:125], v[116:117]
	v_lshl_add_u64 v[118:119], v[122:123], 0, s[26:27]
	v_add_f32_e32 v116, v116, v117
	v_fmamk_f32 v116, v116, 0x3c000000, v177
	v_rsq_f32_e32 v116, v116
	v_lshl_add_u64 v[118:119], v[118:119], 0, v[120:121]
	global_store_dwordx4 v[118:119], v[112:115], off
	v_pk_mul_f32 v[108:109], v[108:109], v[116:117] op_sel_hi:[1,0]
	v_pk_mul_f32 v[110:111], v[110:111], v[116:117] op_sel_hi:[1,0]
	v_pk_mul_f32 v[104:105], v[104:105], v[116:117] op_sel_hi:[1,0]
	v_pk_mul_f32 v[106:107], v[106:107], v[116:117] op_sel_hi:[1,0]
	v_pk_mul_f32 v[110:111], v[134:135], v[110:111]
	v_pk_mul_f32 v[108:109], v[132:133], v[108:109]
	v_pk_mul_f32 v[112:113], v[130:131], v[106:107]
	v_pk_mul_f32 v[106:107], v[128:129], v[104:105]
	v_cvt_pk_bf16_f32 v104, v108, v109
	v_cvt_pk_bf16_f32 v105, v110, v111
	s_nop 0
	v_cvt_pk_bf16_f32 v106, v106, v107
	v_cvt_pk_bf16_f32 v107, v112, v113
	ds_read_b128 v[108:111], v153 offset:16
	v_lshlrev_b64 v[112:113], 8, v[164:165]
	v_lshl_add_u64 v[114:115], s[16:17], 0, v[112:113]
	v_lshl_add_u64 v[114:115], v[114:115], 0, s[26:27]
	v_ashrrev_i32_e32 v153, 31, v152
	s_waitcnt lgkmcnt(0)
	v_mov_b32_e32 v116, v109
	v_mov_b32_e32 v117, v110
	v_mov_b32_e32 v109, v111
	v_pk_add_f32 v[108:109], v[116:117], v[108:109]
	v_lshl_add_u64 v[110:111], v[114:115], 0, v[120:121]
	v_add_f32_e32 v108, v108, v109
	v_fmamk_f32 v108, v108, 0x3c000000, v177
	v_rsq_f32_e32 v108, v108
	v_lshl_add_u32 v109, v162, 5, s0
	global_store_dwordx4 v[110:111], v[104:107], off
	v_pk_mul_f32 v[100:101], v[100:101], v[108:109] op_sel_hi:[1,0]
	v_pk_mul_f32 v[102:103], v[102:103], v[108:109] op_sel_hi:[1,0]
	v_pk_mul_f32 v[96:97], v[96:97], v[108:109] op_sel_hi:[1,0]
	v_pk_mul_f32 v[98:99], v[98:99], v[108:109] op_sel_hi:[1,0]
	v_pk_mul_f32 v[102:103], v[134:135], v[102:103]
	v_pk_mul_f32 v[100:101], v[132:133], v[100:101]
	v_pk_mul_f32 v[104:105], v[130:131], v[98:99]
	v_pk_mul_f32 v[98:99], v[128:129], v[96:97]
	v_cvt_pk_bf16_f32 v96, v100, v101
	v_cvt_pk_bf16_f32 v97, v102, v103
	s_nop 0
	v_cvt_pk_bf16_f32 v98, v98, v99
	v_cvt_pk_bf16_f32 v99, v104, v105
	ds_read_b128 v[100:103], v109
	v_lshl_add_u64 v[104:105], s[12:13], 0, v[112:113]
	s_waitcnt lgkmcnt(0)
	v_mov_b32_e32 v106, v101
	v_mov_b32_e32 v107, v102
	v_mov_b32_e32 v101, v103
	v_pk_add_f32 v[100:101], v[106:107], v[100:101]
	v_lshl_add_u64 v[102:103], v[104:105], 0, s[26:27]
	v_add_f32_e32 v100, v100, v101
	v_fmamk_f32 v100, v100, 0x3c000000, v177
	v_rsq_f32_e32 v100, v100
	v_lshl_add_u64 v[102:103], v[102:103], 0, v[120:121]
	global_store_dwordx4 v[102:103], v[96:99], off
	v_pk_mul_f32 v[92:93], v[92:93], v[100:101] op_sel_hi:[1,0]
	v_pk_mul_f32 v[94:95], v[94:95], v[100:101] op_sel_hi:[1,0]
	v_pk_mul_f32 v[88:89], v[88:89], v[100:101] op_sel_hi:[1,0]
	v_pk_mul_f32 v[90:91], v[90:91], v[100:101] op_sel_hi:[1,0]
	v_pk_mul_f32 v[94:95], v[134:135], v[94:95]
	v_pk_mul_f32 v[92:93], v[132:133], v[92:93]
	v_pk_mul_f32 v[96:97], v[130:131], v[90:91]
	v_pk_mul_f32 v[90:91], v[128:129], v[88:89]
	v_cvt_pk_bf16_f32 v88, v92, v93
	v_cvt_pk_bf16_f32 v89, v94, v95
	s_nop 0
	v_cvt_pk_bf16_f32 v90, v90, v91
	v_cvt_pk_bf16_f32 v91, v96, v97
	ds_read_b128 v[92:95], v109 offset:16
	v_lshlrev_b64 v[96:97], 8, v[162:163]
	v_lshl_add_u64 v[98:99], s[16:17], 0, v[96:97]
	s_waitcnt lgkmcnt(0)
	v_mov_b32_e32 v100, v93
	v_mov_b32_e32 v101, v94
	v_mov_b32_e32 v93, v95
	v_pk_add_f32 v[92:93], v[100:101], v[92:93]
	v_lshl_add_u64 v[94:95], v[98:99], 0, s[26:27]
	v_add_f32_e32 v92, v92, v93
	v_fmamk_f32 v92, v92, 0x3c000000, v177
	v_rsq_f32_e32 v92, v92
	v_lshl_add_u64 v[94:95], v[94:95], 0, v[120:121]
	global_store_dwordx4 v[94:95], v[88:91], off
	v_pk_mul_f32 v[84:85], v[84:85], v[92:93] op_sel_hi:[1,0]
	v_pk_mul_f32 v[86:87], v[86:87], v[92:93] op_sel_hi:[1,0]
	v_pk_mul_f32 v[80:81], v[80:81], v[92:93] op_sel_hi:[1,0]
	v_pk_mul_f32 v[82:83], v[82:83], v[92:93] op_sel_hi:[1,0]
	v_pk_mul_f32 v[86:87], v[134:135], v[86:87]
	v_pk_mul_f32 v[84:85], v[132:133], v[84:85]
	v_pk_mul_f32 v[88:89], v[130:131], v[82:83]
	v_pk_mul_f32 v[82:83], v[128:129], v[80:81]
	v_lshl_add_u32 v92, v160, 5, s0
	v_cvt_pk_bf16_f32 v80, v84, v85
	v_cvt_pk_bf16_f32 v81, v86, v87
	v_cvt_pk_bf16_f32 v82, v82, v83
	v_cvt_pk_bf16_f32 v83, v88, v89
	ds_read_b128 v[84:87], v92
	v_lshl_add_u64 v[88:89], s[12:13], 0, v[96:97]
	s_waitcnt lgkmcnt(0)
	v_mov_b32_e32 v90, v85
	v_mov_b32_e32 v91, v86
	v_mov_b32_e32 v85, v87
	v_pk_add_f32 v[84:85], v[90:91], v[84:85]
	v_lshl_add_u64 v[86:87], v[88:89], 0, s[26:27]
	v_add_f32_e32 v84, v84, v85
	v_fmamk_f32 v84, v84, 0x3c000000, v177
	v_rsq_f32_e32 v84, v84
	v_lshl_add_u64 v[86:87], v[86:87], 0, v[120:121]
	global_store_dwordx4 v[86:87], v[80:83], off
	v_pk_mul_f32 v[76:77], v[76:77], v[84:85] op_sel_hi:[1,0]
	v_pk_mul_f32 v[78:79], v[78:79], v[84:85] op_sel_hi:[1,0]
	v_pk_mul_f32 v[72:73], v[72:73], v[84:85] op_sel_hi:[1,0]
	v_pk_mul_f32 v[74:75], v[74:75], v[84:85] op_sel_hi:[1,0]
	v_pk_mul_f32 v[78:79], v[134:135], v[78:79]
	v_pk_mul_f32 v[76:77], v[132:133], v[76:77]
	v_pk_mul_f32 v[80:81], v[130:131], v[74:75]
	v_pk_mul_f32 v[74:75], v[128:129], v[72:73]
	v_cvt_pk_bf16_f32 v72, v76, v77
	v_cvt_pk_bf16_f32 v73, v78, v79
	s_nop 0
	v_cvt_pk_bf16_f32 v74, v74, v75
	v_cvt_pk_bf16_f32 v75, v80, v81
	ds_read_b128 v[76:79], v92 offset:16
	v_lshlrev_b64 v[80:81], 8, v[160:161]
	v_lshl_add_u64 v[82:83], s[16:17], 0, v[80:81]
	s_waitcnt lgkmcnt(0)
; #define PG8_LAS __attribute__((address_space(3)))
; __device__ __forceinline__ u32x4 pack8(const f32x4& a, const f32x4& b) { u32x4 w; w.x = cvt_pk_bf16(a[0], a[1]); w.y = cvt_pk_bf16(a[2], a[3]); w.z = cvt_pk_bf16(b[0], b[1]); w.w = cvt_pk_bf16(b[2], b[3]); return w; }
; template <bool ROWSCALE>
; __device__ __forceinline__ void head_norm_store(const f32x4 (&acc)[2][2][4][2], const float (&rs)[2][4], const float* gain, bf16_t* d0, bf16_t* d1, PG8_LAS float* red, int wr, int wc, int fr, int fq) {
;     ...
;     for (int ai = 0; ai < 2; ++ai)
; #pragma unroll
;         for (int m = 0; m < 4; ++m) { const int rl = ai * HALF + wr * 64 + m * 16 + fr;
; #pragma unroll
;             for (int bj = 0; bj < 2; ++bj) { const PG8_LAS float* rp = red + (rl * 2 + bj) * 4;
;                 const float ss = (rp[0] + rp[1]) + (rp[2] + rp[3]);
;                 float sc = __builtin_amdgcn_rsqf(ss * (1.0f / 128.0f) + RMS_EPS); if (ROWSCALE) sc *= rs[ai][m];
;                 const f32x4 v0 = acc[ai][bj][m][0] * sc * g0, v1 = acc[ai][bj][m][1] * sc * g1;
;                 *(u32x4*)((bj ? d1 : d0) + (size_t)rl * 128 + wc * 32 + fq * 8) = pack8(v0, v1); } }
	v_mov_b32_e32 v84, v77
	v_mov_b32_e32 v85, v78
	v_mov_b32_e32 v77, v79
	v_pk_add_f32 v[76:77], v[84:85], v[76:77]
	v_lshl_add_u64 v[78:79], v[82:83], 0, s[26:27]
	v_add_f32_e32 v76, v76, v77
	v_fmamk_f32 v76, v76, 0x3c000000, v177
	v_rsq_f32_e32 v76, v76
	v_lshl_add_u64 v[78:79], v[78:79], 0, v[120:121]
	global_store_dwordx4 v[78:79], v[72:75], off
	v_pk_mul_f32 v[68:69], v[68:69], v[76:77] op_sel_hi:[1,0]
	v_pk_mul_f32 v[70:71], v[70:71], v[76:77] op_sel_hi:[1,0]
	v_pk_mul_f32 v[64:65], v[64:65], v[76:77] op_sel_hi:[1,0]
	v_pk_mul_f32 v[66:67], v[66:67], v[76:77] op_sel_hi:[1,0]
	v_pk_mul_f32 v[70:71], v[134:135], v[70:71]
	v_pk_mul_f32 v[68:69], v[132:133], v[68:69]
	v_pk_mul_f32 v[72:73], v[130:131], v[66:67]
	v_pk_mul_f32 v[66:67], v[128:129], v[64:65]
	v_lshl_add_u32 v76, v158, 5, s0
	v_cvt_pk_bf16_f32 v64, v68, v69
	v_cvt_pk_bf16_f32 v65, v70, v71
	v_cvt_pk_bf16_f32 v66, v66, v67
	v_cvt_pk_bf16_f32 v67, v72, v73
	ds_read_b128 v[68:71], v76
	v_lshl_add_u64 v[72:73], s[12:13], 0, v[80:81]
	s_waitcnt lgkmcnt(0)
	v_mov_b32_e32 v74, v69
	v_mov_b32_e32 v75, v70
	v_mov_b32_e32 v69, v71
	v_pk_add_f32 v[68:69], v[74:75], v[68:69]
	v_lshl_add_u64 v[70:71], v[72:73], 0, s[26:27]
	v_add_f32_e32 v68, v68, v69
	v_fmamk_f32 v68, v68, 0x3c000000, v177
	v_rsq_f32_e32 v68, v68
	v_lshl_add_u64 v[70:71], v[70:71], 0, v[120:121]
	global_store_dwordx4 v[70:71], v[64:67], off
	v_pk_mul_f32 v[60:61], v[60:61], v[68:69] op_sel_hi:[1,0]
	v_pk_mul_f32 v[62:63], v[62:63], v[68:69] op_sel_hi:[1,0]
	v_pk_mul_f32 v[56:57], v[56:57], v[68:69] op_sel_hi:[1,0]
	v_pk_mul_f32 v[58:59], v[58:59], v[68:69] op_sel_hi:[1,0]
	v_pk_mul_f32 v[62:63], v[134:135], v[62:63]
	v_pk_mul_f32 v[60:61], v[132:133], v[60:61]
	v_pk_mul_f32 v[64:65], v[130:131], v[58:59]
	v_pk_mul_f32 v[58:59], v[128:129], v[56:57]
	v_cvt_pk_bf16_f32 v56, v60, v61
	v_cvt_pk_bf16_f32 v57, v62, v63
	s_nop 0
	v_cvt_pk_bf16_f32 v58, v58, v59
	v_cvt_pk_bf16_f32 v59, v64, v65
	ds_read_b128 v[60:63], v76 offset:16
	v_lshlrev_b64 v[64:65], 8, v[158:159]
	v_lshl_add_u64 v[66:67], s[16:17], 0, v[64:65]
	s_waitcnt lgkmcnt(0)
	v_mov_b32_e32 v68, v61
	v_mov_b32_e32 v69, v62
	v_mov_b32_e32 v61, v63
	v_pk_add_f32 v[60:61], v[68:69], v[60:61]
	v_lshl_add_u64 v[62:63], v[66:67], 0, s[26:27]
	v_add_f32_e32 v60, v60, v61
	v_fmamk_f32 v60, v60, 0x3c000000, v177
	v_rsq_f32_e32 v60, v60
	v_lshl_add_u64 v[62:63], v[62:63], 0, v[120:121]
	global_store_dwordx4 v[62:63], v[56:59], off
	v_pk_mul_f32 v[52:53], v[52:53], v[60:61] op_sel_hi:[1,0]
	v_pk_mul_f32 v[54:55], v[54:55], v[60:61] op_sel_hi:[1,0]
	v_pk_mul_f32 v[48:49], v[48:49], v[60:61] op_sel_hi:[1,0]
	v_pk_mul_f32 v[50:51], v[50:51], v[60:61] op_sel_hi:[1,0]
	v_pk_mul_f32 v[54:55], v[134:135], v[54:55]
	v_pk_mul_f32 v[52:53], v[132:133], v[52:53]
	v_pk_mul_f32 v[56:57], v[130:131], v[50:51]
	v_pk_mul_f32 v[50:51], v[128:129], v[48:49]
	v_lshl_add_u32 v60, v156, 5, s0
	v_cvt_pk_bf16_f32 v48, v52, v53
	v_cvt_pk_bf16_f32 v49, v54, v55
	v_cvt_pk_bf16_f32 v50, v50, v51
	v_cvt_pk_bf16_f32 v51, v56, v57
	ds_read_b128 v[52:55], v60
	v_lshl_add_u64 v[56:57], s[12:13], 0, v[64:65]
	s_waitcnt lgkmcnt(0)
	v_mov_b32_e32 v58, v53
	v_mov_b32_e32 v59, v54
	v_mov_b32_e32 v53, v55
	v_pk_add_f32 v[52:53], v[58:59], v[52:53]
	v_lshl_add_u64 v[54:55], v[56:57], 0, s[26:27]
	v_add_f32_e32 v52, v52, v53
	v_fmamk_f32 v52, v52, 0x3c000000, v177
	v_rsq_f32_e32 v52, v52
	v_lshl_add_u64 v[54:55], v[54:55], 0, v[120:121]
	global_store_dwordx4 v[54:55], v[48:51], off
	v_pk_mul_f32 v[44:45], v[44:45], v[52:53] op_sel_hi:[1,0]
	v_pk_mul_f32 v[46:47], v[46:47], v[52:53] op_sel_hi:[1,0]
	v_pk_mul_f32 v[40:41], v[40:41], v[52:53] op_sel_hi:[1,0]
	v_pk_mul_f32 v[42:43], v[42:43], v[52:53] op_sel_hi:[1,0]
	v_pk_mul_f32 v[46:47], v[134:135], v[46:47]
	v_pk_mul_f32 v[44:45], v[132:133], v[44:45]
	v_pk_mul_f32 v[48:49], v[130:131], v[42:43]
	v_pk_mul_f32 v[42:43], v[128:129], v[40:41]
	v_cvt_pk_bf16_f32 v40, v44, v45
	v_cvt_pk_bf16_f32 v41, v46, v47
	s_nop 0
	v_cvt_pk_bf16_f32 v42, v42, v43
	v_cvt_pk_bf16_f32 v43, v48, v49
	ds_read_b128 v[44:47], v60 offset:16
	v_lshlrev_b64 v[48:49], 8, v[156:157]
	v_lshl_add_u64 v[50:51], s[16:17], 0, v[48:49]
	s_waitcnt lgkmcnt(0)
	v_mov_b32_e32 v52, v45
	v_mov_b32_e32 v53, v46
	v_mov_b32_e32 v45, v47
	v_pk_add_f32 v[44:45], v[52:53], v[44:45]
	v_lshl_add_u64 v[46:47], v[50:51], 0, s[26:27]
	v_add_f32_e32 v44, v44, v45
	v_fmamk_f32 v44, v44, 0x3c000000, v177
	v_rsq_f32_e32 v44, v44
	v_lshl_add_u64 v[46:47], v[46:47], 0, v[120:121]
	global_store_dwordx4 v[46:47], v[40:43], off
	v_pk_mul_f32 v[36:37], v[36:37], v[44:45] op_sel_hi:[1,0]
	v_pk_mul_f32 v[38:39], v[38:39], v[44:45] op_sel_hi:[1,0]
	v_pk_mul_f32 v[32:33], v[32:33], v[44:45] op_sel_hi:[1,0]
	v_pk_mul_f32 v[34:35], v[34:35], v[44:45] op_sel_hi:[1,0]
	v_pk_mul_f32 v[38:39], v[134:135], v[38:39]
	v_pk_mul_f32 v[36:37], v[132:133], v[36:37]
	v_pk_mul_f32 v[40:41], v[130:131], v[34:35]
	v_pk_mul_f32 v[34:35], v[128:129], v[32:33]
	v_lshl_add_u32 v44, v154, 5, s0
	v_cvt_pk_bf16_f32 v32, v36, v37
	v_cvt_pk_bf16_f32 v33, v38, v39
	v_cvt_pk_bf16_f32 v34, v34, v35
	v_cvt_pk_bf16_f32 v35, v40, v41
	ds_read_b128 v[36:39], v44
	v_lshl_add_u64 v[40:41], s[12:13], 0, v[48:49]
	s_waitcnt lgkmcnt(0)
; #define PG8_LAS __attribute__((address_space(3)))
; __device__ __forceinline__ u32x4 pack8(const f32x4& a, const f32x4& b) { u32x4 w; w.x = cvt_pk_bf16(a[0], a[1]); w.y = cvt_pk_bf16(a[2], a[3]); w.z = cvt_pk_bf16(b[0], b[1]); w.w = cvt_pk_bf16(b[2], b[3]); return w; }
; template <bool ROWSCALE>
; __device__ __forceinline__ void head_norm_store(const f32x4 (&acc)[2][2][4][2], const float (&rs)[2][4], const float* gain, bf16_t* d0, bf16_t* d1, PG8_LAS float* red, int wr, int wc, int fr, int fq) {
;     ...
;     for (int ai = 0; ai < 2; ++ai)
; #pragma unroll
;         for (int m = 0; m < 4; ++m) { const int rl = ai * HALF + wr * 64 + m * 16 + fr;
; #pragma unroll
;             for (int bj = 0; bj < 2; ++bj) { const PG8_LAS float* rp = red + (rl * 2 + bj) * 4;
;                 const float ss = (rp[0] + rp[1]) + (rp[2] + rp[3]);
;                 float sc = __builtin_amdgcn_rsqf(ss * (1.0f / 128.0f) + RMS_EPS); if (ROWSCALE) sc *= rs[ai][m];
;                 const f32x4 v0 = acc[ai][bj][m][0] * sc * g0, v1 = acc[ai][bj][m][1] * sc * g1;
;                 *(u32x4*)((bj ? d1 : d0) + (size_t)rl * 128 + wc * 32 + fq * 8) = pack8(v0, v1); } }
	v_mov_b32_e32 v42, v37
	v_mov_b32_e32 v43, v38
	v_mov_b32_e32 v37, v39
	v_pk_add_f32 v[36:37], v[42:43], v[36:37]
	v_lshl_add_u64 v[38:39], v[40:41], 0, s[26:27]
	v_add_f32_e32 v36, v36, v37
	v_fmamk_f32 v36, v36, 0x3c000000, v177
	v_rsq_f32_e32 v36, v36
	v_lshl_add_u64 v[38:39], v[38:39], 0, v[120:121]
	global_store_dwordx4 v[38:39], v[32:35], off
	v_pk_mul_f32 v[28:29], v[28:29], v[36:37] op_sel_hi:[1,0]
	v_pk_mul_f32 v[30:31], v[30:31], v[36:37] op_sel_hi:[1,0]
	v_pk_mul_f32 v[24:25], v[24:25], v[36:37] op_sel_hi:[1,0]
	v_pk_mul_f32 v[26:27], v[26:27], v[36:37] op_sel_hi:[1,0]
	v_pk_mul_f32 v[30:31], v[134:135], v[30:31]
	v_pk_mul_f32 v[28:29], v[132:133], v[28:29]
	v_pk_mul_f32 v[32:33], v[130:131], v[26:27]
	v_pk_mul_f32 v[26:27], v[128:129], v[24:25]
	v_cvt_pk_bf16_f32 v24, v28, v29
	v_cvt_pk_bf16_f32 v25, v30, v31
	s_nop 0
	v_cvt_pk_bf16_f32 v26, v26, v27
	v_cvt_pk_bf16_f32 v27, v32, v33
	ds_read_b128 v[28:31], v44 offset:16
	v_lshlrev_b64 v[32:33], 8, v[154:155]
	v_lshl_add_u64 v[34:35], s[16:17], 0, v[32:33]
	s_waitcnt lgkmcnt(0)
	v_mov_b32_e32 v36, v29
	v_mov_b32_e32 v37, v30
	v_mov_b32_e32 v29, v31
	v_pk_add_f32 v[28:29], v[36:37], v[28:29]
	v_lshl_add_u64 v[30:31], v[34:35], 0, s[26:27]
	v_add_f32_e32 v28, v28, v29
	v_fmamk_f32 v28, v28, 0x3c000000, v177
	v_rsq_f32_e32 v28, v28
	v_lshl_add_u64 v[30:31], v[30:31], 0, v[120:121]
	global_store_dwordx4 v[30:31], v[24:27], off
	v_pk_mul_f32 v[20:21], v[20:21], v[28:29] op_sel_hi:[1,0]
	v_pk_mul_f32 v[22:23], v[22:23], v[28:29] op_sel_hi:[1,0]
	v_pk_mul_f32 v[16:17], v[16:17], v[28:29] op_sel_hi:[1,0]
	v_pk_mul_f32 v[18:19], v[18:19], v[28:29] op_sel_hi:[1,0]
	v_pk_mul_f32 v[22:23], v[134:135], v[22:23]
	v_pk_mul_f32 v[20:21], v[132:133], v[20:21]
	v_pk_mul_f32 v[24:25], v[130:131], v[18:19]
	v_pk_mul_f32 v[18:19], v[128:129], v[16:17]
	v_lshl_add_u32 v28, v152, 5, s0
	v_cvt_pk_bf16_f32 v16, v20, v21
	v_cvt_pk_bf16_f32 v17, v22, v23
	v_cvt_pk_bf16_f32 v18, v18, v19
	v_cvt_pk_bf16_f32 v19, v24, v25
	ds_read_b128 v[20:23], v28
	v_lshl_add_u64 v[24:25], s[12:13], 0, v[32:33]
	s_waitcnt lgkmcnt(0)
	v_mov_b32_e32 v26, v21
	v_mov_b32_e32 v27, v22
	v_mov_b32_e32 v21, v23
	v_pk_add_f32 v[20:21], v[26:27], v[20:21]
	v_lshl_add_u64 v[22:23], v[24:25], 0, s[26:27]
	v_add_f32_e32 v20, v20, v21
	v_fmamk_f32 v20, v20, 0x3c000000, v177
	v_rsq_f32_e32 v20, v20
	v_lshl_add_u64 v[22:23], v[22:23], 0, v[120:121]
	global_store_dwordx4 v[22:23], v[16:19], off
	v_pk_mul_f32 v[12:13], v[12:13], v[20:21] op_sel_hi:[1,0]
	v_pk_mul_f32 v[14:15], v[14:15], v[20:21] op_sel_hi:[1,0]
	v_pk_mul_f32 v[8:9], v[8:9], v[20:21] op_sel_hi:[1,0]
	v_pk_mul_f32 v[10:11], v[10:11], v[20:21] op_sel_hi:[1,0]
	v_pk_mul_f32 v[14:15], v[134:135], v[14:15]
	v_pk_mul_f32 v[12:13], v[132:133], v[12:13]
	v_pk_mul_f32 v[16:17], v[130:131], v[10:11]
	v_pk_mul_f32 v[10:11], v[128:129], v[8:9]
	v_cvt_pk_bf16_f32 v8, v12, v13
	v_cvt_pk_bf16_f32 v9, v14, v15
	s_nop 0
	v_cvt_pk_bf16_f32 v10, v10, v11
	v_cvt_pk_bf16_f32 v11, v16, v17
	ds_read_b128 v[12:15], v28 offset:16
	v_lshlrev_b64 v[16:17], 8, v[152:153]
	v_lshl_add_u64 v[18:19], s[16:17], 0, v[16:17]
	s_waitcnt lgkmcnt(0)
	v_mov_b32_e32 v20, v13
	v_mov_b32_e32 v21, v14
	v_mov_b32_e32 v13, v15
	v_pk_add_f32 v[12:13], v[20:21], v[12:13]
	v_lshl_add_u64 v[14:15], v[18:19], 0, s[26:27]
	v_add_f32_e32 v12, v12, v13
	v_fmamk_f32 v12, v12, 0x3c000000, v177
	v_rsq_f32_e32 v12, v12
	v_lshl_add_u64 v[14:15], v[14:15], 0, v[120:121]
	global_store_dwordx4 v[14:15], v[8:11], off
	v_pk_mul_f32 v[4:5], v[4:5], v[12:13] op_sel_hi:[1,0]
	s_nop 0
	v_pk_mul_f32 v[4:5], v[132:133], v[4:5]
	v_pk_mul_f32 v[0:1], v[0:1], v[12:13] op_sel_hi:[1,0]
	v_pk_mul_f32 v[2:3], v[2:3], v[12:13] op_sel_hi:[1,0]
	v_pk_mul_f32 v[6:7], v[6:7], v[12:13] op_sel_hi:[1,0]
	v_pk_mul_f32 v[8:9], v[130:131], v[2:3]
	v_pk_mul_f32 v[2:3], v[128:129], v[0:1]
	v_cvt_pk_bf16_f32 v0, v4, v5
	v_lshl_add_u64 v[4:5], s[12:13], 0, v[16:17]
	v_lshl_add_u64 v[4:5], v[4:5], 0, s[26:27]
	v_lshl_add_u64 v[4:5], v[4:5], 0, v[120:121]
	v_pk_mul_f32 v[6:7], v[134:135], v[6:7]
	s_nop 0
	v_cvt_pk_bf16_f32 v1, v6, v7
	v_cvt_pk_bf16_f32 v2, v2, v3
	v_cvt_pk_bf16_f32 v3, v8, v9
	global_store_dwordx4 v[4:5], v[0:3], off

; template <int K> __device__ __forceinline__ float shx(float v) { static_assert(K < 32, "use sum32"); return __int_as_float(__builtin_amdgcn_ds_swizzle(__float_as_int(v), (K << 10) | 0x1f)); }
; __device__ __forceinline__ float sum32(float v) { auto rr = __builtin_amdgcn_permlane32_swap(__float_as_uint(v), __float_as_uint(v), false, false); return __uint_as_float(rr[0]) + __uint_as_float(rr[1]); }
; template <bool ROWSCALE>
; __device__ __forceinline__ void head_norm_store(const f32x4 (&acc)[2][2][4][2], const float (&rs)[2][4], const float* gain, bf16_t* d0, bf16_t* d1, PG8_LAS float* red, int wr, int wc, int fr, int fq) {
;     ...
;             for (int bj = 0; bj < 2; ++bj) { float s = 0.f;
; #pragma unroll
;                 for (int n = 0; n < 2; ++n) { f32x4 v = acc[ai][bj][m][n]; if (ROWSCALE) v = v * rs[ai][m]; s += (v[0] * v[0] + v[1] * v[1]) + (v[2] * v[2] + v[3] * v[3]); }
;                 s += shx<16>(s); s = sum32(s);
;                 if (fq == 0) red[((ai * HALF + wr * 64 + m * 16 + fr) * 2 + bj) * 4 + wc] = s; }
.LBB0_524:
	s_andn2_b64 vcc, exec, s[18:19]
	s_cbranch_vccnz .LBB0_558
	v_mul_f32_e32 v129, v125, v125
	v_mul_f32_e32 v130, v127, v127
	v_fmac_f32_e32 v129, v124, v124
	v_fmac_f32_e32 v130, v126, v126
	v_add_f32_e32 v129, v129, v130
	v_mul_f32_e32 v130, v121, v121
	v_mul_f32_e32 v131, v123, v123
	v_fmac_f32_e32 v130, v120, v120
	v_fmac_f32_e32 v131, v122, v122
	v_add_f32_e32 v130, v130, v131
	v_add_f32_e32 v129, v129, v130
	s_nop 1
	v_mov_b32_e32 v130, v129
	v_mov_b32_e32 v253, v129
	s_nop 1
	v_permlane16_swap_b32_e32 v130, v253
	s_mov_b32 s98, 0xffff
	s_mov_b32 s99, 0xffff
	v_cndmask_b32_e64 v130, v130, v253, s[98:99]
	v_lshlrev_b32_e32 v128, 5, v134
	v_cmp_eq_u32_e32 vcc, 0, v135
	v_add_u32_e32 v128, s58, v128
	s_waitcnt lgkmcnt(0)
	v_add_f32_e32 v129, v129, v130
	v_mov_b32_e32 v130, v129
	s_nop 1
	v_permlane32_swap_b32_e32 v129, v130
	s_and_saveexec_b64 s[18:19], vcc
	v_add_f32_e32 v129, v129, v130
	ds_write_b32 v128, v129
	s_or_b64 exec, exec, s[18:19]
	v_mul_f32_e32 v129, v117, v117
	v_mul_f32_e32 v130, v119, v119
	v_fmac_f32_e32 v129, v116, v116
	v_fmac_f32_e32 v130, v118, v118
	v_add_f32_e32 v129, v129, v130
	v_mul_f32_e32 v130, v113, v113
	v_mul_f32_e32 v131, v115, v115
	v_fmac_f32_e32 v130, v112, v112
	v_fmac_f32_e32 v131, v114, v114
	v_add_f32_e32 v130, v130, v131
	v_add_f32_e32 v129, v129, v130
	s_nop 1
	v_mov_b32_e32 v130, v129
	v_mov_b32_e32 v253, v129
	s_nop 1
	v_permlane16_swap_b32_e32 v130, v253
	s_mov_b32 s98, 0xffff
	s_mov_b32 s99, 0xffff
	v_cndmask_b32_e64 v130, v130, v253, s[98:99]
	s_waitcnt lgkmcnt(0)
	v_add_f32_e32 v129, v129, v130
	v_mov_b32_e32 v130, v129
	s_nop 1
	v_permlane32_swap_b32_e32 v129, v130
	s_and_saveexec_b64 s[18:19], vcc
	v_add_f32_e32 v129, v129, v130
	ds_write_b32 v128, v129 offset:16
	s_or_b64 exec, exec, s[18:19]
	v_mul_f32_e32 v129, v109, v109
	v_mul_f32_e32 v130, v111, v111
	v_fmac_f32_e32 v129, v108, v108
	v_fmac_f32_e32 v130, v110, v110
	v_add_f32_e32 v129, v129, v130
	v_mul_f32_e32 v130, v105, v105
	v_mul_f32_e32 v131, v107, v107
	v_fmac_f32_e32 v130, v104, v104
	v_fmac_f32_e32 v131, v106, v106
	v_add_f32_e32 v130, v130, v131
	v_add_f32_e32 v129, v129, v130
	s_nop 1
	v_mov_b32_e32 v130, v129
	v_mov_b32_e32 v253, v129
	s_nop 1
	v_permlane16_swap_b32_e32 v130, v253
	s_mov_b32 s98, 0xffff
	s_mov_b32 s99, 0xffff
	v_cndmask_b32_e64 v130, v130, v253, s[98:99]
	s_waitcnt lgkmcnt(0)
	v_add_f32_e32 v129, v129, v130
	v_mov_b32_e32 v130, v129
	s_nop 1
	v_permlane32_swap_b32_e32 v129, v130
	s_and_saveexec_b64 s[18:19], vcc
	v_add_f32_e32 v129, v129, v130
	ds_write_b32 v128, v129 offset:512
	s_or_b64 exec, exec, s[18:19]
	v_mul_f32_e32 v129, v101, v101
	v_mul_f32_e32 v130, v103, v103
	v_fmac_f32_e32 v129, v100, v100
	v_fmac_f32_e32 v130, v102, v102
	v_add_f32_e32 v129, v129, v130
	v_mul_f32_e32 v130, v97, v97
	v_mul_f32_e32 v131, v99, v99
	v_fmac_f32_e32 v130, v96, v96
	v_fmac_f32_e32 v131, v98, v98
	v_add_f32_e32 v130, v130, v131
	v_add_f32_e32 v129, v129, v130
	s_nop 1
	v_mov_b32_e32 v130, v129
	v_mov_b32_e32 v253, v129
	s_nop 1
	v_permlane16_swap_b32_e32 v130, v253
	s_mov_b32 s98, 0xffff
	s_mov_b32 s99, 0xffff
	v_cndmask_b32_e64 v130, v130, v253, s[98:99]
	s_waitcnt lgkmcnt(0)
	v_add_f32_e32 v129, v129, v130
	v_mov_b32_e32 v130, v129
	s_nop 1
	v_permlane32_swap_b32_e32 v129, v130
	s_and_saveexec_b64 s[18:19], vcc
	v_add_f32_e32 v129, v129, v130
	ds_write_b32 v128, v129 offset:528
	s_or_b64 exec, exec, s[18:19]
	v_mul_f32_e32 v129, v93, v93
	v_mul_f32_e32 v130, v95, v95
	v_fmac_f32_e32 v129, v92, v92
	v_fmac_f32_e32 v130, v94, v94
	v_add_f32_e32 v129, v129, v130
	v_mul_f32_e32 v130, v89, v89
	v_mul_f32_e32 v131, v91, v91
	v_fmac_f32_e32 v130, v88, v88
	v_fmac_f32_e32 v131, v90, v90
	v_add_f32_e32 v130, v130, v131
	v_add_f32_e32 v129, v129, v130
	s_nop 1
	v_mov_b32_e32 v130, v129
	v_mov_b32_e32 v253, v129
	s_nop 1
	v_permlane16_swap_b32_e32 v130, v253
	s_mov_b32 s98, 0xffff
	s_mov_b32 s99, 0xffff
	v_cndmask_b32_e64 v130, v130, v253, s[98:99]
	s_waitcnt lgkmcnt(0)
	v_add_f32_e32 v129, v129, v130
	v_mov_b32_e32 v130, v129
	s_nop 1
	v_permlane32_swap_b32_e32 v129, v130
	s_and_saveexec_b64 s[18:19], vcc
	v_add_f32_e32 v129, v129, v130
	ds_write_b32 v128, v129 offset:1024
	s_or_b64 exec, exec, s[18:19]
	v_mul_f32_e32 v129, v85, v85
	v_mul_f32_e32 v130, v87, v87
	v_fmac_f32_e32 v129, v84, v84
	v_fmac_f32_e32 v130, v86, v86
	v_add_f32_e32 v129, v129, v130
	v_mul_f32_e32 v130, v81, v81
	v_mul_f32_e32 v131, v83, v83
	v_fmac_f32_e32 v130, v80, v80
	v_fmac_f32_e32 v131, v82, v82
	v_add_f32_e32 v130, v130, v131
	v_add_f32_e32 v129, v129, v130
	s_nop 1
	v_mov_b32_e32 v130, v129
	v_mov_b32_e32 v253, v129
	s_nop 1
	v_permlane16_swap_b32_e32 v130, v253
	s_mov_b32 s98, 0xffff
	s_mov_b32 s99, 0xffff
	v_cndmask_b32_e64 v130, v130, v253, s[98:99]
	s_waitcnt lgkmcnt(0)
	v_add_f32_e32 v129, v129, v130
	v_mov_b32_e32 v130, v129
	s_nop 1
	v_permlane32_swap_b32_e32 v129, v130
	s_and_saveexec_b64 s[18:19], vcc
	v_add_f32_e32 v129, v129, v130
	ds_write_b32 v128, v129 offset:1040
	s_or_b64 exec, exec, s[18:19]
	v_mul_f32_e32 v129, v77, v77
	v_mul_f32_e32 v130, v79, v79
	v_fmac_f32_e32 v129, v76, v76
	v_fmac_f32_e32 v130, v78, v78
	v_add_f32_e32 v129, v129, v130
	v_mul_f32_e32 v130, v73, v73
	v_mul_f32_e32 v131, v75, v75
	v_fmac_f32_e32 v130, v72, v72
	v_fmac_f32_e32 v131, v74, v74
	v_add_f32_e32 v130, v130, v131
	v_add_f32_e32 v129, v129, v130
	s_nop 1
	v_mov_b32_e32 v130, v129
	v_mov_b32_e32 v253, v129
	s_nop 1
	v_permlane16_swap_b32_e32 v130, v253
	s_mov_b32 s98, 0xffff
	s_mov_b32 s99, 0xffff
	v_cndmask_b32_e64 v130, v130, v253, s[98:99]
	s_waitcnt lgkmcnt(0)
; template <int K> __device__ __forceinline__ float shx(float v) { static_assert(K < 32, "use sum32"); return __int_as_float(__builtin_amdgcn_ds_swizzle(__float_as_int(v), (K << 10) | 0x1f)); }
; __device__ __forceinline__ float sum32(float v) { auto rr = __builtin_amdgcn_permlane32_swap(__float_as_uint(v), __float_as_uint(v), false, false); return __uint_as_float(rr[0]) + __uint_as_float(rr[1]); }
; template <bool ROWSCALE>
; __device__ __forceinline__ void head_norm_store(const f32x4 (&acc)[2][2][4][2], const float (&rs)[2][4], const float* gain, bf16_t* d0, bf16_t* d1, PG8_LAS float* red, int wr, int wc, int fr, int fq) {
;     ...
;             for (int bj = 0; bj < 2; ++bj) { float s = 0.f;
; #pragma unroll
;                 for (int n = 0; n < 2; ++n) { f32x4 v = acc[ai][bj][m][n]; if (ROWSCALE) v = v * rs[ai][m]; s += (v[0] * v[0] + v[1] * v[1]) + (v[2] * v[2] + v[3] * v[3]); }
;                 s += shx<16>(s); s = sum32(s);
;                 if (fq == 0) red[((ai * HALF + wr * 64 + m * 16 + fr) * 2 + bj) * 4 + wc] = s; }
	v_add_f32_e32 v129, v129, v130
	v_mov_b32_e32 v130, v129
	s_nop 1
	v_permlane32_swap_b32_e32 v129, v130
	s_and_saveexec_b64 s[18:19], vcc
	v_add_f32_e32 v129, v129, v130
	ds_write_b32 v128, v129 offset:1536
	s_or_b64 exec, exec, s[18:19]
	v_mul_f32_e32 v129, v69, v69
	v_mul_f32_e32 v130, v71, v71
	v_fmac_f32_e32 v129, v68, v68
	v_fmac_f32_e32 v130, v70, v70
	v_add_f32_e32 v129, v129, v130
	v_mul_f32_e32 v130, v65, v65
	v_mul_f32_e32 v131, v67, v67
	v_fmac_f32_e32 v130, v64, v64
	v_fmac_f32_e32 v131, v66, v66
	v_add_f32_e32 v130, v130, v131
	v_add_f32_e32 v129, v129, v130
	s_nop 1
	v_mov_b32_e32 v130, v129
	v_mov_b32_e32 v253, v129
	s_nop 1
	v_permlane16_swap_b32_e32 v130, v253
	s_mov_b32 s98, 0xffff
	s_mov_b32 s99, 0xffff
	v_cndmask_b32_e64 v130, v130, v253, s[98:99]
	s_waitcnt lgkmcnt(0)
	v_add_f32_e32 v129, v129, v130
	v_mov_b32_e32 v130, v129
	s_nop 1
	v_permlane32_swap_b32_e32 v129, v130
	s_and_saveexec_b64 s[18:19], vcc
	v_add_f32_e32 v129, v129, v130
	ds_write_b32 v128, v129 offset:1552
	s_or_b64 exec, exec, s[18:19]
	v_mul_f32_e32 v129, v61, v61
	v_mul_f32_e32 v130, v63, v63
	v_fmac_f32_e32 v129, v60, v60
	v_fmac_f32_e32 v130, v62, v62
	v_add_f32_e32 v129, v129, v130
	v_mul_f32_e32 v130, v57, v57
	v_mul_f32_e32 v131, v59, v59
	v_fmac_f32_e32 v130, v56, v56
	v_fmac_f32_e32 v131, v58, v58
	v_add_f32_e32 v130, v130, v131
	v_add_f32_e32 v129, v129, v130
	s_nop 1
	v_mov_b32_e32 v130, v129
	v_mov_b32_e32 v253, v129
	s_nop 1
	v_permlane16_swap_b32_e32 v130, v253
	s_mov_b32 s98, 0xffff
	s_mov_b32 s99, 0xffff
	v_cndmask_b32_e64 v130, v130, v253, s[98:99]
	s_waitcnt lgkmcnt(0)
	v_add_f32_e32 v129, v129, v130
	v_mov_b32_e32 v130, v129
	s_nop 1
	v_permlane32_swap_b32_e32 v129, v130
	s_and_saveexec_b64 s[18:19], vcc
	v_add_f32_e32 v129, v129, v130
	ds_write_b32 v128, v129 offset:4096
	s_or_b64 exec, exec, s[18:19]
	v_mul_f32_e32 v129, v53, v53
	v_mul_f32_e32 v130, v55, v55
	v_fmac_f32_e32 v129, v52, v52
	v_fmac_f32_e32 v130, v54, v54
	v_add_f32_e32 v129, v129, v130
	v_mul_f32_e32 v130, v49, v49
	v_mul_f32_e32 v131, v51, v51
	v_fmac_f32_e32 v130, v48, v48
	v_fmac_f32_e32 v131, v50, v50
	v_add_f32_e32 v130, v130, v131
	v_add_f32_e32 v129, v129, v130
	s_nop 1
	v_mov_b32_e32 v130, v129
	v_mov_b32_e32 v253, v129
	s_nop 1
	v_permlane16_swap_b32_e32 v130, v253
	s_mov_b32 s98, 0xffff
	s_mov_b32 s99, 0xffff
	v_cndmask_b32_e64 v130, v130, v253, s[98:99]
	s_waitcnt lgkmcnt(0)
	v_add_f32_e32 v129, v129, v130
	v_mov_b32_e32 v130, v129
	s_nop 1
	v_permlane32_swap_b32_e32 v129, v130
	s_and_saveexec_b64 s[18:19], vcc
	v_add_f32_e32 v129, v129, v130
	ds_write_b32 v128, v129 offset:4112
	s_or_b64 exec, exec, s[18:19]
	v_mul_f32_e32 v129, v45, v45
	v_mul_f32_e32 v130, v47, v47
	v_fmac_f32_e32 v129, v44, v44
	v_fmac_f32_e32 v130, v46, v46
	v_add_f32_e32 v129, v129, v130
	v_mul_f32_e32 v130, v41, v41
	v_mul_f32_e32 v131, v43, v43
	v_fmac_f32_e32 v130, v40, v40
	v_fmac_f32_e32 v131, v42, v42
	v_add_f32_e32 v130, v130, v131
	v_add_f32_e32 v129, v129, v130
	s_nop 1
	v_mov_b32_e32 v130, v129
	v_mov_b32_e32 v253, v129
	s_nop 1
	v_permlane16_swap_b32_e32 v130, v253
	s_mov_b32 s98, 0xffff
	s_mov_b32 s99, 0xffff
	v_cndmask_b32_e64 v130, v130, v253, s[98:99]
	s_waitcnt lgkmcnt(0)
	v_add_f32_e32 v129, v129, v130
	v_mov_b32_e32 v130, v129
	s_nop 1
	v_permlane32_swap_b32_e32 v129, v130
	s_and_saveexec_b64 s[18:19], vcc
	v_add_f32_e32 v129, v129, v130
	ds_write_b32 v128, v129 offset:4608
	s_or_b64 exec, exec, s[18:19]
	v_mul_f32_e32 v129, v37, v37
	v_mul_f32_e32 v130, v39, v39
	v_fmac_f32_e32 v129, v36, v36
	v_fmac_f32_e32 v130, v38, v38
	v_add_f32_e32 v129, v129, v130
	v_mul_f32_e32 v130, v33, v33
	v_mul_f32_e32 v131, v35, v35
	v_fmac_f32_e32 v130, v32, v32
	v_fmac_f32_e32 v131, v34, v34
	v_add_f32_e32 v130, v130, v131
	v_add_f32_e32 v129, v129, v130
	s_nop 1
	v_mov_b32_e32 v130, v129
	v_mov_b32_e32 v253, v129
	s_nop 1
	v_permlane16_swap_b32_e32 v130, v253
	s_mov_b32 s98, 0xffff
	s_mov_b32 s99, 0xffff
	v_cndmask_b32_e64 v130, v130, v253, s[98:99]
	s_waitcnt lgkmcnt(0)
	v_add_f32_e32 v129, v129, v130
	v_mov_b32_e32 v130, v129
	s_nop 1
	v_permlane32_swap_b32_e32 v129, v130
	s_and_saveexec_b64 s[18:19], vcc
	v_add_f32_e32 v129, v129, v130
	ds_write_b32 v128, v129 offset:4624
	s_or_b64 exec, exec, s[18:19]
	v_mul_f32_e32 v129, v29, v29
	v_mul_f32_e32 v130, v31, v31
	v_fmac_f32_e32 v129, v28, v28
	v_fmac_f32_e32 v130, v30, v30
	v_add_f32_e32 v129, v129, v130
	v_mul_f32_e32 v130, v25, v25
	v_mul_f32_e32 v131, v27, v27
	v_fmac_f32_e32 v130, v24, v24
	v_fmac_f32_e32 v131, v26, v26
	v_add_f32_e32 v130, v130, v131
	v_add_f32_e32 v129, v129, v130
	s_nop 1
	v_mov_b32_e32 v130, v129
	v_mov_b32_e32 v253, v129
	s_nop 1
	v_permlane16_swap_b32_e32 v130, v253
	s_mov_b32 s98, 0xffff
	s_mov_b32 s99, 0xffff
	v_cndmask_b32_e64 v130, v130, v253, s[98:99]
	s_waitcnt lgkmcnt(0)
	v_add_f32_e32 v129, v129, v130
	v_mov_b32_e32 v130, v129
	s_nop 1
	v_permlane32_swap_b32_e32 v129, v130
	s_and_saveexec_b64 s[18:19], vcc
	v_add_f32_e32 v129, v129, v130
	ds_write_b32 v128, v129 offset:5120
	s_or_b64 exec, exec, s[18:19]
	v_mul_f32_e32 v129, v21, v21
	v_mul_f32_e32 v130, v23, v23
	v_fmac_f32_e32 v129, v20, v20
	v_fmac_f32_e32 v130, v22, v22
	v_add_f32_e32 v129, v129, v130
	v_mul_f32_e32 v130, v17, v17
	v_mul_f32_e32 v131, v19, v19
	v_fmac_f32_e32 v130, v16, v16
	v_fmac_f32_e32 v131, v18, v18
	v_add_f32_e32 v130, v130, v131
	v_add_f32_e32 v129, v129, v130
	s_nop 1
	v_mov_b32_e32 v130, v129
	v_mov_b32_e32 v253, v129
	s_nop 1
	v_permlane16_swap_b32_e32 v130, v253
	s_mov_b32 s98, 0xffff
	s_mov_b32 s99, 0xffff
	v_cndmask_b32_e64 v130, v130, v253, s[98:99]
	s_waitcnt lgkmcnt(0)
; template <int K> __device__ __forceinline__ float shx(float v) { static_assert(K < 32, "use sum32"); return __int_as_float(__builtin_amdgcn_ds_swizzle(__float_as_int(v), (K << 10) | 0x1f)); }
; __device__ __forceinline__ float sum32(float v) { auto rr = __builtin_amdgcn_permlane32_swap(__float_as_uint(v), __float_as_uint(v), false, false); return __uint_as_float(rr[0]) + __uint_as_float(rr[1]); }
; #define PG8_LAS __attribute__((address_space(3)))
; __device__ __forceinline__ u32x4 pack8(const f32x4& a, const f32x4& b) { u32x4 w; w.x = cvt_pk_bf16(a[0], a[1]); w.y = cvt_pk_bf16(a[2], a[3]); w.z = cvt_pk_bf16(b[0], b[1]); w.w = cvt_pk_bf16(b[2], b[3]); return w; }
; template <bool ROWSCALE>
; __device__ __forceinline__ void head_norm_store(const f32x4 (&acc)[2][2][4][2], const float (&rs)[2][4], const float* gain, bf16_t* d0, bf16_t* d1, PG8_LAS float* red, int wr, int wc, int fr, int fq) {
;     ...
;             for (int bj = 0; bj < 2; ++bj) { float s = 0.f;
; #pragma unroll
;                 for (int n = 0; n < 2; ++n) { f32x4 v = acc[ai][bj][m][n]; if (ROWSCALE) v = v * rs[ai][m]; s += (v[0] * v[0] + v[1] * v[1]) + (v[2] * v[2] + v[3] * v[3]); }
;                 s += shx<16>(s); s = sum32(s);
;                 if (fq == 0) red[((ai * HALF + wr * 64 + m * 16 + fr) * 2 + bj) * 4 + wc] = s; }
;     asm volatile("s_waitcnt lgkmcnt(0)" ::: "memory"); __builtin_amdgcn_s_barrier(); asm volatile("" ::: "memory");
;     const f32x4 g0 = *(const f32x4*)(gain + wc * 32 + fq * 8), g1 = *(const f32x4*)(gain + wc * 32 + fq * 8 + 4);
; #pragma unroll
;     for (int ai = 0; ai < 2; ++ai)
; #pragma unroll
;         for (int m = 0; m < 4; ++m) { const int rl = ai * HALF + wr * 64 + m * 16 + fr;
; #pragma unroll
;             for (int bj = 0; bj < 2; ++bj) { const PG8_LAS float* rp = red + (rl * 2 + bj) * 4;
;                 const float ss = (rp[0] + rp[1]) + (rp[2] + rp[3]);
;                 float sc = __builtin_amdgcn_rsqf(ss * (1.0f / 128.0f) + RMS_EPS); if (ROWSCALE) sc *= rs[ai][m];
;                 const f32x4 v0 = acc[ai][bj][m][0] * sc * g0, v1 = acc[ai][bj][m][1] * sc * g1;
;                 *(u32x4*)((bj ? d1 : d0) + (size_t)rl * 128 + wc * 32 + fq * 8) = pack8(v0, v1); } }
	v_add_f32_e32 v129, v129, v130
	v_mov_b32_e32 v130, v129
	s_nop 1
	v_permlane32_swap_b32_e32 v129, v130
	s_and_saveexec_b64 s[18:19], vcc
	v_add_f32_e32 v129, v129, v130
	ds_write_b32 v128, v129 offset:5136
	s_or_b64 exec, exec, s[18:19]
	v_mul_f32_e32 v129, v13, v13
	v_mul_f32_e32 v130, v15, v15
	v_fmac_f32_e32 v129, v12, v12
	v_fmac_f32_e32 v130, v14, v14
	v_add_f32_e32 v129, v129, v130
	v_mul_f32_e32 v130, v9, v9
	v_mul_f32_e32 v131, v11, v11
	v_fmac_f32_e32 v130, v8, v8
	v_fmac_f32_e32 v131, v10, v10
	v_add_f32_e32 v130, v130, v131
	v_add_f32_e32 v129, v129, v130
	s_nop 1
	v_mov_b32_e32 v130, v129
	v_mov_b32_e32 v253, v129
	s_nop 1
	v_permlane16_swap_b32_e32 v130, v253
	s_mov_b32 s98, 0xffff
	s_mov_b32 s99, 0xffff
	v_cndmask_b32_e64 v130, v130, v253, s[98:99]
	s_waitcnt lgkmcnt(0)
	v_add_f32_e32 v129, v129, v130
	v_mov_b32_e32 v130, v129
	s_nop 1
	v_permlane32_swap_b32_e32 v129, v130
	s_and_saveexec_b64 s[18:19], vcc
	v_add_f32_e32 v129, v129, v130
	ds_write_b32 v128, v129 offset:5632
	s_or_b64 exec, exec, s[18:19]
	v_mul_f32_e32 v129, v5, v5
	v_mul_f32_e32 v130, v7, v7
	v_fmac_f32_e32 v129, v4, v4
	v_fmac_f32_e32 v130, v6, v6
	v_add_f32_e32 v129, v129, v130
	v_mul_f32_e32 v130, v1, v1
	v_mul_f32_e32 v131, v3, v3
	v_fmac_f32_e32 v130, v0, v0
	v_fmac_f32_e32 v131, v2, v2
	v_add_f32_e32 v130, v130, v131
	v_add_f32_e32 v129, v129, v130
	s_nop 1
	v_mov_b32_e32 v130, v129
	v_mov_b32_e32 v253, v129
	s_nop 1
	v_permlane16_swap_b32_e32 v130, v253
	s_mov_b32 s98, 0xffff
	s_mov_b32 s99, 0xffff
	v_cndmask_b32_e64 v130, v130, v253, s[98:99]
	s_waitcnt lgkmcnt(0)
	v_add_f32_e32 v129, v129, v130
	v_mov_b32_e32 v130, v129
	s_nop 1
	v_permlane32_swap_b32_e32 v129, v130
	s_and_saveexec_b64 s[18:19], vcc
	v_add_f32_e32 v129, v129, v130
	ds_write_b32 v128, v129 offset:5648
	s_or_b64 exec, exec, s[18:19]
	s_waitcnt lgkmcnt(0)
	s_barrier
	v_lshl_add_u64 v[128:129], v[148:149], 2, s[30:31]
	global_load_dwordx4 v[132:135], v[128:129], off
	s_nop 0
	global_load_dwordx4 v[128:131], v[128:129], off offset:16
	s_add_i32 s18, 0, 0x20000
	v_lshl_add_u32 v151, v164, 5, s18
	ds_read_b128 v[174:177], v151
	v_lshlrev_b64 v[164:165], 8, v[164:165]
	s_lshl_b32 s0, s46, 1
	v_ashrrev_i32_e32 v163, 31, v162
	v_ashrrev_i32_e32 v161, 31, v160
	s_waitcnt lgkmcnt(0)
	v_mov_b32_e32 v178, v175
	v_mov_b32_e32 v179, v176
	v_mov_b32_e32 v175, v177
	v_pk_add_f32 v[174:175], v[178:179], v[174:175]
	v_ashrrev_i32_e32 v159, 31, v158
	v_add_f32_e32 v153, v174, v175
	v_fmamk_f32 v153, v153, 0x3c000000, v172
	v_rsq_f32_e32 v174, v153
	v_ashrrev_i32_e32 v157, 31, v156
	v_ashrrev_i32_e32 v155, 31, v154
	v_pk_mul_f32 v[124:125], v[124:125], v[174:175] op_sel_hi:[1,0]
	v_pk_mul_f32 v[122:123], v[122:123], v[174:175] op_sel_hi:[1,0]
	v_pk_mul_f32 v[126:127], v[126:127], v[174:175] op_sel_hi:[1,0]
	v_pk_mul_f32 v[120:121], v[120:121], v[174:175] op_sel_hi:[1,0]
	s_waitcnt vmcnt(0)
	v_pk_mul_f32 v[124:125], v[132:133], v[124:125]
	v_pk_mul_f32 v[174:175], v[130:131], v[122:123]
	v_pk_mul_f32 v[126:127], v[134:135], v[126:127]
	v_pk_mul_f32 v[120:121], v[128:129], v[120:121]
	v_cvt_pk_bf16_f32 v122, v124, v125
	v_cvt_pk_bf16_f32 v123, v126, v127
	v_lshl_add_u64 v[126:127], s[16:17], 0, v[164:165]
	v_cvt_pk_bf16_f32 v124, v120, v121
	v_cvt_pk_bf16_f32 v125, v174, v175
	ds_read_b128 v[174:177], v151 offset:16
	v_lshlrev_b64 v[120:121], 1, v[148:149]
	v_lshl_add_u64 v[126:127], v[126:127], 0, s[0:1]
	v_lshl_add_u64 v[126:127], v[126:127], 0, v[120:121]
	v_lshl_add_u32 v151, v162, 5, s18
	s_waitcnt lgkmcnt(0)
	v_mov_b32_e32 v178, v175
	v_mov_b32_e32 v179, v176
	v_mov_b32_e32 v175, v177
	v_pk_add_f32 v[174:175], v[178:179], v[174:175]
	global_store_dwordx4 v[126:127], v[122:125], off
	v_add_f32_e32 v153, v174, v175
	v_fmamk_f32 v153, v153, 0x3c000000, v172
	v_rsq_f32_e32 v174, v153
	v_ashrrev_i32_e32 v153, 31, v152
	v_pk_mul_f32 v[116:117], v[116:117], v[174:175] op_sel_hi:[1,0]
	v_pk_mul_f32 v[118:119], v[118:119], v[174:175] op_sel_hi:[1,0]
	v_pk_mul_f32 v[112:113], v[112:113], v[174:175] op_sel_hi:[1,0]
	v_pk_mul_f32 v[114:115], v[114:115], v[174:175] op_sel_hi:[1,0]
	v_pk_mul_f32 v[118:119], v[134:135], v[118:119]
	v_pk_mul_f32 v[116:117], v[132:133], v[116:117]
	v_pk_mul_f32 v[122:123], v[130:131], v[114:115]
	v_pk_mul_f32 v[114:115], v[128:129], v[112:113]
	v_cvt_pk_bf16_f32 v112, v116, v117
	v_cvt_pk_bf16_f32 v113, v118, v119
	s_nop 0
	v_cvt_pk_bf16_f32 v114, v114, v115
	v_cvt_pk_bf16_f32 v115, v122, v123
	ds_read_b128 v[116:119], v151
	v_lshl_add_u64 v[122:123], s[12:13], 0, v[164:165]
	s_waitcnt lgkmcnt(0)
	v_mov_b32_e32 v124, v117
	v_mov_b32_e32 v125, v118
	v_mov_b32_e32 v117, v119
	v_pk_add_f32 v[116:117], v[124:125], v[116:117]
	v_lshl_add_u64 v[118:119], v[122:123], 0, s[0:1]
	v_add_f32_e32 v116, v116, v117
	v_fmamk_f32 v116, v116, 0x3c000000, v172
	v_rsq_f32_e32 v116, v116
	v_lshl_add_u64 v[118:119], v[118:119], 0, v[120:121]
	global_store_dwordx4 v[118:119], v[112:115], off
	v_lshl_add_u32 v118, v160, 5, s18
	v_pk_mul_f32 v[108:109], v[108:109], v[116:117] op_sel_hi:[1,0]
	v_pk_mul_f32 v[110:111], v[110:111], v[116:117] op_sel_hi:[1,0]
	v_pk_mul_f32 v[104:105], v[104:105], v[116:117] op_sel_hi:[1,0]
	v_pk_mul_f32 v[106:107], v[106:107], v[116:117] op_sel_hi:[1,0]
	v_pk_mul_f32 v[110:111], v[134:135], v[110:111]
	v_pk_mul_f32 v[108:109], v[132:133], v[108:109]
	v_pk_mul_f32 v[112:113], v[130:131], v[106:107]
	v_pk_mul_f32 v[106:107], v[128:129], v[104:105]
	v_cvt_pk_bf16_f32 v104, v108, v109
	v_cvt_pk_bf16_f32 v105, v110, v111
	s_nop 0
	v_cvt_pk_bf16_f32 v106, v106, v107
	v_cvt_pk_bf16_f32 v107, v112, v113
	ds_read_b128 v[108:111], v151 offset:16
	v_lshlrev_b64 v[112:113], 8, v[162:163]
	v_lshl_add_u64 v[114:115], s[16:17], 0, v[112:113]
	v_ashrrev_i32_e32 v151, 31, v150
	s_waitcnt lgkmcnt(0)
; #define PG8_LAS __attribute__((address_space(3)))
; __device__ __forceinline__ u32x4 pack8(const f32x4& a, const f32x4& b) { u32x4 w; w.x = cvt_pk_bf16(a[0], a[1]); w.y = cvt_pk_bf16(a[2], a[3]); w.z = cvt_pk_bf16(b[0], b[1]); w.w = cvt_pk_bf16(b[2], b[3]); return w; }
; template <bool ROWSCALE>
; __device__ __forceinline__ void head_norm_store(const f32x4 (&acc)[2][2][4][2], const float (&rs)[2][4], const float* gain, bf16_t* d0, bf16_t* d1, PG8_LAS float* red, int wr, int wc, int fr, int fq) {
;     ...
;     for (int ai = 0; ai < 2; ++ai)
; #pragma unroll
;         for (int m = 0; m < 4; ++m) { const int rl = ai * HALF + wr * 64 + m * 16 + fr;
; #pragma unroll
;             for (int bj = 0; bj < 2; ++bj) { const PG8_LAS float* rp = red + (rl * 2 + bj) * 4;
;                 const float ss = (rp[0] + rp[1]) + (rp[2] + rp[3]);
;                 float sc = __builtin_amdgcn_rsqf(ss * (1.0f / 128.0f) + RMS_EPS); if (ROWSCALE) sc *= rs[ai][m];
;                 const f32x4 v0 = acc[ai][bj][m][0] * sc * g0, v1 = acc[ai][bj][m][1] * sc * g1;
;                 *(u32x4*)((bj ? d1 : d0) + (size_t)rl * 128 + wc * 32 + fq * 8) = pack8(v0, v1); } }
	v_mov_b32_e32 v116, v109
	v_mov_b32_e32 v117, v110
	v_mov_b32_e32 v109, v111
	v_pk_add_f32 v[108:109], v[116:117], v[108:109]
	v_lshl_add_u64 v[110:111], v[114:115], 0, s[0:1]
	v_add_f32_e32 v108, v108, v109
	v_fmamk_f32 v108, v108, 0x3c000000, v172
	v_rsq_f32_e32 v108, v108
	v_lshl_add_u64 v[110:111], v[110:111], 0, v[120:121]
	global_store_dwordx4 v[110:111], v[104:107], off
	v_pk_mul_f32 v[100:101], v[100:101], v[108:109] op_sel_hi:[1,0]
	v_pk_mul_f32 v[102:103], v[102:103], v[108:109] op_sel_hi:[1,0]
	v_pk_mul_f32 v[96:97], v[96:97], v[108:109] op_sel_hi:[1,0]
	v_pk_mul_f32 v[98:99], v[98:99], v[108:109] op_sel_hi:[1,0]
	v_pk_mul_f32 v[102:103], v[134:135], v[102:103]
	v_pk_mul_f32 v[100:101], v[132:133], v[100:101]
	v_pk_mul_f32 v[104:105], v[130:131], v[98:99]
	v_pk_mul_f32 v[98:99], v[128:129], v[96:97]
	v_cvt_pk_bf16_f32 v96, v100, v101
	v_cvt_pk_bf16_f32 v97, v102, v103
	s_nop 0
	v_cvt_pk_bf16_f32 v98, v98, v99
	v_cvt_pk_bf16_f32 v99, v104, v105
	ds_read_b128 v[100:103], v118
	v_lshl_add_u64 v[104:105], s[12:13], 0, v[112:113]
	s_waitcnt lgkmcnt(0)
	v_mov_b32_e32 v106, v101
	v_mov_b32_e32 v107, v102
	v_mov_b32_e32 v101, v103
	v_pk_add_f32 v[100:101], v[106:107], v[100:101]
	v_lshl_add_u64 v[102:103], v[104:105], 0, s[0:1]
	v_add_f32_e32 v100, v100, v101
	v_fmamk_f32 v100, v100, 0x3c000000, v172
	v_rsq_f32_e32 v100, v100
	v_lshl_add_u64 v[102:103], v[102:103], 0, v[120:121]
	global_store_dwordx4 v[102:103], v[96:99], off
	v_lshl_add_u32 v102, v158, 5, s18
	v_pk_mul_f32 v[92:93], v[92:93], v[100:101] op_sel_hi:[1,0]
	v_pk_mul_f32 v[94:95], v[94:95], v[100:101] op_sel_hi:[1,0]
	v_pk_mul_f32 v[88:89], v[88:89], v[100:101] op_sel_hi:[1,0]
	v_pk_mul_f32 v[90:91], v[90:91], v[100:101] op_sel_hi:[1,0]
	v_pk_mul_f32 v[94:95], v[134:135], v[94:95]
	v_pk_mul_f32 v[92:93], v[132:133], v[92:93]
	v_pk_mul_f32 v[96:97], v[130:131], v[90:91]
	v_pk_mul_f32 v[90:91], v[128:129], v[88:89]
	v_cvt_pk_bf16_f32 v88, v92, v93
	v_cvt_pk_bf16_f32 v89, v94, v95
	s_nop 0
	v_cvt_pk_bf16_f32 v90, v90, v91
	v_cvt_pk_bf16_f32 v91, v96, v97
	ds_read_b128 v[92:95], v118 offset:16
	v_lshlrev_b64 v[96:97], 8, v[160:161]
	v_lshl_add_u64 v[98:99], s[16:17], 0, v[96:97]
	s_waitcnt lgkmcnt(0)
	v_mov_b32_e32 v100, v93
	v_mov_b32_e32 v101, v94
	v_mov_b32_e32 v93, v95
	v_pk_add_f32 v[92:93], v[100:101], v[92:93]
	v_lshl_add_u64 v[94:95], v[98:99], 0, s[0:1]
	v_add_f32_e32 v92, v92, v93
	v_fmamk_f32 v92, v92, 0x3c000000, v172
	v_rsq_f32_e32 v92, v92
	v_lshl_add_u64 v[94:95], v[94:95], 0, v[120:121]
	global_store_dwordx4 v[94:95], v[88:91], off
	v_pk_mul_f32 v[84:85], v[84:85], v[92:93] op_sel_hi:[1,0]
	v_pk_mul_f32 v[86:87], v[86:87], v[92:93] op_sel_hi:[1,0]
	v_pk_mul_f32 v[80:81], v[80:81], v[92:93] op_sel_hi:[1,0]
	v_pk_mul_f32 v[82:83], v[82:83], v[92:93] op_sel_hi:[1,0]
	v_pk_mul_f32 v[86:87], v[134:135], v[86:87]
	v_pk_mul_f32 v[84:85], v[132:133], v[84:85]
	v_pk_mul_f32 v[88:89], v[130:131], v[82:83]
	v_pk_mul_f32 v[82:83], v[128:129], v[80:81]
	v_cvt_pk_bf16_f32 v80, v84, v85
	v_cvt_pk_bf16_f32 v81, v86, v87
	s_nop 0
	v_cvt_pk_bf16_f32 v82, v82, v83
	v_cvt_pk_bf16_f32 v83, v88, v89
	ds_read_b128 v[84:87], v102
	v_lshl_add_u64 v[88:89], s[12:13], 0, v[96:97]
	s_waitcnt lgkmcnt(0)
	v_mov_b32_e32 v90, v85
	v_mov_b32_e32 v91, v86
	v_mov_b32_e32 v85, v87
	v_pk_add_f32 v[84:85], v[90:91], v[84:85]
	v_lshl_add_u64 v[86:87], v[88:89], 0, s[0:1]
	v_add_f32_e32 v84, v84, v85
	v_fmamk_f32 v84, v84, 0x3c000000, v172
	v_rsq_f32_e32 v84, v84
	v_lshl_add_u64 v[86:87], v[86:87], 0, v[120:121]
	global_store_dwordx4 v[86:87], v[80:83], off
	v_pk_mul_f32 v[76:77], v[76:77], v[84:85] op_sel_hi:[1,0]
	v_pk_mul_f32 v[78:79], v[78:79], v[84:85] op_sel_hi:[1,0]
	v_pk_mul_f32 v[72:73], v[72:73], v[84:85] op_sel_hi:[1,0]
	v_pk_mul_f32 v[74:75], v[74:75], v[84:85] op_sel_hi:[1,0]
	v_pk_mul_f32 v[78:79], v[134:135], v[78:79]
	v_pk_mul_f32 v[76:77], v[132:133], v[76:77]
	v_pk_mul_f32 v[80:81], v[130:131], v[74:75]
	v_pk_mul_f32 v[74:75], v[128:129], v[72:73]
	v_cvt_pk_bf16_f32 v72, v76, v77
	v_cvt_pk_bf16_f32 v73, v78, v79
	s_nop 0
	v_cvt_pk_bf16_f32 v74, v74, v75
	v_cvt_pk_bf16_f32 v75, v80, v81
	ds_read_b128 v[76:79], v102 offset:16
	v_lshlrev_b64 v[80:81], 8, v[158:159]
	v_lshl_add_u64 v[82:83], s[16:17], 0, v[80:81]
	s_waitcnt lgkmcnt(0)
	v_mov_b32_e32 v84, v77
	v_mov_b32_e32 v85, v78
	v_mov_b32_e32 v77, v79
	v_pk_add_f32 v[76:77], v[84:85], v[76:77]
	v_lshl_add_u64 v[78:79], v[82:83], 0, s[0:1]
	v_add_f32_e32 v76, v76, v77
	v_fmamk_f32 v76, v76, 0x3c000000, v172
	v_rsq_f32_e32 v76, v76
	v_lshl_add_u64 v[78:79], v[78:79], 0, v[120:121]
	global_store_dwordx4 v[78:79], v[72:75], off
	v_pk_mul_f32 v[68:69], v[68:69], v[76:77] op_sel_hi:[1,0]
	v_pk_mul_f32 v[70:71], v[70:71], v[76:77] op_sel_hi:[1,0]
	v_pk_mul_f32 v[64:65], v[64:65], v[76:77] op_sel_hi:[1,0]
	v_pk_mul_f32 v[66:67], v[66:67], v[76:77] op_sel_hi:[1,0]
	v_pk_mul_f32 v[70:71], v[134:135], v[70:71]
	v_pk_mul_f32 v[68:69], v[132:133], v[68:69]
	v_pk_mul_f32 v[72:73], v[130:131], v[66:67]
	v_pk_mul_f32 v[66:67], v[128:129], v[64:65]
	v_lshl_add_u32 v76, v156, 5, s18
	v_cvt_pk_bf16_f32 v64, v68, v69
	v_cvt_pk_bf16_f32 v65, v70, v71
	v_cvt_pk_bf16_f32 v66, v66, v67
	v_cvt_pk_bf16_f32 v67, v72, v73
	ds_read_b128 v[68:71], v76
	v_lshl_add_u64 v[72:73], s[12:13], 0, v[80:81]
	s_waitcnt lgkmcnt(0)
; #define PG8_LAS __attribute__((address_space(3)))
; __device__ __forceinline__ u32x4 pack8(const f32x4& a, const f32x4& b) { u32x4 w; w.x = cvt_pk_bf16(a[0], a[1]); w.y = cvt_pk_bf16(a[2], a[3]); w.z = cvt_pk_bf16(b[0], b[1]); w.w = cvt_pk_bf16(b[2], b[3]); return w; }
; template <bool ROWSCALE>
; __device__ __forceinline__ void head_norm_store(const f32x4 (&acc)[2][2][4][2], const float (&rs)[2][4], const float* gain, bf16_t* d0, bf16_t* d1, PG8_LAS float* red, int wr, int wc, int fr, int fq) {
;     ...
;     for (int ai = 0; ai < 2; ++ai)
; #pragma unroll
;         for (int m = 0; m < 4; ++m) { const int rl = ai * HALF + wr * 64 + m * 16 + fr;
; #pragma unroll
;             for (int bj = 0; bj < 2; ++bj) { const PG8_LAS float* rp = red + (rl * 2 + bj) * 4;
;                 const float ss = (rp[0] + rp[1]) + (rp[2] + rp[3]);
;                 float sc = __builtin_amdgcn_rsqf(ss * (1.0f / 128.0f) + RMS_EPS); if (ROWSCALE) sc *= rs[ai][m];
;                 const f32x4 v0 = acc[ai][bj][m][0] * sc * g0, v1 = acc[ai][bj][m][1] * sc * g1;
;                 *(u32x4*)((bj ? d1 : d0) + (size_t)rl * 128 + wc * 32 + fq * 8) = pack8(v0, v1); } }
	v_mov_b32_e32 v74, v69
	v_mov_b32_e32 v75, v70
	v_mov_b32_e32 v69, v71
	v_pk_add_f32 v[68:69], v[74:75], v[68:69]
	v_lshl_add_u64 v[70:71], v[72:73], 0, s[0:1]
	v_add_f32_e32 v68, v68, v69
	v_fmamk_f32 v68, v68, 0x3c000000, v172
	v_rsq_f32_e32 v68, v68
	v_lshl_add_u64 v[70:71], v[70:71], 0, v[120:121]
	global_store_dwordx4 v[70:71], v[64:67], off
	v_pk_mul_f32 v[60:61], v[60:61], v[68:69] op_sel_hi:[1,0]
	v_pk_mul_f32 v[62:63], v[62:63], v[68:69] op_sel_hi:[1,0]
	v_pk_mul_f32 v[56:57], v[56:57], v[68:69] op_sel_hi:[1,0]
	v_pk_mul_f32 v[58:59], v[58:59], v[68:69] op_sel_hi:[1,0]
	v_pk_mul_f32 v[62:63], v[134:135], v[62:63]
	v_pk_mul_f32 v[60:61], v[132:133], v[60:61]
	v_pk_mul_f32 v[64:65], v[130:131], v[58:59]
	v_pk_mul_f32 v[58:59], v[128:129], v[56:57]
	v_cvt_pk_bf16_f32 v56, v60, v61
	v_cvt_pk_bf16_f32 v57, v62, v63
	s_nop 0
	v_cvt_pk_bf16_f32 v58, v58, v59
	v_cvt_pk_bf16_f32 v59, v64, v65
	ds_read_b128 v[60:63], v76 offset:16
	v_lshlrev_b64 v[64:65], 8, v[156:157]
	v_lshl_add_u64 v[66:67], s[16:17], 0, v[64:65]
	s_waitcnt lgkmcnt(0)
	v_mov_b32_e32 v68, v61
	v_mov_b32_e32 v69, v62
	v_mov_b32_e32 v61, v63
	v_pk_add_f32 v[60:61], v[68:69], v[60:61]
	v_lshl_add_u64 v[62:63], v[66:67], 0, s[0:1]
	v_add_f32_e32 v60, v60, v61
	v_fmamk_f32 v60, v60, 0x3c000000, v172
	v_rsq_f32_e32 v60, v60
	v_lshl_add_u64 v[62:63], v[62:63], 0, v[120:121]
	global_store_dwordx4 v[62:63], v[56:59], off
	v_pk_mul_f32 v[52:53], v[52:53], v[60:61] op_sel_hi:[1,0]
	v_pk_mul_f32 v[54:55], v[54:55], v[60:61] op_sel_hi:[1,0]
	v_pk_mul_f32 v[48:49], v[48:49], v[60:61] op_sel_hi:[1,0]
	v_pk_mul_f32 v[50:51], v[50:51], v[60:61] op_sel_hi:[1,0]
	v_pk_mul_f32 v[54:55], v[134:135], v[54:55]
	v_pk_mul_f32 v[52:53], v[132:133], v[52:53]
	v_pk_mul_f32 v[56:57], v[130:131], v[50:51]
	v_pk_mul_f32 v[50:51], v[128:129], v[48:49]
	v_lshl_add_u32 v60, v154, 5, s18
	v_cvt_pk_bf16_f32 v48, v52, v53
	v_cvt_pk_bf16_f32 v49, v54, v55
	v_cvt_pk_bf16_f32 v50, v50, v51
	v_cvt_pk_bf16_f32 v51, v56, v57
	ds_read_b128 v[52:55], v60
	v_lshl_add_u64 v[56:57], s[12:13], 0, v[64:65]
	s_waitcnt lgkmcnt(0)
	v_mov_b32_e32 v58, v53
	v_mov_b32_e32 v59, v54
	v_mov_b32_e32 v53, v55
	v_pk_add_f32 v[52:53], v[58:59], v[52:53]
	v_lshl_add_u64 v[54:55], v[56:57], 0, s[0:1]
	v_add_f32_e32 v52, v52, v53
	v_fmamk_f32 v52, v52, 0x3c000000, v172
	v_rsq_f32_e32 v52, v52
	v_lshl_add_u64 v[54:55], v[54:55], 0, v[120:121]
	global_store_dwordx4 v[54:55], v[48:51], off
	v_pk_mul_f32 v[44:45], v[44:45], v[52:53] op_sel_hi:[1,0]
	v_pk_mul_f32 v[46:47], v[46:47], v[52:53] op_sel_hi:[1,0]
	v_pk_mul_f32 v[40:41], v[40:41], v[52:53] op_sel_hi:[1,0]
	v_pk_mul_f32 v[42:43], v[42:43], v[52:53] op_sel_hi:[1,0]
	v_pk_mul_f32 v[46:47], v[134:135], v[46:47]
	v_pk_mul_f32 v[44:45], v[132:133], v[44:45]
	v_pk_mul_f32 v[48:49], v[130:131], v[42:43]
	v_pk_mul_f32 v[42:43], v[128:129], v[40:41]
	v_cvt_pk_bf16_f32 v40, v44, v45
	v_cvt_pk_bf16_f32 v41, v46, v47
	s_nop 0
	v_cvt_pk_bf16_f32 v42, v42, v43
	v_cvt_pk_bf16_f32 v43, v48, v49
	ds_read_b128 v[44:47], v60 offset:16
	v_lshlrev_b64 v[48:49], 8, v[154:155]
	v_lshl_add_u64 v[50:51], s[16:17], 0, v[48:49]
	s_waitcnt lgkmcnt(0)
	v_mov_b32_e32 v52, v45
	v_mov_b32_e32 v53, v46
	v_mov_b32_e32 v45, v47
	v_pk_add_f32 v[44:45], v[52:53], v[44:45]
	v_lshl_add_u64 v[46:47], v[50:51], 0, s[0:1]
	v_add_f32_e32 v44, v44, v45
	v_fmamk_f32 v44, v44, 0x3c000000, v172
	v_rsq_f32_e32 v44, v44
	v_lshl_add_u64 v[46:47], v[46:47], 0, v[120:121]
	global_store_dwordx4 v[46:47], v[40:43], off
	v_pk_mul_f32 v[36:37], v[36:37], v[44:45] op_sel_hi:[1,0]
	v_pk_mul_f32 v[38:39], v[38:39], v[44:45] op_sel_hi:[1,0]
	v_pk_mul_f32 v[32:33], v[32:33], v[44:45] op_sel_hi:[1,0]
	v_pk_mul_f32 v[34:35], v[34:35], v[44:45] op_sel_hi:[1,0]
	v_pk_mul_f32 v[38:39], v[134:135], v[38:39]
	v_pk_mul_f32 v[36:37], v[132:133], v[36:37]
	v_pk_mul_f32 v[40:41], v[130:131], v[34:35]
	v_pk_mul_f32 v[34:35], v[128:129], v[32:33]
	v_lshl_add_u32 v44, v152, 5, s18
	v_cvt_pk_bf16_f32 v32, v36, v37
	v_cvt_pk_bf16_f32 v33, v38, v39
	v_cvt_pk_bf16_f32 v34, v34, v35
	v_cvt_pk_bf16_f32 v35, v40, v41
	ds_read_b128 v[36:39], v44
	v_lshl_add_u64 v[40:41], s[12:13], 0, v[48:49]
	s_waitcnt lgkmcnt(0)
; #define PG8_LAS __attribute__((address_space(3)))
; __device__ __forceinline__ u32x4 pack8(const f32x4& a, const f32x4& b) { u32x4 w; w.x = cvt_pk_bf16(a[0], a[1]); w.y = cvt_pk_bf16(a[2], a[3]); w.z = cvt_pk_bf16(b[0], b[1]); w.w = cvt_pk_bf16(b[2], b[3]); return w; }
; template <bool ROWSCALE>
; __device__ __forceinline__ void head_norm_store(const f32x4 (&acc)[2][2][4][2], const float (&rs)[2][4], const float* gain, bf16_t* d0, bf16_t* d1, PG8_LAS float* red, int wr, int wc, int fr, int fq) {
;     ...
;     for (int ai = 0; ai < 2; ++ai)
; #pragma unroll
;         for (int m = 0; m < 4; ++m) { const int rl = ai * HALF + wr * 64 + m * 16 + fr;
; #pragma unroll
;             for (int bj = 0; bj < 2; ++bj) { const PG8_LAS float* rp = red + (rl * 2 + bj) * 4;
;                 const float ss = (rp[0] + rp[1]) + (rp[2] + rp[3]);
;                 float sc = __builtin_amdgcn_rsqf(ss * (1.0f / 128.0f) + RMS_EPS); if (ROWSCALE) sc *= rs[ai][m];
;                 const f32x4 v0 = acc[ai][bj][m][0] * sc * g0, v1 = acc[ai][bj][m][1] * sc * g1;
;                 *(u32x4*)((bj ? d1 : d0) + (size_t)rl * 128 + wc * 32 + fq * 8) = pack8(v0, v1); } }
	v_mov_b32_e32 v42, v37
	v_mov_b32_e32 v43, v38
	v_mov_b32_e32 v37, v39
	v_pk_add_f32 v[36:37], v[42:43], v[36:37]
	v_lshl_add_u64 v[38:39], v[40:41], 0, s[0:1]
	v_add_f32_e32 v36, v36, v37
	v_fmamk_f32 v36, v36, 0x3c000000, v172
	v_rsq_f32_e32 v36, v36
	v_lshl_add_u64 v[38:39], v[38:39], 0, v[120:121]
	global_store_dwordx4 v[38:39], v[32:35], off
	v_pk_mul_f32 v[28:29], v[28:29], v[36:37] op_sel_hi:[1,0]
	v_pk_mul_f32 v[30:31], v[30:31], v[36:37] op_sel_hi:[1,0]
	v_pk_mul_f32 v[24:25], v[24:25], v[36:37] op_sel_hi:[1,0]
	v_pk_mul_f32 v[26:27], v[26:27], v[36:37] op_sel_hi:[1,0]
	v_pk_mul_f32 v[30:31], v[134:135], v[30:31]
	v_pk_mul_f32 v[28:29], v[132:133], v[28:29]
	v_pk_mul_f32 v[32:33], v[130:131], v[26:27]
	v_pk_mul_f32 v[26:27], v[128:129], v[24:25]
	v_cvt_pk_bf16_f32 v24, v28, v29
	v_cvt_pk_bf16_f32 v25, v30, v31
	s_nop 0
	v_cvt_pk_bf16_f32 v26, v26, v27
	v_cvt_pk_bf16_f32 v27, v32, v33
	ds_read_b128 v[28:31], v44 offset:16
	v_lshlrev_b64 v[32:33], 8, v[152:153]
	v_lshl_add_u64 v[34:35], s[16:17], 0, v[32:33]
	s_waitcnt lgkmcnt(0)
	v_mov_b32_e32 v36, v29
	v_mov_b32_e32 v37, v30
	v_mov_b32_e32 v29, v31
	v_pk_add_f32 v[28:29], v[36:37], v[28:29]
	v_lshl_add_u64 v[30:31], v[34:35], 0, s[0:1]
	v_add_f32_e32 v28, v28, v29
	v_fmamk_f32 v28, v28, 0x3c000000, v172
	v_rsq_f32_e32 v28, v28
	v_lshl_add_u64 v[30:31], v[30:31], 0, v[120:121]
	global_store_dwordx4 v[30:31], v[24:27], off
	v_pk_mul_f32 v[20:21], v[20:21], v[28:29] op_sel_hi:[1,0]
	v_pk_mul_f32 v[22:23], v[22:23], v[28:29] op_sel_hi:[1,0]
	v_pk_mul_f32 v[16:17], v[16:17], v[28:29] op_sel_hi:[1,0]
	v_pk_mul_f32 v[18:19], v[18:19], v[28:29] op_sel_hi:[1,0]
	v_pk_mul_f32 v[22:23], v[134:135], v[22:23]
	v_pk_mul_f32 v[20:21], v[132:133], v[20:21]
	v_pk_mul_f32 v[24:25], v[130:131], v[18:19]
	v_pk_mul_f32 v[18:19], v[128:129], v[16:17]
	v_lshl_add_u32 v28, v150, 5, s18
	v_cvt_pk_bf16_f32 v16, v20, v21
	v_cvt_pk_bf16_f32 v17, v22, v23
	v_cvt_pk_bf16_f32 v18, v18, v19
	v_cvt_pk_bf16_f32 v19, v24, v25
	ds_read_b128 v[20:23], v28
	v_lshl_add_u64 v[24:25], s[12:13], 0, v[32:33]
	s_waitcnt lgkmcnt(0)
	v_mov_b32_e32 v26, v21
	v_mov_b32_e32 v27, v22
	v_mov_b32_e32 v21, v23
	v_pk_add_f32 v[20:21], v[26:27], v[20:21]
	v_lshl_add_u64 v[22:23], v[24:25], 0, s[0:1]
	v_add_f32_e32 v20, v20, v21
	v_fmamk_f32 v20, v20, 0x3c000000, v172
	v_rsq_f32_e32 v20, v20
	v_lshl_add_u64 v[22:23], v[22:23], 0, v[120:121]
	global_store_dwordx4 v[22:23], v[16:19], off
	v_pk_mul_f32 v[12:13], v[12:13], v[20:21] op_sel_hi:[1,0]
	v_pk_mul_f32 v[14:15], v[14:15], v[20:21] op_sel_hi:[1,0]
	v_pk_mul_f32 v[8:9], v[8:9], v[20:21] op_sel_hi:[1,0]
	v_pk_mul_f32 v[10:11], v[10:11], v[20:21] op_sel_hi:[1,0]
	v_pk_mul_f32 v[14:15], v[134:135], v[14:15]
	v_pk_mul_f32 v[12:13], v[132:133], v[12:13]
	v_pk_mul_f32 v[16:17], v[130:131], v[10:11]
	v_pk_mul_f32 v[10:11], v[128:129], v[8:9]
	v_cvt_pk_bf16_f32 v8, v12, v13
	v_cvt_pk_bf16_f32 v9, v14, v15
	s_nop 0
	v_cvt_pk_bf16_f32 v10, v10, v11
	v_cvt_pk_bf16_f32 v11, v16, v17
	ds_read_b128 v[12:15], v28 offset:16
	v_lshlrev_b64 v[16:17], 8, v[150:151]
	v_lshl_add_u64 v[18:19], s[16:17], 0, v[16:17]
	s_waitcnt lgkmcnt(0)
	v_mov_b32_e32 v20, v13
	v_mov_b32_e32 v21, v14
	v_mov_b32_e32 v13, v15
	v_pk_add_f32 v[12:13], v[20:21], v[12:13]
	v_lshl_add_u64 v[14:15], v[18:19], 0, s[0:1]
	v_add_f32_e32 v12, v12, v13
	v_fmamk_f32 v12, v12, 0x3c000000, v172
	v_rsq_f32_e32 v12, v12
	v_lshl_add_u64 v[14:15], v[14:15], 0, v[120:121]
	global_store_dwordx4 v[14:15], v[8:11], off
	v_pk_mul_f32 v[4:5], v[4:5], v[12:13] op_sel_hi:[1,0]
	v_pk_mul_f32 v[6:7], v[6:7], v[12:13] op_sel_hi:[1,0]
	v_pk_mul_f32 v[4:5], v[132:133], v[4:5]
	v_pk_mul_f32 v[0:1], v[0:1], v[12:13] op_sel_hi:[1,0]
	v_pk_mul_f32 v[2:3], v[2:3], v[12:13] op_sel_hi:[1,0]
	v_lshl_add_u64 v[132:133], s[12:13], 0, v[16:17]
	v_pk_mul_f32 v[6:7], v[134:135], v[6:7]
	v_pk_mul_f32 v[2:3], v[130:131], v[2:3]
	v_pk_mul_f32 v[0:1], v[128:129], v[0:1]
	v_cvt_pk_bf16_f32 v128, v4, v5
	v_cvt_pk_bf16_f32 v129, v6, v7
	s_nop 0
	v_cvt_pk_bf16_f32 v130, v0, v1
	v_cvt_pk_bf16_f32 v131, v2, v3

; template <int K> __device__ __forceinline__ float shx(float v) { static_assert(K < 32, "use sum32"); return __int_as_float(__builtin_amdgcn_ds_swizzle(__float_as_int(v), (K << 10) | 0x1f)); }
; #define SBAR() __builtin_amdgcn_sched_barrier(0)
; template <class TIn, class TOut, int ost, bool HAS_SS>
; __device__ __forceinline__ void causal_swa_block(const BlockRef<TIn, TOut>& cur_, const BlockRef<TIn, TOut>& nxt_, int skv, int W, char* lds, Seam<TIn>& S, int cbl  ) {
;     ...
;     for (int r = 0; r < 16; ++r) { const unsigned rowoff = ob0 + (unsigned)(((r & 3) + 8 * (r >> 2)) * ost * 2); float ss_ = 0.f;
; #pragma unroll
;         for (int d0 = 0; d0 < 4; ++d0) { const float v = o[d0][r] * rli[r]; ss_ += v * v;
;             const float vn = shx<1>(v);
;             if ((r32e & 1) == 0) *(unsigned*)(Ob + rowoff + d0 * 64) = cvtpk(v, vn); }
;         if (HAS_SS) { ss_ += shx<1>(ss_); ss_ += shx<2>(ss_); ss_ += shx<4>(ss_); ss_ += shx<8>(ss_); ss_ += shx<16>(ss_);
;             if (r32e == 0) *(float*)((char*)cur.SS + (unsigned)(wid * QBLK + 4 * hie + (r & 3) + 8 * (r >> 2)) * 32u) = ss_; }
;         SBAR(); }
.LBB0_932:
	s_or_b64 exec, exec, s[12:13]
	v_mul_f32_e32 v14, v48, v48
	v_fmac_f32_e32 v14, v0, v0
	v_fmac_f32_e32 v14, v32, v32
	v_fmac_f32_e32 v14, v16, v16
	s_nop 1
	v_mov_b32_dpp v0, v14 quad_perm:[1,0,3,2] row_mask:0xf bank_mask:0xf
	v_cmp_eq_u32_e64 s[34:35], 0, v198
	s_waitcnt lgkmcnt(0)
	v_add_f32_e32 v0, v14, v0
	s_nop 1
	v_mov_b32_dpp v14, v0 quad_perm:[2,3,0,1] row_mask:0xf bank_mask:0xf
	s_waitcnt lgkmcnt(0)
	v_add_f32_e32 v0, v0, v14
	s_nop 1
	v_mov_b32_dpp v14, v0 quad_perm:[3,2,1,0] row_mask:0xf bank_mask:0xf
	s_nop 1
	v_mov_b32_dpp v14, v14 row_half_mirror row_mask:0xf bank_mask:0xf
	s_waitcnt lgkmcnt(0)
	v_add_f32_e32 v0, v0, v14
	s_nop 1
	v_mov_b32_dpp v14, v0 row_half_mirror row_mask:0xf bank_mask:0xf
	s_nop 1
	v_mov_b32_dpp v14, v14 row_mirror row_mask:0xf bank_mask:0xf
	s_waitcnt lgkmcnt(0)
	v_add_f32_e32 v0, v0, v14
	s_nop 1
	v_mov_b32_e32 v14, v0
	v_mov_b32_e32 v253, v0
	s_nop 1
	v_permlane16_swap_b32_e32 v14, v253
	s_mov_b32 s98, 0xffff
	s_mov_b32 s99, 0xffff
	v_cndmask_b32_e64 v14, v14, v253, s[98:99]
	s_and_saveexec_b64 s[12:13], s[34:35]
	s_cbranch_execz .LBB0_934
	s_waitcnt lgkmcnt(0)
	v_add_f32_e32 v16, v0, v14
	v_lshlrev_b32_e32 v0, 5, v80
	v_lshl_add_u64 v[14:15], s[86:87], 0, v[0:1]
	global_store_dword v[14:15], v16, off

; template <int K> __device__ __forceinline__ float shx(float v) { static_assert(K < 32, "use sum32"); return __int_as_float(__builtin_amdgcn_ds_swizzle(__float_as_int(v), (K << 10) | 0x1f)); }
; #define SBAR() __builtin_amdgcn_sched_barrier(0)
; template <class TIn, class TOut, int ost, bool HAS_SS>
; __device__ __forceinline__ void causal_swa_block(const BlockRef<TIn, TOut>& cur_, const BlockRef<TIn, TOut>& nxt_, int skv, int W, char* lds, Seam<TIn>& S, int cbl  ) {
;     ...
;     for (int r = 0; r < 16; ++r) { const unsigned rowoff = ob0 + (unsigned)(((r & 3) + 8 * (r >> 2)) * ost * 2); float ss_ = 0.f;
; #pragma unroll
;         for (int d0 = 0; d0 < 4; ++d0) { const float v = o[d0][r] * rli[r]; ss_ += v * v;
;             const float vn = shx<1>(v);
;             if ((r32e & 1) == 0) *(unsigned*)(Ob + rowoff + d0 * 64) = cvtpk(v, vn); }
;         if (HAS_SS) { ss_ += shx<1>(ss_); ss_ += shx<2>(ss_); ss_ += shx<4>(ss_); ss_ += shx<8>(ss_); ss_ += shx<16>(ss_);
;             if (r32e == 0) *(float*)((char*)cur.SS + (unsigned)(wid * QBLK + 4 * hie + (r & 3) + 8 * (r >> 2)) * 32u) = ss_; }
;         SBAR(); }
.LBB0_942:
	s_or_b64 exec, exec, s[12:13]
	v_mul_f32_e32 v14, v48, v48
	v_fmac_f32_e32 v14, v0, v0
	v_fmac_f32_e32 v14, v33, v33
	v_fmac_f32_e32 v14, v17, v17
	s_nop 1
	v_mov_b32_dpp v0, v14 quad_perm:[1,0,3,2] row_mask:0xf bank_mask:0xf
	s_waitcnt lgkmcnt(0)
	v_add_f32_e32 v0, v14, v0
	s_nop 1
	v_mov_b32_dpp v14, v0 quad_perm:[2,3,0,1] row_mask:0xf bank_mask:0xf
	s_waitcnt lgkmcnt(0)
	v_add_f32_e32 v0, v0, v14
	s_nop 1
	v_mov_b32_dpp v14, v0 quad_perm:[3,2,1,0] row_mask:0xf bank_mask:0xf
	s_nop 1
	v_mov_b32_dpp v14, v14 row_half_mirror row_mask:0xf bank_mask:0xf
	s_waitcnt lgkmcnt(0)
	v_add_f32_e32 v0, v0, v14
	s_nop 1
	v_mov_b32_dpp v14, v0 row_half_mirror row_mask:0xf bank_mask:0xf
	s_nop 1
	v_mov_b32_dpp v14, v14 row_mirror row_mask:0xf bank_mask:0xf
	s_waitcnt lgkmcnt(0)
	v_add_f32_e32 v0, v0, v14
	s_nop 1
	v_mov_b32_e32 v14, v0
	v_mov_b32_e32 v253, v0
	s_nop 1
	v_permlane16_swap_b32_e32 v14, v253
	s_mov_b32 s98, 0xffff
	s_mov_b32 s99, 0xffff
	v_cndmask_b32_e64 v14, v14, v253, s[98:99]
	s_and_saveexec_b64 s[12:13], s[34:35]
	s_cbranch_execz .LBB0_944
	s_waitcnt lgkmcnt(0)
	v_add_f32_e32 v17, v0, v14
	v_lshlrev_b32_e32 v0, 5, v16
	v_lshl_add_u64 v[14:15], s[86:87], 0, v[0:1]
	global_store_dword v[14:15], v17, off

; template <int K> __device__ __forceinline__ float shx(float v) { static_assert(K < 32, "use sum32"); return __int_as_float(__builtin_amdgcn_ds_swizzle(__float_as_int(v), (K << 10) | 0x1f)); }
; #define SBAR() __builtin_amdgcn_sched_barrier(0)
; template <class TIn, class TOut, int ost, bool HAS_SS>
; __device__ __forceinline__ void causal_swa_block(const BlockRef<TIn, TOut>& cur_, const BlockRef<TIn, TOut>& nxt_, int skv, int W, char* lds, Seam<TIn>& S, int cbl  ) {
;     ...
;     for (int r = 0; r < 16; ++r) { const unsigned rowoff = ob0 + (unsigned)(((r & 3) + 8 * (r >> 2)) * ost * 2); float ss_ = 0.f;
; #pragma unroll
;         for (int d0 = 0; d0 < 4; ++d0) { const float v = o[d0][r] * rli[r]; ss_ += v * v;
;             const float vn = shx<1>(v);
;             if ((r32e & 1) == 0) *(unsigned*)(Ob + rowoff + d0 * 64) = cvtpk(v, vn); }
;         if (HAS_SS) { ss_ += shx<1>(ss_); ss_ += shx<2>(ss_); ss_ += shx<4>(ss_); ss_ += shx<8>(ss_); ss_ += shx<16>(ss_);
;             if (r32e == 0) *(float*)((char*)cur.SS + (unsigned)(wid * QBLK + 4 * hie + (r & 3) + 8 * (r >> 2)) * 32u) = ss_; }
;         SBAR(); }
.LBB0_952:
	s_or_b64 exec, exec, s[12:13]
	v_mul_f32_e32 v14, v32, v32
	v_fmac_f32_e32 v14, v0, v0
	v_fmac_f32_e32 v14, v33, v33
	v_fmac_f32_e32 v14, v17, v17
	s_nop 1
	v_mov_b32_dpp v0, v14 quad_perm:[1,0,3,2] row_mask:0xf bank_mask:0xf
	s_waitcnt lgkmcnt(0)
	v_add_f32_e32 v0, v14, v0
	s_nop 1
	v_mov_b32_dpp v14, v0 quad_perm:[2,3,0,1] row_mask:0xf bank_mask:0xf
	s_waitcnt lgkmcnt(0)
	v_add_f32_e32 v0, v0, v14
	s_nop 1
	v_mov_b32_dpp v14, v0 quad_perm:[3,2,1,0] row_mask:0xf bank_mask:0xf
	s_nop 1
	v_mov_b32_dpp v14, v14 row_half_mirror row_mask:0xf bank_mask:0xf
	s_waitcnt lgkmcnt(0)
	v_add_f32_e32 v0, v0, v14
	s_nop 1
	v_mov_b32_dpp v14, v0 row_half_mirror row_mask:0xf bank_mask:0xf
	s_nop 1
	v_mov_b32_dpp v14, v14 row_mirror row_mask:0xf bank_mask:0xf
	s_waitcnt lgkmcnt(0)
	v_add_f32_e32 v0, v0, v14
	s_nop 1
	v_mov_b32_e32 v14, v0
	v_mov_b32_e32 v253, v0
	s_nop 1
	v_permlane16_swap_b32_e32 v14, v253
	s_mov_b32 s98, 0xffff
	s_mov_b32 s99, 0xffff
	v_cndmask_b32_e64 v14, v14, v253, s[98:99]
	s_and_saveexec_b64 s[12:13], s[34:35]
	s_cbranch_execz .LBB0_954
	s_waitcnt lgkmcnt(0)
	v_add_f32_e32 v17, v0, v14
	v_lshlrev_b32_e32 v0, 5, v16
	v_lshl_add_u64 v[14:15], s[86:87], 0, v[0:1]
	global_store_dword v[14:15], v17, off

; template <int K> __device__ __forceinline__ float shx(float v) { static_assert(K < 32, "use sum32"); return __int_as_float(__builtin_amdgcn_ds_swizzle(__float_as_int(v), (K << 10) | 0x1f)); }
; #define SBAR() __builtin_amdgcn_sched_barrier(0)
; template <class TIn, class TOut, int ost, bool HAS_SS>
; __device__ __forceinline__ void causal_swa_block(const BlockRef<TIn, TOut>& cur_, const BlockRef<TIn, TOut>& nxt_, int skv, int W, char* lds, Seam<TIn>& S, int cbl  ) {
;     ...
;     for (int r = 0; r < 16; ++r) { const unsigned rowoff = ob0 + (unsigned)(((r & 3) + 8 * (r >> 2)) * ost * 2); float ss_ = 0.f;
; #pragma unroll
;         for (int d0 = 0; d0 < 4; ++d0) { const float v = o[d0][r] * rli[r]; ss_ += v * v;
;             const float vn = shx<1>(v);
;             if ((r32e & 1) == 0) *(unsigned*)(Ob + rowoff + d0 * 64) = cvtpk(v, vn); }
;         if (HAS_SS) { ss_ += shx<1>(ss_); ss_ += shx<2>(ss_); ss_ += shx<4>(ss_); ss_ += shx<8>(ss_); ss_ += shx<16>(ss_);
;             if (r32e == 0) *(float*)((char*)cur.SS + (unsigned)(wid * QBLK + 4 * hie + (r & 3) + 8 * (r >> 2)) * 32u) = ss_; }
;         SBAR(); }
.LBB0_962:
	s_or_b64 exec, exec, s[12:13]
	v_mul_f32_e32 v14, v18, v18
	v_fmac_f32_e32 v14, v0, v0
	v_fmac_f32_e32 v14, v32, v32
	v_fmac_f32_e32 v14, v17, v17
	s_nop 1
	v_mov_b32_dpp v0, v14 quad_perm:[1,0,3,2] row_mask:0xf bank_mask:0xf
	s_waitcnt lgkmcnt(0)
	v_add_f32_e32 v0, v14, v0
	s_nop 1
	v_mov_b32_dpp v14, v0 quad_perm:[2,3,0,1] row_mask:0xf bank_mask:0xf
	s_waitcnt lgkmcnt(0)
	v_add_f32_e32 v0, v0, v14
	s_nop 1
	v_mov_b32_dpp v14, v0 quad_perm:[3,2,1,0] row_mask:0xf bank_mask:0xf
	s_nop 1
	v_mov_b32_dpp v14, v14 row_half_mirror row_mask:0xf bank_mask:0xf
	s_waitcnt lgkmcnt(0)
	v_add_f32_e32 v0, v0, v14
	s_nop 1
	v_mov_b32_dpp v14, v0 row_half_mirror row_mask:0xf bank_mask:0xf
	s_nop 1
	v_mov_b32_dpp v14, v14 row_mirror row_mask:0xf bank_mask:0xf
	s_waitcnt lgkmcnt(0)
	v_add_f32_e32 v0, v0, v14
	s_nop 1
	v_mov_b32_e32 v14, v0
	v_mov_b32_e32 v253, v0
	s_nop 1
	v_permlane16_swap_b32_e32 v14, v253
	s_mov_b32 s98, 0xffff
	s_mov_b32 s99, 0xffff
	v_cndmask_b32_e64 v14, v14, v253, s[98:99]
	s_and_saveexec_b64 s[12:13], s[34:35]
	s_cbranch_execz .LBB0_964
	s_waitcnt lgkmcnt(0)
	v_add_f32_e32 v17, v0, v14
	v_lshlrev_b32_e32 v0, 5, v16
	v_lshl_add_u64 v[14:15], s[86:87], 0, v[0:1]
	global_store_dword v[14:15], v17, off

; template <int K> __device__ __forceinline__ float shx(float v) { static_assert(K < 32, "use sum32"); return __int_as_float(__builtin_amdgcn_ds_swizzle(__float_as_int(v), (K << 10) | 0x1f)); }
; #define SBAR() __builtin_amdgcn_sched_barrier(0)
; template <class TIn, class TOut, int ost, bool HAS_SS>
; __device__ __forceinline__ void causal_swa_block(const BlockRef<TIn, TOut>& cur_, const BlockRef<TIn, TOut>& nxt_, int skv, int W, char* lds, Seam<TIn>& S, int cbl  ) {
;     ...
;     for (int r = 0; r < 16; ++r) { const unsigned rowoff = ob0 + (unsigned)(((r & 3) + 8 * (r >> 2)) * ost * 2); float ss_ = 0.f;
; #pragma unroll
;         for (int d0 = 0; d0 < 4; ++d0) { const float v = o[d0][r] * rli[r]; ss_ += v * v;
;             const float vn = shx<1>(v);
;             if ((r32e & 1) == 0) *(unsigned*)(Ob + rowoff + d0 * 64) = cvtpk(v, vn); }
;         if (HAS_SS) { ss_ += shx<1>(ss_); ss_ += shx<2>(ss_); ss_ += shx<4>(ss_); ss_ += shx<8>(ss_); ss_ += shx<16>(ss_);
;             if (r32e == 0) *(float*)((char*)cur.SS + (unsigned)(wid * QBLK + 4 * hie + (r & 3) + 8 * (r >> 2)) * 32u) = ss_; }
;         SBAR(); }
.LBB0_972:
	s_or_b64 exec, exec, s[12:13]
	v_mul_f32_e32 v14, v17, v17
	v_fmac_f32_e32 v14, v0, v0
	v_fmac_f32_e32 v14, v18, v18
	v_fmac_f32_e32 v14, v16, v16
	s_nop 1
	v_mov_b32_dpp v0, v14 quad_perm:[1,0,3,2] row_mask:0xf bank_mask:0xf
	s_waitcnt lgkmcnt(0)
	v_add_f32_e32 v0, v14, v0
	s_nop 1
	v_mov_b32_dpp v14, v0 quad_perm:[2,3,0,1] row_mask:0xf bank_mask:0xf
	s_waitcnt lgkmcnt(0)
	v_add_f32_e32 v0, v0, v14
	s_nop 1
	v_mov_b32_dpp v14, v0 quad_perm:[3,2,1,0] row_mask:0xf bank_mask:0xf
	s_nop 1
	v_mov_b32_dpp v14, v14 row_half_mirror row_mask:0xf bank_mask:0xf
	s_waitcnt lgkmcnt(0)
	v_add_f32_e32 v0, v0, v14
	s_nop 1
	v_mov_b32_dpp v14, v0 row_half_mirror row_mask:0xf bank_mask:0xf
	s_nop 1
	v_mov_b32_dpp v14, v14 row_mirror row_mask:0xf bank_mask:0xf
	s_waitcnt lgkmcnt(0)
	v_add_f32_e32 v0, v0, v14
	s_nop 1
	v_mov_b32_e32 v14, v0
	v_mov_b32_e32 v253, v0
	s_nop 1
	v_permlane16_swap_b32_e32 v14, v253
	s_mov_b32 s98, 0xffff
	s_mov_b32 s99, 0xffff
	v_cndmask_b32_e64 v14, v14, v253, s[98:99]
	s_and_saveexec_b64 s[12:13], s[34:35]
	s_cbranch_execz .LBB0_974
	s_waitcnt lgkmcnt(0)
	v_add_f32_e32 v16, v0, v14
	v_lshlrev_b32_e32 v0, 5, v10
	v_lshl_add_u64 v[14:15], s[86:87], 0, v[0:1]
	global_store_dword v[14:15], v16, off

; template <int K> __device__ __forceinline__ float shx(float v) { static_assert(K < 32, "use sum32"); return __int_as_float(__builtin_amdgcn_ds_swizzle(__float_as_int(v), (K << 10) | 0x1f)); }
; #define SBAR() __builtin_amdgcn_sched_barrier(0)
; template <class TIn, class TOut, int ost, bool HAS_SS>
; __device__ __forceinline__ void causal_swa_block(const BlockRef<TIn, TOut>& cur_, const BlockRef<TIn, TOut>& nxt_, int skv, int W, char* lds, Seam<TIn>& S, int cbl  ) {
;     ...
;     for (int r = 0; r < 16; ++r) { const unsigned rowoff = ob0 + (unsigned)(((r & 3) + 8 * (r >> 2)) * ost * 2); float ss_ = 0.f;
; #pragma unroll
;         for (int d0 = 0; d0 < 4; ++d0) { const float v = o[d0][r] * rli[r]; ss_ += v * v;
;             const float vn = shx<1>(v);
;             if ((r32e & 1) == 0) *(unsigned*)(Ob + rowoff + d0 * 64) = cvtpk(v, vn); }
;         if (HAS_SS) { ss_ += shx<1>(ss_); ss_ += shx<2>(ss_); ss_ += shx<4>(ss_); ss_ += shx<8>(ss_); ss_ += shx<16>(ss_);
;             if (r32e == 0) *(float*)((char*)cur.SS + (unsigned)(wid * QBLK + 4 * hie + (r & 3) + 8 * (r >> 2)) * 32u) = ss_; }
;         SBAR(); }
.LBB0_982:
	s_or_b64 exec, exec, s[12:13]
	v_mul_f32_e32 v10, v16, v16
	v_fmac_f32_e32 v10, v0, v0
	v_fmac_f32_e32 v10, v17, v17
	v_fmac_f32_e32 v10, v15, v15
	s_nop 1
	v_mov_b32_dpp v0, v10 quad_perm:[1,0,3,2] row_mask:0xf bank_mask:0xf
	s_waitcnt lgkmcnt(0)
	v_add_f32_e32 v0, v10, v0
	s_nop 1
	v_mov_b32_dpp v10, v0 quad_perm:[2,3,0,1] row_mask:0xf bank_mask:0xf
	s_waitcnt lgkmcnt(0)
	v_add_f32_e32 v0, v0, v10
	s_nop 1
	v_mov_b32_dpp v10, v0 quad_perm:[3,2,1,0] row_mask:0xf bank_mask:0xf
	s_nop 1
	v_mov_b32_dpp v10, v10 row_half_mirror row_mask:0xf bank_mask:0xf
	s_waitcnt lgkmcnt(0)
	v_add_f32_e32 v0, v0, v10
	s_nop 1
	v_mov_b32_dpp v10, v0 row_half_mirror row_mask:0xf bank_mask:0xf
	s_nop 1
	v_mov_b32_dpp v10, v10 row_mirror row_mask:0xf bank_mask:0xf
	s_waitcnt lgkmcnt(0)
	v_add_f32_e32 v0, v0, v10
	s_nop 1
	v_mov_b32_e32 v10, v0
	v_mov_b32_e32 v253, v0
	s_nop 1
	v_permlane16_swap_b32_e32 v10, v253
	s_mov_b32 s98, 0xffff
	s_mov_b32 s99, 0xffff
	v_cndmask_b32_e64 v10, v10, v253, s[98:99]
	s_and_saveexec_b64 s[12:13], s[34:35]
	s_cbranch_execz .LBB0_984
	s_waitcnt lgkmcnt(0)
	v_add_f32_e32 v15, v0, v10
	v_lshlrev_b32_e32 v0, 5, v14
	v_lshl_add_u64 v[10:11], s[86:87], 0, v[0:1]
	global_store_dword v[10:11], v15, off

; template <int K> __device__ __forceinline__ float shx(float v) { static_assert(K < 32, "use sum32"); return __int_as_float(__builtin_amdgcn_ds_swizzle(__float_as_int(v), (K << 10) | 0x1f)); }
; #define SBAR() __builtin_amdgcn_sched_barrier(0)
; template <class TIn, class TOut, int ost, bool HAS_SS>
; __device__ __forceinline__ void causal_swa_block(const BlockRef<TIn, TOut>& cur_, const BlockRef<TIn, TOut>& nxt_, int skv, int W, char* lds, Seam<TIn>& S, int cbl  ) {
;     ...
;     for (int r = 0; r < 16; ++r) { const unsigned rowoff = ob0 + (unsigned)(((r & 3) + 8 * (r >> 2)) * ost * 2); float ss_ = 0.f;
; #pragma unroll
;         for (int d0 = 0; d0 < 4; ++d0) { const float v = o[d0][r] * rli[r]; ss_ += v * v;
;             const float vn = shx<1>(v);
;             if ((r32e & 1) == 0) *(unsigned*)(Ob + rowoff + d0 * 64) = cvtpk(v, vn); }
;         if (HAS_SS) { ss_ += shx<1>(ss_); ss_ += shx<2>(ss_); ss_ += shx<4>(ss_); ss_ += shx<8>(ss_); ss_ += shx<16>(ss_);
;             if (r32e == 0) *(float*)((char*)cur.SS + (unsigned)(wid * QBLK + 4 * hie + (r & 3) + 8 * (r >> 2)) * 32u) = ss_; }
;         SBAR(); }
.LBB0_992:
	s_or_b64 exec, exec, s[12:13]
	v_mul_f32_e32 v10, v15, v15
	v_fmac_f32_e32 v10, v0, v0
	v_fmac_f32_e32 v10, v16, v16
	v_fmac_f32_e32 v10, v14, v14
	s_nop 1
	v_mov_b32_dpp v0, v10 quad_perm:[1,0,3,2] row_mask:0xf bank_mask:0xf
	s_waitcnt lgkmcnt(0)
	v_add_f32_e32 v0, v10, v0
	s_nop 1
	v_mov_b32_dpp v10, v0 quad_perm:[2,3,0,1] row_mask:0xf bank_mask:0xf
	s_waitcnt lgkmcnt(0)
	v_add_f32_e32 v0, v0, v10
	s_nop 1
	v_mov_b32_dpp v10, v0 quad_perm:[3,2,1,0] row_mask:0xf bank_mask:0xf
	s_nop 1
	v_mov_b32_dpp v10, v10 row_half_mirror row_mask:0xf bank_mask:0xf
	s_waitcnt lgkmcnt(0)
	v_add_f32_e32 v0, v0, v10
	s_nop 1
	v_mov_b32_dpp v10, v0 row_half_mirror row_mask:0xf bank_mask:0xf
	s_nop 1
	v_mov_b32_dpp v10, v10 row_mirror row_mask:0xf bank_mask:0xf
	s_waitcnt lgkmcnt(0)
	v_add_f32_e32 v0, v0, v10
	s_nop 1
	v_mov_b32_e32 v10, v0
	v_mov_b32_e32 v253, v0
	s_nop 1
	v_permlane16_swap_b32_e32 v10, v253
	s_mov_b32 s98, 0xffff
	s_mov_b32 s99, 0xffff
	v_cndmask_b32_e64 v10, v10, v253, s[98:99]
	s_and_saveexec_b64 s[12:13], s[34:35]
	s_cbranch_execz .LBB0_994
	s_waitcnt lgkmcnt(0)
	v_add_f32_e32 v14, v0, v10
	v_lshlrev_b32_e32 v0, 5, v12
	v_lshl_add_u64 v[10:11], s[86:87], 0, v[0:1]
	global_store_dword v[10:11], v14, off

; template <int K> __device__ __forceinline__ float shx(float v) { static_assert(K < 32, "use sum32"); return __int_as_float(__builtin_amdgcn_ds_swizzle(__float_as_int(v), (K << 10) | 0x1f)); }
; template <class TIn, class TOut, int ost, bool HAS_SS>
; __device__ __forceinline__ void causal_swa_block(const BlockRef<TIn, TOut>& cur_, const BlockRef<TIn, TOut>& nxt_, int skv, int W, char* lds, Seam<TIn>& S, int cbl  ) {
;     ...
;     for (int r = 0; r < 16; ++r) { const unsigned rowoff = ob0 + (unsigned)(((r & 3) + 8 * (r >> 2)) * ost * 2); float ss_ = 0.f;
; #pragma unroll
;         for (int d0 = 0; d0 < 4; ++d0) { const float v = o[d0][r] * rli[r]; ss_ += v * v;
;             const float vn = shx<1>(v);
;             if ((r32e & 1) == 0) *(unsigned*)(Ob + rowoff + d0 * 64) = cvtpk(v, vn); }
;         if (HAS_SS) { ss_ += shx<1>(ss_); ss_ += shx<2>(ss_); ss_ += shx<4>(ss_); ss_ += shx<8>(ss_); ss_ += shx<16>(ss_);
;             if (r32e == 0) *(float*)((char*)cur.SS + (unsigned)(wid * QBLK + 4 * hie + (r & 3) + 8 * (r >> 2)) * 32u) = ss_; }
.LBB0_1002:
	s_or_b64 exec, exec, s[12:13]
	v_mul_f32_e32 v10, v14, v14
	v_fmac_f32_e32 v10, v0, v0
	v_fmac_f32_e32 v10, v15, v15
	v_fmac_f32_e32 v10, v13, v13
	s_nop 1
	v_mov_b32_dpp v0, v10 quad_perm:[1,0,3,2] row_mask:0xf bank_mask:0xf
	s_waitcnt lgkmcnt(0)
	v_add_f32_e32 v0, v10, v0
	s_nop 1
	v_mov_b32_dpp v10, v0 quad_perm:[2,3,0,1] row_mask:0xf bank_mask:0xf
	s_waitcnt lgkmcnt(0)
	v_add_f32_e32 v0, v0, v10
	s_nop 1
	v_mov_b32_dpp v10, v0 quad_perm:[3,2,1,0] row_mask:0xf bank_mask:0xf
	s_nop 1
	v_mov_b32_dpp v10, v10 row_half_mirror row_mask:0xf bank_mask:0xf
	s_waitcnt lgkmcnt(0)
	v_add_f32_e32 v0, v0, v10
	s_nop 1
	v_mov_b32_dpp v10, v0 row_half_mirror row_mask:0xf bank_mask:0xf
	s_nop 1
	v_mov_b32_dpp v10, v10 row_mirror row_mask:0xf bank_mask:0xf
	s_waitcnt lgkmcnt(0)
	v_add_f32_e32 v0, v0, v10
	s_nop 1
	v_mov_b32_e32 v10, v0
	v_mov_b32_e32 v253, v0
	s_nop 1
	v_permlane16_swap_b32_e32 v10, v253
	s_mov_b32 s98, 0xffff
	s_mov_b32 s99, 0xffff
	v_cndmask_b32_e64 v10, v10, v253, s[98:99]
	s_and_saveexec_b64 s[12:13], s[34:35]
	s_cbranch_execz .LBB0_1004
	s_waitcnt lgkmcnt(0)
	v_add_f32_e32 v13, v0, v10
	v_lshlrev_b32_e32 v0, 5, v12
	v_lshl_add_u64 v[10:11], s[86:87], 0, v[0:1]
	global_store_dword v[10:11], v13, off

; template <int K> __device__ __forceinline__ float shx(float v) { static_assert(K < 32, "use sum32"); return __int_as_float(__builtin_amdgcn_ds_swizzle(__float_as_int(v), (K << 10) | 0x1f)); }
; template <class TIn, class TOut, int ost, bool HAS_SS>
; __device__ __forceinline__ void causal_swa_block(const BlockRef<TIn, TOut>& cur_, const BlockRef<TIn, TOut>& nxt_, int skv, int W, char* lds, Seam<TIn>& S, int cbl  ) {
;     ...
;     for (int r = 0; r < 16; ++r) { const unsigned rowoff = ob0 + (unsigned)(((r & 3) + 8 * (r >> 2)) * ost * 2); float ss_ = 0.f;
; #pragma unroll
;         for (int d0 = 0; d0 < 4; ++d0) { const float v = o[d0][r] * rli[r]; ss_ += v * v;
;             const float vn = shx<1>(v);
;             if ((r32e & 1) == 0) *(unsigned*)(Ob + rowoff + d0 * 64) = cvtpk(v, vn); }
;         if (HAS_SS) { ss_ += shx<1>(ss_); ss_ += shx<2>(ss_); ss_ += shx<4>(ss_); ss_ += shx<8>(ss_); ss_ += shx<16>(ss_);
;             if (r32e == 0) *(float*)((char*)cur.SS + (unsigned)(wid * QBLK + 4 * hie + (r & 3) + 8 * (r >> 2)) * 32u) = ss_; }
.LBB0_1012:
	s_or_b64 exec, exec, s[12:13]
	v_mul_f32_e32 v10, v13, v13
	v_fmac_f32_e32 v10, v0, v0
	v_fmac_f32_e32 v10, v14, v14
	v_fmac_f32_e32 v10, v12, v12
	s_nop 1
	v_mov_b32_dpp v0, v10 quad_perm:[1,0,3,2] row_mask:0xf bank_mask:0xf
	s_waitcnt lgkmcnt(0)
	v_add_f32_e32 v0, v10, v0
	s_nop 1
	v_mov_b32_dpp v10, v0 quad_perm:[2,3,0,1] row_mask:0xf bank_mask:0xf
	s_waitcnt lgkmcnt(0)
	v_add_f32_e32 v0, v0, v10
	s_nop 1
	v_mov_b32_dpp v10, v0 quad_perm:[3,2,1,0] row_mask:0xf bank_mask:0xf
	s_nop 1
	v_mov_b32_dpp v10, v10 row_half_mirror row_mask:0xf bank_mask:0xf
	s_waitcnt lgkmcnt(0)
	v_add_f32_e32 v0, v0, v10
	s_nop 1
	v_mov_b32_dpp v10, v0 row_half_mirror row_mask:0xf bank_mask:0xf
	s_nop 1
	v_mov_b32_dpp v10, v10 row_mirror row_mask:0xf bank_mask:0xf
	s_waitcnt lgkmcnt(0)
	v_add_f32_e32 v0, v0, v10
	s_nop 1
	v_mov_b32_e32 v10, v0
	v_mov_b32_e32 v253, v0
	s_nop 1
	v_permlane16_swap_b32_e32 v10, v253
	s_mov_b32 s98, 0xffff
	s_mov_b32 s99, 0xffff
	v_cndmask_b32_e64 v10, v10, v253, s[98:99]
	s_and_saveexec_b64 s[12:13], s[34:35]
	s_cbranch_execz .LBB0_1014
	s_waitcnt lgkmcnt(0)
	v_add_f32_e32 v12, v0, v10
	v_lshlrev_b32_e32 v0, 5, v6
	v_lshl_add_u64 v[10:11], s[86:87], 0, v[0:1]
	global_store_dword v[10:11], v12, off

; template <int K> __device__ __forceinline__ float shx(float v) { static_assert(K < 32, "use sum32"); return __int_as_float(__builtin_amdgcn_ds_swizzle(__float_as_int(v), (K << 10) | 0x1f)); }
; template <class TIn, class TOut, int ost, bool HAS_SS>
; __device__ __forceinline__ void causal_swa_block(const BlockRef<TIn, TOut>& cur_, const BlockRef<TIn, TOut>& nxt_, int skv, int W, char* lds, Seam<TIn>& S, int cbl  ) {
;     ...
;     for (int r = 0; r < 16; ++r) { const unsigned rowoff = ob0 + (unsigned)(((r & 3) + 8 * (r >> 2)) * ost * 2); float ss_ = 0.f;
; #pragma unroll
;         for (int d0 = 0; d0 < 4; ++d0) { const float v = o[d0][r] * rli[r]; ss_ += v * v;
;             const float vn = shx<1>(v);
;             if ((r32e & 1) == 0) *(unsigned*)(Ob + rowoff + d0 * 64) = cvtpk(v, vn); }
;         if (HAS_SS) { ss_ += shx<1>(ss_); ss_ += shx<2>(ss_); ss_ += shx<4>(ss_); ss_ += shx<8>(ss_); ss_ += shx<16>(ss_);
;             if (r32e == 0) *(float*)((char*)cur.SS + (unsigned)(wid * QBLK + 4 * hie + (r & 3) + 8 * (r >> 2)) * 32u) = ss_; }
.LBB0_1022:
	s_or_b64 exec, exec, s[12:13]
	v_mul_f32_e32 v6, v12, v12
	v_fmac_f32_e32 v6, v0, v0
	v_fmac_f32_e32 v6, v13, v13
	v_fmac_f32_e32 v6, v11, v11
	s_nop 1
	v_mov_b32_dpp v0, v6 quad_perm:[1,0,3,2] row_mask:0xf bank_mask:0xf
	s_waitcnt lgkmcnt(0)
	v_add_f32_e32 v0, v6, v0
	s_nop 1
	v_mov_b32_dpp v6, v0 quad_perm:[2,3,0,1] row_mask:0xf bank_mask:0xf
	s_waitcnt lgkmcnt(0)
	v_add_f32_e32 v0, v0, v6
	s_nop 1
	v_mov_b32_dpp v6, v0 quad_perm:[3,2,1,0] row_mask:0xf bank_mask:0xf
	s_nop 1
	v_mov_b32_dpp v6, v6 row_half_mirror row_mask:0xf bank_mask:0xf
	s_waitcnt lgkmcnt(0)
	v_add_f32_e32 v0, v0, v6
	s_nop 1
	v_mov_b32_dpp v6, v0 row_half_mirror row_mask:0xf bank_mask:0xf
	s_nop 1
	v_mov_b32_dpp v6, v6 row_mirror row_mask:0xf bank_mask:0xf
	s_waitcnt lgkmcnt(0)
	v_add_f32_e32 v0, v0, v6
	s_nop 1
	v_mov_b32_e32 v6, v0
	v_mov_b32_e32 v253, v0
	s_nop 1
	v_permlane16_swap_b32_e32 v6, v253
	s_mov_b32 s98, 0xffff
	s_mov_b32 s99, 0xffff
	v_cndmask_b32_e64 v6, v6, v253, s[98:99]
	s_and_saveexec_b64 s[12:13], s[34:35]
	s_cbranch_execz .LBB0_1024
	s_waitcnt lgkmcnt(0)
	v_add_f32_e32 v11, v0, v6
	v_lshlrev_b32_e32 v0, 5, v10
	v_lshl_add_u64 v[6:7], s[86:87], 0, v[0:1]
	global_store_dword v[6:7], v11, off

; template <int K> __device__ __forceinline__ float shx(float v) { static_assert(K < 32, "use sum32"); return __int_as_float(__builtin_amdgcn_ds_swizzle(__float_as_int(v), (K << 10) | 0x1f)); }
; template <class TIn, class TOut, int ost, bool HAS_SS>
; __device__ __forceinline__ void causal_swa_block(const BlockRef<TIn, TOut>& cur_, const BlockRef<TIn, TOut>& nxt_, int skv, int W, char* lds, Seam<TIn>& S, int cbl  ) {
;     ...
;     for (int r = 0; r < 16; ++r) { const unsigned rowoff = ob0 + (unsigned)(((r & 3) + 8 * (r >> 2)) * ost * 2); float ss_ = 0.f;
; #pragma unroll
;         for (int d0 = 0; d0 < 4; ++d0) { const float v = o[d0][r] * rli[r]; ss_ += v * v;
;             const float vn = shx<1>(v);
;             if ((r32e & 1) == 0) *(unsigned*)(Ob + rowoff + d0 * 64) = cvtpk(v, vn); }
;         if (HAS_SS) { ss_ += shx<1>(ss_); ss_ += shx<2>(ss_); ss_ += shx<4>(ss_); ss_ += shx<8>(ss_); ss_ += shx<16>(ss_);
;             if (r32e == 0) *(float*)((char*)cur.SS + (unsigned)(wid * QBLK + 4 * hie + (r & 3) + 8 * (r >> 2)) * 32u) = ss_; }
.LBB0_1032:
	s_or_b64 exec, exec, s[12:13]
	v_mul_f32_e32 v6, v11, v11
	v_fmac_f32_e32 v6, v0, v0
	v_fmac_f32_e32 v6, v12, v12
	v_fmac_f32_e32 v6, v10, v10
	s_nop 1
	v_mov_b32_dpp v0, v6 quad_perm:[1,0,3,2] row_mask:0xf bank_mask:0xf
	s_waitcnt lgkmcnt(0)
	v_add_f32_e32 v0, v6, v0
	s_nop 1
	v_mov_b32_dpp v6, v0 quad_perm:[2,3,0,1] row_mask:0xf bank_mask:0xf
	s_waitcnt lgkmcnt(0)
	v_add_f32_e32 v0, v0, v6
	s_nop 1
	v_mov_b32_dpp v6, v0 quad_perm:[3,2,1,0] row_mask:0xf bank_mask:0xf
	s_nop 1
	v_mov_b32_dpp v6, v6 row_half_mirror row_mask:0xf bank_mask:0xf
	s_waitcnt lgkmcnt(0)
	v_add_f32_e32 v0, v0, v6
	s_nop 1
	v_mov_b32_dpp v6, v0 row_half_mirror row_mask:0xf bank_mask:0xf
	s_nop 1
	v_mov_b32_dpp v6, v6 row_mirror row_mask:0xf bank_mask:0xf
	s_waitcnt lgkmcnt(0)
	v_add_f32_e32 v0, v0, v6
	s_nop 1
	v_mov_b32_e32 v6, v0
	v_mov_b32_e32 v253, v0
	s_nop 1
	v_permlane16_swap_b32_e32 v6, v253
	s_mov_b32 s98, 0xffff
	s_mov_b32 s99, 0xffff
	v_cndmask_b32_e64 v6, v6, v253, s[98:99]
	s_and_saveexec_b64 s[12:13], s[34:35]
	s_cbranch_execz .LBB0_1034
	s_waitcnt lgkmcnt(0)
	v_add_f32_e32 v10, v0, v6
	v_lshlrev_b32_e32 v0, 5, v8
	v_lshl_add_u64 v[6:7], s[86:87], 0, v[0:1]
	global_store_dword v[6:7], v10, off

; template <int K> __device__ __forceinline__ float shx(float v) { static_assert(K < 32, "use sum32"); return __int_as_float(__builtin_amdgcn_ds_swizzle(__float_as_int(v), (K << 10) | 0x1f)); }
; template <class TIn, class TOut, int ost, bool HAS_SS>
; __device__ __forceinline__ void causal_swa_block(const BlockRef<TIn, TOut>& cur_, const BlockRef<TIn, TOut>& nxt_, int skv, int W, char* lds, Seam<TIn>& S, int cbl  ) {
;     ...
;     for (int r = 0; r < 16; ++r) { const unsigned rowoff = ob0 + (unsigned)(((r & 3) + 8 * (r >> 2)) * ost * 2); float ss_ = 0.f;
; #pragma unroll
;         for (int d0 = 0; d0 < 4; ++d0) { const float v = o[d0][r] * rli[r]; ss_ += v * v;
;             const float vn = shx<1>(v);
;             if ((r32e & 1) == 0) *(unsigned*)(Ob + rowoff + d0 * 64) = cvtpk(v, vn); }
;         if (HAS_SS) { ss_ += shx<1>(ss_); ss_ += shx<2>(ss_); ss_ += shx<4>(ss_); ss_ += shx<8>(ss_); ss_ += shx<16>(ss_);
;             if (r32e == 0) *(float*)((char*)cur.SS + (unsigned)(wid * QBLK + 4 * hie + (r & 3) + 8 * (r >> 2)) * 32u) = ss_; }
.LBB0_1042:
	s_or_b64 exec, exec, s[12:13]
	v_mul_f32_e32 v6, v10, v10
	v_fmac_f32_e32 v6, v0, v0
	v_fmac_f32_e32 v6, v11, v11
	v_fmac_f32_e32 v6, v9, v9
	s_nop 1
	v_mov_b32_dpp v0, v6 quad_perm:[1,0,3,2] row_mask:0xf bank_mask:0xf
	s_waitcnt lgkmcnt(0)
	v_add_f32_e32 v0, v6, v0
	s_nop 1
	v_mov_b32_dpp v6, v0 quad_perm:[2,3,0,1] row_mask:0xf bank_mask:0xf
	s_waitcnt lgkmcnt(0)
	v_add_f32_e32 v0, v0, v6
	s_nop 1
	v_mov_b32_dpp v6, v0 quad_perm:[3,2,1,0] row_mask:0xf bank_mask:0xf
	s_nop 1
	v_mov_b32_dpp v6, v6 row_half_mirror row_mask:0xf bank_mask:0xf
	s_waitcnt lgkmcnt(0)
	v_add_f32_e32 v0, v0, v6
	s_nop 1
	v_mov_b32_dpp v6, v0 row_half_mirror row_mask:0xf bank_mask:0xf
	s_nop 1
	v_mov_b32_dpp v6, v6 row_mirror row_mask:0xf bank_mask:0xf
	s_waitcnt lgkmcnt(0)
	v_add_f32_e32 v0, v0, v6
	s_nop 1
	v_mov_b32_e32 v6, v0
	v_mov_b32_e32 v253, v0
	s_nop 1
	v_permlane16_swap_b32_e32 v6, v253
	s_mov_b32 s98, 0xffff
	s_mov_b32 s99, 0xffff
	v_cndmask_b32_e64 v6, v6, v253, s[98:99]
	s_and_saveexec_b64 s[12:13], s[34:35]
	s_cbranch_execz .LBB0_1044
	s_waitcnt lgkmcnt(0)
	v_add_f32_e32 v9, v0, v6
	v_lshlrev_b32_e32 v0, 5, v8
	v_lshl_add_u64 v[6:7], s[86:87], 0, v[0:1]
	global_store_dword v[6:7], v9, off

; template <int K> __device__ __forceinline__ float shx(float v) { static_assert(K < 32, "use sum32"); return __int_as_float(__builtin_amdgcn_ds_swizzle(__float_as_int(v), (K << 10) | 0x1f)); }
; template <class TIn, class TOut, int ost, bool HAS_SS>
; __device__ __forceinline__ void causal_swa_block(const BlockRef<TIn, TOut>& cur_, const BlockRef<TIn, TOut>& nxt_, int skv, int W, char* lds, Seam<TIn>& S, int cbl  ) {
;     ...
;     for (int r = 0; r < 16; ++r) { const unsigned rowoff = ob0 + (unsigned)(((r & 3) + 8 * (r >> 2)) * ost * 2); float ss_ = 0.f;
; #pragma unroll
;         for (int d0 = 0; d0 < 4; ++d0) { const float v = o[d0][r] * rli[r]; ss_ += v * v;
;             const float vn = shx<1>(v);
;             if ((r32e & 1) == 0) *(unsigned*)(Ob + rowoff + d0 * 64) = cvtpk(v, vn); }
;         if (HAS_SS) { ss_ += shx<1>(ss_); ss_ += shx<2>(ss_); ss_ += shx<4>(ss_); ss_ += shx<8>(ss_); ss_ += shx<16>(ss_);
;             if (r32e == 0) *(float*)((char*)cur.SS + (unsigned)(wid * QBLK + 4 * hie + (r & 3) + 8 * (r >> 2)) * 32u) = ss_; }
.LBB0_1052:
	s_or_b64 exec, exec, s[12:13]
	v_mul_f32_e32 v6, v9, v9
	v_fmac_f32_e32 v6, v0, v0
	v_fmac_f32_e32 v6, v10, v10
	v_fmac_f32_e32 v6, v8, v8
	s_nop 1
	v_mov_b32_dpp v0, v6 quad_perm:[1,0,3,2] row_mask:0xf bank_mask:0xf
	s_waitcnt lgkmcnt(0)
	v_add_f32_e32 v0, v6, v0
	s_nop 1
	v_mov_b32_dpp v6, v0 quad_perm:[2,3,0,1] row_mask:0xf bank_mask:0xf
	s_waitcnt lgkmcnt(0)
	v_add_f32_e32 v0, v0, v6
	s_nop 1
	v_mov_b32_dpp v6, v0 quad_perm:[3,2,1,0] row_mask:0xf bank_mask:0xf
	s_nop 1
	v_mov_b32_dpp v6, v6 row_half_mirror row_mask:0xf bank_mask:0xf
	s_waitcnt lgkmcnt(0)
	v_add_f32_e32 v0, v0, v6
	s_nop 1
	v_mov_b32_dpp v6, v0 row_half_mirror row_mask:0xf bank_mask:0xf
	s_nop 1
	v_mov_b32_dpp v6, v6 row_mirror row_mask:0xf bank_mask:0xf
	s_waitcnt lgkmcnt(0)
	v_add_f32_e32 v0, v0, v6
	s_nop 1
	v_mov_b32_e32 v6, v0
	v_mov_b32_e32 v253, v0
	s_nop 1
	v_permlane16_swap_b32_e32 v6, v253
	s_mov_b32 s98, 0xffff
	s_mov_b32 s99, 0xffff
	v_cndmask_b32_e64 v6, v6, v253, s[98:99]
	s_and_saveexec_b64 s[12:13], s[34:35]
	s_cbranch_execz .LBB0_1054
	s_waitcnt lgkmcnt(0)
	v_add_f32_e32 v8, v0, v6
	v_lshlrev_b32_e32 v0, 5, v2
	v_lshl_add_u64 v[6:7], s[86:87], 0, v[0:1]
	global_store_dword v[6:7], v8, off

; template <int K> __device__ __forceinline__ float shx(float v) { static_assert(K < 32, "use sum32"); return __int_as_float(__builtin_amdgcn_ds_swizzle(__float_as_int(v), (K << 10) | 0x1f)); }
; template <class TIn, class TOut, int ost, bool HAS_SS>
; __device__ __forceinline__ void causal_swa_block(const BlockRef<TIn, TOut>& cur_, const BlockRef<TIn, TOut>& nxt_, int skv, int W, char* lds, Seam<TIn>& S, int cbl  ) {
;     ...
;     for (int r = 0; r < 16; ++r) { const unsigned rowoff = ob0 + (unsigned)(((r & 3) + 8 * (r >> 2)) * ost * 2); float ss_ = 0.f;
; #pragma unroll
;         for (int d0 = 0; d0 < 4; ++d0) { const float v = o[d0][r] * rli[r]; ss_ += v * v;
;             const float vn = shx<1>(v);
;             if ((r32e & 1) == 0) *(unsigned*)(Ob + rowoff + d0 * 64) = cvtpk(v, vn); }
;         if (HAS_SS) { ss_ += shx<1>(ss_); ss_ += shx<2>(ss_); ss_ += shx<4>(ss_); ss_ += shx<8>(ss_); ss_ += shx<16>(ss_);
;             if (r32e == 0) *(float*)((char*)cur.SS + (unsigned)(wid * QBLK + 4 * hie + (r & 3) + 8 * (r >> 2)) * 32u) = ss_; }
.LBB0_1062:
	s_or_b64 exec, exec, s[12:13]
	v_mul_f32_e32 v2, v8, v8
	v_fmac_f32_e32 v2, v0, v0
	v_fmac_f32_e32 v2, v9, v9
	v_fmac_f32_e32 v2, v7, v7
	s_nop 1
	v_mov_b32_dpp v0, v2 quad_perm:[1,0,3,2] row_mask:0xf bank_mask:0xf
	s_waitcnt lgkmcnt(0)
	v_add_f32_e32 v0, v2, v0
	s_nop 1
	v_mov_b32_dpp v2, v0 quad_perm:[2,3,0,1] row_mask:0xf bank_mask:0xf
	s_waitcnt lgkmcnt(0)
	v_add_f32_e32 v0, v0, v2
	s_nop 1
	v_mov_b32_dpp v2, v0 quad_perm:[3,2,1,0] row_mask:0xf bank_mask:0xf
	s_nop 1
	v_mov_b32_dpp v2, v2 row_half_mirror row_mask:0xf bank_mask:0xf
	s_waitcnt lgkmcnt(0)
	v_add_f32_e32 v0, v0, v2
	s_nop 1
	v_mov_b32_dpp v2, v0 row_half_mirror row_mask:0xf bank_mask:0xf
	s_nop 1
	v_mov_b32_dpp v2, v2 row_mirror row_mask:0xf bank_mask:0xf
	s_waitcnt lgkmcnt(0)
	v_add_f32_e32 v0, v0, v2
	s_nop 1
	v_mov_b32_e32 v2, v0
	v_mov_b32_e32 v253, v0
	s_nop 1
	v_permlane16_swap_b32_e32 v2, v253
	s_mov_b32 s98, 0xffff
	s_mov_b32 s99, 0xffff
	v_cndmask_b32_e64 v2, v2, v253, s[98:99]
	s_and_saveexec_b64 s[12:13], s[34:35]
	s_cbranch_execz .LBB0_1064
	s_waitcnt lgkmcnt(0)
	v_add_f32_e32 v7, v0, v2
	v_lshlrev_b32_e32 v0, 5, v6
	v_lshl_add_u64 v[2:3], s[86:87], 0, v[0:1]
	global_store_dword v[2:3], v7, off

; template <int K> __device__ __forceinline__ float shx(float v) { static_assert(K < 32, "use sum32"); return __int_as_float(__builtin_amdgcn_ds_swizzle(__float_as_int(v), (K << 10) | 0x1f)); }
; template <class TIn, class TOut, int ost, bool HAS_SS>
; __device__ __forceinline__ void causal_swa_block(const BlockRef<TIn, TOut>& cur_, const BlockRef<TIn, TOut>& nxt_, int skv, int W, char* lds, Seam<TIn>& S, int cbl  ) {
;     ...
;     for (int r = 0; r < 16; ++r) { const unsigned rowoff = ob0 + (unsigned)(((r & 3) + 8 * (r >> 2)) * ost * 2); float ss_ = 0.f;
; #pragma unroll
;         for (int d0 = 0; d0 < 4; ++d0) { const float v = o[d0][r] * rli[r]; ss_ += v * v;
;             const float vn = shx<1>(v);
;             if ((r32e & 1) == 0) *(unsigned*)(Ob + rowoff + d0 * 64) = cvtpk(v, vn); }
;         if (HAS_SS) { ss_ += shx<1>(ss_); ss_ += shx<2>(ss_); ss_ += shx<4>(ss_); ss_ += shx<8>(ss_); ss_ += shx<16>(ss_);
;             if (r32e == 0) *(float*)((char*)cur.SS + (unsigned)(wid * QBLK + 4 * hie + (r & 3) + 8 * (r >> 2)) * 32u) = ss_; }
.LBB0_1072:
	s_or_b64 exec, exec, s[12:13]
	v_mul_f32_e32 v2, v7, v7
	v_fmac_f32_e32 v2, v0, v0
	v_fmac_f32_e32 v2, v8, v8
	v_fmac_f32_e32 v2, v6, v6
	s_nop 1
	v_mov_b32_dpp v0, v2 quad_perm:[1,0,3,2] row_mask:0xf bank_mask:0xf
	s_waitcnt lgkmcnt(0)
	v_add_f32_e32 v0, v2, v0
	s_nop 1
	v_mov_b32_dpp v2, v0 quad_perm:[2,3,0,1] row_mask:0xf bank_mask:0xf
	s_waitcnt lgkmcnt(0)
	v_add_f32_e32 v0, v0, v2
	s_nop 1
	v_mov_b32_dpp v2, v0 quad_perm:[3,2,1,0] row_mask:0xf bank_mask:0xf
	s_nop 1
	v_mov_b32_dpp v2, v2 row_half_mirror row_mask:0xf bank_mask:0xf
	s_waitcnt lgkmcnt(0)
	v_add_f32_e32 v0, v0, v2
	s_nop 1
	v_mov_b32_dpp v2, v0 row_half_mirror row_mask:0xf bank_mask:0xf
	s_nop 1
	v_mov_b32_dpp v2, v2 row_mirror row_mask:0xf bank_mask:0xf
	s_waitcnt lgkmcnt(0)
	v_add_f32_e32 v0, v0, v2
	s_nop 1
	v_mov_b32_e32 v2, v0
	v_mov_b32_e32 v253, v0
	s_nop 1
	v_permlane16_swap_b32_e32 v2, v253
	s_mov_b32 s98, 0xffff
	s_mov_b32 s99, 0xffff
	v_cndmask_b32_e64 v2, v2, v253, s[98:99]
	s_and_saveexec_b64 s[12:13], s[34:35]
	s_cbranch_execz .LBB0_1074
	s_waitcnt lgkmcnt(0)
	v_add_f32_e32 v6, v0, v2
	v_lshlrev_b32_e32 v0, 5, v4
	v_lshl_add_u64 v[2:3], s[86:87], 0, v[0:1]
	global_store_dword v[2:3], v6, off

; template <int K> __device__ __forceinline__ float shx(float v) { static_assert(K < 32, "use sum32"); return __int_as_float(__builtin_amdgcn_ds_swizzle(__float_as_int(v), (K << 10) | 0x1f)); }
; template <class TIn, class TOut, int ost, bool HAS_SS>
; __device__ __forceinline__ void causal_swa_block(const BlockRef<TIn, TOut>& cur_, const BlockRef<TIn, TOut>& nxt_, int skv, int W, char* lds, Seam<TIn>& S, int cbl  ) {
;     ...
;     for (int r = 0; r < 16; ++r) { const unsigned rowoff = ob0 + (unsigned)(((r & 3) + 8 * (r >> 2)) * ost * 2); float ss_ = 0.f;
; #pragma unroll
;         for (int d0 = 0; d0 < 4; ++d0) { const float v = o[d0][r] * rli[r]; ss_ += v * v;
;             const float vn = shx<1>(v);
;             if ((r32e & 1) == 0) *(unsigned*)(Ob + rowoff + d0 * 64) = cvtpk(v, vn); }
;         if (HAS_SS) { ss_ += shx<1>(ss_); ss_ += shx<2>(ss_); ss_ += shx<4>(ss_); ss_ += shx<8>(ss_); ss_ += shx<16>(ss_);
;             if (r32e == 0) *(float*)((char*)cur.SS + (unsigned)(wid * QBLK + 4 * hie + (r & 3) + 8 * (r >> 2)) * 32u) = ss_; }
.LBB0_1082:
	s_or_b64 exec, exec, s[12:13]
	v_mul_f32_e32 v0, v0, v0
	v_fmac_f32_e32 v0, v5, v5
	v_fmac_f32_e32 v0, v7, v7
	v_fmac_f32_e32 v0, v6, v6
	s_nop 1
	v_mov_b32_dpp v2, v0 quad_perm:[1,0,3,2] row_mask:0xf bank_mask:0xf
	s_waitcnt lgkmcnt(0)
	v_add_f32_e32 v0, v0, v2
	s_nop 1
	v_mov_b32_dpp v2, v0 quad_perm:[2,3,0,1] row_mask:0xf bank_mask:0xf
	s_waitcnt lgkmcnt(0)
	v_add_f32_e32 v0, v0, v2
	s_nop 1
	v_mov_b32_dpp v2, v0 quad_perm:[3,2,1,0] row_mask:0xf bank_mask:0xf
	s_nop 1
	v_mov_b32_dpp v2, v2 row_half_mirror row_mask:0xf bank_mask:0xf
	s_waitcnt lgkmcnt(0)
	v_add_f32_e32 v0, v0, v2
	s_nop 1
	v_mov_b32_dpp v2, v0 row_half_mirror row_mask:0xf bank_mask:0xf
	s_nop 1
	v_mov_b32_dpp v2, v2 row_mirror row_mask:0xf bank_mask:0xf
	s_waitcnt lgkmcnt(0)
	v_add_f32_e32 v0, v0, v2
	s_nop 1
	v_mov_b32_e32 v2, v0
	v_mov_b32_e32 v253, v0
	s_nop 1
	v_permlane16_swap_b32_e32 v2, v253
	s_mov_b32 s98, 0xffff
	s_mov_b32 s99, 0xffff
	v_cndmask_b32_e64 v2, v2, v253, s[98:99]
	s_and_saveexec_b64 s[12:13], s[34:35]
	s_cbranch_execz .LBB0_882
	s_waitcnt lgkmcnt(0)
	v_add_f32_e32 v5, v0, v2
	v_lshlrev_b32_e32 v0, 5, v4
	v_lshl_add_u64 v[2:3], s[86:87], 0, v[0:1]
	global_store_dword v[2:3], v5, off
	s_branch .LBB0_882

; template <int K> __device__ __forceinline__ float shx(float v) { static_assert(K < 32, "use sum32"); return __int_as_float(__builtin_amdgcn_ds_swizzle(__float_as_int(v), (K << 10) | 0x1f)); }
; __device__ __forceinline__ float sum32(float v) { auto rr = __builtin_amdgcn_permlane32_swap(__float_as_uint(v), __float_as_uint(v), false, false); return __uint_as_float(rr[0]) + __uint_as_float(rr[1]); }
;     __device__ __forceinline__ void operator()(const f32x4 (&acc)[2][2][4][2], const Unit& u, int wr, int wc, int fr, int fq) const {
;     ...
;             for (int m = 0; m < 4; ++m) { const size_t row = (size_t)u.pm * BM + ai * HALF + wr * 64 + m * 16 + fr;
;                 float sc = 1.f; if (MID) sc = __builtin_amdgcn_rsqf(sum_f(ssql + row * 8, 2) * (1.0f / 1024.0f) + RMS_EPS);
;                 float ss = 0.f;
; #pragma unroll
;                 for (int bj = 0; bj < 2; ++bj) { const size_t o = row * 2048 + u.pn * BM + bj * HALF + wc * 32 + fq * 8;
;                     f32x4 r0, r1;
;                     if (residb) { const u32x4 w = __builtin_nontemporal_load((const u32x4*)(residb + o));     r0 = (f32x4){__uint_as_float(w.x << 16), __uint_as_float(w.x & 0xffff0000u), __uint_as_float(w.y << 16), __uint_as_float(w.y & 0xffff0000u)};
;                                   r1 = (f32x4){__uint_as_float(w.z << 16), __uint_as_float(w.z & 0xffff0000u), __uint_as_float(w.w << 16), __uint_as_float(w.w & 0xffff0000u)}; }
;                     else { r0 = __builtin_nontemporal_load((const f32x4*)(resid + o)); r1 = __builtin_nontemporal_load((const f32x4*)(resid + o + 4)); }
;                     const f32x4 v0 = r0 + acc[ai][bj][m][0] * sc, v1 = r1 + acc[ai][bj][m][1] * sc;
;                     if (outf) { __builtin_nontemporal_store(v0, (f32x4*)(outf + o)); __builtin_nontemporal_store(v1, (f32x4*)(outf + o + 4)); }
;                     ss += (v0[0] * v0[0] + v0[1] * v0[1]) + (v0[2] * v0[2] + v0[3] * v0[3]) + (v1[0] * v1[0] + v1[1] * v1[1]) + (v1[2] * v1[2] + v1[3] * v1[3]);
;                     if (outb) *(u32x4*)(outb + o) = pack8(v0, v1); }
;                 if (ssq_out) { ss += shx<16>(ss); ss = sum32(ss); if (fq == 0) ssq_out[row * 32 + u.pn * 4 + wc] = ss; }
;                 __builtin_amdgcn_sched_barrier(0); }
.LBB0_1222:
	s_lshl_b64 s[12:13], s[60:61], 8
	v_mov_b32_e32 v2, v152
	v_mov_b32_e32 v1, v153
	s_add_u32 s12, s12, s26
	s_addc_u32 s13, s13, s27
	v_ashrrev_i32_e32 v3, 31, v2
	v_lshl_add_u64 v[148:149], s[12:13], 0, v[2:3]
	s_lshl_b32 s12, s0, 8
	s_ashr_i32 s13, s12, 31
	v_lshlrev_b32_e32 v2, 3, v1
	v_ashrrev_i32_e32 v3, 31, v2
	s_or_b64 s[12:13], s[12:13], s[28:29]
	v_lshl_add_u64 v[2:3], s[12:13], 0, v[2:3]
	v_readlane_b32 s80, v252, 8
	v_readlane_b32 s81, v252, 9
	v_cmp_eq_u32_e32 vcc, 0, v1
	s_lshl_b32 s60, s0, 2
	s_ashr_i32 s61, s60, 31
	v_readlane_b32 s82, v252, 10
	v_readlane_b32 s83, v252, 11
	v_readlane_b32 s84, v252, 12
	v_readlane_b32 s85, v252, 13
	v_readlane_b32 s86, v252, 14
	v_readlane_b32 s87, v252, 15
	v_readlane_b32 s88, v252, 16
	v_readlane_b32 s89, v252, 17
	v_readlane_b32 s90, v252, 18
	v_readlane_b32 s91, v252, 19
	v_readlane_b32 s92, v252, 20
	v_readlane_b32 s93, v252, 21
	v_readlane_b32 s94, v252, 22
	v_readlane_b32 s95, v252, 23
	v_lshlrev_b64 v[158:159], 11, v[148:149]
	v_lshl_add_u64 v[166:167], v[2:3], 0, v[158:159]
	v_lshl_add_u64 v[168:169], v[166:167], 2, s[80:81]
	global_load_dwordx4 v[158:161], v[168:169], off offset:16 nt
	global_load_dwordx4 v[162:165], v[168:169], off nt
	v_mov_b32_e32 v150, v240
	s_waitcnt vmcnt(1)
	v_pk_fma_f32 v[160:161], v[126:127], v[150:151], v[160:161] op_sel_hi:[1,0,1]
	s_waitcnt vmcnt(0)
	v_pk_fma_f32 v[130:131], v[130:131], v[150:151], v[164:165] op_sel_hi:[1,0,1]
	v_pk_fma_f32 v[128:129], v[128:129], v[150:151], v[162:163] op_sel_hi:[1,0,1]
	v_pk_fma_f32 v[126:127], v[124:125], v[150:151], v[158:159] op_sel_hi:[1,0,1]
	v_mul_f32_e32 v1, v129, v129
	v_mul_f32_e32 v124, v131, v131
	v_fmac_f32_e32 v1, v128, v128
	v_fmac_f32_e32 v124, v130, v130
	v_add_f32_e32 v1, v1, v124
	v_mul_f32_e32 v124, v127, v127
	v_fmac_f32_e32 v124, v126, v126
	v_add_f32_e32 v1, v124, v1
	v_mul_f32_e32 v124, v161, v161
	v_fmac_f32_e32 v124, v160, v160
	v_lshl_add_u64 v[158:159], v[166:167], 1, s[54:55]
	v_add_f32_e32 v1, v124, v1
	v_cvt_pk_bf16_f32 v124, v128, v129
	v_cvt_pk_bf16_f32 v125, v130, v131
	v_cvt_pk_bf16_f32 v126, v126, v127
	v_cvt_pk_bf16_f32 v127, v160, v161
	global_store_dwordx4 v[158:159], v[124:127], off
	global_load_dwordx4 v[124:127], v[168:169], off offset:528 nt
	s_nop 0
	global_load_dwordx4 v[128:131], v[168:169], off offset:512 nt
	s_waitcnt vmcnt(1)
	v_pk_fma_f32 v[126:127], v[118:119], v[150:151], v[126:127] op_sel_hi:[1,0,1]
	s_waitcnt vmcnt(0)
	v_pk_fma_f32 v[122:123], v[122:123], v[150:151], v[130:131] op_sel_hi:[1,0,1]
	v_pk_fma_f32 v[120:121], v[120:121], v[150:151], v[128:129] op_sel_hi:[1,0,1]
	v_pk_fma_f32 v[118:119], v[116:117], v[150:151], v[124:125] op_sel_hi:[1,0,1]
	v_mul_f32_e32 v116, v121, v121
	v_mul_f32_e32 v117, v123, v123
	v_fmac_f32_e32 v116, v120, v120
	v_fmac_f32_e32 v117, v122, v122
	v_add_f32_e32 v116, v116, v117
	v_mul_f32_e32 v117, v119, v119
	v_fmac_f32_e32 v117, v118, v118
	v_add_f32_e32 v116, v117, v116
	v_mul_f32_e32 v117, v127, v127
	v_fmac_f32_e32 v117, v126, v126
	v_add_f32_e32 v116, v117, v116
	v_add_f32_e32 v1, v1, v116
	v_cvt_pk_bf16_f32 v116, v120, v121
	v_cvt_pk_bf16_f32 v117, v122, v123
	v_cvt_pk_bf16_f32 v118, v118, v119
	v_cvt_pk_bf16_f32 v119, v126, v127
	global_store_dwordx4 v[158:159], v[116:119], off offset:256
	s_nop 1
	v_mov_b32_e32 v116, v1
	v_mov_b32_e32 v253, v1
	s_nop 1
	v_permlane16_swap_b32_e32 v116, v253
	s_mov_b32 s98, 0xffff
	s_mov_b32 s99, 0xffff
	v_cndmask_b32_e64 v116, v116, v253, s[98:99]
	s_waitcnt lgkmcnt(0)
	v_add_f32_e32 v1, v1, v116
	v_mov_b32_e32 v116, v1
	s_nop 1
	v_permlane32_swap_b32_e32 v1, v116
	s_and_saveexec_b64 s[12:13], vcc
	v_readlane_b32 s18, v251, 1
	v_readlane_b32 s19, v251, 2
	s_cbranch_execz .LBB0_1224
	v_lshlrev_b64 v[118:119], 7, v[148:149]
	v_lshl_add_u64 v[118:119], s[22:23], 0, v[118:119]
	v_lshl_add_u64 v[118:119], s[60:61], 2, v[118:119]
	s_lshl_b32 s0, s46, 2
	v_lshl_add_u64 v[118:119], v[118:119], 0, s[0:1]
	v_add_f32_e32 v1, v1, v116
	global_store_dword v[118:119], v1, off
.LBB0_1224:
	s_or_b64 exec, exec, s[12:13]
	v_lshl_add_u64 v[116:117], v[148:149], 0, 16
	v_readlane_b32 s80, v252, 8
	v_readlane_b32 s81, v252, 9
	v_readlane_b32 s82, v252, 10
	v_readlane_b32 s83, v252, 11
	v_readlane_b32 s84, v252, 12
	v_readlane_b32 s85, v252, 13
	v_readlane_b32 s86, v252, 14
	v_readlane_b32 s87, v252, 15
	v_readlane_b32 s88, v252, 16
	v_readlane_b32 s89, v252, 17
	v_readlane_b32 s90, v252, 18
	v_readlane_b32 s91, v252, 19
	v_readlane_b32 s92, v252, 20
	v_readlane_b32 s93, v252, 21
	v_readlane_b32 s94, v252, 22
	v_readlane_b32 s95, v252, 23
	v_lshlrev_b64 v[120:121], 11, v[116:117]
	v_lshl_add_u64 v[128:129], v[120:121], 0, v[2:3]
	v_lshl_add_u64 v[130:131], v[128:129], 2, s[80:81]
	global_load_dwordx4 v[120:123], v[130:131], off offset:16 nt
	global_load_dwordx4 v[124:127], v[130:131], off nt
	v_mov_b32_e32 v118, v241
	s_waitcnt vmcnt(1)
	v_pk_fma_f32 v[122:123], v[110:111], v[118:119], v[122:123] op_sel_hi:[1,0,1]
	s_waitcnt vmcnt(0)
	v_pk_fma_f32 v[114:115], v[114:115], v[118:119], v[126:127] op_sel_hi:[1,0,1]
	v_pk_fma_f32 v[112:113], v[112:113], v[118:119], v[124:125] op_sel_hi:[1,0,1]
	v_pk_fma_f32 v[110:111], v[108:109], v[118:119], v[120:121] op_sel_hi:[1,0,1]
	v_mul_f32_e32 v1, v113, v113
	v_mul_f32_e32 v108, v115, v115
	v_fmac_f32_e32 v1, v112, v112
	v_fmac_f32_e32 v108, v114, v114
	v_add_f32_e32 v1, v1, v108
	v_mul_f32_e32 v108, v111, v111
	v_fmac_f32_e32 v108, v110, v110
	v_add_f32_e32 v1, v108, v1
	v_mul_f32_e32 v108, v123, v123
	v_fmac_f32_e32 v108, v122, v122
	v_lshl_add_u64 v[120:121], v[128:129], 1, s[54:55]
	v_add_f32_e32 v1, v108, v1
	v_cvt_pk_bf16_f32 v108, v112, v113
	v_cvt_pk_bf16_f32 v109, v114, v115
	v_cvt_pk_bf16_f32 v110, v110, v111
	v_cvt_pk_bf16_f32 v111, v122, v123
	global_store_dwordx4 v[120:121], v[108:111], off
	global_load_dwordx4 v[108:111], v[130:131], off offset:528 nt
	s_nop 0
	global_load_dwordx4 v[112:115], v[130:131], off offset:512 nt
	s_waitcnt vmcnt(1)
; template <int K> __device__ __forceinline__ float shx(float v) { static_assert(K < 32, "use sum32"); return __int_as_float(__builtin_amdgcn_ds_swizzle(__float_as_int(v), (K << 10) | 0x1f)); }
; __device__ __forceinline__ float sum32(float v) { auto rr = __builtin_amdgcn_permlane32_swap(__float_as_uint(v), __float_as_uint(v), false, false); return __uint_as_float(rr[0]) + __uint_as_float(rr[1]); }
;     __device__ __forceinline__ void operator()(const f32x4 (&acc)[2][2][4][2], const Unit& u, int wr, int wc, int fr, int fq) const {
;     ...
;             for (int m = 0; m < 4; ++m) { const size_t row = (size_t)u.pm * BM + ai * HALF + wr * 64 + m * 16 + fr;
;                 float sc = 1.f; if (MID) sc = __builtin_amdgcn_rsqf(sum_f(ssql + row * 8, 2) * (1.0f / 1024.0f) + RMS_EPS);
;                 float ss = 0.f;
; #pragma unroll
;                 for (int bj = 0; bj < 2; ++bj) { const size_t o = row * 2048 + u.pn * BM + bj * HALF + wc * 32 + fq * 8;
;                     f32x4 r0, r1;
;                     if (residb) { const u32x4 w = __builtin_nontemporal_load((const u32x4*)(residb + o));     r0 = (f32x4){__uint_as_float(w.x << 16), __uint_as_float(w.x & 0xffff0000u), __uint_as_float(w.y << 16), __uint_as_float(w.y & 0xffff0000u)};
;                                   r1 = (f32x4){__uint_as_float(w.z << 16), __uint_as_float(w.z & 0xffff0000u), __uint_as_float(w.w << 16), __uint_as_float(w.w & 0xffff0000u)}; }
;                     else { r0 = __builtin_nontemporal_load((const f32x4*)(resid + o)); r1 = __builtin_nontemporal_load((const f32x4*)(resid + o + 4)); }
;                     const f32x4 v0 = r0 + acc[ai][bj][m][0] * sc, v1 = r1 + acc[ai][bj][m][1] * sc;
;                     if (outf) { __builtin_nontemporal_store(v0, (f32x4*)(outf + o)); __builtin_nontemporal_store(v1, (f32x4*)(outf + o + 4)); }
;                     ss += (v0[0] * v0[0] + v0[1] * v0[1]) + (v0[2] * v0[2] + v0[3] * v0[3]) + (v1[0] * v1[0] + v1[1] * v1[1]) + (v1[2] * v1[2] + v1[3] * v1[3]);
;                     if (outb) *(u32x4*)(outb + o) = pack8(v0, v1); }
;                 if (ssq_out) { ss += shx<16>(ss); ss = sum32(ss); if (fq == 0) ssq_out[row * 32 + u.pn * 4 + wc] = ss; }
;                 __builtin_amdgcn_sched_barrier(0); }
	v_pk_fma_f32 v[110:111], v[102:103], v[118:119], v[110:111] op_sel_hi:[1,0,1]
	s_waitcnt vmcnt(0)
	v_pk_fma_f32 v[106:107], v[106:107], v[118:119], v[114:115] op_sel_hi:[1,0,1]
	v_pk_fma_f32 v[104:105], v[104:105], v[118:119], v[112:113] op_sel_hi:[1,0,1]
	v_pk_fma_f32 v[102:103], v[100:101], v[118:119], v[108:109] op_sel_hi:[1,0,1]
	v_mul_f32_e32 v100, v105, v105
	v_mul_f32_e32 v101, v107, v107
	v_fmac_f32_e32 v100, v104, v104
	v_fmac_f32_e32 v101, v106, v106
	v_add_f32_e32 v100, v100, v101
	v_mul_f32_e32 v101, v103, v103
	v_fmac_f32_e32 v101, v102, v102
	v_add_f32_e32 v100, v101, v100
	v_mul_f32_e32 v101, v111, v111
	v_fmac_f32_e32 v101, v110, v110
	v_add_f32_e32 v100, v101, v100
	v_add_f32_e32 v1, v1, v100
	v_cvt_pk_bf16_f32 v100, v104, v105
	v_cvt_pk_bf16_f32 v101, v106, v107
	v_cvt_pk_bf16_f32 v102, v102, v103
	v_cvt_pk_bf16_f32 v103, v110, v111
	global_store_dwordx4 v[120:121], v[100:103], off offset:256
	s_nop 1
	v_mov_b32_e32 v100, v1
	v_mov_b32_e32 v253, v1
	s_nop 1
	v_permlane16_swap_b32_e32 v100, v253
	s_mov_b32 s98, 0xffff
	s_mov_b32 s99, 0xffff
	v_cndmask_b32_e64 v100, v100, v253, s[98:99]
	s_waitcnt lgkmcnt(0)
	v_add_f32_e32 v1, v1, v100
	v_mov_b32_e32 v100, v1
	s_nop 1
	v_permlane32_swap_b32_e32 v1, v100
	s_and_saveexec_b64 s[12:13], vcc
	s_cbranch_execz .LBB0_1226
	v_lshlrev_b64 v[102:103], 7, v[116:117]
	v_lshl_add_u64 v[102:103], s[22:23], 0, v[102:103]
	v_lshl_add_u64 v[102:103], s[60:61], 2, v[102:103]
	s_lshl_b32 s0, s46, 2
	v_lshl_add_u64 v[102:103], v[102:103], 0, s[0:1]
	v_add_f32_e32 v1, v1, v100
	global_store_dword v[102:103], v1, off
.LBB0_1226:
	s_or_b64 exec, exec, s[12:13]
	v_lshl_add_u64 v[100:101], v[148:149], 0, 32
	v_readlane_b32 s80, v252, 8
	v_readlane_b32 s81, v252, 9
	v_readlane_b32 s82, v252, 10
	v_readlane_b32 s83, v252, 11
	v_readlane_b32 s84, v252, 12
	v_readlane_b32 s85, v252, 13
	v_readlane_b32 s86, v252, 14
	v_readlane_b32 s87, v252, 15
	v_readlane_b32 s88, v252, 16
	v_readlane_b32 s89, v252, 17
	v_readlane_b32 s90, v252, 18
	v_readlane_b32 s91, v252, 19
	v_readlane_b32 s92, v252, 20
	v_readlane_b32 s93, v252, 21
	v_readlane_b32 s94, v252, 22
	v_readlane_b32 s95, v252, 23
	v_lshlrev_b64 v[104:105], 11, v[100:101]
	v_lshl_add_u64 v[112:113], v[104:105], 0, v[2:3]
	v_lshl_add_u64 v[114:115], v[112:113], 2, s[80:81]
	global_load_dwordx4 v[104:107], v[114:115], off offset:16 nt
	global_load_dwordx4 v[108:111], v[114:115], off nt
	v_mov_b32_e32 v102, v242
	s_waitcnt vmcnt(1)
	v_pk_fma_f32 v[106:107], v[94:95], v[102:103], v[106:107] op_sel_hi:[1,0,1]
	s_waitcnt vmcnt(0)
	v_pk_fma_f32 v[98:99], v[98:99], v[102:103], v[110:111] op_sel_hi:[1,0,1]
	v_pk_fma_f32 v[96:97], v[96:97], v[102:103], v[108:109] op_sel_hi:[1,0,1]
	v_pk_fma_f32 v[94:95], v[92:93], v[102:103], v[104:105] op_sel_hi:[1,0,1]
	v_mul_f32_e32 v1, v97, v97
	v_mul_f32_e32 v92, v99, v99
	v_fmac_f32_e32 v1, v96, v96
	v_fmac_f32_e32 v92, v98, v98
	v_add_f32_e32 v1, v1, v92
	v_mul_f32_e32 v92, v95, v95
	v_fmac_f32_e32 v92, v94, v94
	v_add_f32_e32 v1, v92, v1
	v_mul_f32_e32 v92, v107, v107
	v_fmac_f32_e32 v92, v106, v106
	v_lshl_add_u64 v[104:105], v[112:113], 1, s[54:55]
	v_add_f32_e32 v1, v92, v1
	v_cvt_pk_bf16_f32 v92, v96, v97
	v_cvt_pk_bf16_f32 v93, v98, v99
	v_cvt_pk_bf16_f32 v94, v94, v95
	v_cvt_pk_bf16_f32 v95, v106, v107
	global_store_dwordx4 v[104:105], v[92:95], off
	global_load_dwordx4 v[92:95], v[114:115], off offset:528 nt
	s_nop 0
	global_load_dwordx4 v[96:99], v[114:115], off offset:512 nt
	s_waitcnt vmcnt(1)
	v_pk_fma_f32 v[94:95], v[86:87], v[102:103], v[94:95] op_sel_hi:[1,0,1]
	s_waitcnt vmcnt(0)
	v_pk_fma_f32 v[90:91], v[90:91], v[102:103], v[98:99] op_sel_hi:[1,0,1]
	v_pk_fma_f32 v[88:89], v[88:89], v[102:103], v[96:97] op_sel_hi:[1,0,1]
	v_pk_fma_f32 v[86:87], v[84:85], v[102:103], v[92:93] op_sel_hi:[1,0,1]
	v_mul_f32_e32 v84, v89, v89
	v_mul_f32_e32 v85, v91, v91
	v_fmac_f32_e32 v84, v88, v88
	v_fmac_f32_e32 v85, v90, v90
	v_add_f32_e32 v84, v84, v85
	v_mul_f32_e32 v85, v87, v87
	v_fmac_f32_e32 v85, v86, v86
	v_add_f32_e32 v84, v85, v84
	v_mul_f32_e32 v85, v95, v95
	v_fmac_f32_e32 v85, v94, v94
	v_add_f32_e32 v84, v85, v84
	v_add_f32_e32 v1, v1, v84
	v_cvt_pk_bf16_f32 v84, v88, v89
	v_cvt_pk_bf16_f32 v85, v90, v91
	v_cvt_pk_bf16_f32 v86, v86, v87
	v_cvt_pk_bf16_f32 v87, v94, v95
	global_store_dwordx4 v[104:105], v[84:87], off offset:256
	s_nop 1
	v_mov_b32_e32 v84, v1
	v_mov_b32_e32 v253, v1
	s_nop 1
	v_permlane16_swap_b32_e32 v84, v253
	s_mov_b32 s98, 0xffff
	s_mov_b32 s99, 0xffff
	v_cndmask_b32_e64 v84, v84, v253, s[98:99]
	s_waitcnt lgkmcnt(0)
	v_add_f32_e32 v1, v1, v84
	v_mov_b32_e32 v84, v1
	s_nop 1
	v_permlane32_swap_b32_e32 v1, v84
	s_and_saveexec_b64 s[12:13], vcc
	s_cbranch_execz .LBB0_1228
	v_lshlrev_b64 v[86:87], 7, v[100:101]
	v_lshl_add_u64 v[86:87], s[22:23], 0, v[86:87]
	v_lshl_add_u64 v[86:87], s[60:61], 2, v[86:87]
	s_lshl_b32 s0, s46, 2
	v_lshl_add_u64 v[86:87], v[86:87], 0, s[0:1]
	v_add_f32_e32 v1, v1, v84
	global_store_dword v[86:87], v1, off
; template <int K> __device__ __forceinline__ float shx(float v) { static_assert(K < 32, "use sum32"); return __int_as_float(__builtin_amdgcn_ds_swizzle(__float_as_int(v), (K << 10) | 0x1f)); }
; __device__ __forceinline__ float sum32(float v) { auto rr = __builtin_amdgcn_permlane32_swap(__float_as_uint(v), __float_as_uint(v), false, false); return __uint_as_float(rr[0]) + __uint_as_float(rr[1]); }
;     __device__ __forceinline__ void operator()(const f32x4 (&acc)[2][2][4][2], const Unit& u, int wr, int wc, int fr, int fq) const {
;     ...
;             for (int m = 0; m < 4; ++m) { const size_t row = (size_t)u.pm * BM + ai * HALF + wr * 64 + m * 16 + fr;
;                 float sc = 1.f; if (MID) sc = __builtin_amdgcn_rsqf(sum_f(ssql + row * 8, 2) * (1.0f / 1024.0f) + RMS_EPS);
;                 float ss = 0.f;
; #pragma unroll
;                 for (int bj = 0; bj < 2; ++bj) { const size_t o = row * 2048 + u.pn * BM + bj * HALF + wc * 32 + fq * 8;
;                     f32x4 r0, r1;
;                     if (residb) { const u32x4 w = __builtin_nontemporal_load((const u32x4*)(residb + o));     r0 = (f32x4){__uint_as_float(w.x << 16), __uint_as_float(w.x & 0xffff0000u), __uint_as_float(w.y << 16), __uint_as_float(w.y & 0xffff0000u)};
;                                   r1 = (f32x4){__uint_as_float(w.z << 16), __uint_as_float(w.z & 0xffff0000u), __uint_as_float(w.w << 16), __uint_as_float(w.w & 0xffff0000u)}; }
;                     else { r0 = __builtin_nontemporal_load((const f32x4*)(resid + o)); r1 = __builtin_nontemporal_load((const f32x4*)(resid + o + 4)); }
;                     const f32x4 v0 = r0 + acc[ai][bj][m][0] * sc, v1 = r1 + acc[ai][bj][m][1] * sc;
;                     if (outf) { __builtin_nontemporal_store(v0, (f32x4*)(outf + o)); __builtin_nontemporal_store(v1, (f32x4*)(outf + o + 4)); }
;                     ss += (v0[0] * v0[0] + v0[1] * v0[1]) + (v0[2] * v0[2] + v0[3] * v0[3]) + (v1[0] * v1[0] + v1[1] * v1[1]) + (v1[2] * v1[2] + v1[3] * v1[3]);
;                     if (outb) *(u32x4*)(outb + o) = pack8(v0, v1); }
;                 if (ssq_out) { ss += shx<16>(ss); ss = sum32(ss); if (fq == 0) ssq_out[row * 32 + u.pn * 4 + wc] = ss; }
;                 __builtin_amdgcn_sched_barrier(0); }
.LBB0_1228:
	s_or_b64 exec, exec, s[12:13]
	v_lshl_add_u64 v[84:85], v[148:149], 0, 48
	v_readlane_b32 s80, v252, 8
	v_readlane_b32 s81, v252, 9
	v_readlane_b32 s82, v252, 10
	v_readlane_b32 s83, v252, 11
	v_readlane_b32 s84, v252, 12
	v_readlane_b32 s85, v252, 13
	v_readlane_b32 s86, v252, 14
	v_readlane_b32 s87, v252, 15
	v_readlane_b32 s88, v252, 16
	v_readlane_b32 s89, v252, 17
	v_readlane_b32 s90, v252, 18
	v_readlane_b32 s91, v252, 19
	v_readlane_b32 s92, v252, 20
	v_readlane_b32 s93, v252, 21
	v_readlane_b32 s94, v252, 22
	v_readlane_b32 s95, v252, 23
	v_lshlrev_b64 v[88:89], 11, v[84:85]
	v_lshl_add_u64 v[96:97], v[88:89], 0, v[2:3]
	v_lshl_add_u64 v[98:99], v[96:97], 2, s[80:81]
	global_load_dwordx4 v[88:91], v[98:99], off offset:16 nt
	global_load_dwordx4 v[92:95], v[98:99], off nt
	v_mov_b32_e32 v86, v243
	s_waitcnt vmcnt(1)
	v_pk_fma_f32 v[90:91], v[78:79], v[86:87], v[90:91] op_sel_hi:[1,0,1]
	s_waitcnt vmcnt(0)
	v_pk_fma_f32 v[82:83], v[82:83], v[86:87], v[94:95] op_sel_hi:[1,0,1]
	v_pk_fma_f32 v[80:81], v[80:81], v[86:87], v[92:93] op_sel_hi:[1,0,1]
	v_pk_fma_f32 v[78:79], v[76:77], v[86:87], v[88:89] op_sel_hi:[1,0,1]
	v_mul_f32_e32 v1, v81, v81
	v_mul_f32_e32 v76, v83, v83
	v_fmac_f32_e32 v1, v80, v80
	v_fmac_f32_e32 v76, v82, v82
	v_add_f32_e32 v1, v1, v76
	v_mul_f32_e32 v76, v79, v79
	v_fmac_f32_e32 v76, v78, v78
	v_add_f32_e32 v1, v76, v1
	v_mul_f32_e32 v76, v91, v91
	v_fmac_f32_e32 v76, v90, v90
	v_lshl_add_u64 v[88:89], v[96:97], 1, s[54:55]
	v_add_f32_e32 v1, v76, v1
	v_cvt_pk_bf16_f32 v76, v80, v81
	v_cvt_pk_bf16_f32 v77, v82, v83
	v_cvt_pk_bf16_f32 v78, v78, v79
	v_cvt_pk_bf16_f32 v79, v90, v91
	global_store_dwordx4 v[88:89], v[76:79], off
	global_load_dwordx4 v[76:79], v[98:99], off offset:528 nt
	s_nop 0
	global_load_dwordx4 v[80:83], v[98:99], off offset:512 nt
	s_waitcnt vmcnt(1)
	v_pk_fma_f32 v[78:79], v[70:71], v[86:87], v[78:79] op_sel_hi:[1,0,1]
	s_waitcnt vmcnt(0)
	v_pk_fma_f32 v[74:75], v[74:75], v[86:87], v[82:83] op_sel_hi:[1,0,1]
	v_pk_fma_f32 v[72:73], v[72:73], v[86:87], v[80:81] op_sel_hi:[1,0,1]
	v_pk_fma_f32 v[70:71], v[68:69], v[86:87], v[76:77] op_sel_hi:[1,0,1]
	v_mul_f32_e32 v68, v73, v73
	v_mul_f32_e32 v69, v75, v75
	v_fmac_f32_e32 v68, v72, v72
	v_fmac_f32_e32 v69, v74, v74
	v_add_f32_e32 v68, v68, v69
	v_mul_f32_e32 v69, v71, v71
	v_fmac_f32_e32 v69, v70, v70
	v_add_f32_e32 v68, v69, v68
	v_mul_f32_e32 v69, v79, v79
	v_fmac_f32_e32 v69, v78, v78
	v_add_f32_e32 v68, v69, v68
	v_add_f32_e32 v1, v1, v68
	v_cvt_pk_bf16_f32 v68, v72, v73
	v_cvt_pk_bf16_f32 v69, v74, v75
	v_cvt_pk_bf16_f32 v70, v70, v71
	v_cvt_pk_bf16_f32 v71, v78, v79
	global_store_dwordx4 v[88:89], v[68:71], off offset:256
	s_nop 1
	v_mov_b32_e32 v68, v1
	v_mov_b32_e32 v253, v1
	s_nop 1
	v_permlane16_swap_b32_e32 v68, v253
	s_mov_b32 s98, 0xffff
	s_mov_b32 s99, 0xffff
	v_cndmask_b32_e64 v68, v68, v253, s[98:99]
	s_waitcnt lgkmcnt(0)
	v_add_f32_e32 v1, v1, v68
	v_mov_b32_e32 v68, v1
	s_nop 1
	v_permlane32_swap_b32_e32 v1, v68
	s_and_saveexec_b64 s[12:13], vcc
	s_cbranch_execz .LBB0_1230
	v_lshlrev_b64 v[70:71], 7, v[84:85]
	v_lshl_add_u64 v[70:71], s[22:23], 0, v[70:71]
	v_lshl_add_u64 v[70:71], s[60:61], 2, v[70:71]
	s_lshl_b32 s0, s46, 2
	v_lshl_add_u64 v[70:71], v[70:71], 0, s[0:1]
	v_add_f32_e32 v1, v1, v68
	global_store_dword v[70:71], v1, off
.LBB0_1230:
	s_or_b64 exec, exec, s[12:13]
	v_lshl_add_u64 v[68:69], v[148:149], 0, s[30:31]
	v_readlane_b32 s80, v252, 8
	v_readlane_b32 s81, v252, 9
	v_readlane_b32 s82, v252, 10
	v_readlane_b32 s83, v252, 11
	v_readlane_b32 s84, v252, 12
	v_readlane_b32 s85, v252, 13
	v_readlane_b32 s86, v252, 14
	v_readlane_b32 s87, v252, 15
	v_readlane_b32 s88, v252, 16
	v_readlane_b32 s89, v252, 17
	v_readlane_b32 s90, v252, 18
	v_readlane_b32 s91, v252, 19
	v_readlane_b32 s92, v252, 20
	v_readlane_b32 s93, v252, 21
	v_readlane_b32 s94, v252, 22
	v_readlane_b32 s95, v252, 23
	v_lshlrev_b64 v[72:73], 11, v[68:69]
	v_lshl_add_u64 v[80:81], v[72:73], 0, v[2:3]
	v_lshl_add_u64 v[82:83], v[80:81], 2, s[80:81]
	global_load_dwordx4 v[72:75], v[82:83], off offset:16 nt
	global_load_dwordx4 v[76:79], v[82:83], off nt
	v_mov_b32_e32 v70, v244
	s_waitcnt vmcnt(1)
	v_pk_fma_f32 v[74:75], v[62:63], v[70:71], v[74:75] op_sel_hi:[1,0,1]
	s_waitcnt vmcnt(0)
	v_pk_fma_f32 v[66:67], v[66:67], v[70:71], v[78:79] op_sel_hi:[1,0,1]
	v_pk_fma_f32 v[64:65], v[64:65], v[70:71], v[76:77] op_sel_hi:[1,0,1]
	v_pk_fma_f32 v[62:63], v[60:61], v[70:71], v[72:73] op_sel_hi:[1,0,1]
	v_mul_f32_e32 v1, v65, v65
	v_mul_f32_e32 v60, v67, v67
	v_fmac_f32_e32 v1, v64, v64
	v_fmac_f32_e32 v60, v66, v66
	v_add_f32_e32 v1, v1, v60
	v_mul_f32_e32 v60, v63, v63
	v_fmac_f32_e32 v60, v62, v62
	v_add_f32_e32 v1, v60, v1
	v_mul_f32_e32 v60, v75, v75
	v_fmac_f32_e32 v60, v74, v74
	v_lshl_add_u64 v[72:73], v[80:81], 1, s[54:55]
	v_add_f32_e32 v1, v60, v1
	v_cvt_pk_bf16_f32 v60, v64, v65
	v_cvt_pk_bf16_f32 v61, v66, v67
	v_cvt_pk_bf16_f32 v62, v62, v63
	v_cvt_pk_bf16_f32 v63, v74, v75
	global_store_dwordx4 v[72:73], v[60:63], off
	global_load_dwordx4 v[60:63], v[82:83], off offset:528 nt
	s_nop 0
	global_load_dwordx4 v[64:67], v[82:83], off offset:512 nt
	s_waitcnt vmcnt(1)
	v_pk_fma_f32 v[62:63], v[54:55], v[70:71], v[62:63] op_sel_hi:[1,0,1]
	s_waitcnt vmcnt(0)
	v_pk_fma_f32 v[58:59], v[58:59], v[70:71], v[66:67] op_sel_hi:[1,0,1]
	v_pk_fma_f32 v[56:57], v[56:57], v[70:71], v[64:65] op_sel_hi:[1,0,1]
	v_pk_fma_f32 v[54:55], v[52:53], v[70:71], v[60:61] op_sel_hi:[1,0,1]
	v_mul_f32_e32 v52, v57, v57
	v_mul_f32_e32 v53, v59, v59
	v_fmac_f32_e32 v52, v56, v56
	v_fmac_f32_e32 v53, v58, v58
	v_add_f32_e32 v52, v52, v53
	v_mul_f32_e32 v53, v55, v55
	v_fmac_f32_e32 v53, v54, v54
	v_add_f32_e32 v52, v53, v52
	v_mul_f32_e32 v53, v63, v63
	v_fmac_f32_e32 v53, v62, v62
	v_add_f32_e32 v52, v53, v52
	v_add_f32_e32 v1, v1, v52
	v_cvt_pk_bf16_f32 v52, v56, v57
	v_cvt_pk_bf16_f32 v53, v58, v59
	v_cvt_pk_bf16_f32 v54, v54, v55
	v_cvt_pk_bf16_f32 v55, v62, v63
	global_store_dwordx4 v[72:73], v[52:55], off offset:256
	s_nop 1
	v_mov_b32_e32 v52, v1
	v_mov_b32_e32 v253, v1
	s_nop 1
	v_permlane16_swap_b32_e32 v52, v253
	s_mov_b32 s98, 0xffff
	s_mov_b32 s99, 0xffff
	v_cndmask_b32_e64 v52, v52, v253, s[98:99]
	s_waitcnt lgkmcnt(0)
	v_add_f32_e32 v1, v1, v52
	v_mov_b32_e32 v52, v1
	s_nop 1
	v_permlane32_swap_b32_e32 v1, v52
	s_and_saveexec_b64 s[12:13], vcc
	s_cbranch_execz .LBB0_1232
	v_lshlrev_b64 v[54:55], 7, v[68:69]
	v_lshl_add_u64 v[54:55], s[22:23], 0, v[54:55]
	v_lshl_add_u64 v[54:55], s[60:61], 2, v[54:55]
	s_lshl_b32 s0, s46, 2
	v_lshl_add_u64 v[54:55], v[54:55], 0, s[0:1]
	v_add_f32_e32 v1, v1, v52
	global_store_dword v[54:55], v1, off
; template <int K> __device__ __forceinline__ float shx(float v) { static_assert(K < 32, "use sum32"); return __int_as_float(__builtin_amdgcn_ds_swizzle(__float_as_int(v), (K << 10) | 0x1f)); }
; __device__ __forceinline__ float sum32(float v) { auto rr = __builtin_amdgcn_permlane32_swap(__float_as_uint(v), __float_as_uint(v), false, false); return __uint_as_float(rr[0]) + __uint_as_float(rr[1]); }
;     __device__ __forceinline__ void operator()(const f32x4 (&acc)[2][2][4][2], const Unit& u, int wr, int wc, int fr, int fq) const {
;     ...
;             for (int m = 0; m < 4; ++m) { const size_t row = (size_t)u.pm * BM + ai * HALF + wr * 64 + m * 16 + fr;
;                 float sc = 1.f; if (MID) sc = __builtin_amdgcn_rsqf(sum_f(ssql + row * 8, 2) * (1.0f / 1024.0f) + RMS_EPS);
;                 float ss = 0.f;
; #pragma unroll
;                 for (int bj = 0; bj < 2; ++bj) { const size_t o = row * 2048 + u.pn * BM + bj * HALF + wc * 32 + fq * 8;
;                     f32x4 r0, r1;
;                     if (residb) { const u32x4 w = __builtin_nontemporal_load((const u32x4*)(residb + o));     r0 = (f32x4){__uint_as_float(w.x << 16), __uint_as_float(w.x & 0xffff0000u), __uint_as_float(w.y << 16), __uint_as_float(w.y & 0xffff0000u)};
;                                   r1 = (f32x4){__uint_as_float(w.z << 16), __uint_as_float(w.z & 0xffff0000u), __uint_as_float(w.w << 16), __uint_as_float(w.w & 0xffff0000u)}; }
;                     else { r0 = __builtin_nontemporal_load((const f32x4*)(resid + o)); r1 = __builtin_nontemporal_load((const f32x4*)(resid + o + 4)); }
;                     const f32x4 v0 = r0 + acc[ai][bj][m][0] * sc, v1 = r1 + acc[ai][bj][m][1] * sc;
;                     if (outf) { __builtin_nontemporal_store(v0, (f32x4*)(outf + o)); __builtin_nontemporal_store(v1, (f32x4*)(outf + o + 4)); }
;                     ss += (v0[0] * v0[0] + v0[1] * v0[1]) + (v0[2] * v0[2] + v0[3] * v0[3]) + (v1[0] * v1[0] + v1[1] * v1[1]) + (v1[2] * v1[2] + v1[3] * v1[3]);
;                     if (outb) *(u32x4*)(outb + o) = pack8(v0, v1); }
;                 if (ssq_out) { ss += shx<16>(ss); ss = sum32(ss); if (fq == 0) ssq_out[row * 32 + u.pn * 4 + wc] = ss; }
;                 __builtin_amdgcn_sched_barrier(0); }
.LBB0_1232:
	s_or_b64 exec, exec, s[12:13]
	s_mov_b64 s[12:13], 0x90
	v_lshl_add_u64 v[52:53], v[148:149], 0, s[12:13]
	v_readlane_b32 s80, v252, 8
	v_readlane_b32 s81, v252, 9
	v_readlane_b32 s82, v252, 10
	v_readlane_b32 s83, v252, 11
	v_readlane_b32 s84, v252, 12
	v_readlane_b32 s85, v252, 13
	v_readlane_b32 s86, v252, 14
	v_readlane_b32 s87, v252, 15
	v_readlane_b32 s88, v252, 16
	v_readlane_b32 s89, v252, 17
	v_readlane_b32 s90, v252, 18
	v_readlane_b32 s91, v252, 19
	v_readlane_b32 s92, v252, 20
	v_readlane_b32 s93, v252, 21
	v_readlane_b32 s94, v252, 22
	v_readlane_b32 s95, v252, 23
	v_lshlrev_b64 v[56:57], 11, v[52:53]
	v_lshl_add_u64 v[64:65], v[56:57], 0, v[2:3]
	v_lshl_add_u64 v[66:67], v[64:65], 2, s[80:81]
	global_load_dwordx4 v[56:59], v[66:67], off offset:16 nt
	global_load_dwordx4 v[60:63], v[66:67], off nt
	v_mov_b32_e32 v54, v245
	s_waitcnt vmcnt(1)
	v_pk_fma_f32 v[58:59], v[46:47], v[54:55], v[58:59] op_sel_hi:[1,0,1]
	s_waitcnt vmcnt(0)
	v_pk_fma_f32 v[50:51], v[50:51], v[54:55], v[62:63] op_sel_hi:[1,0,1]
	v_pk_fma_f32 v[48:49], v[48:49], v[54:55], v[60:61] op_sel_hi:[1,0,1]
	v_pk_fma_f32 v[46:47], v[44:45], v[54:55], v[56:57] op_sel_hi:[1,0,1]
	v_mul_f32_e32 v1, v49, v49
	v_mul_f32_e32 v44, v51, v51
	v_fmac_f32_e32 v1, v48, v48
	v_fmac_f32_e32 v44, v50, v50
	v_add_f32_e32 v1, v1, v44
	v_mul_f32_e32 v44, v47, v47
	v_fmac_f32_e32 v44, v46, v46
	v_add_f32_e32 v1, v44, v1
	v_mul_f32_e32 v44, v59, v59
	v_fmac_f32_e32 v44, v58, v58
	v_lshl_add_u64 v[56:57], v[64:65], 1, s[54:55]
	v_add_f32_e32 v1, v44, v1
	v_cvt_pk_bf16_f32 v44, v48, v49
	v_cvt_pk_bf16_f32 v45, v50, v51
	v_cvt_pk_bf16_f32 v46, v46, v47
	v_cvt_pk_bf16_f32 v47, v58, v59
	global_store_dwordx4 v[56:57], v[44:47], off
	global_load_dwordx4 v[44:47], v[66:67], off offset:528 nt
	s_nop 0
	global_load_dwordx4 v[48:51], v[66:67], off offset:512 nt
	s_waitcnt vmcnt(1)
	v_pk_fma_f32 v[46:47], v[38:39], v[54:55], v[46:47] op_sel_hi:[1,0,1]
	s_waitcnt vmcnt(0)
	v_pk_fma_f32 v[42:43], v[42:43], v[54:55], v[50:51] op_sel_hi:[1,0,1]
	v_pk_fma_f32 v[40:41], v[40:41], v[54:55], v[48:49] op_sel_hi:[1,0,1]
	v_pk_fma_f32 v[38:39], v[36:37], v[54:55], v[44:45] op_sel_hi:[1,0,1]
	v_mul_f32_e32 v36, v41, v41
	v_mul_f32_e32 v37, v43, v43
	v_fmac_f32_e32 v36, v40, v40
	v_fmac_f32_e32 v37, v42, v42
	v_add_f32_e32 v36, v36, v37
	v_mul_f32_e32 v37, v39, v39
	v_fmac_f32_e32 v37, v38, v38
	v_add_f32_e32 v36, v37, v36
	v_mul_f32_e32 v37, v47, v47
	v_fmac_f32_e32 v37, v46, v46
	v_add_f32_e32 v36, v37, v36
	v_add_f32_e32 v1, v1, v36
	v_cvt_pk_bf16_f32 v36, v40, v41
	v_cvt_pk_bf16_f32 v37, v42, v43
	v_cvt_pk_bf16_f32 v38, v38, v39
	v_cvt_pk_bf16_f32 v39, v46, v47
	global_store_dwordx4 v[56:57], v[36:39], off offset:256
	s_nop 1
	v_mov_b32_e32 v36, v1
	v_mov_b32_e32 v253, v1
	s_nop 1
	v_permlane16_swap_b32_e32 v36, v253
	s_mov_b32 s98, 0xffff
	s_mov_b32 s99, 0xffff
	v_cndmask_b32_e64 v36, v36, v253, s[98:99]
	s_waitcnt lgkmcnt(0)
	v_add_f32_e32 v1, v1, v36
	v_mov_b32_e32 v36, v1
	s_nop 1
	v_permlane32_swap_b32_e32 v1, v36
	s_and_saveexec_b64 s[12:13], vcc
	s_cbranch_execz .LBB0_1234
	v_lshlrev_b64 v[38:39], 7, v[52:53]
	v_lshl_add_u64 v[38:39], s[22:23], 0, v[38:39]
	v_lshl_add_u64 v[38:39], s[60:61], 2, v[38:39]
	s_lshl_b32 s0, s46, 2
	v_lshl_add_u64 v[38:39], v[38:39], 0, s[0:1]
	v_add_f32_e32 v1, v1, v36
	global_store_dword v[38:39], v1, off
; template <int K> __device__ __forceinline__ float shx(float v) { static_assert(K < 32, "use sum32"); return __int_as_float(__builtin_amdgcn_ds_swizzle(__float_as_int(v), (K << 10) | 0x1f)); }
; __device__ __forceinline__ float sum32(float v) { auto rr = __builtin_amdgcn_permlane32_swap(__float_as_uint(v), __float_as_uint(v), false, false); return __uint_as_float(rr[0]) + __uint_as_float(rr[1]); }
;     __device__ __forceinline__ void operator()(const f32x4 (&acc)[2][2][4][2], const Unit& u, int wr, int wc, int fr, int fq) const {
;     ...
;             for (int m = 0; m < 4; ++m) { const size_t row = (size_t)u.pm * BM + ai * HALF + wr * 64 + m * 16 + fr;
;                 float sc = 1.f; if (MID) sc = __builtin_amdgcn_rsqf(sum_f(ssql + row * 8, 2) * (1.0f / 1024.0f) + RMS_EPS);
;                 float ss = 0.f;
; #pragma unroll
;                 for (int bj = 0; bj < 2; ++bj) { const size_t o = row * 2048 + u.pn * BM + bj * HALF + wc * 32 + fq * 8;
;                     f32x4 r0, r1;
;                     if (residb) { const u32x4 w = __builtin_nontemporal_load((const u32x4*)(residb + o));     r0 = (f32x4){__uint_as_float(w.x << 16), __uint_as_float(w.x & 0xffff0000u), __uint_as_float(w.y << 16), __uint_as_float(w.y & 0xffff0000u)};
;                                   r1 = (f32x4){__uint_as_float(w.z << 16), __uint_as_float(w.z & 0xffff0000u), __uint_as_float(w.w << 16), __uint_as_float(w.w & 0xffff0000u)}; }
;                     else { r0 = __builtin_nontemporal_load((const f32x4*)(resid + o)); r1 = __builtin_nontemporal_load((const f32x4*)(resid + o + 4)); }
;                     const f32x4 v0 = r0 + acc[ai][bj][m][0] * sc, v1 = r1 + acc[ai][bj][m][1] * sc;
;                     if (outf) { __builtin_nontemporal_store(v0, (f32x4*)(outf + o)); __builtin_nontemporal_store(v1, (f32x4*)(outf + o + 4)); }
;                     ss += (v0[0] * v0[0] + v0[1] * v0[1]) + (v0[2] * v0[2] + v0[3] * v0[3]) + (v1[0] * v1[0] + v1[1] * v1[1]) + (v1[2] * v1[2] + v1[3] * v1[3]);
;                     if (outb) *(u32x4*)(outb + o) = pack8(v0, v1); }
;                 if (ssq_out) { ss += shx<16>(ss); ss = sum32(ss); if (fq == 0) ssq_out[row * 32 + u.pn * 4 + wc] = ss; }
;                 __builtin_amdgcn_sched_barrier(0); }
.LBB0_1234:
	s_or_b64 exec, exec, s[12:13]
	s_mov_b64 s[12:13], 0xa0
	v_lshl_add_u64 v[36:37], v[148:149], 0, s[12:13]
	v_readlane_b32 s80, v252, 8
	v_readlane_b32 s81, v252, 9
	v_readlane_b32 s82, v252, 10
	v_readlane_b32 s83, v252, 11
	v_readlane_b32 s84, v252, 12
	v_readlane_b32 s85, v252, 13
	v_readlane_b32 s86, v252, 14
	v_readlane_b32 s87, v252, 15
	v_readlane_b32 s88, v252, 16
	v_readlane_b32 s89, v252, 17
	v_readlane_b32 s90, v252, 18
	v_readlane_b32 s91, v252, 19
	v_readlane_b32 s92, v252, 20
	v_readlane_b32 s93, v252, 21
	v_readlane_b32 s94, v252, 22
	v_readlane_b32 s95, v252, 23
	v_lshlrev_b64 v[40:41], 11, v[36:37]
	v_lshl_add_u64 v[48:49], v[40:41], 0, v[2:3]
	v_lshl_add_u64 v[50:51], v[48:49], 2, s[80:81]
	global_load_dwordx4 v[40:43], v[50:51], off offset:16 nt
	global_load_dwordx4 v[44:47], v[50:51], off nt
	v_mov_b32_e32 v38, v246
	s_waitcnt vmcnt(1)
	v_pk_fma_f32 v[42:43], v[30:31], v[38:39], v[42:43] op_sel_hi:[1,0,1]
	s_waitcnt vmcnt(0)
	v_pk_fma_f32 v[34:35], v[34:35], v[38:39], v[46:47] op_sel_hi:[1,0,1]
	v_pk_fma_f32 v[32:33], v[32:33], v[38:39], v[44:45] op_sel_hi:[1,0,1]
	v_pk_fma_f32 v[30:31], v[28:29], v[38:39], v[40:41] op_sel_hi:[1,0,1]
	v_mul_f32_e32 v1, v33, v33
	v_mul_f32_e32 v28, v35, v35
	v_fmac_f32_e32 v1, v32, v32
	v_fmac_f32_e32 v28, v34, v34
	v_add_f32_e32 v1, v1, v28
	v_mul_f32_e32 v28, v31, v31
	v_fmac_f32_e32 v28, v30, v30
	v_add_f32_e32 v1, v28, v1
	v_mul_f32_e32 v28, v43, v43
	v_fmac_f32_e32 v28, v42, v42
	v_lshl_add_u64 v[40:41], v[48:49], 1, s[54:55]
	v_add_f32_e32 v1, v28, v1
	v_cvt_pk_bf16_f32 v28, v32, v33
	v_cvt_pk_bf16_f32 v29, v34, v35
	v_cvt_pk_bf16_f32 v30, v30, v31
	v_cvt_pk_bf16_f32 v31, v42, v43
	global_store_dwordx4 v[40:41], v[28:31], off
	global_load_dwordx4 v[28:31], v[50:51], off offset:528 nt
	s_nop 0
	global_load_dwordx4 v[32:35], v[50:51], off offset:512 nt
	s_waitcnt vmcnt(1)
	v_pk_fma_f32 v[30:31], v[22:23], v[38:39], v[30:31] op_sel_hi:[1,0,1]
	s_waitcnt vmcnt(0)
	v_pk_fma_f32 v[26:27], v[26:27], v[38:39], v[34:35] op_sel_hi:[1,0,1]
	v_pk_fma_f32 v[24:25], v[24:25], v[38:39], v[32:33] op_sel_hi:[1,0,1]
	v_pk_fma_f32 v[22:23], v[20:21], v[38:39], v[28:29] op_sel_hi:[1,0,1]
	v_mul_f32_e32 v20, v25, v25
	v_mul_f32_e32 v21, v27, v27
	v_fmac_f32_e32 v20, v24, v24
	v_fmac_f32_e32 v21, v26, v26
	v_add_f32_e32 v20, v20, v21
	v_mul_f32_e32 v21, v23, v23
	v_fmac_f32_e32 v21, v22, v22
	v_add_f32_e32 v20, v21, v20
	v_mul_f32_e32 v21, v31, v31
	v_fmac_f32_e32 v21, v30, v30
	v_add_f32_e32 v20, v21, v20
	v_add_f32_e32 v1, v1, v20
	v_cvt_pk_bf16_f32 v20, v24, v25
	v_cvt_pk_bf16_f32 v21, v26, v27
	v_cvt_pk_bf16_f32 v22, v22, v23
	v_cvt_pk_bf16_f32 v23, v30, v31
	global_store_dwordx4 v[40:41], v[20:23], off offset:256
	s_nop 1
	v_mov_b32_e32 v20, v1
	v_mov_b32_e32 v253, v1
	s_nop 1
	v_permlane16_swap_b32_e32 v20, v253
	s_mov_b32 s98, 0xffff
	s_mov_b32 s99, 0xffff
	v_cndmask_b32_e64 v20, v20, v253, s[98:99]
	s_waitcnt lgkmcnt(0)
	v_add_f32_e32 v1, v1, v20
	v_mov_b32_e32 v20, v1
	s_nop 1
	v_permlane32_swap_b32_e32 v1, v20
	s_and_saveexec_b64 s[12:13], vcc
	s_cbranch_execz .LBB0_1236
	v_lshlrev_b64 v[22:23], 7, v[36:37]
	v_lshl_add_u64 v[22:23], s[22:23], 0, v[22:23]
	v_lshl_add_u64 v[22:23], s[60:61], 2, v[22:23]
	s_lshl_b32 s0, s46, 2
	v_lshl_add_u64 v[22:23], v[22:23], 0, s[0:1]
	v_add_f32_e32 v1, v1, v20
	global_store_dword v[22:23], v1, off
.LBB0_1236:
	s_or_b64 exec, exec, s[12:13]
	s_mov_b64 s[12:13], 0xb0
	v_lshl_add_u64 v[20:21], v[148:149], 0, s[12:13]
	v_readlane_b32 s80, v252, 8
	v_readlane_b32 s81, v252, 9
	v_readlane_b32 s82, v252, 10
	v_readlane_b32 s83, v252, 11
	v_readlane_b32 s84, v252, 12
	v_readlane_b32 s85, v252, 13
	v_readlane_b32 s86, v252, 14
	v_readlane_b32 s87, v252, 15
	v_readlane_b32 s88, v252, 16
	v_readlane_b32 s89, v252, 17
	v_readlane_b32 s90, v252, 18
	v_readlane_b32 s91, v252, 19
	v_readlane_b32 s92, v252, 20
	v_readlane_b32 s93, v252, 21
	v_readlane_b32 s94, v252, 22
	v_readlane_b32 s95, v252, 23
	v_lshlrev_b64 v[24:25], 11, v[20:21]
	v_lshl_add_u64 v[2:3], v[24:25], 0, v[2:3]
	v_lshl_add_u64 v[32:33], v[2:3], 2, s[80:81]
	global_load_dwordx4 v[24:27], v[32:33], off offset:16 nt
	global_load_dwordx4 v[28:31], v[32:33], off nt
	v_mov_b32_e32 v22, v247
	s_waitcnt vmcnt(1)
	v_pk_fma_f32 v[26:27], v[14:15], v[22:23], v[26:27] op_sel_hi:[1,0,1]
	s_waitcnt vmcnt(0)
	v_pk_fma_f32 v[18:19], v[18:19], v[22:23], v[30:31] op_sel_hi:[1,0,1]
	v_pk_fma_f32 v[16:17], v[16:17], v[22:23], v[28:29] op_sel_hi:[1,0,1]
	v_pk_fma_f32 v[14:15], v[12:13], v[22:23], v[24:25] op_sel_hi:[1,0,1]
	v_mul_f32_e32 v1, v17, v17
	v_mul_f32_e32 v12, v19, v19
	v_fmac_f32_e32 v1, v16, v16
	v_fmac_f32_e32 v12, v18, v18
	v_add_f32_e32 v1, v1, v12
	v_mul_f32_e32 v12, v15, v15
	v_fmac_f32_e32 v12, v14, v14
	v_add_f32_e32 v1, v12, v1
	v_mul_f32_e32 v12, v27, v27
	v_fmac_f32_e32 v12, v26, v26
	v_lshl_add_u64 v[24:25], v[2:3], 1, s[54:55]
	v_add_f32_e32 v1, v12, v1
	v_cvt_pk_bf16_f32 v12, v16, v17
	v_cvt_pk_bf16_f32 v13, v18, v19
	v_cvt_pk_bf16_f32 v14, v14, v15
	v_cvt_pk_bf16_f32 v15, v26, v27
	global_store_dwordx4 v[24:25], v[12:15], off
	global_load_dwordx4 v[12:15], v[32:33], off offset:528 nt
	s_nop 0
	global_load_dwordx4 v[16:19], v[32:33], off offset:512 nt
	s_waitcnt vmcnt(1)
	v_pk_fma_f32 v[4:5], v[4:5], v[22:23], v[12:13] op_sel_hi:[1,0,1]
	s_waitcnt vmcnt(0)
	v_pk_fma_f32 v[10:11], v[10:11], v[22:23], v[18:19] op_sel_hi:[1,0,1]
	v_pk_fma_f32 v[2:3], v[8:9], v[22:23], v[16:17] op_sel_hi:[1,0,1]
	v_mul_f32_e32 v9, v11, v11
	v_mul_f32_e32 v8, v3, v3
	v_fmac_f32_e32 v8, v2, v2
	v_fmac_f32_e32 v9, v10, v10
	v_add_f32_e32 v8, v8, v9
	v_mul_f32_e32 v9, v5, v5
	v_pk_fma_f32 v[6:7], v[6:7], v[22:23], v[14:15] op_sel_hi:[1,0,1]
	v_fmac_f32_e32 v9, v4, v4
	v_add_f32_e32 v8, v9, v8
	v_mul_f32_e32 v9, v7, v7
	v_fmac_f32_e32 v9, v6, v6
	v_add_f32_e32 v8, v9, v8
	v_add_f32_e32 v1, v1, v8
	v_cvt_pk_bf16_f32 v2, v2, v3
	v_cvt_pk_bf16_f32 v3, v10, v11
	v_cvt_pk_bf16_f32 v4, v4, v5
	v_cvt_pk_bf16_f32 v5, v6, v7
	global_store_dwordx4 v[24:25], v[2:5], off offset:256
	s_nop 1
	v_mov_b32_e32 v2, v1
	v_mov_b32_e32 v253, v1
	s_nop 1
	v_permlane16_swap_b32_e32 v2, v253
	s_mov_b32 s98, 0xffff
	s_mov_b32 s99, 0xffff
	v_cndmask_b32_e64 v2, v2, v253, s[98:99]
	s_waitcnt lgkmcnt(0)
	v_add_f32_e32 v1, v1, v2
	v_mov_b32_e32 v2, v1
	s_nop 1
	v_permlane32_swap_b32_e32 v1, v2
	s_and_saveexec_b64 s[12:13], vcc
	s_cbranch_execz .LBB0_1238
	v_lshlrev_b64 v[4:5], 7, v[20:21]
	v_lshl_add_u64 v[4:5], s[22:23], 0, v[4:5]
	v_lshl_add_u64 v[4:5], s[60:61], 2, v[4:5]
	s_lshl_b32 s0, s46, 2
	v_lshl_add_u64 v[4:5], v[4:5], 0, s[0:1]
	v_add_f32_e32 v1, v1, v2
	global_store_dword v[4:5], v1, off

; template <int K> __device__ __forceinline__ float shx(float v) { static_assert(K < 32, "use sum32"); return __int_as_float(__builtin_amdgcn_ds_swizzle(__float_as_int(v), (K << 10) | 0x1f)); }
; __device__ __forceinline__ float sum32(float v) { auto rr = __builtin_amdgcn_permlane32_swap(__float_as_uint(v), __float_as_uint(v), false, false); return __uint_as_float(rr[0]) + __uint_as_float(rr[1]); }
; template <bool ROWSCALE>
; __device__ __forceinline__ void head_norm_store(const f32x4 (&acc)[2][2][4][2], const float (&rs)[2][4], const float* gain, bf16_t* d0, bf16_t* d1, PG8_LAS float* red, int wr, int wc, int fr, int fq) {
;     ...
;             for (int bj = 0; bj < 2; ++bj) { float s = 0.f;
; #pragma unroll
;                 for (int n = 0; n < 2; ++n) { f32x4 v = acc[ai][bj][m][n]; if (ROWSCALE) v = v * rs[ai][m]; s += (v[0] * v[0] + v[1] * v[1]) + (v[2] * v[2] + v[3] * v[3]); }
;                 s += shx<16>(s); s = sum32(s);
;                 if (fq == 0) red[((ai * HALF + wr * 64 + m * 16 + fr) * 2 + bj) * 4 + wc] = s; }
;     __device__ __forceinline__ void operator()(const f32x4 (&acc)[2][2][4][2], const Unit& u, int wr, int wc, int fr, int fq) const {
;     ...
;         asm volatile("s_waitcnt lgkmcnt(0)" ::: "memory"); __builtin_amdgcn_s_barrier(); asm volatile("" ::: "memory");
;         float rs[2][4];
; #pragma unroll
;         for (int ai = 0; ai < 2; ++ai)
; #pragma unroll
;             for (int m = 0; m < 4; ++m) rs[ai][m] = tab[ai * HALF + wr * 64 + m * 16 + fr];
.LBB0_1314:
	s_or_b64 exec, exec, s[12:13]
	s_waitcnt lgkmcnt(0)
	s_barrier
	v_lshl_add_u32 v129, v156, 2, s46
	ds_read2_b32 v[154:155], v129 offset1:16
	ds_read2_b32 v[152:153], v129 offset0:32 offset1:48
	ds_read2_b32 v[150:151], v129 offset0:128 offset1:144
	ds_read2_b32 v[148:149], v129 offset0:160 offset1:176
	v_lshlrev_b32_e32 v129, 5, v156
	v_cmp_eq_u32_e32 vcc, 0, v128
	s_waitcnt lgkmcnt(0)
	v_pk_mul_f32 v[130:131], v[126:127], v[154:155] op_sel_hi:[1,0]
	v_pk_mul_f32 v[132:133], v[124:125], v[154:155] op_sel_hi:[1,0]
	v_mul_f32_e32 v131, v131, v131
	v_mul_f32_e32 v133, v133, v133
	v_fmac_f32_e32 v133, v132, v132
	v_fmac_f32_e32 v131, v130, v130
	v_add_f32_e32 v134, v133, v131
	v_pk_mul_f32 v[130:131], v[122:123], v[154:155] op_sel_hi:[1,0]
	v_pk_mul_f32 v[132:133], v[120:121], v[154:155] op_sel_hi:[1,0]
	v_mul_f32_e32 v131, v131, v131
	v_mul_f32_e32 v133, v133, v133
	v_fmac_f32_e32 v133, v132, v132
	v_fmac_f32_e32 v131, v130, v130
	v_add_f32_e32 v130, v133, v131
	v_add_f32_e32 v130, v134, v130
	s_nop 1
	v_mov_b32_e32 v131, v130
	v_mov_b32_e32 v253, v130
	s_nop 1
	v_permlane16_swap_b32_e32 v131, v253
	s_mov_b32 s98, 0xffff
	s_mov_b32 s99, 0xffff
	v_cndmask_b32_e64 v131, v131, v253, s[98:99]
	v_add_u32_e32 v129, s47, v129
	s_waitcnt lgkmcnt(0)
	v_add_f32_e32 v130, v130, v131
	v_mov_b32_e32 v131, v130
	s_nop 1
	v_permlane32_swap_b32_e32 v130, v131
	s_and_saveexec_b64 s[12:13], vcc
	v_add_f32_e32 v130, v130, v131
	ds_write_b32 v129, v130
	s_or_b64 exec, exec, s[12:13]
	v_mov_b32_e32 v130, v154
	v_mov_b32_e32 v131, v154
	v_mov_b32_e32 v132, v154
	v_mov_b32_e32 v133, v154
	v_pk_mul_f32 v[166:167], v[116:117], v[130:131]
	v_pk_mul_f32 v[130:131], v[112:113], v[130:131]
	v_pk_mul_f32 v[134:135], v[118:119], v[132:133]
	v_pk_mul_f32 v[132:133], v[114:115], v[132:133]
	v_mul_f32_e32 v131, v131, v131
	v_mul_f32_e32 v157, v167, v167
	v_mul_f32_e32 v135, v135, v135
	v_fmac_f32_e32 v131, v130, v130
	v_mul_f32_e32 v130, v133, v133
	v_fmac_f32_e32 v157, v166, v166
	v_fmac_f32_e32 v135, v134, v134
	v_fmac_f32_e32 v130, v132, v132
	v_add_f32_e32 v134, v157, v135
	v_add_f32_e32 v130, v131, v130
	v_add_f32_e32 v130, v134, v130
	s_nop 1
	v_mov_b32_e32 v131, v130
	v_mov_b32_e32 v253, v130
	s_nop 1
	v_permlane16_swap_b32_e32 v131, v253
	s_mov_b32 s98, 0xffff
	s_mov_b32 s99, 0xffff
	v_cndmask_b32_e64 v131, v131, v253, s[98:99]
	s_waitcnt lgkmcnt(0)
	v_add_f32_e32 v130, v130, v131
	v_mov_b32_e32 v131, v130
	s_nop 1
	v_permlane32_swap_b32_e32 v130, v131
	s_and_saveexec_b64 s[12:13], vcc
	v_add_f32_e32 v130, v130, v131
	ds_write_b32 v129, v130 offset:16
	s_or_b64 exec, exec, s[12:13]
	v_mov_b32_e32 v130, v155
	v_pk_mul_f32 v[132:133], v[110:111], v[130:131] op_sel_hi:[1,0]
	v_pk_mul_f32 v[134:135], v[108:109], v[130:131] op_sel_hi:[1,0]
	v_mul_f32_e32 v133, v133, v133
	v_mul_f32_e32 v131, v135, v135
	v_fmac_f32_e32 v131, v134, v134
	v_fmac_f32_e32 v133, v132, v132
	v_add_f32_e32 v134, v131, v133
	v_pk_mul_f32 v[132:133], v[106:107], v[130:131] op_sel_hi:[1,0]
	v_pk_mul_f32 v[130:131], v[104:105], v[130:131] op_sel_hi:[1,0]
	s_nop 0
	v_mul_f32_e32 v131, v131, v131
	v_fmac_f32_e32 v131, v130, v130
	v_mul_f32_e32 v130, v133, v133
	v_fmac_f32_e32 v130, v132, v132
	v_add_f32_e32 v130, v131, v130
	v_add_f32_e32 v130, v134, v130
	s_nop 1
	v_mov_b32_e32 v131, v130
	v_mov_b32_e32 v253, v130
	s_nop 1
	v_permlane16_swap_b32_e32 v131, v253
	s_mov_b32 s98, 0xffff
	s_mov_b32 s99, 0xffff
	v_cndmask_b32_e64 v131, v131, v253, s[98:99]
	s_waitcnt lgkmcnt(0)
	v_add_f32_e32 v130, v130, v131
	v_mov_b32_e32 v131, v130
	s_nop 1
	v_permlane32_swap_b32_e32 v130, v131
	s_and_saveexec_b64 s[12:13], vcc
	v_add_f32_e32 v130, v130, v131
	ds_write_b32 v129, v130 offset:512
	s_or_b64 exec, exec, s[12:13]
	v_mov_b32_e32 v130, v155
	v_mov_b32_e32 v131, v155
	v_mov_b32_e32 v132, v155
	v_mov_b32_e32 v133, v155
	v_pk_mul_f32 v[166:167], v[100:101], v[130:131]
	v_pk_mul_f32 v[130:131], v[96:97], v[130:131]
	v_pk_mul_f32 v[134:135], v[102:103], v[132:133]
	v_pk_mul_f32 v[132:133], v[98:99], v[132:133]
	v_mul_f32_e32 v131, v131, v131
	v_mul_f32_e32 v157, v167, v167
	v_mul_f32_e32 v135, v135, v135
	v_fmac_f32_e32 v131, v130, v130
	v_mul_f32_e32 v130, v133, v133
	v_fmac_f32_e32 v157, v166, v166
	v_fmac_f32_e32 v135, v134, v134
	v_fmac_f32_e32 v130, v132, v132
	v_add_f32_e32 v134, v157, v135
	v_add_f32_e32 v130, v131, v130
	v_add_f32_e32 v130, v134, v130
	s_nop 1
	v_mov_b32_e32 v131, v130
	v_mov_b32_e32 v253, v130
	s_nop 1
	v_permlane16_swap_b32_e32 v131, v253
	s_mov_b32 s98, 0xffff
	s_mov_b32 s99, 0xffff
	v_cndmask_b32_e64 v131, v131, v253, s[98:99]
	s_waitcnt lgkmcnt(0)
	v_add_f32_e32 v130, v130, v131
	v_mov_b32_e32 v131, v130
	s_nop 1
	v_permlane32_swap_b32_e32 v130, v131
	s_and_saveexec_b64 s[12:13], vcc
	v_add_f32_e32 v130, v130, v131
	ds_write_b32 v129, v130 offset:528
	s_or_b64 exec, exec, s[12:13]
	v_pk_mul_f32 v[130:131], v[94:95], v[152:153] op_sel_hi:[1,0]
	v_pk_mul_f32 v[132:133], v[92:93], v[152:153] op_sel_hi:[1,0]
	v_mul_f32_e32 v131, v131, v131
	v_mul_f32_e32 v133, v133, v133
	v_fmac_f32_e32 v133, v132, v132
	v_fmac_f32_e32 v131, v130, v130
	v_add_f32_e32 v134, v133, v131
	v_pk_mul_f32 v[130:131], v[90:91], v[152:153] op_sel_hi:[1,0]
	v_pk_mul_f32 v[132:133], v[88:89], v[152:153] op_sel_hi:[1,0]
	v_mul_f32_e32 v131, v131, v131
	v_mul_f32_e32 v133, v133, v133
	v_fmac_f32_e32 v133, v132, v132
	v_fmac_f32_e32 v131, v130, v130
	v_add_f32_e32 v130, v133, v131
	v_add_f32_e32 v130, v134, v130
	s_nop 1
	v_mov_b32_e32 v131, v130
	v_mov_b32_e32 v253, v130
	s_nop 1
	v_permlane16_swap_b32_e32 v131, v253
	s_mov_b32 s98, 0xffff
	s_mov_b32 s99, 0xffff
	v_cndmask_b32_e64 v131, v131, v253, s[98:99]
	s_waitcnt lgkmcnt(0)
; template <int K> __device__ __forceinline__ float shx(float v) { static_assert(K < 32, "use sum32"); return __int_as_float(__builtin_amdgcn_ds_swizzle(__float_as_int(v), (K << 10) | 0x1f)); }
; __device__ __forceinline__ float sum32(float v) { auto rr = __builtin_amdgcn_permlane32_swap(__float_as_uint(v), __float_as_uint(v), false, false); return __uint_as_float(rr[0]) + __uint_as_float(rr[1]); }
; template <bool ROWSCALE>
; __device__ __forceinline__ void head_norm_store(const f32x4 (&acc)[2][2][4][2], const float (&rs)[2][4], const float* gain, bf16_t* d0, bf16_t* d1, PG8_LAS float* red, int wr, int wc, int fr, int fq) {
;     ...
;             for (int bj = 0; bj < 2; ++bj) { float s = 0.f;
; #pragma unroll
;                 for (int n = 0; n < 2; ++n) { f32x4 v = acc[ai][bj][m][n]; if (ROWSCALE) v = v * rs[ai][m]; s += (v[0] * v[0] + v[1] * v[1]) + (v[2] * v[2] + v[3] * v[3]); }
;                 s += shx<16>(s); s = sum32(s);
;                 if (fq == 0) red[((ai * HALF + wr * 64 + m * 16 + fr) * 2 + bj) * 4 + wc] = s; }
	v_add_f32_e32 v130, v130, v131
	v_mov_b32_e32 v131, v130
	s_nop 1
	v_permlane32_swap_b32_e32 v130, v131
	s_and_saveexec_b64 s[12:13], vcc
	v_add_f32_e32 v130, v130, v131
	ds_write_b32 v129, v130 offset:1024
	s_or_b64 exec, exec, s[12:13]
	v_mov_b32_e32 v130, v152
	v_mov_b32_e32 v131, v152
	v_mov_b32_e32 v132, v152
	v_mov_b32_e32 v133, v152
	v_pk_mul_f32 v[166:167], v[84:85], v[130:131]
	v_pk_mul_f32 v[130:131], v[80:81], v[130:131]
	v_pk_mul_f32 v[134:135], v[86:87], v[132:133]
	v_pk_mul_f32 v[132:133], v[82:83], v[132:133]
	v_mul_f32_e32 v131, v131, v131
	v_mul_f32_e32 v157, v167, v167
	v_mul_f32_e32 v135, v135, v135
	v_fmac_f32_e32 v131, v130, v130
	v_mul_f32_e32 v130, v133, v133
	v_fmac_f32_e32 v157, v166, v166
	v_fmac_f32_e32 v135, v134, v134
	v_fmac_f32_e32 v130, v132, v132
	v_add_f32_e32 v134, v157, v135
	v_add_f32_e32 v130, v131, v130
	v_add_f32_e32 v130, v134, v130
	s_nop 1
	v_mov_b32_e32 v131, v130
	v_mov_b32_e32 v253, v130
	s_nop 1
	v_permlane16_swap_b32_e32 v131, v253
	s_mov_b32 s98, 0xffff
	s_mov_b32 s99, 0xffff
	v_cndmask_b32_e64 v131, v131, v253, s[98:99]
	s_waitcnt lgkmcnt(0)
	v_add_f32_e32 v130, v130, v131
	v_mov_b32_e32 v131, v130
	s_nop 1
	v_permlane32_swap_b32_e32 v130, v131
	s_and_saveexec_b64 s[12:13], vcc
	v_add_f32_e32 v130, v130, v131
	ds_write_b32 v129, v130 offset:1040
	s_or_b64 exec, exec, s[12:13]
	v_mov_b32_e32 v130, v153
	v_pk_mul_f32 v[132:133], v[78:79], v[130:131] op_sel_hi:[1,0]
	v_pk_mul_f32 v[134:135], v[76:77], v[130:131] op_sel_hi:[1,0]
	v_mul_f32_e32 v133, v133, v133
	v_mul_f32_e32 v131, v135, v135
	v_fmac_f32_e32 v131, v134, v134
	v_fmac_f32_e32 v133, v132, v132
	v_add_f32_e32 v134, v131, v133
	v_pk_mul_f32 v[132:133], v[74:75], v[130:131] op_sel_hi:[1,0]
	v_pk_mul_f32 v[130:131], v[72:73], v[130:131] op_sel_hi:[1,0]
	s_nop 0
	v_mul_f32_e32 v131, v131, v131
	v_fmac_f32_e32 v131, v130, v130
	v_mul_f32_e32 v130, v133, v133
	v_fmac_f32_e32 v130, v132, v132
	v_add_f32_e32 v130, v131, v130
	v_add_f32_e32 v130, v134, v130
	s_nop 1
	v_mov_b32_e32 v131, v130
	v_mov_b32_e32 v253, v130
	s_nop 1
	v_permlane16_swap_b32_e32 v131, v253
	s_mov_b32 s98, 0xffff
	s_mov_b32 s99, 0xffff
	v_cndmask_b32_e64 v131, v131, v253, s[98:99]
	s_waitcnt lgkmcnt(0)
	v_add_f32_e32 v130, v130, v131
	v_mov_b32_e32 v131, v130
	s_nop 1
	v_permlane32_swap_b32_e32 v130, v131
	s_and_saveexec_b64 s[12:13], vcc
	v_add_f32_e32 v130, v130, v131
	ds_write_b32 v129, v130 offset:1536
	s_or_b64 exec, exec, s[12:13]
	v_mov_b32_e32 v130, v153
	v_mov_b32_e32 v131, v153
	v_mov_b32_e32 v132, v153
	v_mov_b32_e32 v133, v153
	v_pk_mul_f32 v[166:167], v[68:69], v[130:131]
	v_pk_mul_f32 v[130:131], v[64:65], v[130:131]
	v_pk_mul_f32 v[134:135], v[70:71], v[132:133]
	v_pk_mul_f32 v[132:133], v[66:67], v[132:133]
	v_mul_f32_e32 v131, v131, v131
	v_mul_f32_e32 v157, v167, v167
	v_mul_f32_e32 v135, v135, v135
	v_fmac_f32_e32 v131, v130, v130
	v_mul_f32_e32 v130, v133, v133
	v_fmac_f32_e32 v157, v166, v166
	v_fmac_f32_e32 v135, v134, v134
	v_fmac_f32_e32 v130, v132, v132
	v_add_f32_e32 v134, v157, v135
	v_add_f32_e32 v130, v131, v130
	v_add_f32_e32 v130, v134, v130
	s_nop 1
	v_mov_b32_e32 v131, v130
	v_mov_b32_e32 v253, v130
	s_nop 1
	v_permlane16_swap_b32_e32 v131, v253
	s_mov_b32 s98, 0xffff
	s_mov_b32 s99, 0xffff
	v_cndmask_b32_e64 v131, v131, v253, s[98:99]
	s_waitcnt lgkmcnt(0)
	v_add_f32_e32 v130, v130, v131
	v_mov_b32_e32 v131, v130
	s_nop 1
	v_permlane32_swap_b32_e32 v130, v131
	s_and_saveexec_b64 s[12:13], vcc
	v_add_f32_e32 v130, v130, v131
	ds_write_b32 v129, v130 offset:1552
	s_or_b64 exec, exec, s[12:13]
	v_pk_mul_f32 v[130:131], v[62:63], v[150:151] op_sel_hi:[1,0]
	v_pk_mul_f32 v[132:133], v[60:61], v[150:151] op_sel_hi:[1,0]
	v_mul_f32_e32 v131, v131, v131
	v_mul_f32_e32 v133, v133, v133
	v_fmac_f32_e32 v133, v132, v132
	v_fmac_f32_e32 v131, v130, v130
	v_add_f32_e32 v134, v133, v131
	v_pk_mul_f32 v[130:131], v[58:59], v[150:151] op_sel_hi:[1,0]
	v_pk_mul_f32 v[132:133], v[56:57], v[150:151] op_sel_hi:[1,0]
	v_mul_f32_e32 v131, v131, v131
	v_mul_f32_e32 v133, v133, v133
	v_fmac_f32_e32 v133, v132, v132
	v_fmac_f32_e32 v131, v130, v130
	v_add_f32_e32 v130, v133, v131
	v_add_f32_e32 v130, v134, v130
	s_nop 1
	v_mov_b32_e32 v131, v130
	v_mov_b32_e32 v253, v130
	s_nop 1
	v_permlane16_swap_b32_e32 v131, v253
	s_mov_b32 s98, 0xffff
	s_mov_b32 s99, 0xffff
	v_cndmask_b32_e64 v131, v131, v253, s[98:99]
	s_waitcnt lgkmcnt(0)
	v_add_f32_e32 v130, v130, v131
	v_mov_b32_e32 v131, v130
	s_nop 1
	v_permlane32_swap_b32_e32 v130, v131
	s_and_saveexec_b64 s[12:13], vcc
	v_add_f32_e32 v130, v130, v131
	ds_write_b32 v129, v130 offset:4096
	s_or_b64 exec, exec, s[12:13]
	v_mov_b32_e32 v130, v150
	v_mov_b32_e32 v131, v150
	v_mov_b32_e32 v132, v150
	v_mov_b32_e32 v133, v150
	v_pk_mul_f32 v[166:167], v[52:53], v[130:131]
	v_pk_mul_f32 v[130:131], v[48:49], v[130:131]
	v_pk_mul_f32 v[134:135], v[54:55], v[132:133]
	v_pk_mul_f32 v[132:133], v[50:51], v[132:133]
	v_mul_f32_e32 v131, v131, v131
	v_mul_f32_e32 v157, v167, v167
	v_mul_f32_e32 v135, v135, v135
	v_fmac_f32_e32 v131, v130, v130
	v_mul_f32_e32 v130, v133, v133
	v_fmac_f32_e32 v157, v166, v166
	v_fmac_f32_e32 v135, v134, v134
	v_fmac_f32_e32 v130, v132, v132
	v_add_f32_e32 v134, v157, v135
	v_add_f32_e32 v130, v131, v130
	v_add_f32_e32 v130, v134, v130
	s_nop 1
	v_mov_b32_e32 v131, v130
	v_mov_b32_e32 v253, v130
	s_nop 1
	v_permlane16_swap_b32_e32 v131, v253
	s_mov_b32 s98, 0xffff
	s_mov_b32 s99, 0xffff
	v_cndmask_b32_e64 v131, v131, v253, s[98:99]
	s_waitcnt lgkmcnt(0)
; template <int K> __device__ __forceinline__ float shx(float v) { static_assert(K < 32, "use sum32"); return __int_as_float(__builtin_amdgcn_ds_swizzle(__float_as_int(v), (K << 10) | 0x1f)); }
; __device__ __forceinline__ float sum32(float v) { auto rr = __builtin_amdgcn_permlane32_swap(__float_as_uint(v), __float_as_uint(v), false, false); return __uint_as_float(rr[0]) + __uint_as_float(rr[1]); }
; template <bool ROWSCALE>
; __device__ __forceinline__ void head_norm_store(const f32x4 (&acc)[2][2][4][2], const float (&rs)[2][4], const float* gain, bf16_t* d0, bf16_t* d1, PG8_LAS float* red, int wr, int wc, int fr, int fq) {
;     ...
;             for (int bj = 0; bj < 2; ++bj) { float s = 0.f;
; #pragma unroll
;                 for (int n = 0; n < 2; ++n) { f32x4 v = acc[ai][bj][m][n]; if (ROWSCALE) v = v * rs[ai][m]; s += (v[0] * v[0] + v[1] * v[1]) + (v[2] * v[2] + v[3] * v[3]); }
;                 s += shx<16>(s); s = sum32(s);
;                 if (fq == 0) red[((ai * HALF + wr * 64 + m * 16 + fr) * 2 + bj) * 4 + wc] = s; }
;     asm volatile("s_waitcnt lgkmcnt(0)" ::: "memory"); __builtin_amdgcn_s_barrier(); asm volatile("" ::: "memory");
	v_add_f32_e32 v130, v130, v131
	v_mov_b32_e32 v131, v130
	s_nop 1
	v_permlane32_swap_b32_e32 v130, v131
	s_and_saveexec_b64 s[12:13], vcc
	v_add_f32_e32 v130, v130, v131
	ds_write_b32 v129, v130 offset:4112
	s_or_b64 exec, exec, s[12:13]
	v_mov_b32_e32 v130, v151
	v_pk_mul_f32 v[132:133], v[46:47], v[130:131] op_sel_hi:[1,0]
	v_pk_mul_f32 v[134:135], v[44:45], v[130:131] op_sel_hi:[1,0]
	v_mul_f32_e32 v133, v133, v133
	v_mul_f32_e32 v131, v135, v135
	v_fmac_f32_e32 v131, v134, v134
	v_fmac_f32_e32 v133, v132, v132
	v_add_f32_e32 v134, v131, v133
	v_pk_mul_f32 v[132:133], v[42:43], v[130:131] op_sel_hi:[1,0]
	v_pk_mul_f32 v[130:131], v[40:41], v[130:131] op_sel_hi:[1,0]
	s_nop 0
	v_mul_f32_e32 v131, v131, v131
	v_fmac_f32_e32 v131, v130, v130
	v_mul_f32_e32 v130, v133, v133
	v_fmac_f32_e32 v130, v132, v132
	v_add_f32_e32 v130, v131, v130
	v_add_f32_e32 v130, v134, v130
	s_nop 1
	v_mov_b32_e32 v131, v130
	v_mov_b32_e32 v253, v130
	s_nop 1
	v_permlane16_swap_b32_e32 v131, v253
	s_mov_b32 s98, 0xffff
	s_mov_b32 s99, 0xffff
	v_cndmask_b32_e64 v131, v131, v253, s[98:99]
	s_waitcnt lgkmcnt(0)
	v_add_f32_e32 v130, v130, v131
	v_mov_b32_e32 v131, v130
	s_nop 1
	v_permlane32_swap_b32_e32 v130, v131
	s_and_saveexec_b64 s[12:13], vcc
	v_add_f32_e32 v130, v130, v131
	ds_write_b32 v129, v130 offset:4608
	s_or_b64 exec, exec, s[12:13]
	v_mov_b32_e32 v130, v151
	v_mov_b32_e32 v131, v151
	v_mov_b32_e32 v132, v151
	v_mov_b32_e32 v133, v151
	v_pk_mul_f32 v[166:167], v[36:37], v[130:131]
	v_pk_mul_f32 v[130:131], v[32:33], v[130:131]
	v_pk_mul_f32 v[134:135], v[38:39], v[132:133]
	v_pk_mul_f32 v[132:133], v[34:35], v[132:133]
	v_mul_f32_e32 v131, v131, v131
	v_mul_f32_e32 v157, v167, v167
	v_mul_f32_e32 v135, v135, v135
	v_fmac_f32_e32 v131, v130, v130
	v_mul_f32_e32 v130, v133, v133
	v_fmac_f32_e32 v157, v166, v166
	v_fmac_f32_e32 v135, v134, v134
	v_fmac_f32_e32 v130, v132, v132
	v_add_f32_e32 v134, v157, v135
	v_add_f32_e32 v130, v131, v130
	v_add_f32_e32 v130, v134, v130
	s_nop 1
	v_mov_b32_e32 v131, v130
	v_mov_b32_e32 v253, v130
	s_nop 1
	v_permlane16_swap_b32_e32 v131, v253
	s_mov_b32 s98, 0xffff
	s_mov_b32 s99, 0xffff
	v_cndmask_b32_e64 v131, v131, v253, s[98:99]
	s_waitcnt lgkmcnt(0)
	v_add_f32_e32 v130, v130, v131
	v_mov_b32_e32 v131, v130
	s_nop 1
	v_permlane32_swap_b32_e32 v130, v131
	s_and_saveexec_b64 s[12:13], vcc
	v_add_f32_e32 v130, v130, v131
	ds_write_b32 v129, v130 offset:4624
	s_or_b64 exec, exec, s[12:13]
	v_pk_mul_f32 v[130:131], v[30:31], v[148:149] op_sel_hi:[1,0]
	v_pk_mul_f32 v[132:133], v[28:29], v[148:149] op_sel_hi:[1,0]
	v_mul_f32_e32 v131, v131, v131
	v_mul_f32_e32 v133, v133, v133
	v_fmac_f32_e32 v133, v132, v132
	v_fmac_f32_e32 v131, v130, v130
	v_add_f32_e32 v134, v133, v131
	v_pk_mul_f32 v[130:131], v[26:27], v[148:149] op_sel_hi:[1,0]
	v_pk_mul_f32 v[132:133], v[24:25], v[148:149] op_sel_hi:[1,0]
	v_mul_f32_e32 v131, v131, v131
	v_mul_f32_e32 v133, v133, v133
	v_fmac_f32_e32 v133, v132, v132
	v_fmac_f32_e32 v131, v130, v130
	v_add_f32_e32 v130, v133, v131
	v_add_f32_e32 v130, v134, v130
	s_nop 1
	v_mov_b32_e32 v131, v130
	v_mov_b32_e32 v253, v130
	s_nop 1
	v_permlane16_swap_b32_e32 v131, v253
	s_mov_b32 s98, 0xffff
	s_mov_b32 s99, 0xffff
	v_cndmask_b32_e64 v131, v131, v253, s[98:99]
	s_waitcnt lgkmcnt(0)
	v_add_f32_e32 v130, v130, v131
	v_mov_b32_e32 v131, v130
	s_nop 1
	v_permlane32_swap_b32_e32 v130, v131
	s_and_saveexec_b64 s[12:13], vcc
	v_add_f32_e32 v130, v130, v131
	ds_write_b32 v129, v130 offset:5120
	s_or_b64 exec, exec, s[12:13]
	v_mov_b32_e32 v130, v148
	v_mov_b32_e32 v131, v148
	v_mov_b32_e32 v132, v148
	v_mov_b32_e32 v133, v148
	v_pk_mul_f32 v[166:167], v[20:21], v[130:131]
	v_pk_mul_f32 v[130:131], v[16:17], v[130:131]
	v_pk_mul_f32 v[134:135], v[22:23], v[132:133]
	v_pk_mul_f32 v[132:133], v[18:19], v[132:133]
	v_mul_f32_e32 v131, v131, v131
	v_mul_f32_e32 v157, v167, v167
	v_mul_f32_e32 v135, v135, v135
	v_fmac_f32_e32 v131, v130, v130
	v_mul_f32_e32 v130, v133, v133
	v_fmac_f32_e32 v157, v166, v166
	v_fmac_f32_e32 v135, v134, v134
	v_fmac_f32_e32 v130, v132, v132
	v_add_f32_e32 v134, v157, v135
	v_add_f32_e32 v130, v131, v130
	v_add_f32_e32 v130, v134, v130
	s_nop 1
	v_mov_b32_e32 v131, v130
	v_mov_b32_e32 v253, v130
	s_nop 1
	v_permlane16_swap_b32_e32 v131, v253
	s_mov_b32 s98, 0xffff
	s_mov_b32 s99, 0xffff
	v_cndmask_b32_e64 v131, v131, v253, s[98:99]
	s_waitcnt lgkmcnt(0)
	v_add_f32_e32 v130, v130, v131
	v_mov_b32_e32 v131, v130
	s_nop 1
	v_permlane32_swap_b32_e32 v130, v131
	s_and_saveexec_b64 s[12:13], vcc
	v_add_f32_e32 v130, v130, v131
	ds_write_b32 v129, v130 offset:5136
	s_or_b64 exec, exec, s[12:13]
	v_mov_b32_e32 v130, v149
	v_pk_mul_f32 v[132:133], v[14:15], v[130:131] op_sel_hi:[1,0]
	v_pk_mul_f32 v[134:135], v[12:13], v[130:131] op_sel_hi:[1,0]
	v_mul_f32_e32 v133, v133, v133
	v_mul_f32_e32 v131, v135, v135
	v_fmac_f32_e32 v131, v134, v134
	v_fmac_f32_e32 v133, v132, v132
	v_add_f32_e32 v134, v131, v133
	v_pk_mul_f32 v[132:133], v[10:11], v[130:131] op_sel_hi:[1,0]
	v_pk_mul_f32 v[130:131], v[8:9], v[130:131] op_sel_hi:[1,0]
	s_nop 0
	v_mul_f32_e32 v131, v131, v131
	v_fmac_f32_e32 v131, v130, v130
	v_mul_f32_e32 v130, v133, v133
	v_fmac_f32_e32 v130, v132, v132
	v_add_f32_e32 v130, v131, v130
	v_add_f32_e32 v130, v134, v130
	s_nop 1
	v_mov_b32_e32 v131, v130
	v_mov_b32_e32 v253, v130
	s_nop 1
	v_permlane16_swap_b32_e32 v131, v253
	s_mov_b32 s98, 0xffff
	s_mov_b32 s99, 0xffff
	v_cndmask_b32_e64 v131, v131, v253, s[98:99]
	s_waitcnt lgkmcnt(0)
	v_add_f32_e32 v130, v130, v131
	v_mov_b32_e32 v131, v130
	s_nop 1
	v_permlane32_swap_b32_e32 v130, v131
	s_and_saveexec_b64 s[12:13], vcc
	v_add_f32_e32 v130, v130, v131
	ds_write_b32 v129, v130 offset:5632
	s_or_b64 exec, exec, s[12:13]
	v_mov_b32_e32 v130, v149
	v_mov_b32_e32 v131, v149
	v_mov_b32_e32 v132, v149
	v_mov_b32_e32 v133, v149
	v_pk_mul_f32 v[166:167], v[4:5], v[130:131]
	v_pk_mul_f32 v[130:131], v[0:1], v[130:131]
	v_pk_mul_f32 v[134:135], v[6:7], v[132:133]
	v_pk_mul_f32 v[132:133], v[2:3], v[132:133]
	v_mul_f32_e32 v131, v131, v131
	v_mul_f32_e32 v157, v167, v167
	v_mul_f32_e32 v135, v135, v135
	v_fmac_f32_e32 v131, v130, v130
	v_mul_f32_e32 v130, v133, v133
	v_fmac_f32_e32 v157, v166, v166
	v_fmac_f32_e32 v135, v134, v134
	v_fmac_f32_e32 v130, v132, v132
	v_add_f32_e32 v134, v157, v135
	v_add_f32_e32 v130, v131, v130
	v_add_f32_e32 v130, v134, v130
	s_nop 1
	v_mov_b32_e32 v131, v130
	v_mov_b32_e32 v253, v130
	s_nop 1
	v_permlane16_swap_b32_e32 v131, v253
	s_mov_b32 s98, 0xffff
	s_mov_b32 s99, 0xffff
	v_cndmask_b32_e64 v131, v131, v253, s[98:99]
	s_waitcnt lgkmcnt(0)
	v_add_f32_e32 v130, v130, v131
	v_mov_b32_e32 v131, v130
	s_nop 1
	v_permlane32_swap_b32_e32 v130, v131
	s_and_saveexec_b64 s[12:13], vcc
	v_add_f32_e32 v130, v130, v131
	ds_write_b32 v129, v130 offset:5648
	s_or_b64 exec, exec, s[12:13]
	v_lshlrev_b32_e32 v170, 3, v128
	v_ashrrev_i32_e32 v171, 31, v170
	s_waitcnt lgkmcnt(0)
	s_barrier
; #define PG8_LAS __attribute__((address_space(3)))
; __device__ __forceinline__ u32x4 pack8(const f32x4& a, const f32x4& b) { u32x4 w; w.x = cvt_pk_bf16(a[0], a[1]); w.y = cvt_pk_bf16(a[2], a[3]); w.z = cvt_pk_bf16(b[0], b[1]); w.w = cvt_pk_bf16(b[2], b[3]); return w; }
; template <bool ROWSCALE>
; __device__ __forceinline__ void head_norm_store(const f32x4 (&acc)[2][2][4][2], const float (&rs)[2][4], const float* gain, bf16_t* d0, bf16_t* d1, PG8_LAS float* red, int wr, int wc, int fr, int fq) {
;     ...
;     const f32x4 g0 = *(const f32x4*)(gain + wc * 32 + fq * 8), g1 = *(const f32x4*)(gain + wc * 32 + fq * 8 + 4);
; #pragma unroll
;     for (int ai = 0; ai < 2; ++ai)
; #pragma unroll
;         for (int m = 0; m < 4; ++m) { const int rl = ai * HALF + wr * 64 + m * 16 + fr;
; #pragma unroll
;             for (int bj = 0; bj < 2; ++bj) { const PG8_LAS float* rp = red + (rl * 2 + bj) * 4;
;                 const float ss = (rp[0] + rp[1]) + (rp[2] + rp[3]);
;                 float sc = __builtin_amdgcn_rsqf(ss * (1.0f / 128.0f) + RMS_EPS); if (ROWSCALE) sc *= rs[ai][m];
;                 const f32x4 v0 = acc[ai][bj][m][0] * sc * g0, v1 = acc[ai][bj][m][1] * sc * g1;
;                 *(u32x4*)((bj ? d1 : d0) + (size_t)rl * 128 + wc * 32 + fq * 8) = pack8(v0, v1); } }
;     __device__ __forceinline__ void operator()(const f32x4 (&acc)[2][2][4][2], const Unit& u, int wr, int wc, int fr, int fq) const {
;     ...
;         bf16_t* d0 = CQ + ((size_t)(b * 4 + h0) * 2048 + s0) * 128; bf16_t* d1 = d0 + (size_t)2048 * 128;
	v_lshl_add_u64 v[128:129], v[170:171], 2, s[28:29]
	global_load_dwordx4 v[132:135], v[128:129], off
	s_nop 0
	global_load_dwordx4 v[128:131], v[128:129], off offset:16
	s_ashr_i32 s12, s60, 1
	s_lshl_b32 s13, s64, 1
	s_and_b32 s12, s12, -4
	s_add_i32 s12, s12, s13
	s_ashr_i32 s13, s12, 31
	s_lshl_b64 s[12:13], s[12:13], 19
	s_add_u32 s12, s42, s12
	s_addc_u32 s13, s43, s13
	s_lshl_b32 s16, s60, 16
	s_and_b32 s16, s16, 0x70000
	s_add_u32 s16, s12, s16
	s_addc_u32 s17, s13, 0
	s_add_u32 s12, s16, 0x80000
	v_add_u32_e32 v156, s21, v156
	s_addc_u32 s13, s17, 0
	s_add_i32 s18, 0, 0x20000
	v_lshl_add_u32 v165, v156, 5, s18
	ds_read_b128 v[166:169], v165
	s_andn2_b64 vcc, exec, s[30:31]
	s_waitcnt lgkmcnt(0)
	v_mov_b32_e32 v172, v167
	v_mov_b32_e32 v173, v168
	v_mov_b32_e32 v167, v169
	v_pk_add_f32 v[166:167], v[172:173], v[166:167]
	v_add_u32_e32 v172, 16, v156
	v_add_f32_e32 v157, v166, v167
	v_fmamk_f32 v157, v157, 0x3c000000, v164
	v_rsq_f32_e32 v166, v157
	v_ashrrev_i32_e32 v157, 31, v156
	v_ashrrev_i32_e32 v173, 31, v172
	v_mul_f32_e32 v166, v154, v166
	v_pk_mul_f32 v[124:125], v[124:125], v[166:167] op_sel_hi:[1,0]
	v_pk_mul_f32 v[122:123], v[122:123], v[166:167] op_sel_hi:[1,0]
	v_pk_mul_f32 v[126:127], v[126:127], v[166:167] op_sel_hi:[1,0]
	v_pk_mul_f32 v[120:121], v[120:121], v[166:167] op_sel_hi:[1,0]
	s_waitcnt vmcnt(0)
	v_pk_mul_f32 v[124:125], v[132:133], v[124:125]
	v_pk_mul_f32 v[166:167], v[130:131], v[122:123]
	v_pk_mul_f32 v[126:127], v[134:135], v[126:127]
	v_pk_mul_f32 v[120:121], v[128:129], v[120:121]
	v_cvt_pk_bf16_f32 v122, v124, v125
	v_cvt_pk_bf16_f32 v123, v126, v127
	v_lshlrev_b64 v[126:127], 8, v[156:157]
	v_cvt_pk_bf16_f32 v124, v120, v121
	v_cvt_pk_bf16_f32 v125, v166, v167
	ds_read_b128 v[166:169], v165 offset:16
	v_lshlrev_b64 v[120:121], 1, v[170:171]
	v_lshl_add_u64 v[170:171], s[16:17], 0, v[126:127]
	v_lshl_add_u64 v[170:171], v[170:171], 0, s[0:1]
	v_lshl_add_u32 v165, v172, 5, s18
	s_waitcnt lgkmcnt(0)
	v_mov_b32_e32 v174, v167
	v_mov_b32_e32 v175, v168
	v_mov_b32_e32 v167, v169
	v_pk_add_f32 v[166:167], v[174:175], v[166:167]
	s_nop 0
	v_add_f32_e32 v157, v166, v167
	v_fmamk_f32 v157, v157, 0x3c000000, v164
	v_rsq_f32_e32 v157, v157
	v_lshl_add_u64 v[166:167], v[170:171], 0, v[120:121]
	global_store_dwordx4 v[166:167], v[122:125], off
	s_nop 1
	v_mul_f32_e32 v122, v154, v157
	v_pk_mul_f32 v[116:117], v[116:117], v[122:123] op_sel_hi:[1,0]
	v_pk_mul_f32 v[118:119], v[118:119], v[122:123] op_sel_hi:[1,0]
	v_pk_mul_f32 v[112:113], v[112:113], v[122:123] op_sel_hi:[1,0]
	v_pk_mul_f32 v[114:115], v[114:115], v[122:123] op_sel_hi:[1,0]
	v_pk_mul_f32 v[118:119], v[134:135], v[118:119]
	v_pk_mul_f32 v[116:117], v[132:133], v[116:117]
	v_pk_mul_f32 v[122:123], v[130:131], v[114:115]
	v_pk_mul_f32 v[114:115], v[128:129], v[112:113]
	v_cvt_pk_bf16_f32 v112, v116, v117
	v_cvt_pk_bf16_f32 v113, v118, v119
	v_lshl_add_u64 v[124:125], s[12:13], 0, v[126:127]
	v_cvt_pk_bf16_f32 v114, v114, v115
	v_cvt_pk_bf16_f32 v115, v122, v123
	ds_read_b128 v[116:119], v165
	v_add_u32_e32 v122, 32, v156
	v_ashrrev_i32_e32 v123, 31, v122
	s_waitcnt lgkmcnt(0)
	v_mov_b32_e32 v126, v117
	v_mov_b32_e32 v127, v118
	v_mov_b32_e32 v117, v119
	v_pk_add_f32 v[116:117], v[126:127], v[116:117]
	s_nop 0
	v_add_f32_e32 v116, v116, v117
	v_fmamk_f32 v116, v116, 0x3c000000, v164
	v_rsq_f32_e32 v118, v116
	v_lshl_add_u64 v[116:117], v[124:125], 0, s[0:1]
	v_lshl_add_u64 v[116:117], v[116:117], 0, v[120:121]
	global_store_dwordx4 v[116:117], v[112:115], off
	s_nop 1
	v_mul_f32_e32 v112, v155, v118
	v_pk_mul_f32 v[108:109], v[108:109], v[112:113] op_sel_hi:[1,0]
	v_pk_mul_f32 v[110:111], v[110:111], v[112:113] op_sel_hi:[1,0]
	v_pk_mul_f32 v[104:105], v[104:105], v[112:113] op_sel_hi:[1,0]
	v_pk_mul_f32 v[106:107], v[106:107], v[112:113] op_sel_hi:[1,0]
	v_pk_mul_f32 v[110:111], v[134:135], v[110:111]
	v_pk_mul_f32 v[108:109], v[132:133], v[108:109]
	v_pk_mul_f32 v[112:113], v[130:131], v[106:107]
	v_pk_mul_f32 v[106:107], v[128:129], v[104:105]
	v_cvt_pk_bf16_f32 v104, v108, v109
	v_cvt_pk_bf16_f32 v105, v110, v111
	s_nop 0
	v_cvt_pk_bf16_f32 v106, v106, v107
	v_cvt_pk_bf16_f32 v107, v112, v113
	ds_read_b128 v[108:111], v165 offset:16
	v_lshlrev_b64 v[112:113], 8, v[172:173]
	v_lshl_add_u64 v[114:115], s[16:17], 0, v[112:113]
	v_lshl_add_u64 v[114:115], v[114:115], 0, s[0:1]
	s_waitcnt lgkmcnt(0)
	v_mov_b32_e32 v116, v109
	v_mov_b32_e32 v117, v110
	v_mov_b32_e32 v109, v111
	v_pk_add_f32 v[108:109], v[116:117], v[108:109]
	v_lshl_add_u32 v111, v122, 5, s18
	v_add_f32_e32 v108, v108, v109
	v_fmamk_f32 v108, v108, 0x3c000000, v164
	v_rsq_f32_e32 v110, v108
	v_lshl_add_u64 v[108:109], v[114:115], 0, v[120:121]
	global_store_dwordx4 v[108:109], v[104:107], off
	s_nop 1
	v_mul_f32_e32 v104, v155, v110
	v_pk_mul_f32 v[100:101], v[100:101], v[104:105] op_sel_hi:[1,0]
	v_pk_mul_f32 v[102:103], v[102:103], v[104:105] op_sel_hi:[1,0]
	v_pk_mul_f32 v[96:97], v[96:97], v[104:105] op_sel_hi:[1,0]
	v_pk_mul_f32 v[98:99], v[98:99], v[104:105] op_sel_hi:[1,0]
	v_pk_mul_f32 v[102:103], v[134:135], v[102:103]
	v_pk_mul_f32 v[100:101], v[132:133], v[100:101]
	v_pk_mul_f32 v[104:105], v[130:131], v[98:99]
	v_pk_mul_f32 v[98:99], v[128:129], v[96:97]
	v_cvt_pk_bf16_f32 v96, v100, v101
	v_cvt_pk_bf16_f32 v97, v102, v103
	s_nop 0
	v_cvt_pk_bf16_f32 v98, v98, v99
	v_cvt_pk_bf16_f32 v99, v104, v105
	ds_read_b128 v[100:103], v111
	v_lshl_add_u64 v[104:105], s[12:13], 0, v[112:113]
	s_waitcnt lgkmcnt(0)
; #define PG8_LAS __attribute__((address_space(3)))
; __device__ __forceinline__ u32x4 pack8(const f32x4& a, const f32x4& b) { u32x4 w; w.x = cvt_pk_bf16(a[0], a[1]); w.y = cvt_pk_bf16(a[2], a[3]); w.z = cvt_pk_bf16(b[0], b[1]); w.w = cvt_pk_bf16(b[2], b[3]); return w; }
; template <bool ROWSCALE>
; __device__ __forceinline__ void head_norm_store(const f32x4 (&acc)[2][2][4][2], const float (&rs)[2][4], const float* gain, bf16_t* d0, bf16_t* d1, PG8_LAS float* red, int wr, int wc, int fr, int fq) {
;     ...
;         for (int m = 0; m < 4; ++m) { const int rl = ai * HALF + wr * 64 + m * 16 + fr;
; #pragma unroll
;             for (int bj = 0; bj < 2; ++bj) { const PG8_LAS float* rp = red + (rl * 2 + bj) * 4;
;                 const float ss = (rp[0] + rp[1]) + (rp[2] + rp[3]);
;                 float sc = __builtin_amdgcn_rsqf(ss * (1.0f / 128.0f) + RMS_EPS); if (ROWSCALE) sc *= rs[ai][m];
;                 const f32x4 v0 = acc[ai][bj][m][0] * sc * g0, v1 = acc[ai][bj][m][1] * sc * g1;
;                 *(u32x4*)((bj ? d1 : d0) + (size_t)rl * 128 + wc * 32 + fq * 8) = pack8(v0, v1); } }
	v_mov_b32_e32 v106, v101
	v_mov_b32_e32 v107, v102
	v_mov_b32_e32 v101, v103
	v_pk_add_f32 v[100:101], v[106:107], v[100:101]
	s_nop 0
	v_add_f32_e32 v100, v100, v101
	v_fmamk_f32 v100, v100, 0x3c000000, v164
	v_rsq_f32_e32 v102, v100
	v_lshl_add_u64 v[100:101], v[104:105], 0, s[0:1]
	v_lshl_add_u64 v[100:101], v[100:101], 0, v[120:121]
	global_store_dwordx4 v[100:101], v[96:99], off
	s_nop 1
	v_mul_f32_e32 v96, v152, v102
	v_pk_mul_f32 v[92:93], v[92:93], v[96:97] op_sel_hi:[1,0]
	v_pk_mul_f32 v[94:95], v[94:95], v[96:97] op_sel_hi:[1,0]
	v_pk_mul_f32 v[88:89], v[88:89], v[96:97] op_sel_hi:[1,0]
	v_pk_mul_f32 v[90:91], v[90:91], v[96:97] op_sel_hi:[1,0]
	v_pk_mul_f32 v[94:95], v[134:135], v[94:95]
	v_pk_mul_f32 v[92:93], v[132:133], v[92:93]
	v_pk_mul_f32 v[96:97], v[130:131], v[90:91]
	v_pk_mul_f32 v[90:91], v[128:129], v[88:89]
	v_cvt_pk_bf16_f32 v88, v92, v93
	v_cvt_pk_bf16_f32 v89, v94, v95
	s_nop 0
	v_cvt_pk_bf16_f32 v90, v90, v91
	v_cvt_pk_bf16_f32 v91, v96, v97
	ds_read_b128 v[92:95], v111 offset:16
	v_lshlrev_b64 v[96:97], 8, v[122:123]
	v_lshl_add_u64 v[98:99], s[16:17], 0, v[96:97]
	s_waitcnt lgkmcnt(0)
	v_mov_b32_e32 v100, v93
	v_mov_b32_e32 v101, v94
	v_mov_b32_e32 v93, v95
	v_pk_add_f32 v[92:93], v[100:101], v[92:93]
	s_nop 0
	v_add_f32_e32 v92, v92, v93
	v_fmamk_f32 v92, v92, 0x3c000000, v164
	v_rsq_f32_e32 v94, v92
	v_lshl_add_u64 v[92:93], v[98:99], 0, s[0:1]
	v_lshl_add_u64 v[92:93], v[92:93], 0, v[120:121]
	global_store_dwordx4 v[92:93], v[88:91], off
	s_nop 1
	v_mul_f32_e32 v88, v152, v94
	v_pk_mul_f32 v[80:81], v[80:81], v[88:89] op_sel_hi:[1,0]
	v_pk_mul_f32 v[82:83], v[82:83], v[88:89] op_sel_hi:[1,0]
	v_pk_mul_f32 v[84:85], v[84:85], v[88:89] op_sel_hi:[1,0]
	v_pk_mul_f32 v[86:87], v[86:87], v[88:89] op_sel_hi:[1,0]
	v_pk_mul_f32 v[88:89], v[130:131], v[82:83]
	v_pk_mul_f32 v[82:83], v[128:129], v[80:81]
	v_pk_mul_f32 v[86:87], v[134:135], v[86:87]
	v_pk_mul_f32 v[84:85], v[132:133], v[84:85]
	v_lshl_add_u64 v[90:91], s[12:13], 0, v[96:97]
	v_cvt_pk_bf16_f32 v80, v84, v85
	v_cvt_pk_bf16_f32 v81, v86, v87
	v_cvt_pk_bf16_f32 v82, v82, v83
	v_cvt_pk_bf16_f32 v83, v88, v89
	v_add_u32_e32 v88, 48, v156
	v_lshl_add_u32 v89, v88, 5, s18
	ds_read_b128 v[84:87], v89
	s_waitcnt lgkmcnt(0)
	v_mov_b32_e32 v92, v85
	v_mov_b32_e32 v93, v86
	v_mov_b32_e32 v85, v87
	v_pk_add_f32 v[84:85], v[92:93], v[84:85]
	s_nop 0
	v_add_f32_e32 v84, v84, v85
	v_fmamk_f32 v84, v84, 0x3c000000, v164
	v_rsq_f32_e32 v86, v84
	v_lshl_add_u64 v[84:85], v[90:91], 0, s[0:1]
	v_lshl_add_u64 v[84:85], v[84:85], 0, v[120:121]
	global_store_dwordx4 v[84:85], v[80:83], off
	s_nop 1
	v_mul_f32_e32 v80, v153, v86
	v_pk_mul_f32 v[76:77], v[76:77], v[80:81] op_sel_hi:[1,0]
	v_pk_mul_f32 v[78:79], v[78:79], v[80:81] op_sel_hi:[1,0]
	v_pk_mul_f32 v[72:73], v[72:73], v[80:81] op_sel_hi:[1,0]
	v_pk_mul_f32 v[74:75], v[74:75], v[80:81] op_sel_hi:[1,0]
	v_pk_mul_f32 v[78:79], v[134:135], v[78:79]
	v_pk_mul_f32 v[76:77], v[132:133], v[76:77]
	v_pk_mul_f32 v[80:81], v[130:131], v[74:75]
	v_pk_mul_f32 v[74:75], v[128:129], v[72:73]
	v_cvt_pk_bf16_f32 v72, v76, v77
	v_cvt_pk_bf16_f32 v73, v78, v79
	s_nop 0
	v_cvt_pk_bf16_f32 v74, v74, v75
	v_cvt_pk_bf16_f32 v75, v80, v81
	ds_read_b128 v[76:79], v89 offset:16
	v_ashrrev_i32_e32 v89, 31, v88
	v_lshlrev_b64 v[80:81], 8, v[88:89]
	v_lshl_add_u64 v[82:83], s[16:17], 0, v[80:81]
	s_waitcnt lgkmcnt(0)
	v_mov_b32_e32 v84, v77
	v_mov_b32_e32 v85, v78
	v_mov_b32_e32 v77, v79
	v_pk_add_f32 v[76:77], v[84:85], v[76:77]
	s_nop 0
	v_add_f32_e32 v76, v76, v77
	v_fmamk_f32 v76, v76, 0x3c000000, v164
	v_rsq_f32_e32 v78, v76
	v_lshl_add_u64 v[76:77], v[82:83], 0, s[0:1]
	v_lshl_add_u64 v[76:77], v[76:77], 0, v[120:121]
	global_store_dwordx4 v[76:77], v[72:75], off
	s_nop 1
	v_mul_f32_e32 v72, v153, v78
	v_pk_mul_f32 v[64:65], v[64:65], v[72:73] op_sel_hi:[1,0]
	v_pk_mul_f32 v[66:67], v[66:67], v[72:73] op_sel_hi:[1,0]
	v_pk_mul_f32 v[68:69], v[68:69], v[72:73] op_sel_hi:[1,0]
	v_pk_mul_f32 v[70:71], v[70:71], v[72:73] op_sel_hi:[1,0]
	v_pk_mul_f32 v[72:73], v[130:131], v[66:67]
	v_pk_mul_f32 v[66:67], v[128:129], v[64:65]
	v_pk_mul_f32 v[70:71], v[134:135], v[70:71]
	v_pk_mul_f32 v[68:69], v[132:133], v[68:69]
	v_lshl_add_u64 v[74:75], s[12:13], 0, v[80:81]
	v_cvt_pk_bf16_f32 v64, v68, v69
	v_cvt_pk_bf16_f32 v65, v70, v71
	v_cvt_pk_bf16_f32 v66, v66, v67
	v_cvt_pk_bf16_f32 v67, v72, v73
	v_add_u32_e32 v72, 0x80, v156
	v_lshl_add_u32 v73, v72, 5, s18
	ds_read_b128 v[68:71], v73
	s_waitcnt lgkmcnt(0)
	v_mov_b32_e32 v76, v69
	v_mov_b32_e32 v77, v70
	v_mov_b32_e32 v69, v71
	v_pk_add_f32 v[68:69], v[76:77], v[68:69]
	s_nop 0
	v_add_f32_e32 v68, v68, v69
	v_fmamk_f32 v68, v68, 0x3c000000, v164
	v_rsq_f32_e32 v70, v68
	v_lshl_add_u64 v[68:69], v[74:75], 0, s[0:1]
	v_lshl_add_u64 v[68:69], v[68:69], 0, v[120:121]
	global_store_dwordx4 v[68:69], v[64:67], off
	s_nop 1
	v_mul_f32_e32 v64, v150, v70
	v_pk_mul_f32 v[60:61], v[60:61], v[64:65] op_sel_hi:[1,0]
	v_pk_mul_f32 v[62:63], v[62:63], v[64:65] op_sel_hi:[1,0]
	v_pk_mul_f32 v[56:57], v[56:57], v[64:65] op_sel_hi:[1,0]
	v_pk_mul_f32 v[58:59], v[58:59], v[64:65] op_sel_hi:[1,0]
	v_pk_mul_f32 v[62:63], v[134:135], v[62:63]
	v_pk_mul_f32 v[60:61], v[132:133], v[60:61]
	v_pk_mul_f32 v[64:65], v[130:131], v[58:59]
	v_pk_mul_f32 v[58:59], v[128:129], v[56:57]
	v_cvt_pk_bf16_f32 v56, v60, v61
	v_cvt_pk_bf16_f32 v57, v62, v63
	s_nop 0
	v_cvt_pk_bf16_f32 v58, v58, v59
	v_cvt_pk_bf16_f32 v59, v64, v65
	ds_read_b128 v[60:63], v73 offset:16
	v_ashrrev_i32_e32 v73, 31, v72
	v_lshlrev_b64 v[64:65], 8, v[72:73]
	v_lshl_add_u64 v[66:67], s[16:17], 0, v[64:65]
	s_waitcnt lgkmcnt(0)
; #define PG8_LAS __attribute__((address_space(3)))
; __device__ __forceinline__ u32x4 pack8(const f32x4& a, const f32x4& b) { u32x4 w; w.x = cvt_pk_bf16(a[0], a[1]); w.y = cvt_pk_bf16(a[2], a[3]); w.z = cvt_pk_bf16(b[0], b[1]); w.w = cvt_pk_bf16(b[2], b[3]); return w; }
; template <bool ROWSCALE>
; __device__ __forceinline__ void head_norm_store(const f32x4 (&acc)[2][2][4][2], const float (&rs)[2][4], const float* gain, bf16_t* d0, bf16_t* d1, PG8_LAS float* red, int wr, int wc, int fr, int fq) {
;     ...
;         for (int m = 0; m < 4; ++m) { const int rl = ai * HALF + wr * 64 + m * 16 + fr;
; #pragma unroll
;             for (int bj = 0; bj < 2; ++bj) { const PG8_LAS float* rp = red + (rl * 2 + bj) * 4;
;                 const float ss = (rp[0] + rp[1]) + (rp[2] + rp[3]);
;                 float sc = __builtin_amdgcn_rsqf(ss * (1.0f / 128.0f) + RMS_EPS); if (ROWSCALE) sc *= rs[ai][m];
;                 const f32x4 v0 = acc[ai][bj][m][0] * sc * g0, v1 = acc[ai][bj][m][1] * sc * g1;
;                 *(u32x4*)((bj ? d1 : d0) + (size_t)rl * 128 + wc * 32 + fq * 8) = pack8(v0, v1); } }
	v_mov_b32_e32 v68, v61
	v_mov_b32_e32 v69, v62
	v_mov_b32_e32 v61, v63
	v_pk_add_f32 v[60:61], v[68:69], v[60:61]
	s_nop 0
	v_add_f32_e32 v60, v60, v61
	v_fmamk_f32 v60, v60, 0x3c000000, v164
	v_rsq_f32_e32 v62, v60
	v_lshl_add_u64 v[60:61], v[66:67], 0, s[0:1]
	v_lshl_add_u64 v[60:61], v[60:61], 0, v[120:121]
	global_store_dwordx4 v[60:61], v[56:59], off
	s_nop 1
	v_mul_f32_e32 v56, v150, v62
	v_pk_mul_f32 v[48:49], v[48:49], v[56:57] op_sel_hi:[1,0]
	v_pk_mul_f32 v[50:51], v[50:51], v[56:57] op_sel_hi:[1,0]
	v_pk_mul_f32 v[52:53], v[52:53], v[56:57] op_sel_hi:[1,0]
	v_pk_mul_f32 v[54:55], v[54:55], v[56:57] op_sel_hi:[1,0]
	v_pk_mul_f32 v[56:57], v[130:131], v[50:51]
	v_pk_mul_f32 v[50:51], v[128:129], v[48:49]
	v_pk_mul_f32 v[54:55], v[134:135], v[54:55]
	v_pk_mul_f32 v[52:53], v[132:133], v[52:53]
	v_lshl_add_u64 v[58:59], s[12:13], 0, v[64:65]
	v_cvt_pk_bf16_f32 v48, v52, v53
	v_cvt_pk_bf16_f32 v49, v54, v55
	v_cvt_pk_bf16_f32 v50, v50, v51
	v_cvt_pk_bf16_f32 v51, v56, v57
	v_add_u32_e32 v56, 0x90, v156
	v_lshl_add_u32 v57, v56, 5, s18
	ds_read_b128 v[52:55], v57
	s_waitcnt lgkmcnt(0)
	v_mov_b32_e32 v60, v53
	v_mov_b32_e32 v61, v54
	v_mov_b32_e32 v53, v55
	v_pk_add_f32 v[52:53], v[60:61], v[52:53]
	s_nop 0
	v_add_f32_e32 v52, v52, v53
	v_fmamk_f32 v52, v52, 0x3c000000, v164
	v_rsq_f32_e32 v54, v52
	v_lshl_add_u64 v[52:53], v[58:59], 0, s[0:1]
	v_lshl_add_u64 v[52:53], v[52:53], 0, v[120:121]
	global_store_dwordx4 v[52:53], v[48:51], off
	s_nop 1
	v_mul_f32_e32 v48, v151, v54
	v_pk_mul_f32 v[44:45], v[44:45], v[48:49] op_sel_hi:[1,0]
	v_pk_mul_f32 v[46:47], v[46:47], v[48:49] op_sel_hi:[1,0]
	v_pk_mul_f32 v[40:41], v[40:41], v[48:49] op_sel_hi:[1,0]
	v_pk_mul_f32 v[42:43], v[42:43], v[48:49] op_sel_hi:[1,0]
	v_pk_mul_f32 v[46:47], v[134:135], v[46:47]
	v_pk_mul_f32 v[44:45], v[132:133], v[44:45]
	v_pk_mul_f32 v[48:49], v[130:131], v[42:43]
	v_pk_mul_f32 v[42:43], v[128:129], v[40:41]
	v_cvt_pk_bf16_f32 v40, v44, v45
	v_cvt_pk_bf16_f32 v41, v46, v47
	s_nop 0
	v_cvt_pk_bf16_f32 v42, v42, v43
	v_cvt_pk_bf16_f32 v43, v48, v49
	ds_read_b128 v[44:47], v57 offset:16
	v_ashrrev_i32_e32 v57, 31, v56
	v_lshlrev_b64 v[48:49], 8, v[56:57]
	v_lshl_add_u64 v[50:51], s[16:17], 0, v[48:49]
	s_waitcnt lgkmcnt(0)
	v_mov_b32_e32 v52, v45
	v_mov_b32_e32 v53, v46
	v_mov_b32_e32 v45, v47
	v_pk_add_f32 v[44:45], v[52:53], v[44:45]
	s_nop 0
	v_add_f32_e32 v44, v44, v45
	v_fmamk_f32 v44, v44, 0x3c000000, v164
	v_rsq_f32_e32 v46, v44
	v_lshl_add_u64 v[44:45], v[50:51], 0, s[0:1]
	v_lshl_add_u64 v[44:45], v[44:45], 0, v[120:121]
	global_store_dwordx4 v[44:45], v[40:43], off
	s_nop 1
	v_mul_f32_e32 v40, v151, v46
	v_pk_mul_f32 v[32:33], v[32:33], v[40:41] op_sel_hi:[1,0]
	v_pk_mul_f32 v[34:35], v[34:35], v[40:41] op_sel_hi:[1,0]
	v_pk_mul_f32 v[36:37], v[36:37], v[40:41] op_sel_hi:[1,0]
	v_pk_mul_f32 v[38:39], v[38:39], v[40:41] op_sel_hi:[1,0]
	v_pk_mul_f32 v[40:41], v[130:131], v[34:35]
	v_pk_mul_f32 v[34:35], v[128:129], v[32:33]
	v_pk_mul_f32 v[38:39], v[134:135], v[38:39]
	v_pk_mul_f32 v[36:37], v[132:133], v[36:37]
	v_lshl_add_u64 v[42:43], s[12:13], 0, v[48:49]
	v_cvt_pk_bf16_f32 v32, v36, v37
	v_cvt_pk_bf16_f32 v33, v38, v39
	v_cvt_pk_bf16_f32 v34, v34, v35
	v_cvt_pk_bf16_f32 v35, v40, v41
	v_add_u32_e32 v40, 0xa0, v156
	v_lshl_add_u32 v41, v40, 5, s18
	ds_read_b128 v[36:39], v41
	s_waitcnt lgkmcnt(0)
	v_mov_b32_e32 v44, v37
	v_mov_b32_e32 v45, v38
	v_mov_b32_e32 v37, v39
	v_pk_add_f32 v[36:37], v[44:45], v[36:37]
	s_nop 0
	v_add_f32_e32 v36, v36, v37
	v_fmamk_f32 v36, v36, 0x3c000000, v164
	v_rsq_f32_e32 v38, v36
	v_lshl_add_u64 v[36:37], v[42:43], 0, s[0:1]
	v_lshl_add_u64 v[36:37], v[36:37], 0, v[120:121]
	global_store_dwordx4 v[36:37], v[32:35], off
	s_nop 1
	v_mul_f32_e32 v32, v148, v38
	v_pk_mul_f32 v[28:29], v[28:29], v[32:33] op_sel_hi:[1,0]
	v_pk_mul_f32 v[30:31], v[30:31], v[32:33] op_sel_hi:[1,0]
	v_pk_mul_f32 v[24:25], v[24:25], v[32:33] op_sel_hi:[1,0]
	v_pk_mul_f32 v[26:27], v[26:27], v[32:33] op_sel_hi:[1,0]
	v_pk_mul_f32 v[30:31], v[134:135], v[30:31]
	v_pk_mul_f32 v[28:29], v[132:133], v[28:29]
	v_pk_mul_f32 v[32:33], v[130:131], v[26:27]
	v_pk_mul_f32 v[26:27], v[128:129], v[24:25]
	v_cvt_pk_bf16_f32 v24, v28, v29
	v_cvt_pk_bf16_f32 v25, v30, v31
	s_nop 0
	v_cvt_pk_bf16_f32 v26, v26, v27
	v_cvt_pk_bf16_f32 v27, v32, v33
	ds_read_b128 v[28:31], v41 offset:16
	v_ashrrev_i32_e32 v41, 31, v40
	v_lshlrev_b64 v[32:33], 8, v[40:41]
	v_lshl_add_u64 v[34:35], s[16:17], 0, v[32:33]
	s_waitcnt lgkmcnt(0)
; #define PG8_LAS __attribute__((address_space(3)))
; __device__ __forceinline__ u32x4 pack8(const f32x4& a, const f32x4& b) { u32x4 w; w.x = cvt_pk_bf16(a[0], a[1]); w.y = cvt_pk_bf16(a[2], a[3]); w.z = cvt_pk_bf16(b[0], b[1]); w.w = cvt_pk_bf16(b[2], b[3]); return w; }
; template <bool ROWSCALE>
; __device__ __forceinline__ void head_norm_store(const f32x4 (&acc)[2][2][4][2], const float (&rs)[2][4], const float* gain, bf16_t* d0, bf16_t* d1, PG8_LAS float* red, int wr, int wc, int fr, int fq) {
;     ...
;         for (int m = 0; m < 4; ++m) { const int rl = ai * HALF + wr * 64 + m * 16 + fr;
; #pragma unroll
;             for (int bj = 0; bj < 2; ++bj) { const PG8_LAS float* rp = red + (rl * 2 + bj) * 4;
;                 const float ss = (rp[0] + rp[1]) + (rp[2] + rp[3]);
;                 float sc = __builtin_amdgcn_rsqf(ss * (1.0f / 128.0f) + RMS_EPS); if (ROWSCALE) sc *= rs[ai][m];
;                 const f32x4 v0 = acc[ai][bj][m][0] * sc * g0, v1 = acc[ai][bj][m][1] * sc * g1;
;                 *(u32x4*)((bj ? d1 : d0) + (size_t)rl * 128 + wc * 32 + fq * 8) = pack8(v0, v1); } }
	v_mov_b32_e32 v36, v29
	v_mov_b32_e32 v37, v30
	v_mov_b32_e32 v29, v31
	v_pk_add_f32 v[28:29], v[36:37], v[28:29]
	s_nop 0
	v_add_f32_e32 v28, v28, v29
	v_fmamk_f32 v28, v28, 0x3c000000, v164
	v_rsq_f32_e32 v30, v28
	v_lshl_add_u64 v[28:29], v[34:35], 0, s[0:1]
	v_lshl_add_u64 v[28:29], v[28:29], 0, v[120:121]
	global_store_dwordx4 v[28:29], v[24:27], off
	s_nop 1
	v_mul_f32_e32 v24, v148, v30
	v_pk_mul_f32 v[16:17], v[16:17], v[24:25] op_sel_hi:[1,0]
	v_pk_mul_f32 v[18:19], v[18:19], v[24:25] op_sel_hi:[1,0]
	v_pk_mul_f32 v[20:21], v[20:21], v[24:25] op_sel_hi:[1,0]
	v_pk_mul_f32 v[22:23], v[22:23], v[24:25] op_sel_hi:[1,0]
	v_pk_mul_f32 v[24:25], v[130:131], v[18:19]
	v_pk_mul_f32 v[18:19], v[128:129], v[16:17]
	v_pk_mul_f32 v[22:23], v[134:135], v[22:23]
	v_pk_mul_f32 v[20:21], v[132:133], v[20:21]
	v_lshl_add_u64 v[26:27], s[12:13], 0, v[32:33]
	v_cvt_pk_bf16_f32 v16, v20, v21
	v_cvt_pk_bf16_f32 v17, v22, v23
	v_cvt_pk_bf16_f32 v18, v18, v19
	v_cvt_pk_bf16_f32 v19, v24, v25
	v_add_u32_e32 v24, 0xb0, v156
	v_lshl_add_u32 v25, v24, 5, s18
	ds_read_b128 v[20:23], v25
	s_waitcnt lgkmcnt(0)
	v_mov_b32_e32 v28, v21
	v_mov_b32_e32 v29, v22
	v_mov_b32_e32 v21, v23
	v_pk_add_f32 v[20:21], v[28:29], v[20:21]
	s_nop 0
	v_add_f32_e32 v20, v20, v21
	v_fmamk_f32 v20, v20, 0x3c000000, v164
	v_rsq_f32_e32 v22, v20
	v_lshl_add_u64 v[20:21], v[26:27], 0, s[0:1]
	v_lshl_add_u64 v[20:21], v[20:21], 0, v[120:121]
	global_store_dwordx4 v[20:21], v[16:19], off
	s_nop 1
	v_mul_f32_e32 v16, v149, v22
	v_pk_mul_f32 v[12:13], v[12:13], v[16:17] op_sel_hi:[1,0]
	v_pk_mul_f32 v[14:15], v[14:15], v[16:17] op_sel_hi:[1,0]
	v_pk_mul_f32 v[8:9], v[8:9], v[16:17] op_sel_hi:[1,0]
	v_pk_mul_f32 v[10:11], v[10:11], v[16:17] op_sel_hi:[1,0]
	v_pk_mul_f32 v[14:15], v[134:135], v[14:15]
	v_pk_mul_f32 v[12:13], v[132:133], v[12:13]
	v_pk_mul_f32 v[16:17], v[130:131], v[10:11]
	v_pk_mul_f32 v[10:11], v[128:129], v[8:9]
	v_cvt_pk_bf16_f32 v8, v12, v13
	v_cvt_pk_bf16_f32 v9, v14, v15
	s_nop 0
	v_cvt_pk_bf16_f32 v10, v10, v11
	v_cvt_pk_bf16_f32 v11, v16, v17
	ds_read_b128 v[12:15], v25 offset:16
	v_ashrrev_i32_e32 v25, 31, v24
	v_lshlrev_b64 v[16:17], 8, v[24:25]
	v_lshl_add_u64 v[18:19], s[16:17], 0, v[16:17]
	s_waitcnt lgkmcnt(0)
	v_mov_b32_e32 v20, v13
	v_mov_b32_e32 v21, v14
	v_mov_b32_e32 v13, v15
	v_pk_add_f32 v[12:13], v[20:21], v[12:13]
	s_nop 0
	v_add_f32_e32 v12, v12, v13
	v_fmamk_f32 v12, v12, 0x3c000000, v164
	v_rsq_f32_e32 v14, v12
	v_lshl_add_u64 v[12:13], v[18:19], 0, s[0:1]
	v_lshl_add_u64 v[12:13], v[12:13], 0, v[120:121]
	global_store_dwordx4 v[12:13], v[8:11], off
	s_nop 1
	v_mul_f32_e32 v8, v149, v14
	v_pk_mul_f32 v[4:5], v[4:5], v[8:9] op_sel_hi:[1,0]
	v_pk_mul_f32 v[0:1], v[0:1], v[8:9] op_sel_hi:[1,0]
	v_pk_mul_f32 v[4:5], v[132:133], v[4:5]
	v_pk_mul_f32 v[2:3], v[2:3], v[8:9] op_sel_hi:[1,0]
	v_pk_mul_f32 v[6:7], v[6:7], v[8:9] op_sel_hi:[1,0]
	v_pk_mul_f32 v[8:9], v[130:131], v[2:3]
	v_pk_mul_f32 v[2:3], v[128:129], v[0:1]
	v_cvt_pk_bf16_f32 v0, v4, v5
	v_lshl_add_u64 v[4:5], s[12:13], 0, v[16:17]
	v_lshl_add_u64 v[4:5], v[4:5], 0, s[0:1]
	v_lshl_add_u64 v[4:5], v[4:5], 0, v[120:121]
	s_mov_b64 s[12:13], -1
	v_pk_mul_f32 v[6:7], v[134:135], v[6:7]
	s_nop 0
	v_cvt_pk_bf16_f32 v1, v6, v7
	v_cvt_pk_bf16_f32 v2, v2, v3
	v_cvt_pk_bf16_f32 v3, v8, v9
	global_store_dwordx4 v[4:5], v[0:3], off
	s_cbranch_vccnz .LBB0_1301
	s_andn2_b64 vcc, exec, s[14:15]
	s_cbranch_vccnz .LBB0_1300
	s_barrier
	s_branch .LBB0_1300

; template <int K> __device__ __forceinline__ float shx(float v) { static_assert(K < 32, "use sum32"); return __int_as_float(__builtin_amdgcn_ds_swizzle(__float_as_int(v), (K << 10) | 0x1f)); }
; __device__ __forceinline__ float sum32(float v) { auto rr = __builtin_amdgcn_permlane32_swap(__float_as_uint(v), __float_as_uint(v), false, false); return __uint_as_float(rr[0]) + __uint_as_float(rr[1]); }
; template <bool ROWSCALE>
; __device__ __forceinline__ void head_norm_store(const f32x4 (&acc)[2][2][4][2], const float (&rs)[2][4], const float* gain, bf16_t* d0, bf16_t* d1, PG8_LAS float* red, int wr, int wc, int fr, int fq) {
;     ...
;             for (int bj = 0; bj < 2; ++bj) { float s = 0.f;
; #pragma unroll
;                 for (int n = 0; n < 2; ++n) { f32x4 v = acc[ai][bj][m][n]; if (ROWSCALE) v = v * rs[ai][m]; s += (v[0] * v[0] + v[1] * v[1]) + (v[2] * v[2] + v[3] * v[3]); }
;                 s += shx<16>(s); s = sum32(s);
;                 if (fq == 0) red[((ai * HALF + wr * 64 + m * 16 + fr) * 2 + bj) * 4 + wc] = s; }
;     __device__ __forceinline__ void operator()(const f32x4 (&acc)[2][2][4][2], const Unit& u, int wr, int wc, int fr, int fq) const {
;     ...
;         if (pn < 2) { float rs[2][4]; head_norm_store<false>(acc, rs, g_ck, d0, d1, red, wr, wc, fr, fq); }
.LBB0_1368:
	s_andn2_b64 vcc, exec, s[18:19]
	s_cbranch_vccnz .LBB0_1402
	v_mul_f32_e32 v129, v125, v125
	v_mul_f32_e32 v130, v127, v127
	v_fmac_f32_e32 v129, v124, v124
	v_fmac_f32_e32 v130, v126, v126
	v_add_f32_e32 v129, v129, v130
	v_mul_f32_e32 v130, v121, v121
	v_mul_f32_e32 v131, v123, v123
	v_fmac_f32_e32 v130, v120, v120
	v_fmac_f32_e32 v131, v122, v122
	v_add_f32_e32 v130, v130, v131
	v_add_f32_e32 v129, v129, v130
	s_nop 1
	v_mov_b32_e32 v130, v129
	v_mov_b32_e32 v253, v129
	s_nop 1
	v_permlane16_swap_b32_e32 v130, v253
	s_mov_b32 s98, 0xffff
	s_mov_b32 s99, 0xffff
	v_cndmask_b32_e64 v130, v130, v253, s[98:99]
	v_lshlrev_b32_e32 v128, 5, v134
	v_cmp_eq_u32_e32 vcc, 0, v135
	v_add_u32_e32 v128, s58, v128
	s_waitcnt lgkmcnt(0)
	v_add_f32_e32 v129, v129, v130
	v_mov_b32_e32 v130, v129
	s_nop 1
	v_permlane32_swap_b32_e32 v129, v130
	s_and_saveexec_b64 s[18:19], vcc
	v_add_f32_e32 v129, v129, v130
	ds_write_b32 v128, v129
	s_or_b64 exec, exec, s[18:19]
	v_mul_f32_e32 v129, v117, v117
	v_mul_f32_e32 v130, v119, v119
	v_fmac_f32_e32 v129, v116, v116
	v_fmac_f32_e32 v130, v118, v118
	v_add_f32_e32 v129, v129, v130
	v_mul_f32_e32 v130, v113, v113
	v_mul_f32_e32 v131, v115, v115
	v_fmac_f32_e32 v130, v112, v112
	v_fmac_f32_e32 v131, v114, v114
	v_add_f32_e32 v130, v130, v131
	v_add_f32_e32 v129, v129, v130
	s_nop 1
	v_mov_b32_e32 v130, v129
	v_mov_b32_e32 v253, v129
	s_nop 1
	v_permlane16_swap_b32_e32 v130, v253
	s_mov_b32 s98, 0xffff
	s_mov_b32 s99, 0xffff
	v_cndmask_b32_e64 v130, v130, v253, s[98:99]
	s_waitcnt lgkmcnt(0)
	v_add_f32_e32 v129, v129, v130
	v_mov_b32_e32 v130, v129
	s_nop 1
	v_permlane32_swap_b32_e32 v129, v130
	s_and_saveexec_b64 s[18:19], vcc
	v_add_f32_e32 v129, v129, v130
	ds_write_b32 v128, v129 offset:16
	s_or_b64 exec, exec, s[18:19]
	v_mul_f32_e32 v129, v109, v109
	v_mul_f32_e32 v130, v111, v111
	v_fmac_f32_e32 v129, v108, v108
	v_fmac_f32_e32 v130, v110, v110
	v_add_f32_e32 v129, v129, v130
	v_mul_f32_e32 v130, v105, v105
	v_mul_f32_e32 v131, v107, v107
	v_fmac_f32_e32 v130, v104, v104
	v_fmac_f32_e32 v131, v106, v106
	v_add_f32_e32 v130, v130, v131
	v_add_f32_e32 v129, v129, v130
	s_nop 1
	v_mov_b32_e32 v130, v129
	v_mov_b32_e32 v253, v129
	s_nop 1
	v_permlane16_swap_b32_e32 v130, v253
	s_mov_b32 s98, 0xffff
	s_mov_b32 s99, 0xffff
	v_cndmask_b32_e64 v130, v130, v253, s[98:99]
	s_waitcnt lgkmcnt(0)
	v_add_f32_e32 v129, v129, v130
	v_mov_b32_e32 v130, v129
	s_nop 1
	v_permlane32_swap_b32_e32 v129, v130
	s_and_saveexec_b64 s[18:19], vcc
	v_add_f32_e32 v129, v129, v130
	ds_write_b32 v128, v129 offset:512
	s_or_b64 exec, exec, s[18:19]
	v_mul_f32_e32 v129, v101, v101
	v_mul_f32_e32 v130, v103, v103
	v_fmac_f32_e32 v129, v100, v100
	v_fmac_f32_e32 v130, v102, v102
	v_add_f32_e32 v129, v129, v130
	v_mul_f32_e32 v130, v97, v97
	v_mul_f32_e32 v131, v99, v99
	v_fmac_f32_e32 v130, v96, v96
	v_fmac_f32_e32 v131, v98, v98
	v_add_f32_e32 v130, v130, v131
	v_add_f32_e32 v129, v129, v130
	s_nop 1
	v_mov_b32_e32 v130, v129
	v_mov_b32_e32 v253, v129
	s_nop 1
	v_permlane16_swap_b32_e32 v130, v253
	s_mov_b32 s98, 0xffff
	s_mov_b32 s99, 0xffff
	v_cndmask_b32_e64 v130, v130, v253, s[98:99]
	s_waitcnt lgkmcnt(0)
	v_add_f32_e32 v129, v129, v130
	v_mov_b32_e32 v130, v129
	s_nop 1
	v_permlane32_swap_b32_e32 v129, v130
	s_and_saveexec_b64 s[18:19], vcc
	v_add_f32_e32 v129, v129, v130
	ds_write_b32 v128, v129 offset:528
	s_or_b64 exec, exec, s[18:19]
	v_mul_f32_e32 v129, v93, v93
	v_mul_f32_e32 v130, v95, v95
	v_fmac_f32_e32 v129, v92, v92
	v_fmac_f32_e32 v130, v94, v94
	v_add_f32_e32 v129, v129, v130
	v_mul_f32_e32 v130, v89, v89
	v_mul_f32_e32 v131, v91, v91
	v_fmac_f32_e32 v130, v88, v88
	v_fmac_f32_e32 v131, v90, v90
	v_add_f32_e32 v130, v130, v131
	v_add_f32_e32 v129, v129, v130
	s_nop 1
	v_mov_b32_e32 v130, v129
	v_mov_b32_e32 v253, v129
	s_nop 1
	v_permlane16_swap_b32_e32 v130, v253
	s_mov_b32 s98, 0xffff
	s_mov_b32 s99, 0xffff
	v_cndmask_b32_e64 v130, v130, v253, s[98:99]
	s_waitcnt lgkmcnt(0)
	v_add_f32_e32 v129, v129, v130
	v_mov_b32_e32 v130, v129
	s_nop 1
	v_permlane32_swap_b32_e32 v129, v130
	s_and_saveexec_b64 s[18:19], vcc
	v_add_f32_e32 v129, v129, v130
	ds_write_b32 v128, v129 offset:1024
	s_or_b64 exec, exec, s[18:19]
	v_mul_f32_e32 v129, v85, v85
	v_mul_f32_e32 v130, v87, v87
	v_fmac_f32_e32 v129, v84, v84
	v_fmac_f32_e32 v130, v86, v86
	v_add_f32_e32 v129, v129, v130
	v_mul_f32_e32 v130, v81, v81
	v_mul_f32_e32 v131, v83, v83
	v_fmac_f32_e32 v130, v80, v80
	v_fmac_f32_e32 v131, v82, v82
	v_add_f32_e32 v130, v130, v131
	v_add_f32_e32 v129, v129, v130
	s_nop 1
	v_mov_b32_e32 v130, v129
	v_mov_b32_e32 v253, v129
	s_nop 1
	v_permlane16_swap_b32_e32 v130, v253
	s_mov_b32 s98, 0xffff
	s_mov_b32 s99, 0xffff
	v_cndmask_b32_e64 v130, v130, v253, s[98:99]
	s_waitcnt lgkmcnt(0)
	v_add_f32_e32 v129, v129, v130
	v_mov_b32_e32 v130, v129
	s_nop 1
	v_permlane32_swap_b32_e32 v129, v130
	s_and_saveexec_b64 s[18:19], vcc
	v_add_f32_e32 v129, v129, v130
	ds_write_b32 v128, v129 offset:1040
	s_or_b64 exec, exec, s[18:19]
	v_mul_f32_e32 v129, v77, v77
	v_mul_f32_e32 v130, v79, v79
	v_fmac_f32_e32 v129, v76, v76
	v_fmac_f32_e32 v130, v78, v78
	v_add_f32_e32 v129, v129, v130
	v_mul_f32_e32 v130, v73, v73
	v_mul_f32_e32 v131, v75, v75
	v_fmac_f32_e32 v130, v72, v72
	v_fmac_f32_e32 v131, v74, v74
	v_add_f32_e32 v130, v130, v131
	v_add_f32_e32 v129, v129, v130
	s_nop 1
	v_mov_b32_e32 v130, v129
	v_mov_b32_e32 v253, v129
	s_nop 1
	v_permlane16_swap_b32_e32 v130, v253
	s_mov_b32 s98, 0xffff
	s_mov_b32 s99, 0xffff
	v_cndmask_b32_e64 v130, v130, v253, s[98:99]
	s_waitcnt lgkmcnt(0)
; template <int K> __device__ __forceinline__ float shx(float v) { static_assert(K < 32, "use sum32"); return __int_as_float(__builtin_amdgcn_ds_swizzle(__float_as_int(v), (K << 10) | 0x1f)); }
; __device__ __forceinline__ float sum32(float v) { auto rr = __builtin_amdgcn_permlane32_swap(__float_as_uint(v), __float_as_uint(v), false, false); return __uint_as_float(rr[0]) + __uint_as_float(rr[1]); }
; template <bool ROWSCALE>
; __device__ __forceinline__ void head_norm_store(const f32x4 (&acc)[2][2][4][2], const float (&rs)[2][4], const float* gain, bf16_t* d0, bf16_t* d1, PG8_LAS float* red, int wr, int wc, int fr, int fq) {
;     ...
;             for (int bj = 0; bj < 2; ++bj) { float s = 0.f;
; #pragma unroll
;                 for (int n = 0; n < 2; ++n) { f32x4 v = acc[ai][bj][m][n]; if (ROWSCALE) v = v * rs[ai][m]; s += (v[0] * v[0] + v[1] * v[1]) + (v[2] * v[2] + v[3] * v[3]); }
;                 s += shx<16>(s); s = sum32(s);
;                 if (fq == 0) red[((ai * HALF + wr * 64 + m * 16 + fr) * 2 + bj) * 4 + wc] = s; }
	v_add_f32_e32 v129, v129, v130
	v_mov_b32_e32 v130, v129
	s_nop 1
	v_permlane32_swap_b32_e32 v129, v130
	s_and_saveexec_b64 s[18:19], vcc
	v_add_f32_e32 v129, v129, v130
	ds_write_b32 v128, v129 offset:1536
	s_or_b64 exec, exec, s[18:19]
	v_mul_f32_e32 v129, v69, v69
	v_mul_f32_e32 v130, v71, v71
	v_fmac_f32_e32 v129, v68, v68
	v_fmac_f32_e32 v130, v70, v70
	v_add_f32_e32 v129, v129, v130
	v_mul_f32_e32 v130, v65, v65
	v_mul_f32_e32 v131, v67, v67
	v_fmac_f32_e32 v130, v64, v64
	v_fmac_f32_e32 v131, v66, v66
	v_add_f32_e32 v130, v130, v131
	v_add_f32_e32 v129, v129, v130
	s_nop 1
	v_mov_b32_e32 v130, v129
	v_mov_b32_e32 v253, v129
	s_nop 1
	v_permlane16_swap_b32_e32 v130, v253
	s_mov_b32 s98, 0xffff
	s_mov_b32 s99, 0xffff
	v_cndmask_b32_e64 v130, v130, v253, s[98:99]
	s_waitcnt lgkmcnt(0)
	v_add_f32_e32 v129, v129, v130
	v_mov_b32_e32 v130, v129
	s_nop 1
	v_permlane32_swap_b32_e32 v129, v130
	s_and_saveexec_b64 s[18:19], vcc
	v_add_f32_e32 v129, v129, v130
	ds_write_b32 v128, v129 offset:1552
	s_or_b64 exec, exec, s[18:19]
	v_mul_f32_e32 v129, v61, v61
	v_mul_f32_e32 v130, v63, v63
	v_fmac_f32_e32 v129, v60, v60
	v_fmac_f32_e32 v130, v62, v62
	v_add_f32_e32 v129, v129, v130
	v_mul_f32_e32 v130, v57, v57
	v_mul_f32_e32 v131, v59, v59
	v_fmac_f32_e32 v130, v56, v56
	v_fmac_f32_e32 v131, v58, v58
	v_add_f32_e32 v130, v130, v131
	v_add_f32_e32 v129, v129, v130
	s_nop 1
	v_mov_b32_e32 v130, v129
	v_mov_b32_e32 v253, v129
	s_nop 1
	v_permlane16_swap_b32_e32 v130, v253
	s_mov_b32 s98, 0xffff
	s_mov_b32 s99, 0xffff
	v_cndmask_b32_e64 v130, v130, v253, s[98:99]
	s_waitcnt lgkmcnt(0)
	v_add_f32_e32 v129, v129, v130
	v_mov_b32_e32 v130, v129
	s_nop 1
	v_permlane32_swap_b32_e32 v129, v130
	s_and_saveexec_b64 s[18:19], vcc
	v_add_f32_e32 v129, v129, v130
	ds_write_b32 v128, v129 offset:4096
	s_or_b64 exec, exec, s[18:19]
	v_mul_f32_e32 v129, v53, v53
	v_mul_f32_e32 v130, v55, v55
	v_fmac_f32_e32 v129, v52, v52
	v_fmac_f32_e32 v130, v54, v54
	v_add_f32_e32 v129, v129, v130
	v_mul_f32_e32 v130, v49, v49
	v_mul_f32_e32 v131, v51, v51
	v_fmac_f32_e32 v130, v48, v48
	v_fmac_f32_e32 v131, v50, v50
	v_add_f32_e32 v130, v130, v131
	v_add_f32_e32 v129, v129, v130
	s_nop 1
	v_mov_b32_e32 v130, v129
	v_mov_b32_e32 v253, v129
	s_nop 1
	v_permlane16_swap_b32_e32 v130, v253
	s_mov_b32 s98, 0xffff
	s_mov_b32 s99, 0xffff
	v_cndmask_b32_e64 v130, v130, v253, s[98:99]
	s_waitcnt lgkmcnt(0)
	v_add_f32_e32 v129, v129, v130
	v_mov_b32_e32 v130, v129
	s_nop 1
	v_permlane32_swap_b32_e32 v129, v130
	s_and_saveexec_b64 s[18:19], vcc
	v_add_f32_e32 v129, v129, v130
	ds_write_b32 v128, v129 offset:4112
	s_or_b64 exec, exec, s[18:19]
	v_mul_f32_e32 v129, v45, v45
	v_mul_f32_e32 v130, v47, v47
	v_fmac_f32_e32 v129, v44, v44
	v_fmac_f32_e32 v130, v46, v46
	v_add_f32_e32 v129, v129, v130
	v_mul_f32_e32 v130, v41, v41
	v_mul_f32_e32 v131, v43, v43
	v_fmac_f32_e32 v130, v40, v40
	v_fmac_f32_e32 v131, v42, v42
	v_add_f32_e32 v130, v130, v131
	v_add_f32_e32 v129, v129, v130
	s_nop 1
	v_mov_b32_e32 v130, v129
	v_mov_b32_e32 v253, v129
	s_nop 1
	v_permlane16_swap_b32_e32 v130, v253
	s_mov_b32 s98, 0xffff
	s_mov_b32 s99, 0xffff
	v_cndmask_b32_e64 v130, v130, v253, s[98:99]
	s_waitcnt lgkmcnt(0)
	v_add_f32_e32 v129, v129, v130
	v_mov_b32_e32 v130, v129
	s_nop 1
	v_permlane32_swap_b32_e32 v129, v130
	s_and_saveexec_b64 s[18:19], vcc
	v_add_f32_e32 v129, v129, v130
	ds_write_b32 v128, v129 offset:4608
	s_or_b64 exec, exec, s[18:19]
	v_mul_f32_e32 v129, v37, v37
	v_mul_f32_e32 v130, v39, v39
	v_fmac_f32_e32 v129, v36, v36
	v_fmac_f32_e32 v130, v38, v38
	v_add_f32_e32 v129, v129, v130
	v_mul_f32_e32 v130, v33, v33
	v_mul_f32_e32 v131, v35, v35
	v_fmac_f32_e32 v130, v32, v32
	v_fmac_f32_e32 v131, v34, v34
	v_add_f32_e32 v130, v130, v131
	v_add_f32_e32 v129, v129, v130
	s_nop 1
	v_mov_b32_e32 v130, v129
	v_mov_b32_e32 v253, v129
	s_nop 1
	v_permlane16_swap_b32_e32 v130, v253
	s_mov_b32 s98, 0xffff
	s_mov_b32 s99, 0xffff
	v_cndmask_b32_e64 v130, v130, v253, s[98:99]
	s_waitcnt lgkmcnt(0)
	v_add_f32_e32 v129, v129, v130
	v_mov_b32_e32 v130, v129
	s_nop 1
	v_permlane32_swap_b32_e32 v129, v130
	s_and_saveexec_b64 s[18:19], vcc
	v_add_f32_e32 v129, v129, v130
	ds_write_b32 v128, v129 offset:4624
	s_or_b64 exec, exec, s[18:19]
	v_mul_f32_e32 v129, v29, v29
	v_mul_f32_e32 v130, v31, v31
	v_fmac_f32_e32 v129, v28, v28
	v_fmac_f32_e32 v130, v30, v30
	v_add_f32_e32 v129, v129, v130
	v_mul_f32_e32 v130, v25, v25
	v_mul_f32_e32 v131, v27, v27
	v_fmac_f32_e32 v130, v24, v24
	v_fmac_f32_e32 v131, v26, v26
	v_add_f32_e32 v130, v130, v131
	v_add_f32_e32 v129, v129, v130
	s_nop 1
	v_mov_b32_e32 v130, v129
	v_mov_b32_e32 v253, v129
	s_nop 1
	v_permlane16_swap_b32_e32 v130, v253
	s_mov_b32 s98, 0xffff
	s_mov_b32 s99, 0xffff
	v_cndmask_b32_e64 v130, v130, v253, s[98:99]
	s_waitcnt lgkmcnt(0)
	v_add_f32_e32 v129, v129, v130
	v_mov_b32_e32 v130, v129
	s_nop 1
	v_permlane32_swap_b32_e32 v129, v130
	s_and_saveexec_b64 s[18:19], vcc
	v_add_f32_e32 v129, v129, v130
	ds_write_b32 v128, v129 offset:5120
	s_or_b64 exec, exec, s[18:19]
	v_mul_f32_e32 v129, v21, v21
	v_mul_f32_e32 v130, v23, v23
	v_fmac_f32_e32 v129, v20, v20
	v_fmac_f32_e32 v130, v22, v22
	v_add_f32_e32 v129, v129, v130
	v_mul_f32_e32 v130, v17, v17
	v_mul_f32_e32 v131, v19, v19
	v_fmac_f32_e32 v130, v16, v16
	v_fmac_f32_e32 v131, v18, v18
	v_add_f32_e32 v130, v130, v131
	v_add_f32_e32 v129, v129, v130
	s_nop 1
	v_mov_b32_e32 v130, v129
	v_mov_b32_e32 v253, v129
	s_nop 1
	v_permlane16_swap_b32_e32 v130, v253
	s_mov_b32 s98, 0xffff
	s_mov_b32 s99, 0xffff
	v_cndmask_b32_e64 v130, v130, v253, s[98:99]
	s_waitcnt lgkmcnt(0)
; template <int K> __device__ __forceinline__ float shx(float v) { static_assert(K < 32, "use sum32"); return __int_as_float(__builtin_amdgcn_ds_swizzle(__float_as_int(v), (K << 10) | 0x1f)); }
; __device__ __forceinline__ float sum32(float v) { auto rr = __builtin_amdgcn_permlane32_swap(__float_as_uint(v), __float_as_uint(v), false, false); return __uint_as_float(rr[0]) + __uint_as_float(rr[1]); }
; #define PG8_LAS __attribute__((address_space(3)))
; __device__ __forceinline__ u32x4 pack8(const f32x4& a, const f32x4& b) { u32x4 w; w.x = cvt_pk_bf16(a[0], a[1]); w.y = cvt_pk_bf16(a[2], a[3]); w.z = cvt_pk_bf16(b[0], b[1]); w.w = cvt_pk_bf16(b[2], b[3]); return w; }
; template <bool ROWSCALE>
; __device__ __forceinline__ void head_norm_store(const f32x4 (&acc)[2][2][4][2], const float (&rs)[2][4], const float* gain, bf16_t* d0, bf16_t* d1, PG8_LAS float* red, int wr, int wc, int fr, int fq) {
;     ...
;             for (int bj = 0; bj < 2; ++bj) { float s = 0.f;
; #pragma unroll
;                 for (int n = 0; n < 2; ++n) { f32x4 v = acc[ai][bj][m][n]; if (ROWSCALE) v = v * rs[ai][m]; s += (v[0] * v[0] + v[1] * v[1]) + (v[2] * v[2] + v[3] * v[3]); }
;                 s += shx<16>(s); s = sum32(s);
;                 if (fq == 0) red[((ai * HALF + wr * 64 + m * 16 + fr) * 2 + bj) * 4 + wc] = s; }
;     asm volatile("s_waitcnt lgkmcnt(0)" ::: "memory"); __builtin_amdgcn_s_barrier(); asm volatile("" ::: "memory");
;     const f32x4 g0 = *(const f32x4*)(gain + wc * 32 + fq * 8), g1 = *(const f32x4*)(gain + wc * 32 + fq * 8 + 4);
; #pragma unroll
;     for (int ai = 0; ai < 2; ++ai)
; #pragma unroll
;         for (int m = 0; m < 4; ++m) { const int rl = ai * HALF + wr * 64 + m * 16 + fr;
; #pragma unroll
;             for (int bj = 0; bj < 2; ++bj) { const PG8_LAS float* rp = red + (rl * 2 + bj) * 4;
;                 const float ss = (rp[0] + rp[1]) + (rp[2] + rp[3]);
;                 float sc = __builtin_amdgcn_rsqf(ss * (1.0f / 128.0f) + RMS_EPS); if (ROWSCALE) sc *= rs[ai][m];
;                 const f32x4 v0 = acc[ai][bj][m][0] * sc * g0, v1 = acc[ai][bj][m][1] * sc * g1;
;                 *(u32x4*)((bj ? d1 : d0) + (size_t)rl * 128 + wc * 32 + fq * 8) = pack8(v0, v1); } }
	v_add_f32_e32 v129, v129, v130
	v_mov_b32_e32 v130, v129
	s_nop 1
	v_permlane32_swap_b32_e32 v129, v130
	s_and_saveexec_b64 s[18:19], vcc
	v_add_f32_e32 v129, v129, v130
	ds_write_b32 v128, v129 offset:5136
	s_or_b64 exec, exec, s[18:19]
	v_mul_f32_e32 v129, v13, v13
	v_mul_f32_e32 v130, v15, v15
	v_fmac_f32_e32 v129, v12, v12
	v_fmac_f32_e32 v130, v14, v14
	v_add_f32_e32 v129, v129, v130
	v_mul_f32_e32 v130, v9, v9
	v_mul_f32_e32 v131, v11, v11
	v_fmac_f32_e32 v130, v8, v8
	v_fmac_f32_e32 v131, v10, v10
	v_add_f32_e32 v130, v130, v131
	v_add_f32_e32 v129, v129, v130
	s_nop 1
	v_mov_b32_e32 v130, v129
	v_mov_b32_e32 v253, v129
	s_nop 1
	v_permlane16_swap_b32_e32 v130, v253
	s_mov_b32 s98, 0xffff
	s_mov_b32 s99, 0xffff
	v_cndmask_b32_e64 v130, v130, v253, s[98:99]
	s_waitcnt lgkmcnt(0)
	v_add_f32_e32 v129, v129, v130
	v_mov_b32_e32 v130, v129
	s_nop 1
	v_permlane32_swap_b32_e32 v129, v130
	s_and_saveexec_b64 s[18:19], vcc
	v_add_f32_e32 v129, v129, v130
	ds_write_b32 v128, v129 offset:5632
	s_or_b64 exec, exec, s[18:19]
	v_mul_f32_e32 v129, v5, v5
	v_mul_f32_e32 v130, v7, v7
	v_fmac_f32_e32 v129, v4, v4
	v_fmac_f32_e32 v130, v6, v6
	v_add_f32_e32 v129, v129, v130
	v_mul_f32_e32 v130, v1, v1
	v_mul_f32_e32 v131, v3, v3
	v_fmac_f32_e32 v130, v0, v0
	v_fmac_f32_e32 v131, v2, v2
	v_add_f32_e32 v130, v130, v131
	v_add_f32_e32 v129, v129, v130
	s_nop 1
	v_mov_b32_e32 v130, v129
	v_mov_b32_e32 v253, v129
	s_nop 1
	v_permlane16_swap_b32_e32 v130, v253
	s_mov_b32 s98, 0xffff
	s_mov_b32 s99, 0xffff
	v_cndmask_b32_e64 v130, v130, v253, s[98:99]
	s_waitcnt lgkmcnt(0)
	v_add_f32_e32 v129, v129, v130
	v_mov_b32_e32 v130, v129
	s_nop 1
	v_permlane32_swap_b32_e32 v129, v130
	s_and_saveexec_b64 s[18:19], vcc
	v_add_f32_e32 v129, v129, v130
	ds_write_b32 v128, v129 offset:5648
	s_or_b64 exec, exec, s[18:19]
	s_waitcnt lgkmcnt(0)
	s_barrier
	v_lshl_add_u64 v[128:129], v[148:149], 2, s[26:27]
	global_load_dwordx4 v[132:135], v[128:129], off
	s_nop 0
	global_load_dwordx4 v[128:131], v[128:129], off offset:16
	s_add_i32 s20, 0, 0x20000
	v_lshl_add_u32 v151, v164, 5, s20
	ds_read_b128 v[174:177], v151
	v_lshlrev_b64 v[164:165], 8, v[164:165]
	s_lshl_b32 s18, s50, 1
	s_mov_b32 s19, s1
	v_ashrrev_i32_e32 v163, 31, v162
	s_waitcnt lgkmcnt(0)
	v_mov_b32_e32 v178, v175
	v_mov_b32_e32 v179, v176
	v_mov_b32_e32 v175, v177
	v_pk_add_f32 v[174:175], v[178:179], v[174:175]
	v_ashrrev_i32_e32 v161, 31, v160
	v_add_f32_e32 v153, v174, v175
	v_fmamk_f32 v153, v153, 0x3c000000, v172
	v_rsq_f32_e32 v174, v153
	v_ashrrev_i32_e32 v159, 31, v158
	v_ashrrev_i32_e32 v157, 31, v156
	v_ashrrev_i32_e32 v155, 31, v154
	v_pk_mul_f32 v[124:125], v[124:125], v[174:175] op_sel_hi:[1,0]
	v_pk_mul_f32 v[122:123], v[122:123], v[174:175] op_sel_hi:[1,0]
	v_pk_mul_f32 v[126:127], v[126:127], v[174:175] op_sel_hi:[1,0]
	v_pk_mul_f32 v[120:121], v[120:121], v[174:175] op_sel_hi:[1,0]
	s_waitcnt vmcnt(0)
	v_pk_mul_f32 v[124:125], v[132:133], v[124:125]
	v_pk_mul_f32 v[174:175], v[130:131], v[122:123]
	v_pk_mul_f32 v[126:127], v[134:135], v[126:127]
	v_pk_mul_f32 v[120:121], v[128:129], v[120:121]
	v_cvt_pk_bf16_f32 v122, v124, v125
	v_cvt_pk_bf16_f32 v123, v126, v127
	v_lshl_add_u64 v[126:127], s[16:17], 0, v[164:165]
	v_cvt_pk_bf16_f32 v124, v120, v121
	v_cvt_pk_bf16_f32 v125, v174, v175
	ds_read_b128 v[174:177], v151 offset:16
	v_lshlrev_b64 v[120:121], 1, v[148:149]
	v_lshl_add_u64 v[126:127], v[126:127], 0, s[18:19]
	v_lshl_add_u64 v[126:127], v[126:127], 0, v[120:121]
	v_lshl_add_u32 v151, v162, 5, s20
	s_waitcnt lgkmcnt(0)
	v_mov_b32_e32 v178, v175
	v_mov_b32_e32 v179, v176
	v_mov_b32_e32 v175, v177
	v_pk_add_f32 v[174:175], v[178:179], v[174:175]
	global_store_dwordx4 v[126:127], v[122:125], off
	v_add_f32_e32 v153, v174, v175
	v_fmamk_f32 v153, v153, 0x3c000000, v172
	v_rsq_f32_e32 v174, v153
	v_ashrrev_i32_e32 v153, 31, v152
	v_pk_mul_f32 v[116:117], v[116:117], v[174:175] op_sel_hi:[1,0]
	v_pk_mul_f32 v[118:119], v[118:119], v[174:175] op_sel_hi:[1,0]
	v_pk_mul_f32 v[112:113], v[112:113], v[174:175] op_sel_hi:[1,0]
	v_pk_mul_f32 v[114:115], v[114:115], v[174:175] op_sel_hi:[1,0]
	v_pk_mul_f32 v[118:119], v[134:135], v[118:119]
	v_pk_mul_f32 v[116:117], v[132:133], v[116:117]
	v_pk_mul_f32 v[122:123], v[130:131], v[114:115]
	v_pk_mul_f32 v[114:115], v[128:129], v[112:113]
	v_cvt_pk_bf16_f32 v112, v116, v117
	v_cvt_pk_bf16_f32 v113, v118, v119
	s_nop 0
	v_cvt_pk_bf16_f32 v114, v114, v115
	v_cvt_pk_bf16_f32 v115, v122, v123
	ds_read_b128 v[116:119], v151
	v_lshl_add_u64 v[122:123], s[12:13], 0, v[164:165]
	s_waitcnt lgkmcnt(0)
	v_mov_b32_e32 v124, v117
	v_mov_b32_e32 v125, v118
	v_mov_b32_e32 v117, v119
	v_pk_add_f32 v[116:117], v[124:125], v[116:117]
	v_lshl_add_u64 v[118:119], v[122:123], 0, s[18:19]
	v_add_f32_e32 v116, v116, v117
	v_fmamk_f32 v116, v116, 0x3c000000, v172
	v_rsq_f32_e32 v116, v116
	v_lshl_add_u64 v[118:119], v[118:119], 0, v[120:121]
	global_store_dwordx4 v[118:119], v[112:115], off
	v_lshl_add_u32 v118, v160, 5, s20
	v_pk_mul_f32 v[108:109], v[108:109], v[116:117] op_sel_hi:[1,0]
	v_pk_mul_f32 v[110:111], v[110:111], v[116:117] op_sel_hi:[1,0]
	v_pk_mul_f32 v[104:105], v[104:105], v[116:117] op_sel_hi:[1,0]
	v_pk_mul_f32 v[106:107], v[106:107], v[116:117] op_sel_hi:[1,0]
	v_pk_mul_f32 v[110:111], v[134:135], v[110:111]
	v_pk_mul_f32 v[108:109], v[132:133], v[108:109]
	v_pk_mul_f32 v[112:113], v[130:131], v[106:107]
	v_pk_mul_f32 v[106:107], v[128:129], v[104:105]
	v_cvt_pk_bf16_f32 v104, v108, v109
	v_cvt_pk_bf16_f32 v105, v110, v111
	s_nop 0
	v_cvt_pk_bf16_f32 v106, v106, v107
	v_cvt_pk_bf16_f32 v107, v112, v113
	ds_read_b128 v[108:111], v151 offset:16
	v_lshlrev_b64 v[112:113], 8, v[162:163]
	v_lshl_add_u64 v[114:115], s[16:17], 0, v[112:113]
	v_ashrrev_i32_e32 v151, 31, v150
	s_waitcnt lgkmcnt(0)
; #define PG8_LAS __attribute__((address_space(3)))
; __device__ __forceinline__ u32x4 pack8(const f32x4& a, const f32x4& b) { u32x4 w; w.x = cvt_pk_bf16(a[0], a[1]); w.y = cvt_pk_bf16(a[2], a[3]); w.z = cvt_pk_bf16(b[0], b[1]); w.w = cvt_pk_bf16(b[2], b[3]); return w; }
; template <bool ROWSCALE>
; __device__ __forceinline__ void head_norm_store(const f32x4 (&acc)[2][2][4][2], const float (&rs)[2][4], const float* gain, bf16_t* d0, bf16_t* d1, PG8_LAS float* red, int wr, int wc, int fr, int fq) {
;     ...
;         for (int m = 0; m < 4; ++m) { const int rl = ai * HALF + wr * 64 + m * 16 + fr;
; #pragma unroll
;             for (int bj = 0; bj < 2; ++bj) { const PG8_LAS float* rp = red + (rl * 2 + bj) * 4;
;                 const float ss = (rp[0] + rp[1]) + (rp[2] + rp[3]);
;                 float sc = __builtin_amdgcn_rsqf(ss * (1.0f / 128.0f) + RMS_EPS); if (ROWSCALE) sc *= rs[ai][m];
;                 const f32x4 v0 = acc[ai][bj][m][0] * sc * g0, v1 = acc[ai][bj][m][1] * sc * g1;
;                 *(u32x4*)((bj ? d1 : d0) + (size_t)rl * 128 + wc * 32 + fq * 8) = pack8(v0, v1); } }
	v_mov_b32_e32 v116, v109
	v_mov_b32_e32 v117, v110
	v_mov_b32_e32 v109, v111
	v_pk_add_f32 v[108:109], v[116:117], v[108:109]
	v_lshl_add_u64 v[110:111], v[114:115], 0, s[18:19]
	v_add_f32_e32 v108, v108, v109
	v_fmamk_f32 v108, v108, 0x3c000000, v172
	v_rsq_f32_e32 v108, v108
	v_lshl_add_u64 v[110:111], v[110:111], 0, v[120:121]
	global_store_dwordx4 v[110:111], v[104:107], off
	v_pk_mul_f32 v[100:101], v[100:101], v[108:109] op_sel_hi:[1,0]
	v_pk_mul_f32 v[102:103], v[102:103], v[108:109] op_sel_hi:[1,0]
	v_pk_mul_f32 v[96:97], v[96:97], v[108:109] op_sel_hi:[1,0]
	v_pk_mul_f32 v[98:99], v[98:99], v[108:109] op_sel_hi:[1,0]
	v_pk_mul_f32 v[102:103], v[134:135], v[102:103]
	v_pk_mul_f32 v[100:101], v[132:133], v[100:101]
	v_pk_mul_f32 v[104:105], v[130:131], v[98:99]
	v_pk_mul_f32 v[98:99], v[128:129], v[96:97]
	v_cvt_pk_bf16_f32 v96, v100, v101
	v_cvt_pk_bf16_f32 v97, v102, v103
	s_nop 0
	v_cvt_pk_bf16_f32 v98, v98, v99
	v_cvt_pk_bf16_f32 v99, v104, v105
	ds_read_b128 v[100:103], v118
	v_lshl_add_u64 v[104:105], s[12:13], 0, v[112:113]
	s_waitcnt lgkmcnt(0)
	v_mov_b32_e32 v106, v101
	v_mov_b32_e32 v107, v102
	v_mov_b32_e32 v101, v103
	v_pk_add_f32 v[100:101], v[106:107], v[100:101]
	v_lshl_add_u64 v[102:103], v[104:105], 0, s[18:19]
	v_add_f32_e32 v100, v100, v101
	v_fmamk_f32 v100, v100, 0x3c000000, v172
	v_rsq_f32_e32 v100, v100
	v_lshl_add_u64 v[102:103], v[102:103], 0, v[120:121]
	global_store_dwordx4 v[102:103], v[96:99], off
	v_pk_mul_f32 v[92:93], v[92:93], v[100:101] op_sel_hi:[1,0]
	v_pk_mul_f32 v[94:95], v[94:95], v[100:101] op_sel_hi:[1,0]
	v_pk_mul_f32 v[88:89], v[88:89], v[100:101] op_sel_hi:[1,0]
	v_pk_mul_f32 v[90:91], v[90:91], v[100:101] op_sel_hi:[1,0]
	v_pk_mul_f32 v[94:95], v[134:135], v[94:95]
	v_pk_mul_f32 v[92:93], v[132:133], v[92:93]
	v_pk_mul_f32 v[96:97], v[130:131], v[90:91]
	v_pk_mul_f32 v[90:91], v[128:129], v[88:89]
	v_cvt_pk_bf16_f32 v88, v92, v93
	v_cvt_pk_bf16_f32 v89, v94, v95
	s_nop 0
	v_cvt_pk_bf16_f32 v90, v90, v91
	v_cvt_pk_bf16_f32 v91, v96, v97
	ds_read_b128 v[92:95], v118 offset:16
	v_lshlrev_b64 v[96:97], 8, v[160:161]
	v_lshl_add_u64 v[98:99], s[16:17], 0, v[96:97]
	s_waitcnt lgkmcnt(0)
	v_mov_b32_e32 v100, v93
	v_mov_b32_e32 v101, v94
	v_mov_b32_e32 v93, v95
	v_pk_add_f32 v[92:93], v[100:101], v[92:93]
	v_lshl_add_u64 v[94:95], v[98:99], 0, s[18:19]
	v_add_f32_e32 v92, v92, v93
	v_fmamk_f32 v92, v92, 0x3c000000, v172
	v_rsq_f32_e32 v92, v92
	v_lshl_add_u64 v[94:95], v[94:95], 0, v[120:121]
	global_store_dwordx4 v[94:95], v[88:91], off
	v_pk_mul_f32 v[84:85], v[84:85], v[92:93] op_sel_hi:[1,0]
	v_pk_mul_f32 v[86:87], v[86:87], v[92:93] op_sel_hi:[1,0]
	v_pk_mul_f32 v[80:81], v[80:81], v[92:93] op_sel_hi:[1,0]
	v_pk_mul_f32 v[82:83], v[82:83], v[92:93] op_sel_hi:[1,0]
	v_pk_mul_f32 v[86:87], v[134:135], v[86:87]
	v_pk_mul_f32 v[84:85], v[132:133], v[84:85]
	v_pk_mul_f32 v[88:89], v[130:131], v[82:83]
	v_pk_mul_f32 v[82:83], v[128:129], v[80:81]
	v_lshl_add_u32 v92, v158, 5, s20
	v_cvt_pk_bf16_f32 v80, v84, v85
	v_cvt_pk_bf16_f32 v81, v86, v87
	v_cvt_pk_bf16_f32 v82, v82, v83
	v_cvt_pk_bf16_f32 v83, v88, v89
	ds_read_b128 v[84:87], v92
	v_lshl_add_u64 v[88:89], s[12:13], 0, v[96:97]
	s_waitcnt lgkmcnt(0)
	v_mov_b32_e32 v90, v85
	v_mov_b32_e32 v91, v86
	v_mov_b32_e32 v85, v87
	v_pk_add_f32 v[84:85], v[90:91], v[84:85]
	v_lshl_add_u64 v[86:87], v[88:89], 0, s[18:19]
	v_add_f32_e32 v84, v84, v85
	v_fmamk_f32 v84, v84, 0x3c000000, v172
	v_rsq_f32_e32 v84, v84
	v_lshl_add_u64 v[86:87], v[86:87], 0, v[120:121]
	global_store_dwordx4 v[86:87], v[80:83], off
	v_pk_mul_f32 v[76:77], v[76:77], v[84:85] op_sel_hi:[1,0]
	v_pk_mul_f32 v[78:79], v[78:79], v[84:85] op_sel_hi:[1,0]
	v_pk_mul_f32 v[72:73], v[72:73], v[84:85] op_sel_hi:[1,0]
	v_pk_mul_f32 v[74:75], v[74:75], v[84:85] op_sel_hi:[1,0]
	v_pk_mul_f32 v[78:79], v[134:135], v[78:79]
	v_pk_mul_f32 v[76:77], v[132:133], v[76:77]
	v_pk_mul_f32 v[80:81], v[130:131], v[74:75]
	v_pk_mul_f32 v[74:75], v[128:129], v[72:73]
	v_cvt_pk_bf16_f32 v72, v76, v77
	v_cvt_pk_bf16_f32 v73, v78, v79
	s_nop 0
	v_cvt_pk_bf16_f32 v74, v74, v75
	v_cvt_pk_bf16_f32 v75, v80, v81
	ds_read_b128 v[76:79], v92 offset:16
	v_lshlrev_b64 v[80:81], 8, v[158:159]
	v_lshl_add_u64 v[82:83], s[16:17], 0, v[80:81]
	s_waitcnt lgkmcnt(0)
	v_mov_b32_e32 v84, v77
	v_mov_b32_e32 v85, v78
	v_mov_b32_e32 v77, v79
	v_pk_add_f32 v[76:77], v[84:85], v[76:77]
	v_lshl_add_u64 v[78:79], v[82:83], 0, s[18:19]
	v_add_f32_e32 v76, v76, v77
	v_fmamk_f32 v76, v76, 0x3c000000, v172
	v_rsq_f32_e32 v76, v76
	v_lshl_add_u64 v[78:79], v[78:79], 0, v[120:121]
	global_store_dwordx4 v[78:79], v[72:75], off
	v_pk_mul_f32 v[68:69], v[68:69], v[76:77] op_sel_hi:[1,0]
	v_pk_mul_f32 v[70:71], v[70:71], v[76:77] op_sel_hi:[1,0]
	v_pk_mul_f32 v[64:65], v[64:65], v[76:77] op_sel_hi:[1,0]
	v_pk_mul_f32 v[66:67], v[66:67], v[76:77] op_sel_hi:[1,0]
	v_pk_mul_f32 v[70:71], v[134:135], v[70:71]
	v_pk_mul_f32 v[68:69], v[132:133], v[68:69]
	v_pk_mul_f32 v[72:73], v[130:131], v[66:67]
	v_pk_mul_f32 v[66:67], v[128:129], v[64:65]
	v_lshl_add_u32 v76, v156, 5, s20
	v_cvt_pk_bf16_f32 v64, v68, v69
	v_cvt_pk_bf16_f32 v65, v70, v71
	v_cvt_pk_bf16_f32 v66, v66, v67
	v_cvt_pk_bf16_f32 v67, v72, v73
	ds_read_b128 v[68:71], v76
	v_lshl_add_u64 v[72:73], s[12:13], 0, v[80:81]
	s_waitcnt lgkmcnt(0)
; #define PG8_LAS __attribute__((address_space(3)))
; __device__ __forceinline__ u32x4 pack8(const f32x4& a, const f32x4& b) { u32x4 w; w.x = cvt_pk_bf16(a[0], a[1]); w.y = cvt_pk_bf16(a[2], a[3]); w.z = cvt_pk_bf16(b[0], b[1]); w.w = cvt_pk_bf16(b[2], b[3]); return w; }
; template <bool ROWSCALE>
; __device__ __forceinline__ void head_norm_store(const f32x4 (&acc)[2][2][4][2], const float (&rs)[2][4], const float* gain, bf16_t* d0, bf16_t* d1, PG8_LAS float* red, int wr, int wc, int fr, int fq) {
;     ...
;         for (int m = 0; m < 4; ++m) { const int rl = ai * HALF + wr * 64 + m * 16 + fr;
; #pragma unroll
;             for (int bj = 0; bj < 2; ++bj) { const PG8_LAS float* rp = red + (rl * 2 + bj) * 4;
;                 const float ss = (rp[0] + rp[1]) + (rp[2] + rp[3]);
;                 float sc = __builtin_amdgcn_rsqf(ss * (1.0f / 128.0f) + RMS_EPS); if (ROWSCALE) sc *= rs[ai][m];
;                 const f32x4 v0 = acc[ai][bj][m][0] * sc * g0, v1 = acc[ai][bj][m][1] * sc * g1;
;                 *(u32x4*)((bj ? d1 : d0) + (size_t)rl * 128 + wc * 32 + fq * 8) = pack8(v0, v1); } }
	v_mov_b32_e32 v74, v69
	v_mov_b32_e32 v75, v70
	v_mov_b32_e32 v69, v71
	v_pk_add_f32 v[68:69], v[74:75], v[68:69]
	v_lshl_add_u64 v[70:71], v[72:73], 0, s[18:19]
	v_add_f32_e32 v68, v68, v69
	v_fmamk_f32 v68, v68, 0x3c000000, v172
	v_rsq_f32_e32 v68, v68
	v_lshl_add_u64 v[70:71], v[70:71], 0, v[120:121]
	global_store_dwordx4 v[70:71], v[64:67], off
	v_pk_mul_f32 v[60:61], v[60:61], v[68:69] op_sel_hi:[1,0]
	v_pk_mul_f32 v[62:63], v[62:63], v[68:69] op_sel_hi:[1,0]
	v_pk_mul_f32 v[56:57], v[56:57], v[68:69] op_sel_hi:[1,0]
	v_pk_mul_f32 v[58:59], v[58:59], v[68:69] op_sel_hi:[1,0]
	v_pk_mul_f32 v[62:63], v[134:135], v[62:63]
	v_pk_mul_f32 v[60:61], v[132:133], v[60:61]
	v_pk_mul_f32 v[64:65], v[130:131], v[58:59]
	v_pk_mul_f32 v[58:59], v[128:129], v[56:57]
	v_cvt_pk_bf16_f32 v56, v60, v61
	v_cvt_pk_bf16_f32 v57, v62, v63
	s_nop 0
	v_cvt_pk_bf16_f32 v58, v58, v59
	v_cvt_pk_bf16_f32 v59, v64, v65
	ds_read_b128 v[60:63], v76 offset:16
	v_lshlrev_b64 v[64:65], 8, v[156:157]
	v_lshl_add_u64 v[66:67], s[16:17], 0, v[64:65]
	s_waitcnt lgkmcnt(0)
	v_mov_b32_e32 v68, v61
	v_mov_b32_e32 v69, v62
	v_mov_b32_e32 v61, v63
	v_pk_add_f32 v[60:61], v[68:69], v[60:61]
	v_lshl_add_u64 v[62:63], v[66:67], 0, s[18:19]
	v_add_f32_e32 v60, v60, v61
	v_fmamk_f32 v60, v60, 0x3c000000, v172
	v_rsq_f32_e32 v60, v60
	v_lshl_add_u64 v[62:63], v[62:63], 0, v[120:121]
	global_store_dwordx4 v[62:63], v[56:59], off
	v_pk_mul_f32 v[52:53], v[52:53], v[60:61] op_sel_hi:[1,0]
	v_pk_mul_f32 v[54:55], v[54:55], v[60:61] op_sel_hi:[1,0]
	v_pk_mul_f32 v[48:49], v[48:49], v[60:61] op_sel_hi:[1,0]
	v_pk_mul_f32 v[50:51], v[50:51], v[60:61] op_sel_hi:[1,0]
	v_pk_mul_f32 v[54:55], v[134:135], v[54:55]
	v_pk_mul_f32 v[52:53], v[132:133], v[52:53]
	v_pk_mul_f32 v[56:57], v[130:131], v[50:51]
	v_pk_mul_f32 v[50:51], v[128:129], v[48:49]
	v_lshl_add_u32 v60, v154, 5, s20
	v_cvt_pk_bf16_f32 v48, v52, v53
	v_cvt_pk_bf16_f32 v49, v54, v55
	v_cvt_pk_bf16_f32 v50, v50, v51
	v_cvt_pk_bf16_f32 v51, v56, v57
	ds_read_b128 v[52:55], v60
	v_lshl_add_u64 v[56:57], s[12:13], 0, v[64:65]
	s_waitcnt lgkmcnt(0)
	v_mov_b32_e32 v58, v53
	v_mov_b32_e32 v59, v54
	v_mov_b32_e32 v53, v55
	v_pk_add_f32 v[52:53], v[58:59], v[52:53]
	v_lshl_add_u64 v[54:55], v[56:57], 0, s[18:19]
	v_add_f32_e32 v52, v52, v53
	v_fmamk_f32 v52, v52, 0x3c000000, v172
	v_rsq_f32_e32 v52, v52
	v_lshl_add_u64 v[54:55], v[54:55], 0, v[120:121]
	global_store_dwordx4 v[54:55], v[48:51], off
	v_pk_mul_f32 v[44:45], v[44:45], v[52:53] op_sel_hi:[1,0]
	v_pk_mul_f32 v[46:47], v[46:47], v[52:53] op_sel_hi:[1,0]
	v_pk_mul_f32 v[40:41], v[40:41], v[52:53] op_sel_hi:[1,0]
	v_pk_mul_f32 v[42:43], v[42:43], v[52:53] op_sel_hi:[1,0]
	v_pk_mul_f32 v[46:47], v[134:135], v[46:47]
	v_pk_mul_f32 v[44:45], v[132:133], v[44:45]
	v_pk_mul_f32 v[48:49], v[130:131], v[42:43]
	v_pk_mul_f32 v[42:43], v[128:129], v[40:41]
	v_cvt_pk_bf16_f32 v40, v44, v45
	v_cvt_pk_bf16_f32 v41, v46, v47
	s_nop 0
	v_cvt_pk_bf16_f32 v42, v42, v43
	v_cvt_pk_bf16_f32 v43, v48, v49
	ds_read_b128 v[44:47], v60 offset:16
	v_lshlrev_b64 v[48:49], 8, v[154:155]
	v_lshl_add_u64 v[50:51], s[16:17], 0, v[48:49]
	s_waitcnt lgkmcnt(0)
	v_mov_b32_e32 v52, v45
	v_mov_b32_e32 v53, v46
	v_mov_b32_e32 v45, v47
	v_pk_add_f32 v[44:45], v[52:53], v[44:45]
	v_lshl_add_u64 v[46:47], v[50:51], 0, s[18:19]
	v_add_f32_e32 v44, v44, v45
	v_fmamk_f32 v44, v44, 0x3c000000, v172
	v_rsq_f32_e32 v44, v44
	v_lshl_add_u64 v[46:47], v[46:47], 0, v[120:121]
	global_store_dwordx4 v[46:47], v[40:43], off
	v_pk_mul_f32 v[36:37], v[36:37], v[44:45] op_sel_hi:[1,0]
	v_pk_mul_f32 v[38:39], v[38:39], v[44:45] op_sel_hi:[1,0]
	v_pk_mul_f32 v[32:33], v[32:33], v[44:45] op_sel_hi:[1,0]
	v_pk_mul_f32 v[34:35], v[34:35], v[44:45] op_sel_hi:[1,0]
	v_pk_mul_f32 v[38:39], v[134:135], v[38:39]
	v_pk_mul_f32 v[36:37], v[132:133], v[36:37]
	v_pk_mul_f32 v[40:41], v[130:131], v[34:35]
	v_pk_mul_f32 v[34:35], v[128:129], v[32:33]
	v_lshl_add_u32 v44, v152, 5, s20
	v_cvt_pk_bf16_f32 v32, v36, v37
	v_cvt_pk_bf16_f32 v33, v38, v39
	v_cvt_pk_bf16_f32 v34, v34, v35
	v_cvt_pk_bf16_f32 v35, v40, v41
	ds_read_b128 v[36:39], v44
	v_lshl_add_u64 v[40:41], s[12:13], 0, v[48:49]
	s_waitcnt lgkmcnt(0)
; #define PG8_LAS __attribute__((address_space(3)))
; __device__ __forceinline__ u32x4 pack8(const f32x4& a, const f32x4& b) { u32x4 w; w.x = cvt_pk_bf16(a[0], a[1]); w.y = cvt_pk_bf16(a[2], a[3]); w.z = cvt_pk_bf16(b[0], b[1]); w.w = cvt_pk_bf16(b[2], b[3]); return w; }
; template <bool ROWSCALE>
; __device__ __forceinline__ void head_norm_store(const f32x4 (&acc)[2][2][4][2], const float (&rs)[2][4], const float* gain, bf16_t* d0, bf16_t* d1, PG8_LAS float* red, int wr, int wc, int fr, int fq) {
;     ...
;         for (int m = 0; m < 4; ++m) { const int rl = ai * HALF + wr * 64 + m * 16 + fr;
; #pragma unroll
;             for (int bj = 0; bj < 2; ++bj) { const PG8_LAS float* rp = red + (rl * 2 + bj) * 4;
;                 const float ss = (rp[0] + rp[1]) + (rp[2] + rp[3]);
;                 float sc = __builtin_amdgcn_rsqf(ss * (1.0f / 128.0f) + RMS_EPS); if (ROWSCALE) sc *= rs[ai][m];
;                 const f32x4 v0 = acc[ai][bj][m][0] * sc * g0, v1 = acc[ai][bj][m][1] * sc * g1;
;                 *(u32x4*)((bj ? d1 : d0) + (size_t)rl * 128 + wc * 32 + fq * 8) = pack8(v0, v1); } }
	v_mov_b32_e32 v42, v37
	v_mov_b32_e32 v43, v38
	v_mov_b32_e32 v37, v39
	v_pk_add_f32 v[36:37], v[42:43], v[36:37]
	v_lshl_add_u64 v[38:39], v[40:41], 0, s[18:19]
	v_add_f32_e32 v36, v36, v37
	v_fmamk_f32 v36, v36, 0x3c000000, v172
	v_rsq_f32_e32 v36, v36
	v_lshl_add_u64 v[38:39], v[38:39], 0, v[120:121]
	global_store_dwordx4 v[38:39], v[32:35], off
	v_pk_mul_f32 v[28:29], v[28:29], v[36:37] op_sel_hi:[1,0]
	v_pk_mul_f32 v[30:31], v[30:31], v[36:37] op_sel_hi:[1,0]
	v_pk_mul_f32 v[24:25], v[24:25], v[36:37] op_sel_hi:[1,0]
	v_pk_mul_f32 v[26:27], v[26:27], v[36:37] op_sel_hi:[1,0]
	v_pk_mul_f32 v[30:31], v[134:135], v[30:31]
	v_pk_mul_f32 v[28:29], v[132:133], v[28:29]
	v_pk_mul_f32 v[32:33], v[130:131], v[26:27]
	v_pk_mul_f32 v[26:27], v[128:129], v[24:25]
	v_cvt_pk_bf16_f32 v24, v28, v29
	v_cvt_pk_bf16_f32 v25, v30, v31
	s_nop 0
	v_cvt_pk_bf16_f32 v26, v26, v27
	v_cvt_pk_bf16_f32 v27, v32, v33
	ds_read_b128 v[28:31], v44 offset:16
	v_lshlrev_b64 v[32:33], 8, v[152:153]
	v_lshl_add_u64 v[34:35], s[16:17], 0, v[32:33]
	s_waitcnt lgkmcnt(0)
	v_mov_b32_e32 v36, v29
	v_mov_b32_e32 v37, v30
	v_mov_b32_e32 v29, v31
	v_pk_add_f32 v[28:29], v[36:37], v[28:29]
	v_lshl_add_u64 v[30:31], v[34:35], 0, s[18:19]
	v_add_f32_e32 v28, v28, v29
	v_fmamk_f32 v28, v28, 0x3c000000, v172
	v_rsq_f32_e32 v28, v28
	v_lshl_add_u64 v[30:31], v[30:31], 0, v[120:121]
	global_store_dwordx4 v[30:31], v[24:27], off
	v_pk_mul_f32 v[20:21], v[20:21], v[28:29] op_sel_hi:[1,0]
	v_pk_mul_f32 v[22:23], v[22:23], v[28:29] op_sel_hi:[1,0]
	v_pk_mul_f32 v[16:17], v[16:17], v[28:29] op_sel_hi:[1,0]
	v_pk_mul_f32 v[18:19], v[18:19], v[28:29] op_sel_hi:[1,0]
	v_pk_mul_f32 v[22:23], v[134:135], v[22:23]
	v_pk_mul_f32 v[20:21], v[132:133], v[20:21]
	v_pk_mul_f32 v[24:25], v[130:131], v[18:19]
	v_pk_mul_f32 v[18:19], v[128:129], v[16:17]
	v_lshl_add_u32 v28, v150, 5, s20
	v_cvt_pk_bf16_f32 v16, v20, v21
	v_cvt_pk_bf16_f32 v17, v22, v23
	v_cvt_pk_bf16_f32 v18, v18, v19
	v_cvt_pk_bf16_f32 v19, v24, v25
	ds_read_b128 v[20:23], v28
	v_lshl_add_u64 v[24:25], s[12:13], 0, v[32:33]
	s_waitcnt lgkmcnt(0)
	v_mov_b32_e32 v26, v21
	v_mov_b32_e32 v27, v22
	v_mov_b32_e32 v21, v23
	v_pk_add_f32 v[20:21], v[26:27], v[20:21]
	v_lshl_add_u64 v[22:23], v[24:25], 0, s[18:19]
	v_add_f32_e32 v20, v20, v21
	v_fmamk_f32 v20, v20, 0x3c000000, v172
	v_rsq_f32_e32 v20, v20
	v_lshl_add_u64 v[22:23], v[22:23], 0, v[120:121]
	global_store_dwordx4 v[22:23], v[16:19], off
	v_pk_mul_f32 v[12:13], v[12:13], v[20:21] op_sel_hi:[1,0]
	v_pk_mul_f32 v[14:15], v[14:15], v[20:21] op_sel_hi:[1,0]
	v_pk_mul_f32 v[8:9], v[8:9], v[20:21] op_sel_hi:[1,0]
	v_pk_mul_f32 v[10:11], v[10:11], v[20:21] op_sel_hi:[1,0]
	v_pk_mul_f32 v[14:15], v[134:135], v[14:15]
	v_pk_mul_f32 v[12:13], v[132:133], v[12:13]
	v_pk_mul_f32 v[16:17], v[130:131], v[10:11]
	v_pk_mul_f32 v[10:11], v[128:129], v[8:9]
	v_cvt_pk_bf16_f32 v8, v12, v13
	v_cvt_pk_bf16_f32 v9, v14, v15
	s_nop 0
	v_cvt_pk_bf16_f32 v10, v10, v11
	v_cvt_pk_bf16_f32 v11, v16, v17
	ds_read_b128 v[12:15], v28 offset:16
	v_lshlrev_b64 v[16:17], 8, v[150:151]
	v_lshl_add_u64 v[18:19], s[16:17], 0, v[16:17]
	s_waitcnt lgkmcnt(0)
	v_mov_b32_e32 v20, v13
	v_mov_b32_e32 v21, v14
	v_mov_b32_e32 v13, v15
	v_pk_add_f32 v[12:13], v[20:21], v[12:13]
	v_lshl_add_u64 v[14:15], v[18:19], 0, s[18:19]
	v_add_f32_e32 v12, v12, v13
	v_fmamk_f32 v12, v12, 0x3c000000, v172
	v_rsq_f32_e32 v12, v12
	v_lshl_add_u64 v[14:15], v[14:15], 0, v[120:121]
	global_store_dwordx4 v[14:15], v[8:11], off
	v_pk_mul_f32 v[4:5], v[4:5], v[12:13] op_sel_hi:[1,0]
	v_pk_mul_f32 v[6:7], v[6:7], v[12:13] op_sel_hi:[1,0]
	v_pk_mul_f32 v[4:5], v[132:133], v[4:5]
	v_pk_mul_f32 v[0:1], v[0:1], v[12:13] op_sel_hi:[1,0]
	v_pk_mul_f32 v[2:3], v[2:3], v[12:13] op_sel_hi:[1,0]
	v_lshl_add_u64 v[132:133], s[12:13], 0, v[16:17]
	v_pk_mul_f32 v[6:7], v[134:135], v[6:7]
	v_pk_mul_f32 v[2:3], v[130:131], v[2:3]
	v_pk_mul_f32 v[0:1], v[128:129], v[0:1]
	v_cvt_pk_bf16_f32 v128, v4, v5
	v_cvt_pk_bf16_f32 v129, v6, v7
	s_nop 0
	v_cvt_pk_bf16_f32 v130, v0, v1
	v_cvt_pk_bf16_f32 v131, v2, v3

; template <int K> __device__ __forceinline__ float shx(float v) { static_assert(K < 32, "use sum32"); return __int_as_float(__builtin_amdgcn_ds_swizzle(__float_as_int(v), (K << 10) | 0x1f)); }
; __device__ __forceinline__ float sum32(float v) { auto rr = __builtin_amdgcn_permlane32_swap(__float_as_uint(v), __float_as_uint(v), false, false); return __uint_as_float(rr[0]) + __uint_as_float(rr[1]); }
; __device__ __forceinline__ u32x4 pack8(const f32x4& a, const f32x4& b) { u32x4 w; w.x = cvt_pk_bf16(a[0], a[1]); w.y = cvt_pk_bf16(a[2], a[3]); w.z = cvt_pk_bf16(b[0], b[1]); w.w = cvt_pk_bf16(b[2], b[3]); return w; }
;     __device__ __forceinline__ void operator()(const f32x4 (&acc)[2][2][4][2], const Unit& u, int wr, int wc, int fr, int fq) const {
;     ...
;                 for (int bj = 0; bj < 2; ++bj) { const size_t o = row * 2048 + u.pn * BM + bj * HALF + wc * 32 + fq * 8;
;                     f32x4 r0, r1;
;                     if (residb) { const u32x4 w = __builtin_nontemporal_load((const u32x4*)(residb + o));     r0 = (f32x4){__uint_as_float(w.x << 16), __uint_as_float(w.x & 0xffff0000u), __uint_as_float(w.y << 16), __uint_as_float(w.y & 0xffff0000u)};
;                                   r1 = (f32x4){__uint_as_float(w.z << 16), __uint_as_float(w.z & 0xffff0000u), __uint_as_float(w.w << 16), __uint_as_float(w.w & 0xffff0000u)}; }
;                     else { r0 = __builtin_nontemporal_load((const f32x4*)(resid + o)); r1 = __builtin_nontemporal_load((const f32x4*)(resid + o + 4)); }
;                     const f32x4 v0 = r0 + acc[ai][bj][m][0] * sc, v1 = r1 + acc[ai][bj][m][1] * sc;
;                     if (outf) { __builtin_nontemporal_store(v0, (f32x4*)(outf + o)); __builtin_nontemporal_store(v1, (f32x4*)(outf + o + 4)); }
;                     ss += (v0[0] * v0[0] + v0[1] * v0[1]) + (v0[2] * v0[2] + v0[3] * v0[3]) + (v1[0] * v1[0] + v1[1] * v1[1]) + (v1[2] * v1[2] + v1[3] * v1[3]);
;                     if (outb) *(u32x4*)(outb + o) = pack8(v0, v1); }
;                 if (ssq_out) { ss += shx<16>(ss); ss = sum32(ss); if (fq == 0) ssq_out[row * 32 + u.pn * 4 + wc] = ss; }
.LBB0_1741:
	s_ashr_i32 s13, s12, 31
	s_lshl_b64 s[12:13], s[12:13], 8
	v_mov_b32_e32 v144, v149
	v_mov_b32_e32 v154, v148
	s_add_u32 s12, s12, s41
	s_addc_u32 s13, s13, s46
	v_ashrrev_i32_e32 v145, 31, v144
	v_lshl_add_u64 v[144:145], s[12:13], 0, v[144:145]
	s_lshl_b32 s12, s0, 8
	s_ashr_i32 s13, s12, 31
	v_lshlrev_b32_e32 v146, 3, v154
	v_ashrrev_i32_e32 v147, 31, v146
	s_or_b64 s[12:13], s[12:13], s[16:17]
	v_lshl_add_u64 v[146:147], s[12:13], 0, v[146:147]
	v_cmp_eq_u32_e32 vcc, 0, v154
	v_lshlrev_b64 v[154:155], 11, v[144:145]
	v_lshl_add_u64 v[154:155], v[146:147], 0, v[154:155]
	v_lshlrev_b64 v[158:159], 1, v[154:155]
	v_lshl_add_u64 v[160:161], s[54:55], 0, v[158:159]
	global_load_dwordx4 v[154:157], v[160:161], off nt
	s_lshl_b32 s12, s0, 2
	s_ashr_i32 s13, s12, 31
	s_waitcnt vmcnt(0)
	v_lshlrev_b32_e32 v162, 16, v154
	v_and_b32_e32 v163, 0xffff0000, v154
	v_lshlrev_b32_e32 v154, 16, v155
	v_and_b32_e32 v155, 0xffff0000, v155
	v_lshlrev_b32_e32 v164, 16, v156
	v_and_b32_e32 v165, 0xffff0000, v156
	v_lshlrev_b32_e32 v156, 16, v157
	v_and_b32_e32 v157, 0xffff0000, v157
	v_pk_add_f32 v[126:127], v[126:127], v[154:155]
	v_pk_add_f32 v[124:125], v[124:125], v[162:163]
	v_pk_add_f32 v[154:155], v[122:123], v[156:157]
	v_pk_add_f32 v[122:123], v[120:121], v[164:165]
	v_mul_f32_e32 v120, v125, v125
	v_mul_f32_e32 v121, v127, v127
	v_fmac_f32_e32 v120, v124, v124
	v_fmac_f32_e32 v121, v126, v126
	v_add_f32_e32 v120, v120, v121
	v_mul_f32_e32 v121, v123, v123
	v_fmac_f32_e32 v121, v122, v122
	v_add_f32_e32 v120, v121, v120
	v_mul_f32_e32 v121, v155, v155
	v_fmac_f32_e32 v121, v154, v154
	v_add_f32_e32 v156, v121, v120
	v_cvt_pk_bf16_f32 v120, v124, v125
	v_cvt_pk_bf16_f32 v121, v126, v127
	v_cvt_pk_bf16_f32 v122, v122, v123
	v_cvt_pk_bf16_f32 v123, v154, v155
	v_lshl_add_u64 v[124:125], s[48:49], 0, v[158:159]
	global_store_dwordx4 v[124:125], v[120:123], off
	global_load_dwordx4 v[120:123], v[160:161], off offset:256 nt
	s_waitcnt vmcnt(0)
	v_lshlrev_b32_e32 v126, 16, v120
	v_and_b32_e32 v127, 0xffff0000, v120
	v_lshlrev_b32_e32 v120, 16, v121
	v_and_b32_e32 v121, 0xffff0000, v121
	v_lshlrev_b32_e32 v154, 16, v122
	v_and_b32_e32 v155, 0xffff0000, v122
	v_lshlrev_b32_e32 v122, 16, v123
	v_and_b32_e32 v123, 0xffff0000, v123
	v_pk_add_f32 v[118:119], v[118:119], v[120:121]
	v_pk_add_f32 v[116:117], v[116:117], v[126:127]
	v_pk_add_f32 v[120:121], v[114:115], v[122:123]
	v_pk_add_f32 v[114:115], v[112:113], v[154:155]
	v_mul_f32_e32 v112, v117, v117
	v_mul_f32_e32 v113, v119, v119
	v_fmac_f32_e32 v112, v116, v116
	v_fmac_f32_e32 v113, v118, v118
	v_add_f32_e32 v112, v112, v113
	v_mul_f32_e32 v113, v115, v115
	v_fmac_f32_e32 v113, v114, v114
	v_add_f32_e32 v112, v113, v112
	v_mul_f32_e32 v113, v121, v121
	v_fmac_f32_e32 v113, v120, v120
	v_add_f32_e32 v112, v113, v112
	v_add_f32_e32 v122, v156, v112
	v_cvt_pk_bf16_f32 v112, v116, v117
	v_cvt_pk_bf16_f32 v113, v118, v119
	v_cvt_pk_bf16_f32 v114, v114, v115
	v_cvt_pk_bf16_f32 v115, v120, v121
	global_store_dwordx4 v[124:125], v[112:115], off offset:256
	s_nop 1
	v_mov_b32_e32 v112, v122
	v_mov_b32_e32 v253, v122
	s_nop 1
	v_permlane16_swap_b32_e32 v112, v253
	s_mov_b32 s98, 0xffff
	s_mov_b32 s99, 0xffff
	v_cndmask_b32_e64 v112, v112, v253, s[98:99]
	s_waitcnt lgkmcnt(0)
	v_add_f32_e32 v112, v122, v112
	v_mov_b32_e32 v113, v112
	s_nop 1
	v_permlane32_swap_b32_e32 v112, v113
	s_and_saveexec_b64 s[20:21], vcc
	s_cbranch_execz .LBB0_1743
	v_lshlrev_b64 v[114:115], 7, v[144:145]
	v_lshl_add_u64 v[114:115], s[2:3], 0, v[114:115]
	v_lshl_add_u64 v[114:115], s[12:13], 2, v[114:115]
	s_lshl_b32 s0, s40, 2
	v_lshl_add_u64 v[114:115], v[114:115], 0, s[0:1]
	v_add_f32_e32 v112, v112, v113
	global_store_dword v[114:115], v112, off
.LBB0_1743:
	s_or_b64 exec, exec, s[20:21]
	v_lshl_add_u64 v[112:113], v[144:145], 0, 16
	v_lshlrev_b64 v[114:115], 11, v[112:113]
	v_lshl_add_u64 v[114:115], v[114:115], 0, v[146:147]
	v_lshlrev_b64 v[118:119], 1, v[114:115]
	v_lshl_add_u64 v[120:121], s[54:55], 0, v[118:119]
	global_load_dwordx4 v[114:117], v[120:121], off nt
	v_lshl_add_u64 v[118:119], s[48:49], 0, v[118:119]
	s_waitcnt vmcnt(0)
	v_lshlrev_b32_e32 v122, 16, v114
	v_and_b32_e32 v123, 0xffff0000, v114
	v_lshlrev_b32_e32 v114, 16, v115
	v_and_b32_e32 v115, 0xffff0000, v115
	v_lshlrev_b32_e32 v124, 16, v116
	v_and_b32_e32 v125, 0xffff0000, v116
	v_lshlrev_b32_e32 v116, 16, v117
	v_and_b32_e32 v117, 0xffff0000, v117
	v_pk_add_f32 v[114:115], v[110:111], v[114:115]
	v_pk_add_f32 v[122:123], v[108:109], v[122:123]
	v_pk_add_f32 v[116:117], v[106:107], v[116:117]
	v_pk_add_f32 v[124:125], v[104:105], v[124:125]
	v_cvt_pk_bf16_f32 v104, v122, v123
	v_cvt_pk_bf16_f32 v105, v114, v115
	v_mul_f32_e32 v115, v115, v115
	v_cvt_pk_bf16_f32 v106, v124, v125
	v_cvt_pk_bf16_f32 v107, v116, v117
	global_load_dwordx4 v[108:111], v[120:121], off offset:256 nt
	v_mul_f32_e32 v120, v123, v123
	v_mul_f32_e32 v121, v125, v125
	v_fmac_f32_e32 v120, v122, v122
	v_fmac_f32_e32 v115, v114, v114
	v_mul_f32_e32 v117, v117, v117
	v_fmac_f32_e32 v121, v124, v124
	global_store_dwordx4 v[118:119], v[104:107], off
	v_fmac_f32_e32 v117, v116, v116
	s_nop 0
	v_add_f32_e32 v104, v120, v115
	v_add_f32_e32 v104, v121, v104
	v_add_f32_e32 v114, v117, v104
	s_waitcnt vmcnt(1)
	v_lshlrev_b32_e32 v104, 16, v108
	v_and_b32_e32 v105, 0xffff0000, v108
	v_lshlrev_b32_e32 v106, 16, v109
	v_and_b32_e32 v107, 0xffff0000, v109
	v_lshlrev_b32_e32 v108, 16, v110
	v_and_b32_e32 v109, 0xffff0000, v110
	v_lshlrev_b32_e32 v110, 16, v111
	v_and_b32_e32 v111, 0xffff0000, v111
	v_pk_add_f32 v[102:103], v[102:103], v[106:107]
	v_pk_add_f32 v[100:101], v[100:101], v[104:105]
	v_pk_add_f32 v[104:105], v[98:99], v[110:111]
	v_pk_add_f32 v[98:99], v[96:97], v[108:109]
	v_mul_f32_e32 v97, v101, v101
	v_mul_f32_e32 v106, v103, v103
	v_mul_f32_e32 v107, v99, v99
	v_fmac_f32_e32 v97, v100, v100
	v_fmac_f32_e32 v106, v102, v102
	v_mul_f32_e32 v108, v105, v105
	v_fmac_f32_e32 v107, v98, v98
	v_add_f32_e32 v97, v97, v106
	v_fmac_f32_e32 v108, v104, v104
	v_add_f32_e32 v97, v107, v97
	v_add_f32_e32 v97, v108, v97
	v_cvt_pk_bf16_f32 v96, v100, v101
	v_add_f32_e32 v100, v114, v97
	s_nop 1
	v_mov_b32_e32 v101, v100
	v_mov_b32_e32 v253, v100
	s_nop 1
	v_permlane16_swap_b32_e32 v101, v253
	s_mov_b32 s98, 0xffff
	s_mov_b32 s99, 0xffff
	v_cndmask_b32_e64 v101, v101, v253, s[98:99]
	v_cvt_pk_bf16_f32 v97, v102, v103
	v_cvt_pk_bf16_f32 v98, v98, v99
	v_cvt_pk_bf16_f32 v99, v104, v105
	global_store_dwordx4 v[118:119], v[96:99], off offset:256
	s_waitcnt lgkmcnt(0)
	s_nop 0
	v_add_f32_e32 v96, v100, v101
	v_mov_b32_e32 v97, v96
	s_nop 1
	v_permlane32_swap_b32_e32 v96, v97
	s_and_saveexec_b64 s[20:21], vcc
	s_cbranch_execz .LBB0_1745
	v_lshlrev_b64 v[98:99], 7, v[112:113]
	v_lshl_add_u64 v[98:99], s[2:3], 0, v[98:99]
	v_lshl_add_u64 v[98:99], s[12:13], 2, v[98:99]
	s_lshl_b32 s0, s40, 2
	v_lshl_add_u64 v[98:99], v[98:99], 0, s[0:1]
	v_add_f32_e32 v96, v96, v97
	global_store_dword v[98:99], v96, off
; template <int K> __device__ __forceinline__ float shx(float v) { static_assert(K < 32, "use sum32"); return __int_as_float(__builtin_amdgcn_ds_swizzle(__float_as_int(v), (K << 10) | 0x1f)); }
; __device__ __forceinline__ float sum32(float v) { auto rr = __builtin_amdgcn_permlane32_swap(__float_as_uint(v), __float_as_uint(v), false, false); return __uint_as_float(rr[0]) + __uint_as_float(rr[1]); }
; __device__ __forceinline__ u32x4 pack8(const f32x4& a, const f32x4& b) { u32x4 w; w.x = cvt_pk_bf16(a[0], a[1]); w.y = cvt_pk_bf16(a[2], a[3]); w.z = cvt_pk_bf16(b[0], b[1]); w.w = cvt_pk_bf16(b[2], b[3]); return w; }
;     __device__ __forceinline__ void operator()(const f32x4 (&acc)[2][2][4][2], const Unit& u, int wr, int wc, int fr, int fq) const {
;     ...
;                 for (int bj = 0; bj < 2; ++bj) { const size_t o = row * 2048 + u.pn * BM + bj * HALF + wc * 32 + fq * 8;
;                     f32x4 r0, r1;
;                     if (residb) { const u32x4 w = __builtin_nontemporal_load((const u32x4*)(residb + o));     r0 = (f32x4){__uint_as_float(w.x << 16), __uint_as_float(w.x & 0xffff0000u), __uint_as_float(w.y << 16), __uint_as_float(w.y & 0xffff0000u)};
;                                   r1 = (f32x4){__uint_as_float(w.z << 16), __uint_as_float(w.z & 0xffff0000u), __uint_as_float(w.w << 16), __uint_as_float(w.w & 0xffff0000u)}; }
;                     else { r0 = __builtin_nontemporal_load((const f32x4*)(resid + o)); r1 = __builtin_nontemporal_load((const f32x4*)(resid + o + 4)); }
;                     const f32x4 v0 = r0 + acc[ai][bj][m][0] * sc, v1 = r1 + acc[ai][bj][m][1] * sc;
;                     if (outf) { __builtin_nontemporal_store(v0, (f32x4*)(outf + o)); __builtin_nontemporal_store(v1, (f32x4*)(outf + o + 4)); }
;                     ss += (v0[0] * v0[0] + v0[1] * v0[1]) + (v0[2] * v0[2] + v0[3] * v0[3]) + (v1[0] * v1[0] + v1[1] * v1[1]) + (v1[2] * v1[2] + v1[3] * v1[3]);
;                     if (outb) *(u32x4*)(outb + o) = pack8(v0, v1); }
;                 if (ssq_out) { ss += shx<16>(ss); ss = sum32(ss); if (fq == 0) ssq_out[row * 32 + u.pn * 4 + wc] = ss; }
.LBB0_1745:
	s_or_b64 exec, exec, s[20:21]
	v_lshl_add_u64 v[96:97], v[144:145], 0, 32
	v_lshlrev_b64 v[98:99], 11, v[96:97]
	v_lshl_add_u64 v[98:99], v[98:99], 0, v[146:147]
	v_lshlrev_b64 v[102:103], 1, v[98:99]
	v_lshl_add_u64 v[104:105], s[54:55], 0, v[102:103]
	global_load_dwordx4 v[98:101], v[104:105], off nt
	v_lshl_add_u64 v[102:103], s[48:49], 0, v[102:103]
	s_waitcnt vmcnt(0)
	v_lshlrev_b32_e32 v106, 16, v98
	v_and_b32_e32 v107, 0xffff0000, v98
	v_lshlrev_b32_e32 v98, 16, v99
	v_and_b32_e32 v99, 0xffff0000, v99
	v_lshlrev_b32_e32 v108, 16, v100
	v_and_b32_e32 v109, 0xffff0000, v100
	v_lshlrev_b32_e32 v100, 16, v101
	v_and_b32_e32 v101, 0xffff0000, v101
	v_pk_add_f32 v[98:99], v[94:95], v[98:99]
	v_pk_add_f32 v[106:107], v[92:93], v[106:107]
	v_pk_add_f32 v[100:101], v[90:91], v[100:101]
	v_pk_add_f32 v[108:109], v[88:89], v[108:109]
	v_cvt_pk_bf16_f32 v88, v106, v107
	v_cvt_pk_bf16_f32 v89, v98, v99
	v_mul_f32_e32 v99, v99, v99
	v_cvt_pk_bf16_f32 v90, v108, v109
	v_cvt_pk_bf16_f32 v91, v100, v101
	global_load_dwordx4 v[92:95], v[104:105], off offset:256 nt
	v_mul_f32_e32 v104, v107, v107
	v_mul_f32_e32 v105, v109, v109
	v_fmac_f32_e32 v104, v106, v106
	v_fmac_f32_e32 v99, v98, v98
	v_mul_f32_e32 v101, v101, v101
	v_fmac_f32_e32 v105, v108, v108
	global_store_dwordx4 v[102:103], v[88:91], off
	v_fmac_f32_e32 v101, v100, v100
	s_nop 0
	v_add_f32_e32 v88, v104, v99
	v_add_f32_e32 v88, v105, v88
	v_add_f32_e32 v98, v101, v88
	s_waitcnt vmcnt(1)
	v_lshlrev_b32_e32 v88, 16, v92
	v_and_b32_e32 v89, 0xffff0000, v92
	v_lshlrev_b32_e32 v90, 16, v93
	v_and_b32_e32 v91, 0xffff0000, v93
	v_lshlrev_b32_e32 v92, 16, v94
	v_and_b32_e32 v93, 0xffff0000, v94
	v_lshlrev_b32_e32 v94, 16, v95
	v_and_b32_e32 v95, 0xffff0000, v95
	v_pk_add_f32 v[86:87], v[86:87], v[90:91]
	v_pk_add_f32 v[84:85], v[84:85], v[88:89]
	v_pk_add_f32 v[88:89], v[82:83], v[94:95]
	v_pk_add_f32 v[82:83], v[80:81], v[92:93]
	v_mul_f32_e32 v81, v85, v85
	v_mul_f32_e32 v90, v87, v87
	v_mul_f32_e32 v91, v83, v83
	v_fmac_f32_e32 v81, v84, v84
	v_fmac_f32_e32 v90, v86, v86
	v_mul_f32_e32 v92, v89, v89
	v_fmac_f32_e32 v91, v82, v82
	v_add_f32_e32 v81, v81, v90
	v_fmac_f32_e32 v92, v88, v88
	v_add_f32_e32 v81, v91, v81
	v_add_f32_e32 v81, v92, v81
	v_cvt_pk_bf16_f32 v80, v84, v85
	v_add_f32_e32 v84, v98, v81
	s_nop 1
	v_mov_b32_e32 v85, v84
	v_mov_b32_e32 v253, v84
	s_nop 1
	v_permlane16_swap_b32_e32 v85, v253
	s_mov_b32 s98, 0xffff
	s_mov_b32 s99, 0xffff
	v_cndmask_b32_e64 v85, v85, v253, s[98:99]
	v_cvt_pk_bf16_f32 v81, v86, v87
	v_cvt_pk_bf16_f32 v82, v82, v83
	v_cvt_pk_bf16_f32 v83, v88, v89
	global_store_dwordx4 v[102:103], v[80:83], off offset:256
	s_waitcnt lgkmcnt(0)
	s_nop 0
	v_add_f32_e32 v80, v84, v85
	v_mov_b32_e32 v81, v80
	s_nop 1
	v_permlane32_swap_b32_e32 v80, v81
	s_and_saveexec_b64 s[20:21], vcc
	s_cbranch_execz .LBB0_1747
	v_lshlrev_b64 v[82:83], 7, v[96:97]
	v_lshl_add_u64 v[82:83], s[2:3], 0, v[82:83]
	v_lshl_add_u64 v[82:83], s[12:13], 2, v[82:83]
	s_lshl_b32 s0, s40, 2
	v_lshl_add_u64 v[82:83], v[82:83], 0, s[0:1]
	v_add_f32_e32 v80, v80, v81
	global_store_dword v[82:83], v80, off
.LBB0_1747:
	s_or_b64 exec, exec, s[20:21]
	v_lshl_add_u64 v[80:81], v[144:145], 0, 48
	v_lshlrev_b64 v[82:83], 11, v[80:81]
	v_lshl_add_u64 v[82:83], v[82:83], 0, v[146:147]
	v_lshlrev_b64 v[86:87], 1, v[82:83]
	v_lshl_add_u64 v[88:89], s[54:55], 0, v[86:87]
	global_load_dwordx4 v[82:85], v[88:89], off nt
	v_lshl_add_u64 v[86:87], s[48:49], 0, v[86:87]
	s_waitcnt vmcnt(0)
	v_lshlrev_b32_e32 v90, 16, v82
	v_and_b32_e32 v91, 0xffff0000, v82
	v_lshlrev_b32_e32 v82, 16, v83
	v_and_b32_e32 v83, 0xffff0000, v83
	v_lshlrev_b32_e32 v92, 16, v84
	v_and_b32_e32 v93, 0xffff0000, v84
	v_lshlrev_b32_e32 v84, 16, v85
	v_and_b32_e32 v85, 0xffff0000, v85
	v_pk_add_f32 v[82:83], v[78:79], v[82:83]
	v_pk_add_f32 v[90:91], v[76:77], v[90:91]
	v_pk_add_f32 v[84:85], v[74:75], v[84:85]
	v_pk_add_f32 v[92:93], v[72:73], v[92:93]
	v_cvt_pk_bf16_f32 v72, v90, v91
	v_cvt_pk_bf16_f32 v73, v82, v83
	v_mul_f32_e32 v83, v83, v83
	v_cvt_pk_bf16_f32 v74, v92, v93
	v_cvt_pk_bf16_f32 v75, v84, v85
	global_load_dwordx4 v[76:79], v[88:89], off offset:256 nt
	v_mul_f32_e32 v88, v91, v91
	v_mul_f32_e32 v89, v93, v93
	v_fmac_f32_e32 v88, v90, v90
	v_fmac_f32_e32 v83, v82, v82
	v_mul_f32_e32 v85, v85, v85
	v_fmac_f32_e32 v89, v92, v92
	global_store_dwordx4 v[86:87], v[72:75], off
	v_fmac_f32_e32 v85, v84, v84
	s_nop 0
	v_add_f32_e32 v72, v88, v83
	v_add_f32_e32 v72, v89, v72
	v_add_f32_e32 v82, v85, v72
	s_waitcnt vmcnt(1)
	v_lshlrev_b32_e32 v72, 16, v76
	v_and_b32_e32 v73, 0xffff0000, v76
	v_lshlrev_b32_e32 v74, 16, v77
	v_and_b32_e32 v75, 0xffff0000, v77
	v_lshlrev_b32_e32 v76, 16, v78
	v_and_b32_e32 v77, 0xffff0000, v78
	v_lshlrev_b32_e32 v78, 16, v79
	v_and_b32_e32 v79, 0xffff0000, v79
	v_pk_add_f32 v[70:71], v[70:71], v[74:75]
	v_pk_add_f32 v[68:69], v[68:69], v[72:73]
	v_pk_add_f32 v[72:73], v[66:67], v[78:79]
	v_pk_add_f32 v[66:67], v[64:65], v[76:77]
	v_mul_f32_e32 v65, v69, v69
	v_mul_f32_e32 v74, v71, v71
	v_mul_f32_e32 v75, v67, v67
	v_fmac_f32_e32 v65, v68, v68
	v_fmac_f32_e32 v74, v70, v70
	v_mul_f32_e32 v76, v73, v73
	v_fmac_f32_e32 v75, v66, v66
	v_add_f32_e32 v65, v65, v74
	v_fmac_f32_e32 v76, v72, v72
	v_add_f32_e32 v65, v75, v65
	v_add_f32_e32 v65, v76, v65
	v_cvt_pk_bf16_f32 v64, v68, v69
	v_add_f32_e32 v68, v82, v65
	s_nop 1
	v_mov_b32_e32 v69, v68
	v_mov_b32_e32 v253, v68
	s_nop 1
	v_permlane16_swap_b32_e32 v69, v253
	s_mov_b32 s98, 0xffff
	s_mov_b32 s99, 0xffff
	v_cndmask_b32_e64 v69, v69, v253, s[98:99]
	v_cvt_pk_bf16_f32 v65, v70, v71
	v_cvt_pk_bf16_f32 v66, v66, v67
	v_cvt_pk_bf16_f32 v67, v72, v73
	global_store_dwordx4 v[86:87], v[64:67], off offset:256
	s_waitcnt lgkmcnt(0)
	s_nop 0
	v_add_f32_e32 v64, v68, v69
	v_mov_b32_e32 v65, v64
	s_nop 1
	v_permlane32_swap_b32_e32 v64, v65
	s_and_saveexec_b64 s[20:21], vcc
	s_cbranch_execz .LBB0_1749
	v_lshlrev_b64 v[66:67], 7, v[80:81]
	v_lshl_add_u64 v[66:67], s[2:3], 0, v[66:67]
	v_lshl_add_u64 v[66:67], s[12:13], 2, v[66:67]
	s_lshl_b32 s0, s40, 2
	v_lshl_add_u64 v[66:67], v[66:67], 0, s[0:1]
	v_add_f32_e32 v64, v64, v65
	global_store_dword v[66:67], v64, off
; template <int K> __device__ __forceinline__ float shx(float v) { static_assert(K < 32, "use sum32"); return __int_as_float(__builtin_amdgcn_ds_swizzle(__float_as_int(v), (K << 10) | 0x1f)); }
; __device__ __forceinline__ float sum32(float v) { auto rr = __builtin_amdgcn_permlane32_swap(__float_as_uint(v), __float_as_uint(v), false, false); return __uint_as_float(rr[0]) + __uint_as_float(rr[1]); }
;     __device__ __forceinline__ void operator()(const f32x4 (&acc)[2][2][4][2], const Unit& u, int wr, int wc, int fr, int fq) const {
;     ...
;             for (int m = 0; m < 4; ++m) { const size_t row = (size_t)u.pm * BM + ai * HALF + wr * 64 + m * 16 + fr;
;                 float sc = 1.f; if (MID) sc = __builtin_amdgcn_rsqf(sum_f(ssql + row * 8, 2) * (1.0f / 1024.0f) + RMS_EPS);
;                 float ss = 0.f;
; #pragma unroll
;                 for (int bj = 0; bj < 2; ++bj) { const size_t o = row * 2048 + u.pn * BM + bj * HALF + wc * 32 + fq * 8;
;                     f32x4 r0, r1;
;                     if (residb) { const u32x4 w = __builtin_nontemporal_load((const u32x4*)(residb + o));     r0 = (f32x4){__uint_as_float(w.x << 16), __uint_as_float(w.x & 0xffff0000u), __uint_as_float(w.y << 16), __uint_as_float(w.y & 0xffff0000u)};
;                                   r1 = (f32x4){__uint_as_float(w.z << 16), __uint_as_float(w.z & 0xffff0000u), __uint_as_float(w.w << 16), __uint_as_float(w.w & 0xffff0000u)}; }
;                     else { r0 = __builtin_nontemporal_load((const f32x4*)(resid + o)); r1 = __builtin_nontemporal_load((const f32x4*)(resid + o + 4)); }
;                     const f32x4 v0 = r0 + acc[ai][bj][m][0] * sc, v1 = r1 + acc[ai][bj][m][1] * sc;
;                     if (outf) { __builtin_nontemporal_store(v0, (f32x4*)(outf + o)); __builtin_nontemporal_store(v1, (f32x4*)(outf + o + 4)); }
;                     ss += (v0[0] * v0[0] + v0[1] * v0[1]) + (v0[2] * v0[2] + v0[3] * v0[3]) + (v1[0] * v1[0] + v1[1] * v1[1]) + (v1[2] * v1[2] + v1[3] * v1[3]);
;                     if (outb) *(u32x4*)(outb + o) = pack8(v0, v1); }
;                 if (ssq_out) { ss += shx<16>(ss); ss = sum32(ss); if (fq == 0) ssq_out[row * 32 + u.pn * 4 + wc] = ss; }
;                 __builtin_amdgcn_sched_barrier(0); }
.LBB0_1749:
	s_or_b64 exec, exec, s[20:21]
	v_lshl_add_u64 v[64:65], v[144:145], 0, s[18:19]
	v_lshlrev_b64 v[66:67], 11, v[64:65]
	v_lshl_add_u64 v[66:67], v[66:67], 0, v[146:147]
	v_lshlrev_b64 v[70:71], 1, v[66:67]
	v_lshl_add_u64 v[72:73], s[54:55], 0, v[70:71]
	global_load_dwordx4 v[66:69], v[72:73], off nt
	v_lshl_add_u64 v[70:71], s[48:49], 0, v[70:71]
	s_waitcnt vmcnt(0)
	v_lshlrev_b32_e32 v74, 16, v66
	v_and_b32_e32 v75, 0xffff0000, v66
	v_lshlrev_b32_e32 v66, 16, v67
	v_and_b32_e32 v67, 0xffff0000, v67
	v_lshlrev_b32_e32 v76, 16, v68
	v_and_b32_e32 v77, 0xffff0000, v68
	v_lshlrev_b32_e32 v68, 16, v69
	v_and_b32_e32 v69, 0xffff0000, v69
	v_pk_add_f32 v[66:67], v[62:63], v[66:67]
	v_pk_add_f32 v[74:75], v[60:61], v[74:75]
	v_pk_add_f32 v[68:69], v[58:59], v[68:69]
	v_pk_add_f32 v[76:77], v[56:57], v[76:77]
	v_cvt_pk_bf16_f32 v56, v74, v75
	v_cvt_pk_bf16_f32 v57, v66, v67
	v_mul_f32_e32 v67, v67, v67
	v_cvt_pk_bf16_f32 v58, v76, v77
	v_cvt_pk_bf16_f32 v59, v68, v69
	global_load_dwordx4 v[60:63], v[72:73], off offset:256 nt
	v_mul_f32_e32 v72, v75, v75
	v_mul_f32_e32 v73, v77, v77
	v_fmac_f32_e32 v72, v74, v74
	v_fmac_f32_e32 v67, v66, v66
	v_mul_f32_e32 v69, v69, v69
	v_fmac_f32_e32 v73, v76, v76
	global_store_dwordx4 v[70:71], v[56:59], off
	v_fmac_f32_e32 v69, v68, v68
	s_nop 0
	v_add_f32_e32 v56, v72, v67
	v_add_f32_e32 v56, v73, v56
	v_add_f32_e32 v66, v69, v56
	s_waitcnt vmcnt(1)
	v_lshlrev_b32_e32 v56, 16, v60
	v_and_b32_e32 v57, 0xffff0000, v60
	v_lshlrev_b32_e32 v58, 16, v61
	v_and_b32_e32 v59, 0xffff0000, v61
	v_lshlrev_b32_e32 v60, 16, v62
	v_and_b32_e32 v61, 0xffff0000, v62
	v_lshlrev_b32_e32 v62, 16, v63
	v_and_b32_e32 v63, 0xffff0000, v63
	v_pk_add_f32 v[54:55], v[54:55], v[58:59]
	v_pk_add_f32 v[52:53], v[52:53], v[56:57]
	v_pk_add_f32 v[56:57], v[50:51], v[62:63]
	v_pk_add_f32 v[50:51], v[48:49], v[60:61]
	v_mul_f32_e32 v49, v53, v53
	v_mul_f32_e32 v58, v55, v55
	v_mul_f32_e32 v59, v51, v51
	v_fmac_f32_e32 v49, v52, v52
	v_fmac_f32_e32 v58, v54, v54
	v_mul_f32_e32 v60, v57, v57
	v_fmac_f32_e32 v59, v50, v50
	v_add_f32_e32 v49, v49, v58
	v_fmac_f32_e32 v60, v56, v56
	v_add_f32_e32 v49, v59, v49
	v_add_f32_e32 v49, v60, v49
	v_cvt_pk_bf16_f32 v48, v52, v53
	v_add_f32_e32 v52, v66, v49
	s_nop 1
	v_mov_b32_e32 v53, v52
	v_mov_b32_e32 v253, v52
	s_nop 1
	v_permlane16_swap_b32_e32 v53, v253
	s_mov_b32 s98, 0xffff
	s_mov_b32 s99, 0xffff
	v_cndmask_b32_e64 v53, v53, v253, s[98:99]
	v_cvt_pk_bf16_f32 v49, v54, v55
	v_cvt_pk_bf16_f32 v50, v50, v51
	v_cvt_pk_bf16_f32 v51, v56, v57
	global_store_dwordx4 v[70:71], v[48:51], off offset:256
	s_waitcnt lgkmcnt(0)
	s_nop 0
	v_add_f32_e32 v48, v52, v53
	v_mov_b32_e32 v49, v48
	s_nop 1
	v_permlane32_swap_b32_e32 v48, v49
	s_and_saveexec_b64 s[20:21], vcc
	s_cbranch_execz .LBB0_1751
	v_lshlrev_b64 v[50:51], 7, v[64:65]
	v_lshl_add_u64 v[50:51], s[2:3], 0, v[50:51]
	v_lshl_add_u64 v[50:51], s[12:13], 2, v[50:51]
	s_lshl_b32 s0, s40, 2
	v_lshl_add_u64 v[50:51], v[50:51], 0, s[0:1]
	v_add_f32_e32 v48, v48, v49
	global_store_dword v[50:51], v48, off
.LBB0_1751:
	s_or_b64 exec, exec, s[20:21]
	s_mov_b64 s[20:21], 0x90
	v_lshl_add_u64 v[48:49], v[144:145], 0, s[20:21]
	v_lshlrev_b64 v[50:51], 11, v[48:49]
	v_lshl_add_u64 v[50:51], v[50:51], 0, v[146:147]
	v_lshlrev_b64 v[54:55], 1, v[50:51]
	v_lshl_add_u64 v[56:57], s[54:55], 0, v[54:55]
	global_load_dwordx4 v[50:53], v[56:57], off nt
	v_lshl_add_u64 v[54:55], s[48:49], 0, v[54:55]
	s_waitcnt vmcnt(0)
	v_lshlrev_b32_e32 v58, 16, v50
	v_and_b32_e32 v59, 0xffff0000, v50
	v_lshlrev_b32_e32 v50, 16, v51
	v_and_b32_e32 v51, 0xffff0000, v51
	v_lshlrev_b32_e32 v60, 16, v52
	v_and_b32_e32 v61, 0xffff0000, v52
	v_lshlrev_b32_e32 v52, 16, v53
	v_and_b32_e32 v53, 0xffff0000, v53
	v_pk_add_f32 v[50:51], v[46:47], v[50:51]
	v_pk_add_f32 v[58:59], v[44:45], v[58:59]
	v_pk_add_f32 v[52:53], v[42:43], v[52:53]
	v_pk_add_f32 v[60:61], v[40:41], v[60:61]
	v_cvt_pk_bf16_f32 v40, v58, v59
	v_cvt_pk_bf16_f32 v41, v50, v51
	v_mul_f32_e32 v51, v51, v51
	v_cvt_pk_bf16_f32 v42, v60, v61
	v_cvt_pk_bf16_f32 v43, v52, v53
	global_load_dwordx4 v[44:47], v[56:57], off offset:256 nt
	v_mul_f32_e32 v56, v59, v59
	v_mul_f32_e32 v57, v61, v61
	v_fmac_f32_e32 v56, v58, v58
	v_fmac_f32_e32 v51, v50, v50
	v_mul_f32_e32 v53, v53, v53
	v_fmac_f32_e32 v57, v60, v60
	global_store_dwordx4 v[54:55], v[40:43], off
	v_fmac_f32_e32 v53, v52, v52
	s_nop 0
	v_add_f32_e32 v40, v56, v51
	v_add_f32_e32 v40, v57, v40
	v_add_f32_e32 v50, v53, v40
	s_waitcnt vmcnt(1)
	v_lshlrev_b32_e32 v40, 16, v44
	v_and_b32_e32 v41, 0xffff0000, v44
	v_lshlrev_b32_e32 v42, 16, v45
	v_and_b32_e32 v43, 0xffff0000, v45
	v_lshlrev_b32_e32 v44, 16, v46
	v_and_b32_e32 v45, 0xffff0000, v46
	v_lshlrev_b32_e32 v46, 16, v47
	v_and_b32_e32 v47, 0xffff0000, v47
	v_pk_add_f32 v[38:39], v[38:39], v[42:43]
	v_pk_add_f32 v[36:37], v[36:37], v[40:41]
	v_pk_add_f32 v[40:41], v[34:35], v[46:47]
	v_pk_add_f32 v[34:35], v[32:33], v[44:45]
	v_mul_f32_e32 v33, v37, v37
	v_mul_f32_e32 v42, v39, v39
	v_mul_f32_e32 v43, v35, v35
	v_fmac_f32_e32 v33, v36, v36
	v_fmac_f32_e32 v42, v38, v38
	v_mul_f32_e32 v44, v41, v41
	v_fmac_f32_e32 v43, v34, v34
	v_add_f32_e32 v33, v33, v42
	v_fmac_f32_e32 v44, v40, v40
	v_add_f32_e32 v33, v43, v33
	v_add_f32_e32 v33, v44, v33
	v_cvt_pk_bf16_f32 v32, v36, v37
	v_add_f32_e32 v36, v50, v33
	s_nop 1
	v_mov_b32_e32 v37, v36
	v_mov_b32_e32 v253, v36
	s_nop 1
	v_permlane16_swap_b32_e32 v37, v253
	s_mov_b32 s98, 0xffff
	s_mov_b32 s99, 0xffff
	v_cndmask_b32_e64 v37, v37, v253, s[98:99]
	v_cvt_pk_bf16_f32 v33, v38, v39
	v_cvt_pk_bf16_f32 v34, v34, v35
	v_cvt_pk_bf16_f32 v35, v40, v41
	global_store_dwordx4 v[54:55], v[32:35], off offset:256
	s_waitcnt lgkmcnt(0)
	s_nop 0
	v_add_f32_e32 v32, v36, v37
	v_mov_b32_e32 v33, v32
	s_nop 1
	v_permlane32_swap_b32_e32 v32, v33
	s_and_saveexec_b64 s[20:21], vcc
	s_cbranch_execz .LBB0_1753
	v_lshlrev_b64 v[34:35], 7, v[48:49]
	v_lshl_add_u64 v[34:35], s[2:3], 0, v[34:35]
	v_lshl_add_u64 v[34:35], s[12:13], 2, v[34:35]
	s_lshl_b32 s0, s40, 2
	v_lshl_add_u64 v[34:35], v[34:35], 0, s[0:1]
	v_add_f32_e32 v32, v32, v33
	global_store_dword v[34:35], v32, off
; template <int K> __device__ __forceinline__ float shx(float v) { static_assert(K < 32, "use sum32"); return __int_as_float(__builtin_amdgcn_ds_swizzle(__float_as_int(v), (K << 10) | 0x1f)); }
; __device__ __forceinline__ float sum32(float v) { auto rr = __builtin_amdgcn_permlane32_swap(__float_as_uint(v), __float_as_uint(v), false, false); return __uint_as_float(rr[0]) + __uint_as_float(rr[1]); }
;     __device__ __forceinline__ void operator()(const f32x4 (&acc)[2][2][4][2], const Unit& u, int wr, int wc, int fr, int fq) const {
;     ...
;             for (int m = 0; m < 4; ++m) { const size_t row = (size_t)u.pm * BM + ai * HALF + wr * 64 + m * 16 + fr;
;                 float sc = 1.f; if (MID) sc = __builtin_amdgcn_rsqf(sum_f(ssql + row * 8, 2) * (1.0f / 1024.0f) + RMS_EPS);
;                 float ss = 0.f;
; #pragma unroll
;                 for (int bj = 0; bj < 2; ++bj) { const size_t o = row * 2048 + u.pn * BM + bj * HALF + wc * 32 + fq * 8;
;                     f32x4 r0, r1;
;                     if (residb) { const u32x4 w = __builtin_nontemporal_load((const u32x4*)(residb + o));     r0 = (f32x4){__uint_as_float(w.x << 16), __uint_as_float(w.x & 0xffff0000u), __uint_as_float(w.y << 16), __uint_as_float(w.y & 0xffff0000u)};
;                                   r1 = (f32x4){__uint_as_float(w.z << 16), __uint_as_float(w.z & 0xffff0000u), __uint_as_float(w.w << 16), __uint_as_float(w.w & 0xffff0000u)}; }
;                     else { r0 = __builtin_nontemporal_load((const f32x4*)(resid + o)); r1 = __builtin_nontemporal_load((const f32x4*)(resid + o + 4)); }
;                     const f32x4 v0 = r0 + acc[ai][bj][m][0] * sc, v1 = r1 + acc[ai][bj][m][1] * sc;
;                     if (outf) { __builtin_nontemporal_store(v0, (f32x4*)(outf + o)); __builtin_nontemporal_store(v1, (f32x4*)(outf + o + 4)); }
;                     ss += (v0[0] * v0[0] + v0[1] * v0[1]) + (v0[2] * v0[2] + v0[3] * v0[3]) + (v1[0] * v1[0] + v1[1] * v1[1]) + (v1[2] * v1[2] + v1[3] * v1[3]);
;                     if (outb) *(u32x4*)(outb + o) = pack8(v0, v1); }
;                 if (ssq_out) { ss += shx<16>(ss); ss = sum32(ss); if (fq == 0) ssq_out[row * 32 + u.pn * 4 + wc] = ss; }
;                 __builtin_amdgcn_sched_barrier(0); }
.LBB0_1753:
	s_or_b64 exec, exec, s[20:21]
	s_mov_b64 s[20:21], 0xa0
	v_lshl_add_u64 v[32:33], v[144:145], 0, s[20:21]
	v_lshlrev_b64 v[34:35], 11, v[32:33]
	v_lshl_add_u64 v[34:35], v[34:35], 0, v[146:147]
	v_lshlrev_b64 v[38:39], 1, v[34:35]
	v_lshl_add_u64 v[40:41], s[54:55], 0, v[38:39]
	global_load_dwordx4 v[34:37], v[40:41], off nt
	v_lshl_add_u64 v[38:39], s[48:49], 0, v[38:39]
	s_waitcnt vmcnt(0)
	v_lshlrev_b32_e32 v42, 16, v34
	v_and_b32_e32 v43, 0xffff0000, v34
	v_lshlrev_b32_e32 v34, 16, v35
	v_and_b32_e32 v35, 0xffff0000, v35
	v_lshlrev_b32_e32 v44, 16, v36
	v_and_b32_e32 v45, 0xffff0000, v36
	v_lshlrev_b32_e32 v36, 16, v37
	v_and_b32_e32 v37, 0xffff0000, v37
	v_pk_add_f32 v[34:35], v[30:31], v[34:35]
	v_pk_add_f32 v[42:43], v[28:29], v[42:43]
	v_pk_add_f32 v[36:37], v[26:27], v[36:37]
	v_pk_add_f32 v[44:45], v[24:25], v[44:45]
	v_cvt_pk_bf16_f32 v24, v42, v43
	v_cvt_pk_bf16_f32 v25, v34, v35
	v_mul_f32_e32 v35, v35, v35
	v_cvt_pk_bf16_f32 v26, v44, v45
	v_cvt_pk_bf16_f32 v27, v36, v37
	global_load_dwordx4 v[28:31], v[40:41], off offset:256 nt
	v_mul_f32_e32 v40, v43, v43
	v_mul_f32_e32 v41, v45, v45
	v_fmac_f32_e32 v40, v42, v42
	v_fmac_f32_e32 v35, v34, v34
	v_mul_f32_e32 v37, v37, v37
	v_fmac_f32_e32 v41, v44, v44
	global_store_dwordx4 v[38:39], v[24:27], off
	v_fmac_f32_e32 v37, v36, v36
	s_nop 0
	v_add_f32_e32 v24, v40, v35
	v_add_f32_e32 v24, v41, v24
	v_add_f32_e32 v34, v37, v24
	s_waitcnt vmcnt(1)
	v_lshlrev_b32_e32 v24, 16, v28
	v_and_b32_e32 v25, 0xffff0000, v28
	v_lshlrev_b32_e32 v26, 16, v29
	v_and_b32_e32 v27, 0xffff0000, v29
	v_lshlrev_b32_e32 v28, 16, v30
	v_and_b32_e32 v29, 0xffff0000, v30
	v_lshlrev_b32_e32 v30, 16, v31
	v_and_b32_e32 v31, 0xffff0000, v31
	v_pk_add_f32 v[22:23], v[22:23], v[26:27]
	v_pk_add_f32 v[20:21], v[20:21], v[24:25]
	v_pk_add_f32 v[24:25], v[18:19], v[30:31]
	v_pk_add_f32 v[18:19], v[16:17], v[28:29]
	v_mul_f32_e32 v17, v21, v21
	v_mul_f32_e32 v26, v23, v23
	v_mul_f32_e32 v27, v19, v19
	v_fmac_f32_e32 v17, v20, v20
	v_fmac_f32_e32 v26, v22, v22
	v_mul_f32_e32 v28, v25, v25
	v_fmac_f32_e32 v27, v18, v18
	v_add_f32_e32 v17, v17, v26
	v_fmac_f32_e32 v28, v24, v24
	v_add_f32_e32 v17, v27, v17
	v_add_f32_e32 v17, v28, v17
	v_cvt_pk_bf16_f32 v16, v20, v21
	v_add_f32_e32 v20, v34, v17
	s_nop 1
	v_mov_b32_e32 v21, v20
	v_mov_b32_e32 v253, v20
	s_nop 1
	v_permlane16_swap_b32_e32 v21, v253
	s_mov_b32 s98, 0xffff
	s_mov_b32 s99, 0xffff
	v_cndmask_b32_e64 v21, v21, v253, s[98:99]
	v_cvt_pk_bf16_f32 v17, v22, v23
	v_cvt_pk_bf16_f32 v18, v18, v19
	v_cvt_pk_bf16_f32 v19, v24, v25
	global_store_dwordx4 v[38:39], v[16:19], off offset:256
	s_waitcnt lgkmcnt(0)
	s_nop 0
	v_add_f32_e32 v16, v20, v21
	v_mov_b32_e32 v17, v16
	s_nop 1
	v_permlane32_swap_b32_e32 v16, v17
	s_and_saveexec_b64 s[20:21], vcc
	s_cbranch_execz .LBB0_1755
	v_lshlrev_b64 v[18:19], 7, v[32:33]
	v_lshl_add_u64 v[18:19], s[2:3], 0, v[18:19]
	v_lshl_add_u64 v[18:19], s[12:13], 2, v[18:19]
	s_lshl_b32 s0, s40, 2
	v_lshl_add_u64 v[18:19], v[18:19], 0, s[0:1]
	v_add_f32_e32 v16, v16, v17
	global_store_dword v[18:19], v16, off
.LBB0_1755:
	s_or_b64 exec, exec, s[20:21]
	s_mov_b64 s[20:21], 0xb0
	v_lshl_add_u64 v[16:17], v[144:145], 0, s[20:21]
	v_lshlrev_b64 v[18:19], 11, v[16:17]
	v_lshl_add_u64 v[18:19], v[18:19], 0, v[146:147]
	v_lshlrev_b64 v[22:23], 1, v[18:19]
	v_lshl_add_u64 v[24:25], s[54:55], 0, v[22:23]
	global_load_dwordx4 v[18:21], v[24:25], off nt
	v_lshl_add_u64 v[22:23], s[48:49], 0, v[22:23]
	s_waitcnt vmcnt(0)
	v_lshlrev_b32_e32 v26, 16, v18
	v_and_b32_e32 v27, 0xffff0000, v18
	v_lshlrev_b32_e32 v18, 16, v19
	v_and_b32_e32 v19, 0xffff0000, v19
	v_lshlrev_b32_e32 v28, 16, v20
	v_and_b32_e32 v29, 0xffff0000, v20
	v_lshlrev_b32_e32 v20, 16, v21
	v_and_b32_e32 v21, 0xffff0000, v21
	v_pk_add_f32 v[18:19], v[14:15], v[18:19]
	v_pk_add_f32 v[26:27], v[12:13], v[26:27]
	v_pk_add_f32 v[20:21], v[10:11], v[20:21]
	v_pk_add_f32 v[28:29], v[8:9], v[28:29]
	v_cvt_pk_bf16_f32 v8, v26, v27
	v_cvt_pk_bf16_f32 v9, v18, v19
	v_mul_f32_e32 v19, v19, v19
	v_cvt_pk_bf16_f32 v10, v28, v29
	v_cvt_pk_bf16_f32 v11, v20, v21
	global_load_dwordx4 v[12:15], v[24:25], off offset:256 nt
	v_mul_f32_e32 v24, v27, v27
	v_mul_f32_e32 v25, v29, v29
	v_fmac_f32_e32 v24, v26, v26
	v_fmac_f32_e32 v19, v18, v18
	v_mul_f32_e32 v21, v21, v21
	v_fmac_f32_e32 v25, v28, v28
	global_store_dwordx4 v[22:23], v[8:11], off
	v_fmac_f32_e32 v21, v20, v20
	s_nop 0
	v_add_f32_e32 v8, v24, v19
	v_add_f32_e32 v8, v25, v8
	v_add_f32_e32 v18, v21, v8
	s_waitcnt vmcnt(1)
	v_lshlrev_b32_e32 v8, 16, v12
	v_and_b32_e32 v9, 0xffff0000, v12
	v_lshlrev_b32_e32 v10, 16, v13
	v_and_b32_e32 v11, 0xffff0000, v13
	v_lshlrev_b32_e32 v12, 16, v14
	v_and_b32_e32 v13, 0xffff0000, v14
	v_lshlrev_b32_e32 v14, 16, v15
	v_and_b32_e32 v15, 0xffff0000, v15
	v_pk_add_f32 v[6:7], v[6:7], v[10:11]
	v_pk_add_f32 v[4:5], v[4:5], v[8:9]
	v_pk_add_f32 v[8:9], v[2:3], v[14:15]
	v_pk_add_f32 v[2:3], v[0:1], v[12:13]
	v_mul_f32_e32 v1, v5, v5
	v_mul_f32_e32 v10, v7, v7
	v_mul_f32_e32 v11, v3, v3
	v_fmac_f32_e32 v1, v4, v4
	v_fmac_f32_e32 v10, v6, v6
	v_mul_f32_e32 v12, v9, v9
	v_fmac_f32_e32 v11, v2, v2
	v_add_f32_e32 v1, v1, v10
	v_fmac_f32_e32 v12, v8, v8
	v_add_f32_e32 v1, v11, v1
	v_add_f32_e32 v1, v12, v1
	v_cvt_pk_bf16_f32 v0, v4, v5
	v_add_f32_e32 v4, v18, v1
	s_nop 1
	v_mov_b32_e32 v5, v4
	v_mov_b32_e32 v253, v4
	s_nop 1
	v_permlane16_swap_b32_e32 v5, v253
	s_mov_b32 s98, 0xffff
	s_mov_b32 s99, 0xffff
	v_cndmask_b32_e64 v5, v5, v253, s[98:99]
	v_cvt_pk_bf16_f32 v1, v6, v7
	v_cvt_pk_bf16_f32 v2, v2, v3
	v_cvt_pk_bf16_f32 v3, v8, v9
	global_store_dwordx4 v[22:23], v[0:3], off offset:256
	s_waitcnt lgkmcnt(0)
	s_nop 0
	v_add_f32_e32 v0, v4, v5
	v_mov_b32_e32 v1, v0
	s_nop 1
	v_permlane32_swap_b32_e32 v0, v1
	s_and_saveexec_b64 s[20:21], vcc
	s_cbranch_execz .LBB0_1757
	v_lshlrev_b64 v[2:3], 7, v[16:17]
	v_lshl_add_u64 v[2:3], s[2:3], 0, v[2:3]
	v_lshl_add_u64 v[2:3], s[12:13], 2, v[2:3]
	s_lshl_b32 s0, s40, 2
	v_lshl_add_u64 v[2:3], v[2:3], 0, s[0:1]
	v_add_f32_e32 v0, v0, v1
	global_store_dword v[2:3], v0, off
